# GEMM k-loops: the duplicate s_waitcnt lgkmcnt(0) between s_setprio 1 and the first MFMA of each cluster deleted (74 sites)
# baseline (speedup 1.0000x reference)
; #define PG8_STAGE(bufoff, gbase, voff) do { _Pragma("unroll") for (int _i = 0; _i < 2; ++_i) { const char* _gb = (const char*)(gbase) + (size_t)_i * (voff##_q); asm volatile("" : "+s"(_gb)); \
;         __builtin_amdgcn_global_load_lds((const unsigned*)(_gb + (voff)), (LAS unsigned*)(lds + (bufoff) + ldsw + _i * 8192), 16, 0, 0); } } while (0)
; #define PG8_LDA(dst, b, h) do { _Pragma("unroll") for (int m = 0; m < 4; ++m) _Pragma("unroll") for (int k = 0; k < 2; ++k) dst[m][k] = *(const LAS bf16x8*)(lds + PG8_SA(b, h) + aoff + m * 2048 + k * 1024); } while (0)
; #define PG8_LDB(dst, b, h) do { _Pragma("unroll") for (int n = 0; n < 2; ++n) _Pragma("unroll") for (int k = 0; k < 2; ++k) dst[n][k] = *(const LAS bf16x8*)(lds + PG8_SB(b, h) + boff + n * 2048 + k * 1024); } while (0)
; #define PG8_MMA(ai, bj, At, Bt) do { __builtin_amdgcn_s_setprio(1); _Pragma("unroll") for (int m = 0; m < 4; ++m) _Pragma("unroll") for (int n = 0; n < 2; ++n) _Pragma("unroll") for (int k = 0; k < 2; ++k) \
;         acc[ai][bj][m][n] = __builtin_amdgcn_mfma_f32_16x16x32_bf16(Bt[n][k], At[m][k], acc[ai][bj][m][n], 0, 0, 0); __builtin_amdgcn_s_setprio(0); } while (0)
; #define PG8_BAR __builtin_amdgcn_s_barrier()
; template <class Epi, class Sched>
; __device__ __forceinline__ void gemm_phase(int wv, LAS unsigned char* lds, const Gemm g, const Sched& S, const Epi& E) { LIDS
;     ...
;         const bool has_next = S.next(ui + 1, nxt);
;         const char* nA = has_next ? (const char*)g.A + (size_t)nxt.pm * g.tstepA : cA; const char* nB = has_next ? (const char*)g.Bt + (size_t)nxt.pn * g.tstepB : cB;
;         for (int t = 0; t < nt; t += 2) {
;             const bool last = (t == nt - 2);
;             const char* a1 = cA + (size_t)(t + 1) * kstepA;
;             const char* a2 = last ? nA : cA + (size_t)(t + 2) * kstepA; const char* b2 = last ? nB : cB + (size_t)(t + 2) * kstepB;
;             const char* a3 = a2 + kstepA; const char* b3 = b2 + kstepB;
;             asm volatile("" : "+s"(a1), "+s"(a2), "+s"(b2), "+s"(a3), "+s"(b3));
;             PG8_LDB(B0, 0, 0); PG8_SCHED; PG8_LDA(At, 0, 0); PG8_STAGE(PG8_SA(1, 1), a1 + hstepA, voffA);
;             PG8_WAIT_L(8); PG8_BAR; PG8_WAIT_L(0); PG8_MMA(0, 0, At, B0); PG8_BAR; PG8_SCHED;
;             PG8_LDB(B1, 0, 1); PG8_STAGE(PG8_SB(0, 0), b2, voffB);
;             PG8_BAR; PG8_WAIT_L(0); PG8_MMA(0, 1, At, B1); PG8_BAR;
.LBB0_31:
	s_add_u32 s58, s72, 0x80
	s_addc_u32 s59, s73, 0
	s_add_u32 s72, s72, 0x100
	s_addc_u32 s73, s73, 0
	s_cmp_eq_u32 s56, 28
	s_cselect_b32 s84, s31, s72
	s_cselect_b32 s85, s11, s73
	s_cselect_b32 s7, s9, s55
	s_cselect_b32 s6, s52, s53
	s_add_u32 s86, s84, 0x80
	s_addc_u32 s87, s85, 0
	s_add_u32 s78, s6, 0x80
	s_addc_u32 s79, s7, 0
	s_add_i32 s57, 16, 0x10000
	v_add_u32_e32 v133, s57, v131
	ds_read_b128 v[134:137], v133
	ds_read_b128 v[138:141], v133 offset:1024
	ds_read_b128 v[142:145], v133 offset:2048
	ds_read_b128 v[146:149], v133 offset:3072
	s_add_u32 s76, s58, 0x80000
	s_addc_u32 s77, s59, 0
	s_add_i32 m0, s21, 0xc000
	s_add_u32 s58, s58, 0xc0000
	ds_read_b128 v[150:153], v132
	ds_read_b128 v[154:157], v132 offset:1024
	ds_read_b128 v[158:161], v132 offset:2048
	ds_read_b128 v[162:165], v132 offset:3072
	ds_read_b128 v[166:169], v132 offset:4096
	ds_read_b128 v[170:173], v132 offset:5120
	ds_read_b128 v[178:181], v132 offset:6144
	ds_read_b128 v[182:185], v132 offset:7168
	s_addc_u32 s59, s59, 0
	v_lshl_add_u64 v[174:175], s[76:77], 0, v[128:129]
	global_load_lds_dwordx4 v[174:175], off
	s_add_i32 m0, s21, 0xe000
	v_lshl_add_u64 v[174:175], s[58:59], 0, v[128:129]
	global_load_lds_dwordx4 v[174:175], off
	s_waitcnt lgkmcnt(8)
	s_barrier
	s_waitcnt lgkmcnt(0)
	s_setprio 1
	v_mfma_f32_16x16x32_bf16 v[124:127], v[134:137], v[150:153], v[124:127]
	v_mfma_f32_16x16x32_bf16 v[120:123], v[142:145], v[150:153], v[120:123]
	v_mfma_f32_16x16x32_bf16 v[116:119], v[134:137], v[158:161], v[116:119]
	v_mfma_f32_16x16x32_bf16 v[108:111], v[142:145], v[158:161], v[108:111]
	v_mfma_f32_16x16x32_bf16 v[100:103], v[134:137], v[166:169], v[100:103]
	v_mfma_f32_16x16x32_bf16 v[92:95], v[142:145], v[166:169], v[92:95]
	v_mfma_f32_16x16x32_bf16 v[84:87], v[134:137], v[178:181], v[84:87]
	v_mfma_f32_16x16x32_bf16 v[76:79], v[142:145], v[178:181], v[76:79]
	v_mfma_f32_16x16x32_bf16 v[124:127], v[138:141], v[154:157], v[124:127]
	v_mfma_f32_16x16x32_bf16 v[120:123], v[146:149], v[154:157], v[120:123]
	v_mfma_f32_16x16x32_bf16 v[116:119], v[138:141], v[162:165], v[116:119]
	v_mfma_f32_16x16x32_bf16 v[108:111], v[146:149], v[162:165], v[108:111]
	v_mfma_f32_16x16x32_bf16 v[100:103], v[138:141], v[170:173], v[100:103]
	v_mfma_f32_16x16x32_bf16 v[92:95], v[146:149], v[170:173], v[92:95]
	v_mfma_f32_16x16x32_bf16 v[84:87], v[138:141], v[182:185], v[84:87]
	v_mfma_f32_16x16x32_bf16 v[76:79], v[146:149], v[182:185], v[76:79]
	s_setprio 0
	s_barrier
	s_add_i32 s63, 16, 0x14000
	v_add_u32_e32 v133, s63, v131
	s_mov_b64 s[58:59], s[6:7]
	ds_read_b128 v[186:189], v133
	ds_read_b128 v[190:193], v133 offset:1024
	ds_read_b128 v[194:197], v133 offset:2048
	ds_read_b128 v[198:201], v133 offset:3072
	s_add_i32 s57, s57, s20
	v_lshl_add_u64 v[174:175], s[58:59], 0, v[176:177]
	s_add_u32 s58, s6, 0x40000
	s_mov_b32 m0, s57
	s_addc_u32 s59, s7, 0
	global_load_lds_dwordx4 v[174:175], off
	s_add_i32 m0, s57, 0x2000
	v_lshl_add_u64 v[174:175], s[58:59], 0, v[176:177]
	global_load_lds_dwordx4 v[174:175], off
	s_barrier
	s_waitcnt lgkmcnt(0)
	s_setprio 1
	v_mfma_f32_16x16x32_bf16 v[112:115], v[186:189], v[150:153], v[112:115]
	v_mfma_f32_16x16x32_bf16 v[104:107], v[194:197], v[150:153], v[104:107]
	v_mfma_f32_16x16x32_bf16 v[96:99], v[186:189], v[158:161], v[96:99]
	v_mfma_f32_16x16x32_bf16 v[88:91], v[194:197], v[158:161], v[88:91]
	v_mfma_f32_16x16x32_bf16 v[80:83], v[186:189], v[166:169], v[80:83]
	v_mfma_f32_16x16x32_bf16 v[72:75], v[194:197], v[166:169], v[72:75]
	v_mfma_f32_16x16x32_bf16 v[68:71], v[186:189], v[178:181], v[68:71]
	v_mfma_f32_16x16x32_bf16 v[64:67], v[194:197], v[178:181], v[64:67]
	v_mfma_f32_16x16x32_bf16 v[112:115], v[190:193], v[154:157], v[112:115]
	v_mfma_f32_16x16x32_bf16 v[104:107], v[198:201], v[154:157], v[104:107]
	v_mfma_f32_16x16x32_bf16 v[96:99], v[190:193], v[162:165], v[96:99]
	v_mfma_f32_16x16x32_bf16 v[88:91], v[198:201], v[162:165], v[88:91]
	v_mfma_f32_16x16x32_bf16 v[80:83], v[190:193], v[170:173], v[80:83]
	v_mfma_f32_16x16x32_bf16 v[72:75], v[198:201], v[170:173], v[72:75]
	v_mfma_f32_16x16x32_bf16 v[68:71], v[190:193], v[182:185], v[68:71]
	v_mfma_f32_16x16x32_bf16 v[64:67], v[198:201], v[182:185], v[64:67]
	s_setprio 0
	s_mov_b64 s[58:59], s[84:85]
	s_barrier
	ds_read_b128 v[150:153], v132 offset:16384
	ds_read_b128 v[154:157], v132 offset:17408
	ds_read_b128 v[158:161], v132 offset:18432
	ds_read_b128 v[162:165], v132 offset:19456
	ds_read_b128 v[166:169], v132 offset:20480
	ds_read_b128 v[170:173], v132 offset:21504
	ds_read_b128 v[178:181], v132 offset:22528
	ds_read_b128 v[182:185], v132 offset:23552
	s_mov_b32 m0, s21
	v_lshl_add_u64 v[174:175], s[58:59], 0, v[128:129]
	s_add_u32 s58, s84, 0x40000
	s_addc_u32 s59, s85, 0
	global_load_lds_dwordx4 v[174:175], off
	s_mov_b32 m0, s22
	v_lshl_add_u64 v[174:175], s[58:59], 0, v[128:129]
	global_load_lds_dwordx4 v[174:175], off
	s_barrier
	s_waitcnt lgkmcnt(0)
	s_setprio 1
	v_mfma_f32_16x16x32_bf16 v[60:63], v[134:137], v[150:153], v[60:63]
	v_mfma_f32_16x16x32_bf16 v[56:59], v[142:145], v[150:153], v[56:59]
	v_mfma_f32_16x16x32_bf16 v[52:55], v[134:137], v[158:161], v[52:55]
	v_mfma_f32_16x16x32_bf16 v[44:47], v[142:145], v[158:161], v[44:47]
	v_mfma_f32_16x16x32_bf16 v[36:39], v[134:137], v[166:169], v[36:39]
	v_mfma_f32_16x16x32_bf16 v[28:31], v[142:145], v[166:169], v[28:31]
	v_mfma_f32_16x16x32_bf16 v[20:23], v[134:137], v[178:181], v[20:23]
	v_mfma_f32_16x16x32_bf16 v[12:15], v[142:145], v[178:181], v[12:15]
	v_mfma_f32_16x16x32_bf16 v[60:63], v[138:141], v[154:157], v[60:63]
	v_mfma_f32_16x16x32_bf16 v[56:59], v[146:149], v[154:157], v[56:59]
	v_mfma_f32_16x16x32_bf16 v[52:55], v[138:141], v[162:165], v[52:55]
	v_mfma_f32_16x16x32_bf16 v[44:47], v[146:149], v[162:165], v[44:47]
	v_mfma_f32_16x16x32_bf16 v[36:39], v[138:141], v[170:173], v[36:39]
	v_mfma_f32_16x16x32_bf16 v[28:31], v[146:149], v[170:173], v[28:31]
	v_mfma_f32_16x16x32_bf16 v[20:23], v[138:141], v[182:185], v[20:23]
	v_mfma_f32_16x16x32_bf16 v[12:15], v[146:149], v[182:185], v[12:15]
	s_setprio 0
	s_barrier
; #define PG8_STAGE(bufoff, gbase, voff) do { _Pragma("unroll") for (int _i = 0; _i < 2; ++_i) { const char* _gb = (const char*)(gbase) + (size_t)_i * (voff##_q); asm volatile("" : "+s"(_gb)); \
;         __builtin_amdgcn_global_load_lds((const unsigned*)(_gb + (voff)), (LAS unsigned*)(lds + (bufoff) + ldsw + _i * 8192), 16, 0, 0); } } while (0)
; #define PG8_LDA(dst, b, h) do { _Pragma("unroll") for (int m = 0; m < 4; ++m) _Pragma("unroll") for (int k = 0; k < 2; ++k) dst[m][k] = *(const LAS bf16x8*)(lds + PG8_SA(b, h) + aoff + m * 2048 + k * 1024); } while (0)
; #define PG8_LDB(dst, b, h) do { _Pragma("unroll") for (int n = 0; n < 2; ++n) _Pragma("unroll") for (int k = 0; k < 2; ++k) dst[n][k] = *(const LAS bf16x8*)(lds + PG8_SB(b, h) + boff + n * 2048 + k * 1024); } while (0)
; #define PG8_MMA(ai, bj, At, Bt) do { __builtin_amdgcn_s_setprio(1); _Pragma("unroll") for (int m = 0; m < 4; ++m) _Pragma("unroll") for (int n = 0; n < 2; ++n) _Pragma("unroll") for (int k = 0; k < 2; ++k) \
;         acc[ai][bj][m][n] = __builtin_amdgcn_mfma_f32_16x16x32_bf16(Bt[n][k], At[m][k], acc[ai][bj][m][n], 0, 0, 0); __builtin_amdgcn_s_setprio(0); } while (0)
; #define PG8_WAIT_V(n) asm volatile("s_waitcnt vmcnt(" #n ")" ::: "memory")
; #define PG8_WAIT_L(n) asm volatile("s_waitcnt lgkmcnt(" #n ")" ::: "memory")
; #define PG8_BAR __builtin_amdgcn_s_barrier()
; #define PG8_SCHED __builtin_amdgcn_sched_barrier(0)
; template <class Epi, class Sched>
; __device__ __forceinline__ void gemm_phase(int wv, LAS unsigned char* lds, const Gemm g, const Sched& S, const Epi& E) { LIDS
;     ...
;             PG8_STAGE(PG8_SB(0, 1), b2 + hstepB, voffB);
;             PG8_WAIT_V(6); PG8_BAR; PG8_MMA(1, 1, At, B1); PG8_BAR;
;             PG8_LDB(B0, 1, 0); PG8_SCHED; PG8_LDA(At, 1, 0); PG8_STAGE(PG8_SA(0, 1), a2 + hstepA, voffA);
;             PG8_WAIT_L(8); PG8_BAR; PG8_WAIT_L(0); PG8_MMA(0, 0, At, B0); PG8_BAR; PG8_SCHED;
;             PG8_LDB(B1, 1, 1); PG8_STAGE(PG8_SB(1, 0), b3, voffB);
;             PG8_BAR; PG8_WAIT_L(0); PG8_MMA(0, 1, At, B1); PG8_BAR;
;             PG8_LDA(At, 1, 1); PG8_STAGE(PG8_SA(1, 0), a3, voffA);
;             PG8_BAR; PG8_WAIT_L(0); PG8_MMA(1, 0, At, B0); PG8_BAR; PG8_SCHED;
	s_add_u32 s58, s6, 0x80000
	s_addc_u32 s59, s7, 0
	s_add_i32 s57, s63, s20
	s_add_u32 s6, s6, 0xc0000
	s_mov_b32 m0, s57
	v_lshl_add_u64 v[134:135], s[58:59], 0, v[176:177]
	s_addc_u32 s7, s7, 0
	global_load_lds_dwordx4 v[134:135], off
	s_add_i32 m0, s57, 0x2000
	v_lshl_add_u64 v[134:135], s[6:7], 0, v[176:177]
	global_load_lds_dwordx4 v[134:135], off
	s_waitcnt vmcnt(6)
	s_barrier
	s_setprio 1
	v_mfma_f32_16x16x32_bf16 v[48:51], v[186:189], v[150:153], v[48:51]
	v_mfma_f32_16x16x32_bf16 v[40:43], v[194:197], v[150:153], v[40:43]
	v_mfma_f32_16x16x32_bf16 v[32:35], v[186:189], v[158:161], v[32:35]
	v_mfma_f32_16x16x32_bf16 v[24:27], v[194:197], v[158:161], v[24:27]
	v_mfma_f32_16x16x32_bf16 v[16:19], v[186:189], v[166:169], v[16:19]
	v_mfma_f32_16x16x32_bf16 v[8:11], v[194:197], v[166:169], v[8:11]
	v_mfma_f32_16x16x32_bf16 v[4:7], v[186:189], v[178:181], v[4:7]
	v_mfma_f32_16x16x32_bf16 v[0:3], v[194:197], v[178:181], v[0:3]
	v_mfma_f32_16x16x32_bf16 v[48:51], v[190:193], v[154:157], v[48:51]
	v_mfma_f32_16x16x32_bf16 v[40:43], v[198:201], v[154:157], v[40:43]
	v_mfma_f32_16x16x32_bf16 v[32:35], v[190:193], v[162:165], v[32:35]
	v_mfma_f32_16x16x32_bf16 v[24:27], v[198:201], v[162:165], v[24:27]
	v_mfma_f32_16x16x32_bf16 v[16:19], v[190:193], v[170:173], v[16:19]
	v_mfma_f32_16x16x32_bf16 v[8:11], v[198:201], v[170:173], v[8:11]
	v_mfma_f32_16x16x32_bf16 v[4:7], v[190:193], v[182:185], v[4:7]
	v_mfma_f32_16x16x32_bf16 v[0:3], v[198:201], v[182:185], v[0:3]
	s_setprio 0
	s_add_i32 s57, 16, 0x18000
	v_add_u32_e32 v133, s57, v131
	s_barrier
	ds_read_b128 v[134:137], v133
	ds_read_b128 v[138:141], v133 offset:1024
	ds_read_b128 v[142:145], v133 offset:2048
	ds_read_b128 v[146:149], v133 offset:3072
	s_add_u32 s6, s84, 0x80000
	s_addc_u32 s7, s85, 0
	ds_read_b128 v[150:153], v132 offset:32768
	ds_read_b128 v[154:157], v132 offset:33792
	ds_read_b128 v[158:161], v132 offset:34816
	ds_read_b128 v[162:165], v132 offset:35840
	ds_read_b128 v[166:169], v132 offset:36864
	ds_read_b128 v[170:173], v132 offset:37888
	ds_read_b128 v[178:181], v132 offset:38912
	ds_read_b128 v[182:185], v132 offset:39936
	s_mov_b32 m0, s23
	v_lshl_add_u64 v[174:175], s[6:7], 0, v[128:129]
	s_add_u32 s6, s84, 0xc0000
	s_addc_u32 s7, s85, 0
	global_load_lds_dwordx4 v[174:175], off
	s_mov_b32 m0, s24
	v_lshl_add_u64 v[174:175], s[6:7], 0, v[128:129]
	global_load_lds_dwordx4 v[174:175], off
	s_waitcnt lgkmcnt(8)
	s_barrier
	s_waitcnt lgkmcnt(0)
	s_setprio 1
	v_mfma_f32_16x16x32_bf16 v[124:127], v[134:137], v[150:153], v[124:127]
	v_mfma_f32_16x16x32_bf16 v[120:123], v[142:145], v[150:153], v[120:123]
	v_mfma_f32_16x16x32_bf16 v[116:119], v[134:137], v[158:161], v[116:119]
	v_mfma_f32_16x16x32_bf16 v[108:111], v[142:145], v[158:161], v[108:111]
	v_mfma_f32_16x16x32_bf16 v[100:103], v[134:137], v[166:169], v[100:103]
	v_mfma_f32_16x16x32_bf16 v[92:95], v[142:145], v[166:169], v[92:95]
	v_mfma_f32_16x16x32_bf16 v[84:87], v[134:137], v[178:181], v[84:87]
	v_mfma_f32_16x16x32_bf16 v[76:79], v[142:145], v[178:181], v[76:79]
	v_mfma_f32_16x16x32_bf16 v[124:127], v[138:141], v[154:157], v[124:127]
	v_mfma_f32_16x16x32_bf16 v[120:123], v[146:149], v[154:157], v[120:123]
	v_mfma_f32_16x16x32_bf16 v[116:119], v[138:141], v[162:165], v[116:119]
	v_mfma_f32_16x16x32_bf16 v[108:111], v[146:149], v[162:165], v[108:111]
	v_mfma_f32_16x16x32_bf16 v[100:103], v[138:141], v[170:173], v[100:103]
	v_mfma_f32_16x16x32_bf16 v[92:95], v[146:149], v[170:173], v[92:95]
	v_mfma_f32_16x16x32_bf16 v[84:87], v[138:141], v[182:185], v[84:87]
	v_mfma_f32_16x16x32_bf16 v[76:79], v[146:149], v[182:185], v[76:79]
	s_setprio 0
	s_barrier
	s_add_i32 s58, 16, 0x1c000
	v_add_u32_e32 v133, s58, v131
	s_mov_b64 s[6:7], s[78:79]
	ds_read_b128 v[186:189], v133
	ds_read_b128 v[190:193], v133 offset:1024
	ds_read_b128 v[194:197], v133 offset:2048
	ds_read_b128 v[198:201], v133 offset:3072
	s_add_i32 s57, s57, s20
	v_lshl_add_u64 v[174:175], s[6:7], 0, v[176:177]
	s_add_u32 s6, s78, 0x40000
	s_mov_b32 m0, s57
	s_addc_u32 s7, s79, 0
	global_load_lds_dwordx4 v[174:175], off
	s_add_i32 m0, s57, 0x2000
	v_lshl_add_u64 v[174:175], s[6:7], 0, v[176:177]
	global_load_lds_dwordx4 v[174:175], off
	s_barrier
	s_waitcnt lgkmcnt(0)
	s_setprio 1
	v_mfma_f32_16x16x32_bf16 v[112:115], v[186:189], v[150:153], v[112:115]
	v_mfma_f32_16x16x32_bf16 v[104:107], v[194:197], v[150:153], v[104:107]
	v_mfma_f32_16x16x32_bf16 v[96:99], v[186:189], v[158:161], v[96:99]
	v_mfma_f32_16x16x32_bf16 v[88:91], v[194:197], v[158:161], v[88:91]
	v_mfma_f32_16x16x32_bf16 v[80:83], v[186:189], v[166:169], v[80:83]
	v_mfma_f32_16x16x32_bf16 v[72:75], v[194:197], v[166:169], v[72:75]
	v_mfma_f32_16x16x32_bf16 v[68:71], v[186:189], v[178:181], v[68:71]
	v_mfma_f32_16x16x32_bf16 v[64:67], v[194:197], v[178:181], v[64:67]
	v_mfma_f32_16x16x32_bf16 v[112:115], v[190:193], v[154:157], v[112:115]
	v_mfma_f32_16x16x32_bf16 v[104:107], v[198:201], v[154:157], v[104:107]
	v_mfma_f32_16x16x32_bf16 v[96:99], v[190:193], v[162:165], v[96:99]
	v_mfma_f32_16x16x32_bf16 v[88:91], v[198:201], v[162:165], v[88:91]
	v_mfma_f32_16x16x32_bf16 v[80:83], v[190:193], v[170:173], v[80:83]
	v_mfma_f32_16x16x32_bf16 v[72:75], v[198:201], v[170:173], v[72:75]
	v_mfma_f32_16x16x32_bf16 v[68:71], v[190:193], v[182:185], v[68:71]
	v_mfma_f32_16x16x32_bf16 v[64:67], v[198:201], v[182:185], v[64:67]
	s_setprio 0
	s_mov_b64 s[6:7], s[86:87]
	s_barrier
; #define PG8_STAGE(bufoff, gbase, voff) do { _Pragma("unroll") for (int _i = 0; _i < 2; ++_i) { const char* _gb = (const char*)(gbase) + (size_t)_i * (voff##_q); asm volatile("" : "+s"(_gb)); \
;         __builtin_amdgcn_global_load_lds((const unsigned*)(_gb + (voff)), (LAS unsigned*)(lds + (bufoff) + ldsw + _i * 8192), 16, 0, 0); } } while (0)
; #define PG8_LDA(dst, b, h) do { _Pragma("unroll") for (int m = 0; m < 4; ++m) _Pragma("unroll") for (int k = 0; k < 2; ++k) dst[m][k] = *(const LAS bf16x8*)(lds + PG8_SA(b, h) + aoff + m * 2048 + k * 1024); } while (0)
; #define PG8_LDB(dst, b, h) do { _Pragma("unroll") for (int n = 0; n < 2; ++n) _Pragma("unroll") for (int k = 0; k < 2; ++k) dst[n][k] = *(const LAS bf16x8*)(lds + PG8_SB(b, h) + boff + n * 2048 + k * 1024); } while (0)
; #define PG8_MMA(ai, bj, At, Bt) do { __builtin_amdgcn_s_setprio(1); _Pragma("unroll") for (int m = 0; m < 4; ++m) _Pragma("unroll") for (int n = 0; n < 2; ++n) _Pragma("unroll") for (int k = 0; k < 2; ++k) \
;         acc[ai][bj][m][n] = __builtin_amdgcn_mfma_f32_16x16x32_bf16(Bt[n][k], At[m][k], acc[ai][bj][m][n], 0, 0, 0); __builtin_amdgcn_s_setprio(0); } while (0)
; #define PG8_WAIT_V(n) asm volatile("s_waitcnt vmcnt(" #n ")" ::: "memory")
; #define PG8_WAIT_L(n) asm volatile("s_waitcnt lgkmcnt(" #n ")" ::: "memory")
; #define PG8_BAR __builtin_amdgcn_s_barrier()
; #define PG8_SCHED __builtin_amdgcn_sched_barrier(0)
; template <class Epi, class Sched>
; __device__ __forceinline__ void gemm_phase(int wv, LAS unsigned char* lds, const Gemm g, const Sched& S, const Epi& E) { LIDS
;     ...
;             PG8_LDB(B1, 1, 1); PG8_STAGE(PG8_SB(1, 0), b3, voffB);
;             PG8_BAR; PG8_WAIT_L(0); PG8_MMA(0, 1, At, B1); PG8_BAR;
;             PG8_LDA(At, 1, 1); PG8_STAGE(PG8_SA(1, 0), a3, voffA);
;             PG8_BAR; PG8_WAIT_L(0); PG8_MMA(1, 0, At, B0); PG8_BAR; PG8_SCHED;
;             PG8_STAGE(PG8_SB(1, 1), b3 + hstepB, voffB);
;             PG8_WAIT_V(6); PG8_BAR; PG8_MMA(1, 1, At, B1); PG8_BAR;
	ds_read_b128 v[150:153], v132 offset:49152
	ds_read_b128 v[154:157], v132 offset:50176
	ds_read_b128 v[158:161], v132 offset:51200
	ds_read_b128 v[162:165], v132 offset:52224
	ds_read_b128 v[166:169], v132 offset:53248
	ds_read_b128 v[170:173], v132 offset:54272
	ds_read_b128 v[178:181], v132 offset:55296
	ds_read_b128 v[182:185], v132 offset:56320
	s_mov_b32 m0, s27
	v_lshl_add_u64 v[174:175], s[6:7], 0, v[128:129]
	s_add_u32 s6, s86, 0x40000
	s_addc_u32 s7, s87, 0
	global_load_lds_dwordx4 v[174:175], off
	s_mov_b32 m0, s28
	v_lshl_add_u64 v[174:175], s[6:7], 0, v[128:129]
	global_load_lds_dwordx4 v[174:175], off
	s_barrier
	s_waitcnt lgkmcnt(0)
	s_setprio 1
	v_mfma_f32_16x16x32_bf16 v[60:63], v[134:137], v[150:153], v[60:63]
	v_mfma_f32_16x16x32_bf16 v[56:59], v[142:145], v[150:153], v[56:59]
	v_mfma_f32_16x16x32_bf16 v[52:55], v[134:137], v[158:161], v[52:55]
	v_mfma_f32_16x16x32_bf16 v[44:47], v[142:145], v[158:161], v[44:47]
	v_mfma_f32_16x16x32_bf16 v[36:39], v[134:137], v[166:169], v[36:39]
	v_mfma_f32_16x16x32_bf16 v[28:31], v[142:145], v[166:169], v[28:31]
	v_mfma_f32_16x16x32_bf16 v[20:23], v[134:137], v[178:181], v[20:23]
	v_mfma_f32_16x16x32_bf16 v[12:15], v[142:145], v[178:181], v[12:15]
	v_mfma_f32_16x16x32_bf16 v[60:63], v[138:141], v[154:157], v[60:63]
	v_mfma_f32_16x16x32_bf16 v[56:59], v[146:149], v[154:157], v[56:59]
	v_mfma_f32_16x16x32_bf16 v[52:55], v[138:141], v[162:165], v[52:55]
	v_mfma_f32_16x16x32_bf16 v[44:47], v[146:149], v[162:165], v[44:47]
	v_mfma_f32_16x16x32_bf16 v[36:39], v[138:141], v[170:173], v[36:39]
	v_mfma_f32_16x16x32_bf16 v[28:31], v[146:149], v[170:173], v[28:31]
	v_mfma_f32_16x16x32_bf16 v[20:23], v[138:141], v[182:185], v[20:23]
	v_mfma_f32_16x16x32_bf16 v[12:15], v[146:149], v[182:185], v[12:15]
	s_setprio 0
	s_barrier
	s_add_u32 s6, s78, 0x80000
	s_addc_u32 s7, s79, 0
	s_add_i32 s57, s58, s20
	v_lshl_add_u64 v[134:135], s[6:7], 0, v[176:177]
	s_add_u32 s6, s78, 0xc0000
	s_mov_b32 m0, s57
	s_addc_u32 s7, s79, 0
	global_load_lds_dwordx4 v[134:135], off
	s_add_i32 m0, s57, 0x2000
	v_lshl_add_u64 v[134:135], s[6:7], 0, v[176:177]
	global_load_lds_dwordx4 v[134:135], off
	s_waitcnt vmcnt(6)
	s_barrier
	s_setprio 1
	v_mfma_f32_16x16x32_bf16 v[48:51], v[186:189], v[150:153], v[48:51]
	v_mfma_f32_16x16x32_bf16 v[40:43], v[194:197], v[150:153], v[40:43]
	v_mfma_f32_16x16x32_bf16 v[32:35], v[186:189], v[158:161], v[32:35]
	v_mfma_f32_16x16x32_bf16 v[24:27], v[194:197], v[158:161], v[24:27]
	v_mfma_f32_16x16x32_bf16 v[16:19], v[186:189], v[166:169], v[16:19]
	v_mfma_f32_16x16x32_bf16 v[8:11], v[194:197], v[166:169], v[8:11]
	v_mfma_f32_16x16x32_bf16 v[4:7], v[186:189], v[178:181], v[4:7]
	v_mfma_f32_16x16x32_bf16 v[0:3], v[194:197], v[178:181], v[0:3]
	v_mfma_f32_16x16x32_bf16 v[48:51], v[190:193], v[154:157], v[48:51]
	v_mfma_f32_16x16x32_bf16 v[40:43], v[198:201], v[154:157], v[40:43]
	v_mfma_f32_16x16x32_bf16 v[32:35], v[190:193], v[162:165], v[32:35]
	v_mfma_f32_16x16x32_bf16 v[24:27], v[198:201], v[162:165], v[24:27]
	v_mfma_f32_16x16x32_bf16 v[16:19], v[190:193], v[170:173], v[16:19]
	v_mfma_f32_16x16x32_bf16 v[8:11], v[198:201], v[170:173], v[8:11]
	v_mfma_f32_16x16x32_bf16 v[4:7], v[190:193], v[182:185], v[4:7]
	v_mfma_f32_16x16x32_bf16 v[0:3], v[198:201], v[182:185], v[0:3]
	s_setprio 0
	s_add_i32 s56, s56, 2
	s_add_u32 s53, s53, 0x100
	s_addc_u32 s55, s55, 0
	s_cmp_gt_u32 s56, 29
	s_barrier
	s_cbranch_scc0 .LBB0_31
; __device__ __forceinline__ u32x4 pack8(f32x4 a, f32x4 b) { u32x4 r; r[0] = cvt_pk_bf16(a[0], a[1]); r[1] = cvt_pk_bf16(a[2], a[3]); r[2] = cvt_pk_bf16(b[0], b[1]); r[3] = cvt_pk_bf16(b[2], b[3]); return r; }
; #define PG8_WAIT_V(n) asm volatile("s_waitcnt vmcnt(" #n ")" ::: "memory")
; #define PG8_BAR __builtin_amdgcn_s_barrier()
; template <class Epi, class Sched>
; __device__ __forceinline__ void gemm_phase(int wv, LAS unsigned char* lds, const Gemm g, const Sched& S, const Epi& E) { LIDS
;     ...
;         if (!has_next) break;
; #pragma unroll
;         for (int a = 0; a < 2; ++a)
; #pragma unroll
;             for (int b = 0; b < 2; ++b)
; #pragma unroll
;                 for (int m = 0; m < 4; ++m)
; #pragma unroll
;                     for (int n = 0; n < 2; ++n) acc[a][b][m][n] = zero4;
;         cur = nxt; cA = nA; cB = nB; ++ui;
;     }
;     PG8_WAIT_V(0);
;     if (wr == 0) PG8_BAR;
;     PG8_BAR;
;     __device__ __forceinline__ void operator()(const AccT& acc, const Unit& u, int wr, int wc, int fr, int fq) const {
;     ...
; #pragma unroll
;         for (int ai = 0; ai < 2; ++ai)
; #pragma unroll
;             for (int m = 0; m < 4; ++m) {
;                 const int row = row0 + ai * HALF + m * 16;
; #pragma unroll
;                 for (int bj = 0; bj < 2; ++bj) *(u32x4*)(outb + (size_t)row * DM + colbase + bj * HALF) = pack8(acc[ai][bj][m][0], acc[ai][bj][m][1]);
	s_lshl_b32 s6, s62, 8
	v_mbcnt_lo_u32_b32 v133, -1, 0
	v_mbcnt_hi_u32_b32 v133, -1, v133
	s_add_i32 s6, s6, s25
	v_and_or_b32 v134, v133, 15, s6
	s_lshl_b32 s6, s30, 8
	v_ashrrev_i32_e32 v133, 1, v133
	s_or_b32 s6, s6, s26
	v_and_b32_e32 v133, -8, v133
	v_add_u32_e32 v136, s6, v133
	v_ashrrev_i32_e32 v135, 31, v134
	v_readlane_b32 s6, v254, 42
	v_ashrrev_i32_e32 v137, 31, v136
	v_lshlrev_b64 v[138:139], 12, v[134:135]
	v_readlane_b32 s7, v254, 43
	v_cvt_pk_bf16_f32 v124, v124, v125
	v_cvt_pk_bf16_f32 v125, v126, v127
	v_cvt_pk_bf16_f32 v126, v120, v121
	v_cvt_pk_bf16_f32 v127, v122, v123
	v_lshlrev_b64 v[122:123], 1, v[136:137]
	s_nop 0
	v_lshl_add_u64 v[120:121], s[6:7], 0, v[138:139]
	v_lshl_add_u64 v[120:121], v[120:121], 0, v[122:123]
	global_store_dwordx4 v[120:121], v[124:127], off
	v_cvt_pk_bf16_f32 v112, v112, v113
	v_cvt_pk_bf16_f32 v113, v114, v115
	v_cvt_pk_bf16_f32 v114, v104, v105
	v_or_b32_e32 v104, 16, v134
	v_ashrrev_i32_e32 v105, 31, v104
	v_cvt_pk_bf16_f32 v115, v106, v107
	global_store_dwordx4 v[120:121], v[112:115], off offset:256
	v_readlane_b32 s52, v254, 58
	s_mov_b32 s30, s8
	v_lshlrev_b64 v[112:113], 12, v[104:105]
	v_cvt_pk_bf16_f32 v104, v116, v117
	v_cvt_pk_bf16_f32 v105, v118, v119
	v_cvt_pk_bf16_f32 v106, v108, v109
	v_lshl_add_u64 v[108:109], s[6:7], 0, v[112:113]
	v_lshl_add_u64 v[108:109], v[108:109], 0, v[122:123]
	v_cvt_pk_bf16_f32 v107, v110, v111
	global_store_dwordx4 v[108:109], v[104:107], off
	v_cvt_pk_bf16_f32 v96, v96, v97
	v_cvt_pk_bf16_f32 v97, v98, v99
	v_cvt_pk_bf16_f32 v98, v88, v89
	v_or_b32_e32 v88, 32, v134
	v_ashrrev_i32_e32 v89, 31, v88
	v_cvt_pk_bf16_f32 v99, v90, v91
	global_store_dwordx4 v[108:109], v[96:99], off offset:256
	s_mov_b32 s62, s10
	s_mov_b64 s[78:79], s[68:69]
	v_lshlrev_b64 v[96:97], 12, v[88:89]
	v_cvt_pk_bf16_f32 v88, v100, v101
	v_cvt_pk_bf16_f32 v89, v102, v103
	v_cvt_pk_bf16_f32 v90, v92, v93
	v_lshl_add_u64 v[92:93], s[6:7], 0, v[96:97]
	v_lshl_add_u64 v[92:93], v[92:93], 0, v[122:123]
	v_cvt_pk_bf16_f32 v91, v94, v95
	global_store_dwordx4 v[92:93], v[88:91], off
	v_cvt_pk_bf16_f32 v80, v80, v81
	v_cvt_pk_bf16_f32 v81, v82, v83
	v_cvt_pk_bf16_f32 v82, v72, v73
	v_or_b32_e32 v72, 48, v134
	v_ashrrev_i32_e32 v73, 31, v72
	v_cvt_pk_bf16_f32 v83, v74, v75
	global_store_dwordx4 v[92:93], v[80:83], off offset:256
	s_mov_b64 s[72:73], s[12:13]
	v_readlane_b32 s53, v254, 59
	v_lshlrev_b64 v[80:81], 12, v[72:73]
	v_cvt_pk_bf16_f32 v72, v84, v85
	v_cvt_pk_bf16_f32 v73, v86, v87
	v_cvt_pk_bf16_f32 v74, v76, v77
	v_lshl_add_u64 v[76:77], s[6:7], 0, v[80:81]
	v_lshl_add_u64 v[76:77], v[76:77], 0, v[122:123]
	s_mov_b64 s[6:7], 0x80000
	v_cvt_pk_bf16_f32 v75, v78, v79
	global_store_dwordx4 v[76:77], v[72:75], off
	v_cvt_pk_bf16_f32 v68, v68, v69
	v_cvt_pk_bf16_f32 v69, v70, v71
	v_cvt_pk_bf16_f32 v70, v64, v65
	v_cvt_pk_bf16_f32 v71, v66, v67
	global_store_dwordx4 v[76:77], v[68:71], off offset:256
	v_cvt_pk_bf16_f32 v60, v60, v61
	v_cvt_pk_bf16_f32 v61, v62, v63
	v_cvt_pk_bf16_f32 v62, v56, v57
	v_lshl_add_u64 v[56:57], v[120:121], 0, s[6:7]
	s_mov_b32 s6, 0x80000
	v_cvt_pk_bf16_f32 v63, v58, v59
	v_add_co_u32_e32 v58, vcc, s6, v120
	s_mov_b64 s[6:7], 0x90000
	s_nop 0
	v_addc_co_u32_e32 v59, vcc, 0, v121, vcc
	global_store_dwordx4 v[58:59], v[60:63], off
	v_cvt_pk_bf16_f32 v48, v48, v49
	v_cvt_pk_bf16_f32 v49, v50, v51
	v_cvt_pk_bf16_f32 v50, v40, v41
	v_cvt_pk_bf16_f32 v51, v42, v43
	global_store_dwordx4 v[56:57], v[48:51], off offset:256
	v_cvt_pk_bf16_f32 v40, v52, v53
	v_cvt_pk_bf16_f32 v41, v54, v55
	v_cvt_pk_bf16_f32 v42, v44, v45
	v_lshl_add_u64 v[44:45], v[120:121], 0, s[6:7]
	s_mov_b32 s6, 0x90000
	v_cvt_pk_bf16_f32 v43, v46, v47
	v_add_co_u32_e32 v46, vcc, s6, v120
	s_mov_b64 s[6:7], 0xa0000
	s_nop 0
	v_addc_co_u32_e32 v47, vcc, 0, v121, vcc
	global_store_dwordx4 v[46:47], v[40:43], off
	v_cvt_pk_bf16_f32 v32, v32, v33
	v_cvt_pk_bf16_f32 v33, v34, v35
	v_cvt_pk_bf16_f32 v34, v24, v25
	v_cvt_pk_bf16_f32 v35, v26, v27
	global_store_dwordx4 v[44:45], v[32:35], off offset:256
	v_cvt_pk_bf16_f32 v24, v36, v37
	v_cvt_pk_bf16_f32 v25, v38, v39
	v_cvt_pk_bf16_f32 v26, v28, v29
	v_lshl_add_u64 v[28:29], v[120:121], 0, s[6:7]
	s_mov_b32 s6, 0xa0000
	v_cvt_pk_bf16_f32 v27, v30, v31
	v_add_co_u32_e32 v30, vcc, s6, v120
	s_mov_b64 s[6:7], 0xb0000
	s_nop 0
	v_addc_co_u32_e32 v31, vcc, 0, v121, vcc
	global_store_dwordx4 v[30:31], v[24:27], off
	v_cvt_pk_bf16_f32 v16, v16, v17
	v_cvt_pk_bf16_f32 v17, v18, v19
	v_cvt_pk_bf16_f32 v18, v8, v9
	v_cvt_pk_bf16_f32 v19, v10, v11
	global_store_dwordx4 v[28:29], v[16:19], off offset:256
	v_cvt_pk_bf16_f32 v8, v20, v21
	v_cvt_pk_bf16_f32 v9, v22, v23
	v_cvt_pk_bf16_f32 v10, v12, v13
	v_lshl_add_u64 v[12:13], v[120:121], 0, s[6:7]
	s_mov_b32 s6, 0xb0000
	v_cvt_pk_bf16_f32 v11, v14, v15
	v_add_co_u32_e32 v14, vcc, s6, v120
	s_nop 1
	v_addc_co_u32_e32 v15, vcc, 0, v121, vcc
	s_and_b64 vcc, exec, s[4:5]
	global_store_dwordx4 v[14:15], v[8:11], off
	v_cvt_pk_bf16_f32 v4, v4, v5
	v_cvt_pk_bf16_f32 v5, v6, v7
	v_cvt_pk_bf16_f32 v6, v0, v1
	v_cvt_pk_bf16_f32 v7, v2, v3
	global_store_dwordx4 v[12:13], v[4:7], off offset:256
	s_cbranch_vccz .LBB0_24
	s_waitcnt vmcnt(0)
	s_cmpk_gt_u32 s18, 0xff
	s_cbranch_scc1 .LBB0_35
	s_barrier

; #define PG8_STAGE(bufoff, gbase, voff) do { _Pragma("unroll") for (int _i = 0; _i < 2; ++_i) { const char* _gb = (const char*)(gbase) + (size_t)_i * (voff##_q); asm volatile("" : "+s"(_gb)); \
;         __builtin_amdgcn_global_load_lds((const unsigned*)(_gb + (voff)), (LAS unsigned*)(lds + (bufoff) + ldsw + _i * 8192), 16, 0, 0); } } while (0)
; #define PG8_LDA(dst, b, h) do { _Pragma("unroll") for (int m = 0; m < 4; ++m) _Pragma("unroll") for (int k = 0; k < 2; ++k) dst[m][k] = *(const LAS bf16x8*)(lds + PG8_SA(b, h) + aoff + m * 2048 + k * 1024); } while (0)
; #define PG8_LDB(dst, b, h) do { _Pragma("unroll") for (int n = 0; n < 2; ++n) _Pragma("unroll") for (int k = 0; k < 2; ++k) dst[n][k] = *(const LAS bf16x8*)(lds + PG8_SB(b, h) + boff + n * 2048 + k * 1024); } while (0)
; #define PG8_WAIT_L(n) asm volatile("s_waitcnt lgkmcnt(" #n ")" ::: "memory")
; #define PG8_BAR __builtin_amdgcn_s_barrier()
; #define PG8_SCHED __builtin_amdgcn_sched_barrier(0)
; template <class Epi, class Sched>
; __device__ __forceinline__ void gemm_phase(int wv, LAS unsigned char* lds, const Gemm g, const Sched& S, const Epi& E) { LIDS
;     ...
;         const bool has_next = S.next(ui + 1, nxt);
;         const char* nA = has_next ? (const char*)g.A + (size_t)nxt.pm * g.tstepA : cA; const char* nB = has_next ? (const char*)g.Bt + (size_t)nxt.pn * g.tstepB : cB;
;         for (int t = 0; t < nt; t += 2) {
;             const bool last = (t == nt - 2);
;             const char* a1 = cA + (size_t)(t + 1) * kstepA;
;             const char* a2 = last ? nA : cA + (size_t)(t + 2) * kstepA; const char* b2 = last ? nB : cB + (size_t)(t + 2) * kstepB;
;             const char* a3 = a2 + kstepA; const char* b3 = b2 + kstepB;
;             asm volatile("" : "+s"(a1), "+s"(a2), "+s"(b2), "+s"(a3), "+s"(b3));
;             PG8_LDB(B0, 0, 0); PG8_SCHED; PG8_LDA(At, 0, 0); PG8_STAGE(PG8_SA(1, 1), a1 + hstepA, voffA);
;             PG8_WAIT_L(8); PG8_BAR; PG8_WAIT_L(0); PG8_MMA(0, 0, At, B0); PG8_BAR; PG8_SCHED;
;             PG8_LDB(B1, 0, 1); PG8_STAGE(PG8_SB(0, 0), b2, voffB);
;             PG8_BAR; PG8_WAIT_L(0); PG8_MMA(0, 1, At, B1); PG8_BAR;
;             PG8_LDA(At, 0, 1); PG8_STAGE(PG8_SA(0, 0), a2, voffA);
;             PG8_BAR; PG8_WAIT_L(0); PG8_MMA(1, 0, At, B0); PG8_BAR; PG8_SCHED;
.LBB0_54:
	s_add_u32 s22, s72, 0x200000
	s_addc_u32 s23, s73, 0
	s_add_u32 s72, s72, 0x400000
	s_addc_u32 s73, s73, 0
	s_cmp_eq_u32 s21, 12
	s_cselect_b32 s84, s17, s72
	s_cselect_b32 s85, s11, s73
	s_cselect_b32 s7, s9, s20
	s_cselect_b32 s6, s18, s19
	s_add_u32 s86, s84, 0x200000
	s_addc_u32 s87, s85, 0
	s_add_u32 s78, s6, 0x80
	s_addc_u32 s79, s7, 0
	s_add_i32 s26, 16, 0x10000
	v_add_u32_e32 v116, s26, v173
	ds_read_b128 v[56:59], v116
	ds_read_b128 v[76:79], v116 offset:1024
	ds_read_b128 v[96:99], v116 offset:2048
	ds_read_b128 v[116:119], v116 offset:3072
	s_add_u32 s24, s22, 0x1000
	s_addc_u32 s25, s23, 0
	s_add_i32 m0, s69, 0xc000
	s_add_u32 s22, s22, 0x1800
	ds_read_b128 v[128:131], v174
	ds_read_b128 v[148:151], v174 offset:1024
	ds_read_b128 v[152:155], v174 offset:2048
	ds_read_b128 v[156:159], v174 offset:3072
	ds_read_b128 v[162:165], v174 offset:4096
	ds_read_b128 v[166:169], v174 offset:5120
	ds_read_b128 v[178:181], v174 offset:6144
	ds_read_b128 v[182:185], v174 offset:7168
	s_addc_u32 s23, s23, 0
	v_lshl_add_u64 v[170:171], s[24:25], 0, v[160:161]
	global_load_lds_dwordx4 v[170:171], off
	s_add_i32 m0, s69, 0xe000
	v_lshl_add_u64 v[170:171], s[22:23], 0, v[160:161]
	global_load_lds_dwordx4 v[170:171], off
	s_waitcnt lgkmcnt(8)
	s_barrier
	s_waitcnt lgkmcnt(0)
	s_setprio 1
	v_mfma_f32_16x16x32_bf16 v[140:143], v[56:59], v[128:131], v[140:143]
	v_mfma_f32_16x16x32_bf16 v[132:135], v[96:99], v[128:131], v[132:135]
	v_mfma_f32_16x16x32_bf16 v[120:123], v[56:59], v[152:155], v[120:123]
	v_mfma_f32_16x16x32_bf16 v[108:111], v[96:99], v[152:155], v[108:111]
	v_mfma_f32_16x16x32_bf16 v[100:103], v[56:59], v[162:165], v[100:103]
	v_mfma_f32_16x16x32_bf16 v[88:91], v[96:99], v[162:165], v[88:91]
	v_mfma_f32_16x16x32_bf16 v[80:83], v[56:59], v[178:181], v[80:83]
	v_mfma_f32_16x16x32_bf16 v[68:71], v[96:99], v[178:181], v[68:71]
	v_mfma_f32_16x16x32_bf16 v[140:143], v[76:79], v[148:151], v[140:143]
	v_mfma_f32_16x16x32_bf16 v[132:135], v[116:119], v[148:151], v[132:135]
	v_mfma_f32_16x16x32_bf16 v[120:123], v[76:79], v[156:159], v[120:123]
	v_mfma_f32_16x16x32_bf16 v[108:111], v[116:119], v[156:159], v[108:111]
	v_mfma_f32_16x16x32_bf16 v[100:103], v[76:79], v[166:169], v[100:103]
	v_mfma_f32_16x16x32_bf16 v[88:91], v[116:119], v[166:169], v[88:91]
	v_mfma_f32_16x16x32_bf16 v[80:83], v[76:79], v[182:185], v[80:83]
	v_mfma_f32_16x16x32_bf16 v[68:71], v[116:119], v[182:185], v[68:71]
	s_setprio 0
	s_barrier
	s_add_i32 s24, 16, 0x14000
	v_add_u32_e32 v170, s24, v173
	s_mov_b64 s[22:23], s[6:7]
	ds_read_b128 v[186:189], v170
	ds_read_b128 v[190:193], v170 offset:1024
	ds_read_b128 v[194:197], v170 offset:2048
	ds_read_b128 v[198:201], v170 offset:3072
	s_add_i32 s25, s26, s59
	v_lshl_add_u64 v[170:171], s[22:23], 0, v[176:177]
	s_add_u32 s22, s6, 0x20000
	s_mov_b32 m0, s25
	s_addc_u32 s23, s7, 0
	global_load_lds_dwordx4 v[170:171], off
	s_add_i32 m0, s25, 0x2000
	v_lshl_add_u64 v[170:171], s[22:23], 0, v[176:177]
	global_load_lds_dwordx4 v[170:171], off
	s_barrier
	s_waitcnt lgkmcnt(0)
	s_setprio 1
	v_mfma_f32_16x16x32_bf16 v[144:147], v[186:189], v[128:131], v[144:147]
	v_mfma_f32_16x16x32_bf16 v[124:127], v[186:189], v[152:155], v[124:127]
	v_mfma_f32_16x16x32_bf16 v[112:115], v[194:197], v[152:155], v[112:115]
	v_mfma_f32_16x16x32_bf16 v[104:107], v[186:189], v[162:165], v[104:107]
	v_mfma_f32_16x16x32_bf16 v[92:95], v[194:197], v[162:165], v[92:95]
	v_mfma_f32_16x16x32_bf16 v[84:87], v[186:189], v[178:181], v[84:87]
	v_mfma_f32_16x16x32_bf16 v[72:75], v[194:197], v[178:181], v[72:75]
	v_mfma_f32_16x16x32_bf16 v[144:147], v[190:193], v[148:151], v[144:147]
	v_mfma_f32_16x16x32_bf16 v[128:131], v[194:197], v[128:131], v[136:139]
	v_mfma_f32_16x16x32_bf16 v[124:127], v[190:193], v[156:159], v[124:127]
	v_mfma_f32_16x16x32_bf16 v[112:115], v[198:201], v[156:159], v[112:115]
	v_mfma_f32_16x16x32_bf16 v[104:107], v[190:193], v[166:169], v[104:107]
	v_mfma_f32_16x16x32_bf16 v[92:95], v[198:201], v[166:169], v[92:95]
	v_mfma_f32_16x16x32_bf16 v[84:87], v[190:193], v[182:185], v[84:87]
	v_mfma_f32_16x16x32_bf16 v[72:75], v[198:201], v[182:185], v[72:75]
	v_mfma_f32_16x16x32_bf16 v[128:131], v[198:201], v[148:151], v[128:131]
	s_setprio 0
	s_mov_b64 s[22:23], s[84:85]
	s_barrier
	ds_read_b128 v[136:139], v174 offset:16384
	ds_read_b128 v[148:151], v174 offset:17408
	ds_read_b128 v[152:155], v174 offset:18432
	ds_read_b128 v[156:159], v174 offset:19456
	ds_read_b128 v[162:165], v174 offset:20480
	ds_read_b128 v[166:169], v174 offset:21504
	ds_read_b128 v[178:181], v174 offset:22528
	ds_read_b128 v[182:185], v174 offset:23552
	s_mov_b32 m0, s69
	v_lshl_add_u64 v[170:171], s[22:23], 0, v[160:161]
	s_add_u32 s22, s84, 0x800
	s_addc_u32 s23, s85, 0
	global_load_lds_dwordx4 v[170:171], off
	s_mov_b32 m0, s88
	v_lshl_add_u64 v[170:171], s[22:23], 0, v[160:161]
	global_load_lds_dwordx4 v[170:171], off
	s_barrier
	s_waitcnt lgkmcnt(0)
	s_setprio 1
	v_mfma_f32_16x16x32_bf16 v[60:63], v[56:59], v[136:139], v[60:63]
	v_mfma_f32_16x16x32_bf16 v[48:51], v[96:99], v[136:139], v[48:51]
	v_mfma_f32_16x16x32_bf16 v[40:43], v[56:59], v[152:155], v[40:43]
	v_mfma_f32_16x16x32_bf16 v[32:35], v[96:99], v[152:155], v[32:35]
	v_mfma_f32_16x16x32_bf16 v[24:27], v[56:59], v[162:165], v[24:27]
	v_mfma_f32_16x16x32_bf16 v[16:19], v[96:99], v[162:165], v[16:19]
	v_mfma_f32_16x16x32_bf16 v[8:11], v[56:59], v[178:181], v[8:11]
	v_mfma_f32_16x16x32_bf16 v[0:3], v[96:99], v[178:181], v[0:3]
	v_mfma_f32_16x16x32_bf16 v[60:63], v[76:79], v[148:151], v[60:63]
	v_mfma_f32_16x16x32_bf16 v[48:51], v[116:119], v[148:151], v[48:51]
	v_mfma_f32_16x16x32_bf16 v[40:43], v[76:79], v[156:159], v[40:43]
	v_mfma_f32_16x16x32_bf16 v[32:35], v[116:119], v[156:159], v[32:35]
	v_mfma_f32_16x16x32_bf16 v[24:27], v[76:79], v[166:169], v[24:27]
	v_mfma_f32_16x16x32_bf16 v[16:19], v[116:119], v[166:169], v[16:19]
	v_mfma_f32_16x16x32_bf16 v[8:11], v[76:79], v[182:185], v[8:11]
	v_mfma_f32_16x16x32_bf16 v[0:3], v[116:119], v[182:185], v[0:3]
	s_setprio 0
	s_barrier
; #define PG8_STAGE(bufoff, gbase, voff) do { _Pragma("unroll") for (int _i = 0; _i < 2; ++_i) { const char* _gb = (const char*)(gbase) + (size_t)_i * (voff##_q); asm volatile("" : "+s"(_gb)); \
;         __builtin_amdgcn_global_load_lds((const unsigned*)(_gb + (voff)), (LAS unsigned*)(lds + (bufoff) + ldsw + _i * 8192), 16, 0, 0); } } while (0)
; #define PG8_LDA(dst, b, h) do { _Pragma("unroll") for (int m = 0; m < 4; ++m) _Pragma("unroll") for (int k = 0; k < 2; ++k) dst[m][k] = *(const LAS bf16x8*)(lds + PG8_SA(b, h) + aoff + m * 2048 + k * 1024); } while (0)
; #define PG8_LDB(dst, b, h) do { _Pragma("unroll") for (int n = 0; n < 2; ++n) _Pragma("unroll") for (int k = 0; k < 2; ++k) dst[n][k] = *(const LAS bf16x8*)(lds + PG8_SB(b, h) + boff + n * 2048 + k * 1024); } while (0)
; #define PG8_MMA(ai, bj, At, Bt) do { __builtin_amdgcn_s_setprio(1); _Pragma("unroll") for (int m = 0; m < 4; ++m) _Pragma("unroll") for (int n = 0; n < 2; ++n) _Pragma("unroll") for (int k = 0; k < 2; ++k) \
;         acc[ai][bj][m][n] = __builtin_amdgcn_mfma_f32_16x16x32_bf16(Bt[n][k], At[m][k], acc[ai][bj][m][n], 0, 0, 0); __builtin_amdgcn_s_setprio(0); } while (0)
; #define PG8_WAIT_V(n) asm volatile("s_waitcnt vmcnt(" #n ")" ::: "memory")
; #define PG8_WAIT_L(n) asm volatile("s_waitcnt lgkmcnt(" #n ")" ::: "memory")
; #define PG8_BAR __builtin_amdgcn_s_barrier()
; #define PG8_SCHED __builtin_amdgcn_sched_barrier(0)
; template <class Epi, class Sched>
; __device__ __forceinline__ void gemm_phase(int wv, LAS unsigned char* lds, const Gemm g, const Sched& S, const Epi& E) { LIDS
;     ...
;             PG8_STAGE(PG8_SB(0, 1), b2 + hstepB, voffB);
;             PG8_WAIT_V(6); PG8_BAR; PG8_MMA(1, 1, At, B1); PG8_BAR;
;             PG8_LDB(B0, 1, 0); PG8_SCHED; PG8_LDA(At, 1, 0); PG8_STAGE(PG8_SA(0, 1), a2 + hstepA, voffA);
;             PG8_WAIT_L(8); PG8_BAR; PG8_WAIT_L(0); PG8_MMA(0, 0, At, B0); PG8_BAR; PG8_SCHED;
;             PG8_LDB(B1, 1, 1); PG8_STAGE(PG8_SB(1, 0), b3, voffB);
;             PG8_BAR; PG8_WAIT_L(0); PG8_MMA(0, 1, At, B1); PG8_BAR;
;             PG8_LDA(At, 1, 1); PG8_STAGE(PG8_SA(1, 0), a3, voffA);
;             PG8_BAR; PG8_WAIT_L(0); PG8_MMA(1, 0, At, B0); PG8_BAR; PG8_SCHED;
	s_add_u32 s22, s6, 0x40000
	s_addc_u32 s23, s7, 0
	s_nop 0
	v_lshl_add_u64 v[56:57], s[22:23], 0, v[176:177]
	s_add_i32 s22, s24, s59
	s_add_u32 s6, s6, 0x60000
	s_mov_b32 m0, s22
	s_addc_u32 s7, s7, 0
	global_load_lds_dwordx4 v[56:57], off
	s_add_i32 m0, s22, 0x2000
	v_lshl_add_u64 v[56:57], s[6:7], 0, v[176:177]
	global_load_lds_dwordx4 v[56:57], off
	s_waitcnt vmcnt(6)
	s_barrier
	s_setprio 1
	v_mfma_f32_16x16x32_bf16 v[52:55], v[194:197], v[136:139], v[52:55]
	v_mfma_f32_16x16x32_bf16 v[44:47], v[186:189], v[152:155], v[44:47]
	v_mfma_f32_16x16x32_bf16 v[36:39], v[194:197], v[152:155], v[36:39]
	v_mfma_f32_16x16x32_bf16 v[28:31], v[186:189], v[162:165], v[28:31]
	v_mfma_f32_16x16x32_bf16 v[20:23], v[194:197], v[162:165], v[20:23]
	v_mfma_f32_16x16x32_bf16 v[12:15], v[186:189], v[178:181], v[12:15]
	v_mfma_f32_16x16x32_bf16 v[4:7], v[194:197], v[178:181], v[4:7]
	v_mfma_f32_16x16x32_bf16 v[56:59], v[186:189], v[136:139], v[64:67]
	v_mfma_f32_16x16x32_bf16 v[52:55], v[198:201], v[148:151], v[52:55]
	v_mfma_f32_16x16x32_bf16 v[44:47], v[190:193], v[156:159], v[44:47]
	v_mfma_f32_16x16x32_bf16 v[36:39], v[198:201], v[156:159], v[36:39]
	v_mfma_f32_16x16x32_bf16 v[28:31], v[190:193], v[166:169], v[28:31]
	v_mfma_f32_16x16x32_bf16 v[20:23], v[198:201], v[166:169], v[20:23]
	v_mfma_f32_16x16x32_bf16 v[12:15], v[190:193], v[182:185], v[12:15]
	v_mfma_f32_16x16x32_bf16 v[4:7], v[198:201], v[182:185], v[4:7]
	v_mfma_f32_16x16x32_bf16 v[56:59], v[190:193], v[148:151], v[56:59]
	s_setprio 0
	s_add_i32 s22, 16, 0x18000
	v_add_u32_e32 v116, s22, v173
	s_barrier
	ds_read_b128 v[64:67], v116
	ds_read_b128 v[76:79], v116 offset:1024
	ds_read_b128 v[96:99], v116 offset:2048
	ds_read_b128 v[116:119], v116 offset:3072
	s_add_u32 s6, s84, 0x1000
	s_addc_u32 s7, s85, 0
	ds_read_b128 v[136:139], v174 offset:32768
	ds_read_b128 v[148:151], v174 offset:33792
	ds_read_b128 v[152:155], v174 offset:34816
	ds_read_b128 v[156:159], v174 offset:35840
	ds_read_b128 v[162:165], v174 offset:36864
	ds_read_b128 v[166:169], v174 offset:37888
	ds_read_b128 v[178:181], v174 offset:38912
	ds_read_b128 v[182:185], v174 offset:39936
	s_mov_b32 m0, s89
	v_lshl_add_u64 v[170:171], s[6:7], 0, v[160:161]
	s_add_u32 s6, s84, 0x1800
	s_addc_u32 s7, s85, 0
	global_load_lds_dwordx4 v[170:171], off
	s_mov_b32 m0, s90
	v_lshl_add_u64 v[170:171], s[6:7], 0, v[160:161]
	global_load_lds_dwordx4 v[170:171], off
	s_waitcnt lgkmcnt(8)
	s_barrier
	s_waitcnt lgkmcnt(0)
	s_setprio 1
	v_mfma_f32_16x16x32_bf16 v[140:143], v[64:67], v[136:139], v[140:143]
	v_mfma_f32_16x16x32_bf16 v[132:135], v[96:99], v[136:139], v[132:135]
	v_mfma_f32_16x16x32_bf16 v[120:123], v[64:67], v[152:155], v[120:123]
	v_mfma_f32_16x16x32_bf16 v[108:111], v[96:99], v[152:155], v[108:111]
	v_mfma_f32_16x16x32_bf16 v[100:103], v[64:67], v[162:165], v[100:103]
	v_mfma_f32_16x16x32_bf16 v[88:91], v[96:99], v[162:165], v[88:91]
	v_mfma_f32_16x16x32_bf16 v[80:83], v[64:67], v[178:181], v[80:83]
	v_mfma_f32_16x16x32_bf16 v[68:71], v[96:99], v[178:181], v[68:71]
	v_mfma_f32_16x16x32_bf16 v[140:143], v[76:79], v[148:151], v[140:143]
	v_mfma_f32_16x16x32_bf16 v[132:135], v[116:119], v[148:151], v[132:135]
	v_mfma_f32_16x16x32_bf16 v[120:123], v[76:79], v[156:159], v[120:123]
	v_mfma_f32_16x16x32_bf16 v[108:111], v[116:119], v[156:159], v[108:111]
	v_mfma_f32_16x16x32_bf16 v[100:103], v[76:79], v[166:169], v[100:103]
	v_mfma_f32_16x16x32_bf16 v[88:91], v[116:119], v[166:169], v[88:91]
	v_mfma_f32_16x16x32_bf16 v[80:83], v[76:79], v[182:185], v[80:83]
	v_mfma_f32_16x16x32_bf16 v[68:71], v[116:119], v[182:185], v[68:71]
	s_setprio 0
	s_barrier
	s_add_i32 s23, 16, 0x1c000
	v_add_u32_e32 v170, s23, v173
	s_mov_b64 s[6:7], s[78:79]
	ds_read_b128 v[186:189], v170
	ds_read_b128 v[190:193], v170 offset:1024
	ds_read_b128 v[194:197], v170 offset:2048
	ds_read_b128 v[198:201], v170 offset:3072
	s_add_i32 s22, s22, s59
	v_lshl_add_u64 v[170:171], s[6:7], 0, v[176:177]
	s_add_u32 s6, s78, 0x20000
	s_mov_b32 m0, s22
	s_addc_u32 s7, s79, 0
	global_load_lds_dwordx4 v[170:171], off
	s_add_i32 m0, s22, 0x2000
	v_lshl_add_u64 v[170:171], s[6:7], 0, v[176:177]
	global_load_lds_dwordx4 v[170:171], off
	s_barrier
	s_waitcnt lgkmcnt(0)
	s_setprio 1
	v_mfma_f32_16x16x32_bf16 v[144:147], v[186:189], v[136:139], v[144:147]
	v_mfma_f32_16x16x32_bf16 v[128:131], v[194:197], v[136:139], v[128:131]
	v_mfma_f32_16x16x32_bf16 v[124:127], v[186:189], v[152:155], v[124:127]
	v_mfma_f32_16x16x32_bf16 v[112:115], v[194:197], v[152:155], v[112:115]
	v_mfma_f32_16x16x32_bf16 v[104:107], v[186:189], v[162:165], v[104:107]
	v_mfma_f32_16x16x32_bf16 v[92:95], v[194:197], v[162:165], v[92:95]
	v_mfma_f32_16x16x32_bf16 v[84:87], v[186:189], v[178:181], v[84:87]
	v_mfma_f32_16x16x32_bf16 v[72:75], v[194:197], v[178:181], v[72:75]
	v_mfma_f32_16x16x32_bf16 v[144:147], v[190:193], v[148:151], v[144:147]
	v_mfma_f32_16x16x32_bf16 v[136:139], v[198:201], v[148:151], v[128:131]
	v_mfma_f32_16x16x32_bf16 v[124:127], v[190:193], v[156:159], v[124:127]
	v_mfma_f32_16x16x32_bf16 v[112:115], v[198:201], v[156:159], v[112:115]
	v_mfma_f32_16x16x32_bf16 v[104:107], v[190:193], v[166:169], v[104:107]
	v_mfma_f32_16x16x32_bf16 v[92:95], v[198:201], v[166:169], v[92:95]
	v_mfma_f32_16x16x32_bf16 v[84:87], v[190:193], v[182:185], v[84:87]
	v_mfma_f32_16x16x32_bf16 v[72:75], v[198:201], v[182:185], v[72:75]
	s_setprio 0
	s_mov_b64 s[6:7], s[86:87]
	s_barrier
; #define PG8_STAGE(bufoff, gbase, voff) do { _Pragma("unroll") for (int _i = 0; _i < 2; ++_i) { const char* _gb = (const char*)(gbase) + (size_t)_i * (voff##_q); asm volatile("" : "+s"(_gb)); \
;         __builtin_amdgcn_global_load_lds((const unsigned*)(_gb + (voff)), (LAS unsigned*)(lds + (bufoff) + ldsw + _i * 8192), 16, 0, 0); } } while (0)
; #define PG8_LDA(dst, b, h) do { _Pragma("unroll") for (int m = 0; m < 4; ++m) _Pragma("unroll") for (int k = 0; k < 2; ++k) dst[m][k] = *(const LAS bf16x8*)(lds + PG8_SA(b, h) + aoff + m * 2048 + k * 1024); } while (0)
; #define PG8_LDB(dst, b, h) do { _Pragma("unroll") for (int n = 0; n < 2; ++n) _Pragma("unroll") for (int k = 0; k < 2; ++k) dst[n][k] = *(const LAS bf16x8*)(lds + PG8_SB(b, h) + boff + n * 2048 + k * 1024); } while (0)
; #define PG8_MMA(ai, bj, At, Bt) do { __builtin_amdgcn_s_setprio(1); _Pragma("unroll") for (int m = 0; m < 4; ++m) _Pragma("unroll") for (int n = 0; n < 2; ++n) _Pragma("unroll") for (int k = 0; k < 2; ++k) \
;         acc[ai][bj][m][n] = __builtin_amdgcn_mfma_f32_16x16x32_bf16(Bt[n][k], At[m][k], acc[ai][bj][m][n], 0, 0, 0); __builtin_amdgcn_s_setprio(0); } while (0)
; #define PG8_WAIT_V(n) asm volatile("s_waitcnt vmcnt(" #n ")" ::: "memory")
; #define PG8_WAIT_L(n) asm volatile("s_waitcnt lgkmcnt(" #n ")" ::: "memory")
; #define PG8_BAR __builtin_amdgcn_s_barrier()
; template <class Epi, class Sched>
; __device__ __forceinline__ void gemm_phase(int wv, LAS unsigned char* lds, const Gemm g, const Sched& S, const Epi& E) { LIDS
;     ...
;             PG8_LDB(B1, 1, 1); PG8_STAGE(PG8_SB(1, 0), b3, voffB);
;             PG8_BAR; PG8_WAIT_L(0); PG8_MMA(0, 1, At, B1); PG8_BAR;
;             PG8_LDA(At, 1, 1); PG8_STAGE(PG8_SA(1, 0), a3, voffA);
;             PG8_BAR; PG8_WAIT_L(0); PG8_MMA(1, 0, At, B0); PG8_BAR; PG8_SCHED;
;             PG8_STAGE(PG8_SB(1, 1), b3 + hstepB, voffB);
;             PG8_WAIT_V(6); PG8_BAR; PG8_MMA(1, 1, At, B1); PG8_BAR;
;     __device__ __forceinline__ void operator()(const AccT& acc, const Unit& u, int wr, int wc, int fr, int fq) const {
;         const int row0 = u.pm * BM + wr * 64 + fr, ch = u.pn * 128 + wc * 32 + 8 * fq;
;         u32x4 gsv[8];
; #pragma unroll
;         for (int rr = 0; rr < 8; ++rr) gsv[rr] = *(const u32x4*)(proj + (size_t)(row0 + (rr >> 2) * HALF + (rr & 3) * 16) * NIN + C_GS + ch);
;         __builtin_amdgcn_sched_barrier(0);
	ds_read_b128 v[128:131], v174 offset:49152
	ds_read_b128 v[148:151], v174 offset:50176
	ds_read_b128 v[152:155], v174 offset:51200
	ds_read_b128 v[156:159], v174 offset:52224
	ds_read_b128 v[162:165], v174 offset:53248
	ds_read_b128 v[166:169], v174 offset:54272
	ds_read_b128 v[178:181], v174 offset:55296
	ds_read_b128 v[182:185], v174 offset:56320
	s_mov_b32 m0, s95
	v_lshl_add_u64 v[170:171], s[6:7], 0, v[160:161]
	s_add_u32 s6, s86, 0x800
	s_addc_u32 s7, s87, 0
	global_load_lds_dwordx4 v[170:171], off
	s_mov_b32 m0, s57
	v_lshl_add_u64 v[170:171], s[6:7], 0, v[160:161]
	global_load_lds_dwordx4 v[170:171], off
	s_barrier
	s_waitcnt lgkmcnt(0)
	s_setprio 1
	v_mfma_f32_16x16x32_bf16 v[60:63], v[64:67], v[128:131], v[60:63]
	v_mfma_f32_16x16x32_bf16 v[48:51], v[96:99], v[128:131], v[48:51]
	v_mfma_f32_16x16x32_bf16 v[40:43], v[64:67], v[152:155], v[40:43]
	v_mfma_f32_16x16x32_bf16 v[32:35], v[96:99], v[152:155], v[32:35]
	v_mfma_f32_16x16x32_bf16 v[24:27], v[64:67], v[162:165], v[24:27]
	v_mfma_f32_16x16x32_bf16 v[16:19], v[96:99], v[162:165], v[16:19]
	v_mfma_f32_16x16x32_bf16 v[8:11], v[64:67], v[178:181], v[8:11]
	v_mfma_f32_16x16x32_bf16 v[0:3], v[96:99], v[178:181], v[0:3]
	v_mfma_f32_16x16x32_bf16 v[60:63], v[76:79], v[148:151], v[60:63]
	v_mfma_f32_16x16x32_bf16 v[48:51], v[116:119], v[148:151], v[48:51]
	v_mfma_f32_16x16x32_bf16 v[40:43], v[76:79], v[156:159], v[40:43]
	v_mfma_f32_16x16x32_bf16 v[32:35], v[116:119], v[156:159], v[32:35]
	v_mfma_f32_16x16x32_bf16 v[24:27], v[76:79], v[166:169], v[24:27]
	v_mfma_f32_16x16x32_bf16 v[16:19], v[116:119], v[166:169], v[16:19]
	v_mfma_f32_16x16x32_bf16 v[8:11], v[76:79], v[182:185], v[8:11]
	v_mfma_f32_16x16x32_bf16 v[0:3], v[116:119], v[182:185], v[0:3]
	s_setprio 0
	s_barrier
	s_add_u32 s6, s78, 0x40000
	s_addc_u32 s7, s79, 0
	s_add_i32 s22, s23, s59
	v_lshl_add_u64 v[64:65], s[6:7], 0, v[176:177]
	s_add_u32 s6, s78, 0x60000
	s_mov_b32 m0, s22
	s_addc_u32 s7, s79, 0
	global_load_lds_dwordx4 v[64:65], off
	s_add_i32 m0, s22, 0x2000
	v_lshl_add_u64 v[64:65], s[6:7], 0, v[176:177]
	global_load_lds_dwordx4 v[64:65], off
	s_waitcnt vmcnt(6)
	s_barrier
	s_setprio 1
	v_mfma_f32_16x16x32_bf16 v[56:59], v[186:189], v[128:131], v[56:59]
	v_mfma_f32_16x16x32_bf16 v[52:55], v[194:197], v[128:131], v[52:55]
	v_mfma_f32_16x16x32_bf16 v[44:47], v[186:189], v[152:155], v[44:47]
	v_mfma_f32_16x16x32_bf16 v[36:39], v[194:197], v[152:155], v[36:39]
	v_mfma_f32_16x16x32_bf16 v[28:31], v[186:189], v[162:165], v[28:31]
	v_mfma_f32_16x16x32_bf16 v[20:23], v[194:197], v[162:165], v[20:23]
	v_mfma_f32_16x16x32_bf16 v[12:15], v[186:189], v[178:181], v[12:15]
	v_mfma_f32_16x16x32_bf16 v[4:7], v[194:197], v[178:181], v[4:7]
	v_mfma_f32_16x16x32_bf16 v[64:67], v[190:193], v[148:151], v[56:59]
	v_mfma_f32_16x16x32_bf16 v[52:55], v[198:201], v[148:151], v[52:55]
	v_mfma_f32_16x16x32_bf16 v[44:47], v[190:193], v[156:159], v[44:47]
	v_mfma_f32_16x16x32_bf16 v[36:39], v[198:201], v[156:159], v[36:39]
	v_mfma_f32_16x16x32_bf16 v[28:31], v[190:193], v[166:169], v[28:31]
	v_mfma_f32_16x16x32_bf16 v[20:23], v[198:201], v[166:169], v[20:23]
	v_mfma_f32_16x16x32_bf16 v[12:15], v[190:193], v[182:185], v[12:15]
	v_mfma_f32_16x16x32_bf16 v[4:7], v[198:201], v[182:185], v[4:7]
	s_setprio 0
	s_add_i32 s21, s21, 2
	s_add_u32 s19, s19, 0x100
	s_addc_u32 s20, s20, 0
	s_cmp_gt_u32 s21, 13
	s_barrier
	s_cbranch_scc0 .LBB0_54
	s_lshl_b32 s6, s68, 8
	v_mbcnt_lo_u32_b32 v56, -1, 0
	v_mbcnt_hi_u32_b32 v56, -1, v56
	s_add_i32 s6, s6, s91
	v_and_or_b32 v178, v56, 15, s6
	s_lshl_b32 s6, s16, 7
	v_ashrrev_i32_e32 v56, 1, v56
	s_or_b32 s6, s6, s94
	v_and_b32_e32 v56, -8, v56
	v_add_u32_e32 v56, s6, v56
	v_ashrrev_i32_e32 v179, 31, v178
	v_readlane_b32 s6, v254, 46
	v_ashrrev_i32_e32 v57, 31, v56
	v_lshlrev_b64 v[58:59], 13, v[178:179]
	v_readlane_b32 s7, v254, 47
	v_or_b32_e32 v170, 16, v178
	v_lshlrev_b64 v[162:163], 1, v[56:57]
	v_lshl_add_u64 v[58:59], s[6:7], 0, v[58:59]
	v_ashrrev_i32_e32 v171, 31, v170
	v_lshl_add_u64 v[56:57], v[58:59], 0, v[162:163]
	s_movk_i32 s9, 0x1000
	v_lshlrev_b64 v[58:59], 13, v[170:171]
	v_add_co_u32_e32 v56, vcc, s9, v56
	v_lshl_add_u64 v[58:59], s[6:7], 0, v[58:59]
	s_nop 0
	v_addc_co_u32_e32 v57, vcc, 0, v57, vcc
	v_lshl_add_u64 v[58:59], v[58:59], 0, v[162:163]
	v_or_b32_e32 v168, 32, v178
	v_add_co_u32_e32 v58, vcc, s9, v58
	v_ashrrev_i32_e32 v169, 31, v168
	s_nop 0
	v_addc_co_u32_e32 v59, vcc, 0, v59, vcc
	global_load_dwordx4 v[156:159], v[56:57], off offset:1664
	global_load_dwordx4 v[152:155], v[58:59], off offset:1664
	v_lshlrev_b64 v[56:57], 13, v[168:169]
	v_or_b32_e32 v166, 48, v178
	v_lshl_add_u64 v[56:57], s[6:7], 0, v[56:57]
	v_ashrrev_i32_e32 v167, 31, v166
	v_lshl_add_u64 v[56:57], v[56:57], 0, v[162:163]
	v_lshlrev_b64 v[58:59], 13, v[166:167]
	v_add_co_u32_e32 v56, vcc, s9, v56
	v_lshl_add_u64 v[58:59], s[6:7], 0, v[58:59]
	s_nop 0
	v_addc_co_u32_e32 v57, vcc, 0, v57, vcc
	v_lshl_add_u64 v[58:59], v[58:59], 0, v[162:163]
	v_add_u32_e32 v164, 0x80, v178
	v_add_co_u32_e32 v58, vcc, s9, v58
	v_ashrrev_i32_e32 v165, 31, v164
	s_nop 0
	v_addc_co_u32_e32 v59, vcc, 0, v59, vcc
	global_load_dwordx4 v[148:151], v[56:57], off offset:1664
	global_load_dwordx4 v[128:131], v[58:59], off offset:1664
	v_lshlrev_b64 v[56:57], 13, v[164:165]
	v_add_u32_e32 v58, 0x90, v178
	v_lshl_add_u64 v[56:57], s[6:7], 0, v[56:57]
	v_ashrrev_i32_e32 v59, 31, v58
	v_lshl_add_u64 v[56:57], v[56:57], 0, v[162:163]
	v_lshlrev_b64 v[58:59], 13, v[58:59]
	v_add_co_u32_e32 v56, vcc, s9, v56
	v_lshl_add_u64 v[58:59], s[6:7], 0, v[58:59]
	s_nop 0
	v_addc_co_u32_e32 v57, vcc, 0, v57, vcc
	v_lshl_add_u64 v[58:59], v[58:59], 0, v[162:163]
	v_add_co_u32_e32 v58, vcc, s9, v58
	s_nop 1
	v_addc_co_u32_e32 v59, vcc, 0, v59, vcc
	global_load_dwordx4 v[116:119], v[56:57], off offset:1664
	global_load_dwordx4 v[96:99], v[58:59], off offset:1664
	v_add_u32_e32 v56, 0xa0, v178
	v_ashrrev_i32_e32 v57, 31, v56
	v_lshlrev_b64 v[56:57], 13, v[56:57]
	v_add_u32_e32 v58, 0xb0, v178
	v_lshl_add_u64 v[56:57], s[6:7], 0, v[56:57]
	v_ashrrev_i32_e32 v59, 31, v58
	v_lshl_add_u64 v[56:57], v[56:57], 0, v[162:163]
	v_lshlrev_b64 v[58:59], 13, v[58:59]
	v_add_co_u32_e32 v56, vcc, s9, v56
	v_lshl_add_u64 v[58:59], s[6:7], 0, v[58:59]
	s_nop 0
	v_addc_co_u32_e32 v57, vcc, 0, v57, vcc
	v_lshl_add_u64 v[58:59], v[58:59], 0, v[162:163]
	v_add_co_u32_e32 v58, vcc, s9, v58
	s_nop 1
	v_addc_co_u32_e32 v59, vcc, 0, v59, vcc
	global_load_dwordx4 v[76:79], v[56:57], off offset:1664
	s_nop 0
	global_load_dwordx4 v[56:59], v[58:59], off offset:1664
	s_waitcnt vmcnt(0)
; __device__ __forceinline__ unsigned cvt_pk_bf16(float lo, float hi) { unsigned r; asm volatile("v_cvt_pk_bf16_f32 %0, %1, %2" : "=v"(r) : "v"(lo), "v"(hi)); return r; }
; __device__ __forceinline__ float bflo(unsigned w) { return __uint_as_float(w << 16); }
; __device__ __forceinline__ float bfhi(unsigned w) { return __uint_as_float(w & 0xffff0000u); }
; __device__ __forceinline__ float sig_silu_(float g, float b) { return b * fast_rcp((1.0f + fast_exp2(-1.4426950408889634f * g)) * (1.0f + fast_exp2(-1.4426950408889634f * b))); }
;     __device__ __forceinline__ void operator()(const AccT& acc, const Unit& u, int wr, int wc, int fr, int fq) const {
;     ...
; #pragma unroll
;         for (int ai = 0; ai < 2; ++ai)
; #pragma unroll
;             for (int m = 0; m < 4; ++m) {
;                 const int row = row0 + ai * HALF + m * 16;
; #pragma unroll
;                 for (int n = 0; n < 2; ++n) {
;                     const unsigned g_lo = gsv[ai * 4 + m][2 * n], g_hi = gsv[ai * 4 + m][2 * n + 1];
;                     const f32x4 a0 = acc[ai][0][m][n], g0 = acc[ai][1][m][n];
;                     const float o0 = a0[0] * sig_silu_(g0[0], bflo(g_lo)), o1 = a0[1] * sig_silu_(g0[1], bfhi(g_lo));
;                     const float o2 = a0[2] * sig_silu_(g0[2], bflo(g_hi)), o3 = a0[3] * sig_silu_(g0[3], bfhi(g_hi));
;                     u32x2 w; w[0] = cvt_pk_bf16(o0, o1); w[1] = cvt_pk_bf16(o2, o3);
;                     *(u32x2*)(mixed + (size_t)row * DM + 1024 + ch + 4 * n) = w;
	v_lshlrev_b32_e32 v175, 16, v156
	v_mul_f32_e32 v144, 0xbfb8aa3b, v144
	v_exp_f32_e32 v180, v144
	v_mul_f32_e32 v144, 0xbfb8aa3b, v175
	v_exp_f32_e32 v181, v144
	v_readlane_b32 s6, v254, 50
	v_lshlrev_b64 v[178:179], 12, v[178:179]
	v_readlane_b32 s7, v254, 51
	v_pk_add_f32 v[180:181], v[180:181], 1.0 op_sel_hi:[1,0]
	s_nop 0
	v_mul_f32_e32 v144, v180, v181
	v_rcp_f32_e32 v144, v144
	s_nop 0
	v_mul_f32_e32 v144, v144, v175
	v_mul_f32_e32 v175, v140, v144
	v_and_b32_e32 v140, 0xffff0000, v156
	v_mul_f32_e32 v144, 0xbfb8aa3b, v145
	v_mul_f32_e32 v145, 0xbfb8aa3b, v140
	v_exp_f32_e32 v144, v144
	v_exp_f32_e32 v145, v145
	s_nop 0
	v_pk_add_f32 v[144:145], v[144:145], 1.0 op_sel_hi:[1,0]
	s_nop 0
	v_mul_f32_e32 v144, v144, v145
	v_rcp_f32_e32 v144, v144
	v_lshlrev_b32_e32 v145, 16, v157
	v_mul_f32_e32 v140, v144, v140
	v_mul_f32_e32 v144, v141, v140
	v_mul_f32_e32 v140, 0xbfb8aa3b, v146
	v_mul_f32_e32 v141, 0xbfb8aa3b, v145
	v_exp_f32_e32 v140, v140
	v_exp_f32_e32 v141, v141
	s_nop 0
	v_pk_add_f32 v[140:141], v[140:141], 1.0 op_sel_hi:[1,0]
	s_nop 0
	v_mul_f32_e32 v140, v140, v141
	v_rcp_f32_e32 v140, v140
	s_nop 0
	v_mul_f32_e32 v140, v140, v145
	v_mul_f32_e32 v145, v142, v140
	v_and_b32_e32 v142, 0xffff0000, v157
	v_mul_f32_e32 v140, 0xbfb8aa3b, v147
	v_mul_f32_e32 v141, 0xbfb8aa3b, v142
	v_exp_f32_e32 v140, v140
	v_exp_f32_e32 v141, v141
	s_nop 0
	v_pk_add_f32 v[140:141], v[140:141], 1.0 op_sel_hi:[1,0]
	s_nop 0
	v_mul_f32_e32 v140, v140, v141
	v_rcp_f32_e32 v140, v140
	s_nop 0
	v_mul_f32_e32 v140, v140, v142
	v_mul_f32_e32 v140, v143, v140
	v_cvt_pk_bf16_f32 v142, v175, v144
	v_cvt_pk_bf16_f32 v143, v145, v140
	v_lshl_add_u64 v[140:141], s[6:7], 0, v[178:179]
	v_lshl_add_u64 v[140:141], v[140:141], 0, v[162:163]
	global_store_dwordx2 v[140:141], v[142:143], off offset:2048
	v_lshlrev_b32_e32 v144, 16, v158
	v_mul_f32_e32 v136, 0xbfb8aa3b, v136
	v_exp_f32_e32 v142, v136
	v_mul_f32_e32 v136, 0xbfb8aa3b, v144
	v_exp_f32_e32 v143, v136
	s_nop 0
	v_pk_add_f32 v[142:143], v[142:143], 1.0 op_sel_hi:[1,0]
	s_nop 0
	v_mul_f32_e32 v136, v142, v143
	v_rcp_f32_e32 v136, v136
	s_nop 0
	v_mul_f32_e32 v136, v136, v144
	v_mul_f32_e32 v142, v132, v136
	v_and_b32_e32 v132, 0xffff0000, v158
	v_mul_f32_e32 v136, 0xbfb8aa3b, v137
	v_mul_f32_e32 v137, 0xbfb8aa3b, v132
	v_exp_f32_e32 v136, v136
	v_exp_f32_e32 v137, v137
	s_nop 0
	v_pk_add_f32 v[136:137], v[136:137], 1.0 op_sel_hi:[1,0]
	s_nop 0
	v_mul_f32_e32 v136, v136, v137
	v_rcp_f32_e32 v136, v136
	v_lshlrev_b32_e32 v137, 16, v159
	v_mul_f32_e32 v132, v136, v132
	v_mul_f32_e32 v136, v133, v132
	v_mul_f32_e32 v132, 0xbfb8aa3b, v138
	v_mul_f32_e32 v133, 0xbfb8aa3b, v137
	v_exp_f32_e32 v132, v132
	v_exp_f32_e32 v133, v133
	s_nop 0
	v_pk_add_f32 v[132:133], v[132:133], 1.0 op_sel_hi:[1,0]
	s_nop 0
	v_mul_f32_e32 v132, v132, v133
	v_rcp_f32_e32 v132, v132
	s_nop 0
	v_mul_f32_e32 v132, v132, v137
	v_and_b32_e32 v137, 0xffff0000, v159
	v_mul_f32_e32 v134, v134, v132
	v_mul_f32_e32 v132, 0xbfb8aa3b, v139
	v_mul_f32_e32 v133, 0xbfb8aa3b, v137
	v_exp_f32_e32 v132, v132
	v_exp_f32_e32 v133, v133
	s_nop 0
	v_pk_add_f32 v[132:133], v[132:133], 1.0 op_sel_hi:[1,0]
	s_nop 0
	v_mul_f32_e32 v132, v132, v133
	v_rcp_f32_e32 v132, v132
	s_nop 0
	v_mul_f32_e32 v132, v132, v137
	v_mul_f32_e32 v133, v135, v132
	v_cvt_pk_bf16_f32 v132, v142, v136
	v_cvt_pk_bf16_f32 v133, v134, v133
	global_store_dwordx2 v[140:141], v[132:133], off offset:2056
	v_lshlrev_b32_e32 v136, 16, v152
	v_mul_f32_e32 v124, 0xbfb8aa3b, v124
	v_exp_f32_e32 v134, v124
	v_mul_f32_e32 v124, 0xbfb8aa3b, v136
	v_exp_f32_e32 v135, v124
	v_lshlrev_b64 v[132:133], 12, v[170:171]
	v_pk_add_f32 v[134:135], v[134:135], 1.0 op_sel_hi:[1,0]
	s_nop 0
	v_mul_f32_e32 v124, v134, v135
	v_rcp_f32_e32 v124, v124
	s_nop 0
	v_mul_f32_e32 v124, v124, v136
	v_mul_f32_e32 v134, v120, v124
	v_and_b32_e32 v120, 0xffff0000, v152
	v_mul_f32_e32 v124, 0xbfb8aa3b, v125
	v_mul_f32_e32 v125, 0xbfb8aa3b, v120
	v_exp_f32_e32 v124, v124
	v_exp_f32_e32 v125, v125
	s_nop 0
	v_pk_add_f32 v[124:125], v[124:125], 1.0 op_sel_hi:[1,0]
	s_nop 0
	v_mul_f32_e32 v124, v124, v125
	v_rcp_f32_e32 v124, v124
	v_lshlrev_b32_e32 v125, 16, v153
	v_mul_f32_e32 v120, v124, v120
	v_mul_f32_e32 v124, v121, v120
	v_mul_f32_e32 v120, 0xbfb8aa3b, v126
	v_mul_f32_e32 v121, 0xbfb8aa3b, v125
	v_exp_f32_e32 v120, v120
	v_exp_f32_e32 v121, v121
	s_nop 0
	v_pk_add_f32 v[120:121], v[120:121], 1.0 op_sel_hi:[1,0]
	s_nop 0
	v_mul_f32_e32 v120, v120, v121
	v_rcp_f32_e32 v120, v120
	s_nop 0
	v_mul_f32_e32 v120, v120, v125
	v_and_b32_e32 v125, 0xffff0000, v153
	v_mul_f32_e32 v122, v122, v120
	v_mul_f32_e32 v120, 0xbfb8aa3b, v127
	v_mul_f32_e32 v121, 0xbfb8aa3b, v125
	v_exp_f32_e32 v120, v120
	v_exp_f32_e32 v121, v121
	s_nop 0
	v_pk_add_f32 v[120:121], v[120:121], 1.0 op_sel_hi:[1,0]
	s_nop 0
	v_mul_f32_e32 v120, v120, v121
	v_rcp_f32_e32 v120, v120
	s_nop 0
	v_mul_f32_e32 v120, v120, v125
	v_mul_f32_e32 v121, v123, v120
	v_cvt_pk_bf16_f32 v120, v134, v124
	v_cvt_pk_bf16_f32 v121, v122, v121
	v_lshl_add_u64 v[122:123], s[6:7], 0, v[132:133]
	v_lshl_add_u64 v[122:123], v[122:123], 0, v[162:163]
	global_store_dwordx2 v[122:123], v[120:121], off offset:2048
	v_lshlrev_b32_e32 v124, 16, v154
	v_mul_f32_e32 v112, 0xbfb8aa3b, v112
	v_exp_f32_e32 v120, v112
	v_mul_f32_e32 v112, 0xbfb8aa3b, v124
	v_exp_f32_e32 v121, v112
	s_nop 0
	v_pk_add_f32 v[120:121], v[120:121], 1.0 op_sel_hi:[1,0]
	s_nop 0
	v_mul_f32_e32 v112, v120, v121
	v_rcp_f32_e32 v112, v112
	s_nop 0
	v_mul_f32_e32 v112, v112, v124
	v_mul_f32_e32 v120, v108, v112
	v_and_b32_e32 v108, 0xffff0000, v154
	v_mul_f32_e32 v112, 0xbfb8aa3b, v113
	v_mul_f32_e32 v113, 0xbfb8aa3b, v108
; __device__ __forceinline__ unsigned cvt_pk_bf16(float lo, float hi) { unsigned r; asm volatile("v_cvt_pk_bf16_f32 %0, %1, %2" : "=v"(r) : "v"(lo), "v"(hi)); return r; }
; __device__ __forceinline__ float bflo(unsigned w) { return __uint_as_float(w << 16); }
; __device__ __forceinline__ float bfhi(unsigned w) { return __uint_as_float(w & 0xffff0000u); }
; __device__ __forceinline__ float sig_silu_(float g, float b) { return b * fast_rcp((1.0f + fast_exp2(-1.4426950408889634f * g)) * (1.0f + fast_exp2(-1.4426950408889634f * b))); }
;     __device__ __forceinline__ void operator()(const AccT& acc, const Unit& u, int wr, int wc, int fr, int fq) const {
;     ...
; #pragma unroll
;         for (int ai = 0; ai < 2; ++ai)
; #pragma unroll
;             for (int m = 0; m < 4; ++m) {
;                 const int row = row0 + ai * HALF + m * 16;
; #pragma unroll
;                 for (int n = 0; n < 2; ++n) {
;                     const unsigned g_lo = gsv[ai * 4 + m][2 * n], g_hi = gsv[ai * 4 + m][2 * n + 1];
;                     const f32x4 a0 = acc[ai][0][m][n], g0 = acc[ai][1][m][n];
;                     const float o0 = a0[0] * sig_silu_(g0[0], bflo(g_lo)), o1 = a0[1] * sig_silu_(g0[1], bfhi(g_lo));
;                     const float o2 = a0[2] * sig_silu_(g0[2], bflo(g_hi)), o3 = a0[3] * sig_silu_(g0[3], bfhi(g_hi));
;                     u32x2 w; w[0] = cvt_pk_bf16(o0, o1); w[1] = cvt_pk_bf16(o2, o3);
;                     *(u32x2*)(mixed + (size_t)row * DM + 1024 + ch + 4 * n) = w;
	v_exp_f32_e32 v112, v112
	v_exp_f32_e32 v113, v113
	s_nop 0
	v_pk_add_f32 v[112:113], v[112:113], 1.0 op_sel_hi:[1,0]
	s_nop 0
	v_mul_f32_e32 v112, v112, v113
	v_rcp_f32_e32 v112, v112
	v_lshlrev_b32_e32 v113, 16, v155
	v_mul_f32_e32 v108, v112, v108
	v_mul_f32_e32 v112, v109, v108
	v_mul_f32_e32 v108, 0xbfb8aa3b, v114
	v_mul_f32_e32 v109, 0xbfb8aa3b, v113
	v_exp_f32_e32 v108, v108
	v_exp_f32_e32 v109, v109
	s_nop 0
	v_pk_add_f32 v[108:109], v[108:109], 1.0 op_sel_hi:[1,0]
	s_nop 0
	v_mul_f32_e32 v108, v108, v109
	v_rcp_f32_e32 v108, v108
	s_nop 0
	v_mul_f32_e32 v108, v108, v113
	v_and_b32_e32 v113, 0xffff0000, v155
	v_mul_f32_e32 v110, v110, v108
	v_mul_f32_e32 v108, 0xbfb8aa3b, v115
	v_mul_f32_e32 v109, 0xbfb8aa3b, v113
	v_exp_f32_e32 v108, v108
	v_exp_f32_e32 v109, v109
	s_nop 0
	v_pk_add_f32 v[108:109], v[108:109], 1.0 op_sel_hi:[1,0]
	s_nop 0
	v_mul_f32_e32 v108, v108, v109
	v_rcp_f32_e32 v108, v108
	s_nop 0
	v_mul_f32_e32 v108, v108, v113
	v_mul_f32_e32 v109, v111, v108
	v_cvt_pk_bf16_f32 v108, v120, v112
	v_cvt_pk_bf16_f32 v109, v110, v109
	global_store_dwordx2 v[122:123], v[108:109], off offset:2056
	v_lshlrev_b32_e32 v112, 16, v148
	v_mul_f32_e32 v104, 0xbfb8aa3b, v104
	v_exp_f32_e32 v110, v104
	v_mul_f32_e32 v104, 0xbfb8aa3b, v112
	v_exp_f32_e32 v111, v104
	v_lshlrev_b64 v[108:109], 12, v[168:169]
	v_pk_add_f32 v[110:111], v[110:111], 1.0 op_sel_hi:[1,0]
	s_nop 0
	v_mul_f32_e32 v104, v110, v111
	v_rcp_f32_e32 v104, v104
	s_nop 0
	v_mul_f32_e32 v104, v104, v112
	v_mul_f32_e32 v110, v100, v104
	v_and_b32_e32 v100, 0xffff0000, v148
	v_mul_f32_e32 v104, 0xbfb8aa3b, v105
	v_mul_f32_e32 v105, 0xbfb8aa3b, v100
	v_exp_f32_e32 v104, v104
	v_exp_f32_e32 v105, v105
	s_nop 0
	v_pk_add_f32 v[104:105], v[104:105], 1.0 op_sel_hi:[1,0]
	s_nop 0
	v_mul_f32_e32 v104, v104, v105
	v_rcp_f32_e32 v104, v104
	v_lshlrev_b32_e32 v105, 16, v149
	v_mul_f32_e32 v100, v104, v100
	v_mul_f32_e32 v104, v101, v100
	v_mul_f32_e32 v100, 0xbfb8aa3b, v106
	v_mul_f32_e32 v101, 0xbfb8aa3b, v105
	v_exp_f32_e32 v100, v100
	v_exp_f32_e32 v101, v101
	s_nop 0
	v_pk_add_f32 v[100:101], v[100:101], 1.0 op_sel_hi:[1,0]
	s_nop 0
	v_mul_f32_e32 v100, v100, v101
	v_rcp_f32_e32 v100, v100
	s_nop 0
	v_mul_f32_e32 v100, v100, v105
	v_and_b32_e32 v105, 0xffff0000, v149
	v_mul_f32_e32 v102, v102, v100
	v_mul_f32_e32 v100, 0xbfb8aa3b, v107
	v_mul_f32_e32 v101, 0xbfb8aa3b, v105
	v_exp_f32_e32 v100, v100
	v_exp_f32_e32 v101, v101
	s_nop 0
	v_pk_add_f32 v[100:101], v[100:101], 1.0 op_sel_hi:[1,0]
	s_nop 0
	v_mul_f32_e32 v100, v100, v101
	v_rcp_f32_e32 v100, v100
	s_nop 0
	v_mul_f32_e32 v100, v100, v105
	v_mul_f32_e32 v101, v103, v100
	v_cvt_pk_bf16_f32 v100, v110, v104
	v_cvt_pk_bf16_f32 v101, v102, v101
	v_lshl_add_u64 v[102:103], s[6:7], 0, v[108:109]
	v_lshl_add_u64 v[102:103], v[102:103], 0, v[162:163]
	global_store_dwordx2 v[102:103], v[100:101], off offset:2048
	v_lshlrev_b32_e32 v104, 16, v150
	v_mul_f32_e32 v92, 0xbfb8aa3b, v92
	v_exp_f32_e32 v100, v92
	v_mul_f32_e32 v92, 0xbfb8aa3b, v104
	v_exp_f32_e32 v101, v92
	s_nop 0
	v_pk_add_f32 v[100:101], v[100:101], 1.0 op_sel_hi:[1,0]
	s_nop 0
	v_mul_f32_e32 v92, v100, v101
	v_rcp_f32_e32 v92, v92
	s_nop 0
	v_mul_f32_e32 v92, v92, v104
	v_mul_f32_e32 v100, v88, v92
	v_and_b32_e32 v88, 0xffff0000, v150
	v_mul_f32_e32 v92, 0xbfb8aa3b, v93
	v_mul_f32_e32 v93, 0xbfb8aa3b, v88
	v_exp_f32_e32 v92, v92
	v_exp_f32_e32 v93, v93
	s_nop 0
	v_pk_add_f32 v[92:93], v[92:93], 1.0 op_sel_hi:[1,0]
	s_nop 0
	v_mul_f32_e32 v92, v92, v93
	v_rcp_f32_e32 v92, v92
	v_lshlrev_b32_e32 v93, 16, v151
	v_mul_f32_e32 v88, v92, v88
	v_mul_f32_e32 v92, v89, v88
	v_mul_f32_e32 v88, 0xbfb8aa3b, v94
	v_mul_f32_e32 v89, 0xbfb8aa3b, v93
	v_exp_f32_e32 v88, v88
	v_exp_f32_e32 v89, v89
	s_nop 0
	v_pk_add_f32 v[88:89], v[88:89], 1.0 op_sel_hi:[1,0]
	s_nop 0
	v_mul_f32_e32 v88, v88, v89
	v_rcp_f32_e32 v88, v88
	s_nop 0
	v_mul_f32_e32 v88, v88, v93
	v_and_b32_e32 v93, 0xffff0000, v151
	v_mul_f32_e32 v90, v90, v88
	v_mul_f32_e32 v88, 0xbfb8aa3b, v95
	v_mul_f32_e32 v89, 0xbfb8aa3b, v93
	v_exp_f32_e32 v88, v88
	v_exp_f32_e32 v89, v89
	s_nop 0
	v_pk_add_f32 v[88:89], v[88:89], 1.0 op_sel_hi:[1,0]
	s_nop 0
	v_mul_f32_e32 v88, v88, v89
	v_rcp_f32_e32 v88, v88
	s_nop 0
	v_mul_f32_e32 v88, v88, v93
	v_mul_f32_e32 v89, v91, v88
	v_cvt_pk_bf16_f32 v88, v100, v92
	v_cvt_pk_bf16_f32 v89, v90, v89
	global_store_dwordx2 v[102:103], v[88:89], off offset:2056
	v_lshlrev_b32_e32 v92, 16, v128
	v_mul_f32_e32 v84, 0xbfb8aa3b, v84
	v_exp_f32_e32 v90, v84
	v_mul_f32_e32 v84, 0xbfb8aa3b, v92
	v_exp_f32_e32 v91, v84
	v_lshlrev_b64 v[88:89], 12, v[166:167]
	v_pk_add_f32 v[90:91], v[90:91], 1.0 op_sel_hi:[1,0]
	s_nop 0
	v_mul_f32_e32 v84, v90, v91
	v_rcp_f32_e32 v84, v84
	s_nop 0
	v_mul_f32_e32 v84, v84, v92
	v_mul_f32_e32 v90, v80, v84
	v_and_b32_e32 v80, 0xffff0000, v128
	v_mul_f32_e32 v84, 0xbfb8aa3b, v85
	v_mul_f32_e32 v85, 0xbfb8aa3b, v80
	v_exp_f32_e32 v84, v84
	v_exp_f32_e32 v85, v85
	s_nop 0
	v_pk_add_f32 v[84:85], v[84:85], 1.0 op_sel_hi:[1,0]
	s_nop 0
	v_mul_f32_e32 v84, v84, v85
	v_rcp_f32_e32 v84, v84
	v_lshlrev_b32_e32 v85, 16, v129
	v_mul_f32_e32 v80, v84, v80
	v_mul_f32_e32 v84, v81, v80
	v_mul_f32_e32 v80, 0xbfb8aa3b, v86
	v_mul_f32_e32 v81, 0xbfb8aa3b, v85
	v_exp_f32_e32 v80, v80
	v_exp_f32_e32 v81, v81
	s_nop 0
	v_pk_add_f32 v[80:81], v[80:81], 1.0 op_sel_hi:[1,0]
	s_nop 0
	v_mul_f32_e32 v80, v80, v81
	v_rcp_f32_e32 v80, v80
	s_nop 0
	v_mul_f32_e32 v80, v80, v85
	v_and_b32_e32 v85, 0xffff0000, v129
	v_mul_f32_e32 v82, v82, v80
	v_mul_f32_e32 v80, 0xbfb8aa3b, v87
	v_mul_f32_e32 v81, 0xbfb8aa3b, v85
	v_exp_f32_e32 v80, v80
	v_exp_f32_e32 v81, v81
	s_nop 0
; __device__ __forceinline__ unsigned cvt_pk_bf16(float lo, float hi) { unsigned r; asm volatile("v_cvt_pk_bf16_f32 %0, %1, %2" : "=v"(r) : "v"(lo), "v"(hi)); return r; }
; __device__ __forceinline__ float bflo(unsigned w) { return __uint_as_float(w << 16); }
; __device__ __forceinline__ float bfhi(unsigned w) { return __uint_as_float(w & 0xffff0000u); }
; __device__ __forceinline__ float sig_silu_(float g, float b) { return b * fast_rcp((1.0f + fast_exp2(-1.4426950408889634f * g)) * (1.0f + fast_exp2(-1.4426950408889634f * b))); }
;     __device__ __forceinline__ void operator()(const AccT& acc, const Unit& u, int wr, int wc, int fr, int fq) const {
;     ...
; #pragma unroll
;         for (int ai = 0; ai < 2; ++ai)
; #pragma unroll
;             for (int m = 0; m < 4; ++m) {
;                 const int row = row0 + ai * HALF + m * 16;
; #pragma unroll
;                 for (int n = 0; n < 2; ++n) {
;                     const unsigned g_lo = gsv[ai * 4 + m][2 * n], g_hi = gsv[ai * 4 + m][2 * n + 1];
;                     const f32x4 a0 = acc[ai][0][m][n], g0 = acc[ai][1][m][n];
;                     const float o0 = a0[0] * sig_silu_(g0[0], bflo(g_lo)), o1 = a0[1] * sig_silu_(g0[1], bfhi(g_lo));
;                     const float o2 = a0[2] * sig_silu_(g0[2], bflo(g_hi)), o3 = a0[3] * sig_silu_(g0[3], bfhi(g_hi));
;                     u32x2 w; w[0] = cvt_pk_bf16(o0, o1); w[1] = cvt_pk_bf16(o2, o3);
;                     *(u32x2*)(mixed + (size_t)row * DM + 1024 + ch + 4 * n) = w;
	v_pk_add_f32 v[80:81], v[80:81], 1.0 op_sel_hi:[1,0]
	s_nop 0
	v_mul_f32_e32 v80, v80, v81
	v_rcp_f32_e32 v80, v80
	s_nop 0
	v_mul_f32_e32 v80, v80, v85
	v_mul_f32_e32 v81, v83, v80
	v_cvt_pk_bf16_f32 v80, v90, v84
	v_cvt_pk_bf16_f32 v81, v82, v81
	v_lshl_add_u64 v[82:83], s[6:7], 0, v[88:89]
	v_lshl_add_u64 v[82:83], v[82:83], 0, v[162:163]
	global_store_dwordx2 v[82:83], v[80:81], off offset:2048
	v_lshlrev_b32_e32 v84, 16, v130
	v_mul_f32_e32 v72, 0xbfb8aa3b, v72
	v_exp_f32_e32 v80, v72
	v_mul_f32_e32 v72, 0xbfb8aa3b, v84
	v_exp_f32_e32 v81, v72
	s_nop 0
	v_pk_add_f32 v[80:81], v[80:81], 1.0 op_sel_hi:[1,0]
	s_nop 0
	v_mul_f32_e32 v72, v80, v81
	v_rcp_f32_e32 v72, v72
	s_nop 0
	v_mul_f32_e32 v72, v72, v84
	v_mul_f32_e32 v80, v68, v72
	v_and_b32_e32 v68, 0xffff0000, v130
	v_mul_f32_e32 v72, 0xbfb8aa3b, v73
	v_mul_f32_e32 v73, 0xbfb8aa3b, v68
	v_exp_f32_e32 v72, v72
	v_exp_f32_e32 v73, v73
	s_nop 0
	v_pk_add_f32 v[72:73], v[72:73], 1.0 op_sel_hi:[1,0]
	s_nop 0
	v_mul_f32_e32 v72, v72, v73
	v_rcp_f32_e32 v72, v72
	v_lshlrev_b32_e32 v73, 16, v131
	v_mul_f32_e32 v68, v72, v68
	v_mul_f32_e32 v72, v69, v68
	v_mul_f32_e32 v68, 0xbfb8aa3b, v74
	v_mul_f32_e32 v69, 0xbfb8aa3b, v73
	v_exp_f32_e32 v68, v68
	v_exp_f32_e32 v69, v69
	s_nop 0
	v_pk_add_f32 v[68:69], v[68:69], 1.0 op_sel_hi:[1,0]
	s_nop 0
	v_mul_f32_e32 v68, v68, v69
	v_rcp_f32_e32 v68, v68
	s_nop 0
	v_mul_f32_e32 v68, v68, v73
	v_and_b32_e32 v73, 0xffff0000, v131
	v_mul_f32_e32 v70, v70, v68
	v_mul_f32_e32 v68, 0xbfb8aa3b, v75
	v_mul_f32_e32 v69, 0xbfb8aa3b, v73
	v_exp_f32_e32 v68, v68
	v_exp_f32_e32 v69, v69
	s_nop 0
	v_pk_add_f32 v[68:69], v[68:69], 1.0 op_sel_hi:[1,0]
	s_nop 0
	v_mul_f32_e32 v68, v68, v69
	v_rcp_f32_e32 v68, v68
	s_nop 0
	v_mul_f32_e32 v68, v68, v73
	v_mul_f32_e32 v69, v71, v68
	v_cvt_pk_bf16_f32 v68, v80, v72
	v_cvt_pk_bf16_f32 v69, v70, v69
	global_store_dwordx2 v[82:83], v[68:69], off offset:2056
	v_lshlrev_b32_e32 v72, 16, v116
	v_mul_f32_e32 v64, 0xbfb8aa3b, v64
	v_exp_f32_e32 v70, v64
	v_mul_f32_e32 v64, 0xbfb8aa3b, v72
	v_exp_f32_e32 v71, v64
	v_lshlrev_b64 v[68:69], 12, v[164:165]
	v_pk_add_f32 v[70:71], v[70:71], 1.0 op_sel_hi:[1,0]
	s_nop 0
	v_mul_f32_e32 v64, v70, v71
	v_rcp_f32_e32 v64, v64
	s_nop 0
	v_mul_f32_e32 v64, v64, v72
	v_mul_f32_e32 v70, v60, v64
	v_and_b32_e32 v60, 0xffff0000, v116
	v_mul_f32_e32 v64, 0xbfb8aa3b, v65
	v_mul_f32_e32 v65, 0xbfb8aa3b, v60
	v_exp_f32_e32 v64, v64
	v_exp_f32_e32 v65, v65
	s_nop 0
	v_pk_add_f32 v[64:65], v[64:65], 1.0 op_sel_hi:[1,0]
	s_nop 0
	v_mul_f32_e32 v64, v64, v65
	v_rcp_f32_e32 v64, v64
	v_lshlrev_b32_e32 v65, 16, v117
	v_mul_f32_e32 v60, v64, v60
	v_mul_f32_e32 v64, v61, v60
	v_mul_f32_e32 v60, 0xbfb8aa3b, v66
	v_mul_f32_e32 v61, 0xbfb8aa3b, v65
	v_exp_f32_e32 v60, v60
	v_exp_f32_e32 v61, v61
	s_nop 0
	v_pk_add_f32 v[60:61], v[60:61], 1.0 op_sel_hi:[1,0]
	s_nop 0
	v_mul_f32_e32 v60, v60, v61
	v_rcp_f32_e32 v60, v60
	s_nop 0
	v_mul_f32_e32 v60, v60, v65
	v_and_b32_e32 v65, 0xffff0000, v117
	v_mul_f32_e32 v62, v62, v60
	v_mul_f32_e32 v60, 0xbfb8aa3b, v67
	v_mul_f32_e32 v61, 0xbfb8aa3b, v65
	v_exp_f32_e32 v60, v60
	v_exp_f32_e32 v61, v61
	s_nop 0
	v_pk_add_f32 v[60:61], v[60:61], 1.0 op_sel_hi:[1,0]
	s_nop 0
	v_mul_f32_e32 v60, v60, v61
	v_rcp_f32_e32 v60, v60
	s_nop 0
	v_mul_f32_e32 v60, v60, v65
	v_mul_f32_e32 v61, v63, v60
	v_cvt_pk_bf16_f32 v60, v70, v64
	v_cvt_pk_bf16_f32 v61, v62, v61
	v_lshl_add_u64 v[62:63], s[6:7], 0, v[68:69]
	v_lshl_add_u64 v[62:63], v[62:63], 0, v[162:163]
	global_store_dwordx2 v[62:63], v[60:61], off offset:2048
	v_lshlrev_b32_e32 v64, 16, v118
	v_mul_f32_e32 v52, 0xbfb8aa3b, v52
	v_exp_f32_e32 v60, v52
	v_mul_f32_e32 v52, 0xbfb8aa3b, v64
	v_exp_f32_e32 v61, v52
	s_nop 0
	v_pk_add_f32 v[60:61], v[60:61], 1.0 op_sel_hi:[1,0]
	s_nop 0
	v_mul_f32_e32 v52, v60, v61
	v_rcp_f32_e32 v52, v52
	s_nop 0
	v_mul_f32_e32 v52, v52, v64
	v_mul_f32_e32 v60, v48, v52
	v_and_b32_e32 v48, 0xffff0000, v118
	v_mul_f32_e32 v52, 0xbfb8aa3b, v53
	v_mul_f32_e32 v53, 0xbfb8aa3b, v48
	v_exp_f32_e32 v52, v52
	v_exp_f32_e32 v53, v53
	s_nop 0
	v_pk_add_f32 v[52:53], v[52:53], 1.0 op_sel_hi:[1,0]
	s_nop 0
	v_mul_f32_e32 v52, v52, v53
	v_rcp_f32_e32 v52, v52
	v_lshlrev_b32_e32 v53, 16, v119
	v_mul_f32_e32 v48, v52, v48
	v_mul_f32_e32 v52, v49, v48
	v_mul_f32_e32 v48, 0xbfb8aa3b, v54
	v_mul_f32_e32 v49, 0xbfb8aa3b, v53
	v_exp_f32_e32 v48, v48
	v_exp_f32_e32 v49, v49
	s_nop 0
	v_pk_add_f32 v[48:49], v[48:49], 1.0 op_sel_hi:[1,0]
	s_nop 0
	v_mul_f32_e32 v48, v48, v49
	v_rcp_f32_e32 v48, v48
	s_nop 0
	v_mul_f32_e32 v48, v48, v53
	v_and_b32_e32 v53, 0xffff0000, v119
	v_mul_f32_e32 v50, v50, v48
	v_mul_f32_e32 v48, 0xbfb8aa3b, v55
	v_mul_f32_e32 v49, 0xbfb8aa3b, v53
	v_exp_f32_e32 v48, v48
	v_exp_f32_e32 v49, v49
	s_nop 0
	v_pk_add_f32 v[48:49], v[48:49], 1.0 op_sel_hi:[1,0]
	s_nop 0
	v_mul_f32_e32 v48, v48, v49
	v_rcp_f32_e32 v48, v48
	s_nop 0
	v_mul_f32_e32 v48, v48, v53
	v_mul_f32_e32 v49, v51, v48
	v_cvt_pk_bf16_f32 v48, v60, v52
	v_cvt_pk_bf16_f32 v49, v50, v49
	global_store_dwordx2 v[62:63], v[48:49], off offset:2056
	v_lshlrev_b32_e32 v50, 16, v96
	v_mul_f32_e32 v44, 0xbfb8aa3b, v44
	v_exp_f32_e32 v48, v44
	v_mul_f32_e32 v44, 0xbfb8aa3b, v50
	v_exp_f32_e32 v49, v44
	s_mov_b64 s[6:7], 0x90000
	v_pk_add_f32 v[48:49], v[48:49], 1.0 op_sel_hi:[1,0]
	s_nop 0
	v_mul_f32_e32 v44, v48, v49
	v_rcp_f32_e32 v44, v44
	s_nop 0
	v_mul_f32_e32 v44, v44, v50
	v_mul_f32_e32 v48, v40, v44
	v_and_b32_e32 v40, 0xffff0000, v96
	v_mul_f32_e32 v44, 0xbfb8aa3b, v45
	v_mul_f32_e32 v45, 0xbfb8aa3b, v40
	v_exp_f32_e32 v44, v44
	v_exp_f32_e32 v45, v45
	s_nop 0
	v_pk_add_f32 v[44:45], v[44:45], 1.0 op_sel_hi:[1,0]
	s_nop 0
; __device__ __forceinline__ unsigned cvt_pk_bf16(float lo, float hi) { unsigned r; asm volatile("v_cvt_pk_bf16_f32 %0, %1, %2" : "=v"(r) : "v"(lo), "v"(hi)); return r; }
; __device__ __forceinline__ float bflo(unsigned w) { return __uint_as_float(w << 16); }
; __device__ __forceinline__ float bfhi(unsigned w) { return __uint_as_float(w & 0xffff0000u); }
; __device__ __forceinline__ float sig_silu_(float g, float b) { return b * fast_rcp((1.0f + fast_exp2(-1.4426950408889634f * g)) * (1.0f + fast_exp2(-1.4426950408889634f * b))); }
;     __device__ __forceinline__ void operator()(const AccT& acc, const Unit& u, int wr, int wc, int fr, int fq) const {
;     ...
; #pragma unroll
;         for (int ai = 0; ai < 2; ++ai)
; #pragma unroll
;             for (int m = 0; m < 4; ++m) {
;                 const int row = row0 + ai * HALF + m * 16;
; #pragma unroll
;                 for (int n = 0; n < 2; ++n) {
;                     const unsigned g_lo = gsv[ai * 4 + m][2 * n], g_hi = gsv[ai * 4 + m][2 * n + 1];
;                     const f32x4 a0 = acc[ai][0][m][n], g0 = acc[ai][1][m][n];
;                     const float o0 = a0[0] * sig_silu_(g0[0], bflo(g_lo)), o1 = a0[1] * sig_silu_(g0[1], bfhi(g_lo));
;                     const float o2 = a0[2] * sig_silu_(g0[2], bflo(g_hi)), o3 = a0[3] * sig_silu_(g0[3], bfhi(g_hi));
;                     u32x2 w; w[0] = cvt_pk_bf16(o0, o1); w[1] = cvt_pk_bf16(o2, o3);
;                     *(u32x2*)(mixed + (size_t)row * DM + 1024 + ch + 4 * n) = w;
	v_mul_f32_e32 v44, v44, v45
	v_rcp_f32_e32 v44, v44
	v_lshlrev_b32_e32 v45, 16, v97
	v_mul_f32_e32 v40, v44, v40
	v_mul_f32_e32 v44, v41, v40
	v_mul_f32_e32 v40, 0xbfb8aa3b, v46
	v_mul_f32_e32 v41, 0xbfb8aa3b, v45
	v_exp_f32_e32 v40, v40
	v_exp_f32_e32 v41, v41
	s_nop 0
	v_pk_add_f32 v[40:41], v[40:41], 1.0 op_sel_hi:[1,0]
	s_nop 0
	v_mul_f32_e32 v40, v40, v41
	v_rcp_f32_e32 v40, v40
	s_nop 0
	v_mul_f32_e32 v40, v40, v45
	v_and_b32_e32 v45, 0xffff0000, v97
	v_mul_f32_e32 v42, v42, v40
	v_mul_f32_e32 v40, 0xbfb8aa3b, v47
	v_mul_f32_e32 v41, 0xbfb8aa3b, v45
	v_exp_f32_e32 v40, v40
	v_exp_f32_e32 v41, v41
	s_nop 0
	v_pk_add_f32 v[40:41], v[40:41], 1.0 op_sel_hi:[1,0]
	s_nop 0
	v_mul_f32_e32 v40, v40, v41
	v_rcp_f32_e32 v40, v40
	s_nop 0
	v_mul_f32_e32 v40, v40, v45
	v_mul_f32_e32 v41, v43, v40
	v_cvt_pk_bf16_f32 v40, v48, v44
	v_cvt_pk_bf16_f32 v41, v42, v41
	v_lshl_add_u64 v[42:43], v[140:141], 0, s[6:7]
	global_store_dwordx2 v[42:43], v[40:41], off offset:2048
	v_lshlrev_b32_e32 v44, 16, v98
	v_mul_f32_e32 v36, 0xbfb8aa3b, v36
	v_exp_f32_e32 v40, v36
	v_mul_f32_e32 v36, 0xbfb8aa3b, v44
	v_exp_f32_e32 v41, v36
	s_nop 0
	v_pk_add_f32 v[40:41], v[40:41], 1.0 op_sel_hi:[1,0]
	s_nop 0
	v_mul_f32_e32 v36, v40, v41
	v_rcp_f32_e32 v36, v36
	s_nop 0
	v_mul_f32_e32 v36, v36, v44
	v_mul_f32_e32 v40, v32, v36
	v_and_b32_e32 v32, 0xffff0000, v98
	v_mul_f32_e32 v36, 0xbfb8aa3b, v37
	v_mul_f32_e32 v37, 0xbfb8aa3b, v32
	v_exp_f32_e32 v36, v36
	v_exp_f32_e32 v37, v37
	s_nop 0
	v_pk_add_f32 v[36:37], v[36:37], 1.0 op_sel_hi:[1,0]
	s_nop 0
	v_mul_f32_e32 v36, v36, v37
	v_rcp_f32_e32 v36, v36
	v_lshlrev_b32_e32 v37, 16, v99
	v_mul_f32_e32 v32, v36, v32
	v_mul_f32_e32 v36, v33, v32
	v_mul_f32_e32 v32, 0xbfb8aa3b, v38
	v_mul_f32_e32 v33, 0xbfb8aa3b, v37
	v_exp_f32_e32 v32, v32
	v_exp_f32_e32 v33, v33
	s_nop 0
	v_pk_add_f32 v[32:33], v[32:33], 1.0 op_sel_hi:[1,0]
	s_nop 0
	v_mul_f32_e32 v32, v32, v33
	v_rcp_f32_e32 v32, v32
	s_nop 0
	v_mul_f32_e32 v32, v32, v37
	v_and_b32_e32 v37, 0xffff0000, v99
	v_mul_f32_e32 v34, v34, v32
	v_mul_f32_e32 v32, 0xbfb8aa3b, v39
	v_mul_f32_e32 v33, 0xbfb8aa3b, v37
	v_exp_f32_e32 v32, v32
	v_exp_f32_e32 v33, v33
	s_nop 0
	v_pk_add_f32 v[32:33], v[32:33], 1.0 op_sel_hi:[1,0]
	s_nop 0
	v_mul_f32_e32 v32, v32, v33
	v_rcp_f32_e32 v32, v32
	s_nop 0
	v_mul_f32_e32 v32, v32, v37
	v_mul_f32_e32 v33, v35, v32
	v_cvt_pk_bf16_f32 v32, v40, v36
	v_cvt_pk_bf16_f32 v33, v34, v33
	global_store_dwordx2 v[42:43], v[32:33], off offset:2056
	v_lshlrev_b32_e32 v34, 16, v76
	v_mul_f32_e32 v28, 0xbfb8aa3b, v28
	v_exp_f32_e32 v32, v28
	v_mul_f32_e32 v28, 0xbfb8aa3b, v34
	v_exp_f32_e32 v33, v28
	s_mov_b64 s[6:7], 0xa0000
	v_pk_add_f32 v[32:33], v[32:33], 1.0 op_sel_hi:[1,0]
	s_nop 0
	v_mul_f32_e32 v28, v32, v33
	v_rcp_f32_e32 v28, v28
	s_nop 0
	v_mul_f32_e32 v28, v28, v34
	v_mul_f32_e32 v32, v24, v28
	v_and_b32_e32 v24, 0xffff0000, v76
	v_mul_f32_e32 v28, 0xbfb8aa3b, v29
	v_mul_f32_e32 v29, 0xbfb8aa3b, v24
	v_exp_f32_e32 v28, v28
	v_exp_f32_e32 v29, v29
	s_nop 0
	v_pk_add_f32 v[28:29], v[28:29], 1.0 op_sel_hi:[1,0]
	s_nop 0
	v_mul_f32_e32 v28, v28, v29
	v_rcp_f32_e32 v28, v28
	v_lshlrev_b32_e32 v29, 16, v77
	v_mul_f32_e32 v24, v28, v24
	v_mul_f32_e32 v28, v25, v24
	v_mul_f32_e32 v24, 0xbfb8aa3b, v30
	v_mul_f32_e32 v25, 0xbfb8aa3b, v29
	v_exp_f32_e32 v24, v24
	v_exp_f32_e32 v25, v25
	s_nop 0
	v_pk_add_f32 v[24:25], v[24:25], 1.0 op_sel_hi:[1,0]
	s_nop 0
	v_mul_f32_e32 v24, v24, v25
	v_rcp_f32_e32 v24, v24
	s_nop 0
	v_mul_f32_e32 v24, v24, v29
	v_and_b32_e32 v29, 0xffff0000, v77
	v_mul_f32_e32 v26, v26, v24
	v_mul_f32_e32 v24, 0xbfb8aa3b, v31
	v_mul_f32_e32 v25, 0xbfb8aa3b, v29
	v_exp_f32_e32 v24, v24
	v_exp_f32_e32 v25, v25
	s_nop 0
	v_pk_add_f32 v[24:25], v[24:25], 1.0 op_sel_hi:[1,0]
	s_nop 0
	v_mul_f32_e32 v24, v24, v25
	v_rcp_f32_e32 v24, v24
	s_nop 0
	v_mul_f32_e32 v24, v24, v29
	v_mul_f32_e32 v25, v27, v24
	v_cvt_pk_bf16_f32 v24, v32, v28
	v_cvt_pk_bf16_f32 v25, v26, v25
	v_lshl_add_u64 v[26:27], v[140:141], 0, s[6:7]
	global_store_dwordx2 v[26:27], v[24:25], off offset:2048
	v_lshlrev_b32_e32 v28, 16, v78
	v_mul_f32_e32 v20, 0xbfb8aa3b, v20
	v_exp_f32_e32 v24, v20
	v_mul_f32_e32 v20, 0xbfb8aa3b, v28
	v_exp_f32_e32 v25, v20
	s_nop 0
	v_pk_add_f32 v[24:25], v[24:25], 1.0 op_sel_hi:[1,0]
	s_nop 0
	v_mul_f32_e32 v20, v24, v25
	v_rcp_f32_e32 v20, v20
	s_nop 0
	v_mul_f32_e32 v20, v20, v28
; __device__ __forceinline__ unsigned cvt_pk_bf16(float lo, float hi) { unsigned r; asm volatile("v_cvt_pk_bf16_f32 %0, %1, %2" : "=v"(r) : "v"(lo), "v"(hi)); return r; }
; __device__ __forceinline__ float bflo(unsigned w) { return __uint_as_float(w << 16); }
; __device__ __forceinline__ float bfhi(unsigned w) { return __uint_as_float(w & 0xffff0000u); }
; __device__ __forceinline__ float sig_silu_(float g, float b) { return b * fast_rcp((1.0f + fast_exp2(-1.4426950408889634f * g)) * (1.0f + fast_exp2(-1.4426950408889634f * b))); }
; #define PG8_WAIT_V(n) asm volatile("s_waitcnt vmcnt(" #n ")" ::: "memory")
; #define PG8_BAR __builtin_amdgcn_s_barrier()
; template <class Epi, class Sched>
; __device__ __forceinline__ void gemm_phase(int wv, LAS unsigned char* lds, const Gemm g, const Sched& S, const Epi& E) { LIDS
;     ...
;         if (!has_next) break;
; #pragma unroll
;         for (int a = 0; a < 2; ++a)
; #pragma unroll
;             for (int b = 0; b < 2; ++b)
; #pragma unroll
;                 for (int m = 0; m < 4; ++m)
; #pragma unroll
;                     for (int n = 0; n < 2; ++n) acc[a][b][m][n] = zero4;
;         cur = nxt; cA = nA; cB = nB; ++ui;
;     }
;     PG8_WAIT_V(0);
;     if (wr == 0) PG8_BAR;
;     PG8_BAR;
;     __device__ __forceinline__ void operator()(const AccT& acc, const Unit& u, int wr, int wc, int fr, int fq) const {
;     ...
;                 for (int n = 0; n < 2; ++n) {
;                     const unsigned g_lo = gsv[ai * 4 + m][2 * n], g_hi = gsv[ai * 4 + m][2 * n + 1];
;                     const f32x4 a0 = acc[ai][0][m][n], g0 = acc[ai][1][m][n];
;                     const float o0 = a0[0] * sig_silu_(g0[0], bflo(g_lo)), o1 = a0[1] * sig_silu_(g0[1], bfhi(g_lo));
;                     const float o2 = a0[2] * sig_silu_(g0[2], bflo(g_hi)), o3 = a0[3] * sig_silu_(g0[3], bfhi(g_hi));
;                     u32x2 w; w[0] = cvt_pk_bf16(o0, o1); w[1] = cvt_pk_bf16(o2, o3);
;                     *(u32x2*)(mixed + (size_t)row * DM + 1024 + ch + 4 * n) = w;
;                     __builtin_amdgcn_sched_barrier(0);
;                 }
	v_mul_f32_e32 v24, v16, v20
	v_and_b32_e32 v16, 0xffff0000, v78
	v_mul_f32_e32 v20, 0xbfb8aa3b, v21
	v_mul_f32_e32 v21, 0xbfb8aa3b, v16
	v_exp_f32_e32 v20, v20
	v_exp_f32_e32 v21, v21
	s_nop 0
	v_pk_add_f32 v[20:21], v[20:21], 1.0 op_sel_hi:[1,0]
	s_nop 0
	v_mul_f32_e32 v20, v20, v21
	v_rcp_f32_e32 v20, v20
	v_lshlrev_b32_e32 v21, 16, v79
	v_mul_f32_e32 v16, v20, v16
	v_mul_f32_e32 v20, v17, v16
	v_mul_f32_e32 v16, 0xbfb8aa3b, v22
	v_mul_f32_e32 v17, 0xbfb8aa3b, v21
	v_exp_f32_e32 v16, v16
	v_exp_f32_e32 v17, v17
	s_nop 0
	v_pk_add_f32 v[16:17], v[16:17], 1.0 op_sel_hi:[1,0]
	s_nop 0
	v_mul_f32_e32 v16, v16, v17
	v_rcp_f32_e32 v16, v16
	s_nop 0
	v_mul_f32_e32 v16, v16, v21
	v_and_b32_e32 v21, 0xffff0000, v79
	v_mul_f32_e32 v18, v18, v16
	v_mul_f32_e32 v16, 0xbfb8aa3b, v23
	v_mul_f32_e32 v17, 0xbfb8aa3b, v21
	v_exp_f32_e32 v16, v16
	v_exp_f32_e32 v17, v17
	s_nop 0
	v_pk_add_f32 v[16:17], v[16:17], 1.0 op_sel_hi:[1,0]
	s_nop 0
	v_mul_f32_e32 v16, v16, v17
	v_rcp_f32_e32 v16, v16
	s_nop 0
	v_mul_f32_e32 v16, v16, v21
	v_mul_f32_e32 v17, v19, v16
	v_cvt_pk_bf16_f32 v16, v24, v20
	v_cvt_pk_bf16_f32 v17, v18, v17
	global_store_dwordx2 v[26:27], v[16:17], off offset:2056
	v_lshlrev_b32_e32 v18, 16, v56
	v_mul_f32_e32 v12, 0xbfb8aa3b, v12
	v_exp_f32_e32 v16, v12
	v_mul_f32_e32 v12, 0xbfb8aa3b, v18
	v_exp_f32_e32 v17, v12
	s_mov_b64 s[6:7], 0xb0000
	v_pk_add_f32 v[16:17], v[16:17], 1.0 op_sel_hi:[1,0]
	s_nop 0
	v_mul_f32_e32 v12, v16, v17
	v_rcp_f32_e32 v12, v12
	s_nop 0
	v_mul_f32_e32 v12, v12, v18
	v_mul_f32_e32 v16, v8, v12
	v_and_b32_e32 v8, 0xffff0000, v56
	v_mul_f32_e32 v12, 0xbfb8aa3b, v13
	v_mul_f32_e32 v13, 0xbfb8aa3b, v8
	v_exp_f32_e32 v12, v12
	v_exp_f32_e32 v13, v13
	s_nop 0
	v_pk_add_f32 v[12:13], v[12:13], 1.0 op_sel_hi:[1,0]
	s_nop 0
	v_mul_f32_e32 v12, v12, v13
	v_rcp_f32_e32 v12, v12
	v_lshlrev_b32_e32 v13, 16, v57
	v_mul_f32_e32 v8, v12, v8
	v_mul_f32_e32 v12, v9, v8
	v_mul_f32_e32 v8, 0xbfb8aa3b, v14
	v_mul_f32_e32 v9, 0xbfb8aa3b, v13
	v_exp_f32_e32 v8, v8
	v_exp_f32_e32 v9, v9
	s_nop 0
	v_pk_add_f32 v[8:9], v[8:9], 1.0 op_sel_hi:[1,0]
	s_nop 0
	v_mul_f32_e32 v8, v8, v9
	v_rcp_f32_e32 v8, v8
	s_nop 0
	v_mul_f32_e32 v8, v8, v13
	v_and_b32_e32 v13, 0xffff0000, v57
	v_mul_f32_e32 v10, v10, v8
	v_mul_f32_e32 v8, 0xbfb8aa3b, v15
	v_mul_f32_e32 v9, 0xbfb8aa3b, v13
	v_exp_f32_e32 v8, v8
	v_exp_f32_e32 v9, v9
	s_nop 0
	v_pk_add_f32 v[8:9], v[8:9], 1.0 op_sel_hi:[1,0]
	s_nop 0
	v_mul_f32_e32 v8, v8, v9
	v_rcp_f32_e32 v8, v8
	s_nop 0
	v_mul_f32_e32 v8, v8, v13
	v_mul_f32_e32 v9, v11, v8
	v_cvt_pk_bf16_f32 v8, v16, v12
	v_cvt_pk_bf16_f32 v9, v10, v9
	v_lshl_add_u64 v[10:11], v[140:141], 0, s[6:7]
	global_store_dwordx2 v[10:11], v[8:9], off offset:2048
	v_lshlrev_b32_e32 v12, 16, v58
	v_mul_f32_e32 v4, 0xbfb8aa3b, v4
	v_exp_f32_e32 v8, v4
	v_mul_f32_e32 v4, 0xbfb8aa3b, v12
	v_exp_f32_e32 v9, v4
	s_nop 0
	v_pk_add_f32 v[8:9], v[8:9], 1.0 op_sel_hi:[1,0]
	s_nop 0
	v_mul_f32_e32 v4, v8, v9
	v_rcp_f32_e32 v4, v4
	s_nop 0
	v_mul_f32_e32 v4, v4, v12
	v_mul_f32_e32 v8, v0, v4
	v_and_b32_e32 v0, 0xffff0000, v58
	v_mul_f32_e32 v4, 0xbfb8aa3b, v5
	v_mul_f32_e32 v5, 0xbfb8aa3b, v0
	v_exp_f32_e32 v4, v4
	v_exp_f32_e32 v5, v5
	s_nop 0
	v_pk_add_f32 v[4:5], v[4:5], 1.0 op_sel_hi:[1,0]
	s_nop 0
	v_mul_f32_e32 v4, v4, v5
	v_rcp_f32_e32 v4, v4
	v_lshlrev_b32_e32 v5, 16, v59
	v_mul_f32_e32 v0, v4, v0
	v_mul_f32_e32 v4, v1, v0
	v_mul_f32_e32 v0, 0xbfb8aa3b, v6
	v_mul_f32_e32 v1, 0xbfb8aa3b, v5
	v_exp_f32_e32 v0, v0
	v_exp_f32_e32 v1, v1
	s_nop 0
	v_pk_add_f32 v[0:1], v[0:1], 1.0 op_sel_hi:[1,0]
	s_nop 0
	v_mul_f32_e32 v0, v0, v1
	v_rcp_f32_e32 v0, v0
	s_nop 0
	v_mul_f32_e32 v0, v0, v5
	v_and_b32_e32 v5, 0xffff0000, v59
	v_mul_f32_e32 v2, v2, v0
	v_mul_f32_e32 v0, 0xbfb8aa3b, v7
	v_mul_f32_e32 v1, 0xbfb8aa3b, v5
	v_exp_f32_e32 v0, v0
	v_exp_f32_e32 v1, v1
	s_nop 0
	v_pk_add_f32 v[0:1], v[0:1], 1.0 op_sel_hi:[1,0]
	s_nop 0
	v_mul_f32_e32 v0, v0, v1
	v_rcp_f32_e32 v0, v0
	s_nop 0
	v_mul_f32_e32 v0, v0, v5
	v_mul_f32_e32 v1, v3, v0
	v_cvt_pk_bf16_f32 v0, v8, v4
	v_cvt_pk_bf16_f32 v1, v2, v1
	global_store_dwordx2 v[10:11], v[0:1], off offset:2056
	s_and_b64 vcc, exec, s[4:5]
	s_mov_b32 s16, s8
	s_mov_b32 s68, s10
	s_mov_b64 s[78:79], s[62:63]
	s_mov_b64 s[72:73], s[12:13]
	s_cbranch_vccz .LBB0_47
	s_waitcnt vmcnt(0)
	s_cmpk_gt_u32 s93, 0xff
	s_cbranch_scc1 .LBB0_58
	s_barrier

; #define PG8_STAGE(bufoff, gbase, voff) do { _Pragma("unroll") for (int _i = 0; _i < 2; ++_i) { const char* _gb = (const char*)(gbase) + (size_t)_i * (voff##_q); asm volatile("" : "+s"(_gb)); \
;         __builtin_amdgcn_global_load_lds((const unsigned*)(_gb + (voff)), (LAS unsigned*)(lds + (bufoff) + ldsw + _i * 8192), 16, 0, 0); } } while (0)
; #define PG8_LDA(dst, b, h) do { _Pragma("unroll") for (int m = 0; m < 4; ++m) _Pragma("unroll") for (int k = 0; k < 2; ++k) dst[m][k] = *(const LAS bf16x8*)(lds + PG8_SA(b, h) + aoff + m * 2048 + k * 1024); } while (0)
; #define PG8_LDB(dst, b, h) do { _Pragma("unroll") for (int n = 0; n < 2; ++n) _Pragma("unroll") for (int k = 0; k < 2; ++k) dst[n][k] = *(const LAS bf16x8*)(lds + PG8_SB(b, h) + boff + n * 2048 + k * 1024); } while (0)
; #define PG8_WAIT_L(n) asm volatile("s_waitcnt lgkmcnt(" #n ")" ::: "memory")
; #define PG8_BAR __builtin_amdgcn_s_barrier()
; #define PG8_SCHED __builtin_amdgcn_sched_barrier(0)
; template <class Epi, class Sched>
; __device__ __forceinline__ void gemm_phase(int wv, LAS unsigned char* lds, const Gemm g, const Sched& S, const Epi& E) { LIDS
;     ...
;         const bool has_next = S.next(ui + 1, nxt);
;         const char* nA = has_next ? (const char*)g.A + (size_t)nxt.pm * g.tstepA : cA; const char* nB = has_next ? (const char*)g.Bt + (size_t)nxt.pn * g.tstepB : cB;
;         for (int t = 0; t < nt; t += 2) {
;             const bool last = (t == nt - 2);
;             const char* a1 = cA + (size_t)(t + 1) * kstepA;
;             const char* a2 = last ? nA : cA + (size_t)(t + 2) * kstepA; const char* b2 = last ? nB : cB + (size_t)(t + 2) * kstepB;
;             const char* a3 = a2 + kstepA; const char* b3 = b2 + kstepB;
;             asm volatile("" : "+s"(a1), "+s"(a2), "+s"(b2), "+s"(a3), "+s"(b3));
;             PG8_LDB(B0, 0, 0); PG8_SCHED; PG8_LDA(At, 0, 0); PG8_STAGE(PG8_SA(1, 1), a1 + hstepA, voffA);
;             PG8_WAIT_L(8); PG8_BAR; PG8_WAIT_L(0); PG8_MMA(0, 0, At, B0); PG8_BAR; PG8_SCHED;
;             PG8_LDB(B1, 0, 1); PG8_STAGE(PG8_SB(0, 0), b2, voffB);
;             PG8_BAR; PG8_WAIT_L(0); PG8_MMA(0, 1, At, B1); PG8_BAR;
;             PG8_LDA(At, 0, 1); PG8_STAGE(PG8_SA(0, 0), a2, voffA);
;             PG8_BAR; PG8_WAIT_L(0); PG8_MMA(1, 0, At, B0); PG8_BAR; PG8_SCHED;
.LBB0_67:
	s_add_u32 s18, s78, 0x80
	s_addc_u32 s19, s79, 0
	s_add_u32 s6, s78, 0x100
	s_addc_u32 s7, s79, 0
	s_add_u32 s88, s72, 0x100
	s_addc_u32 s89, s73, 0
	s_add_u32 s90, s78, 0x180
	s_addc_u32 s91, s79, 0
	s_add_u32 s86, s72, 0x180
	s_addc_u32 s87, s73, 0
	s_add_i32 s23, 16, 0x10000
	s_mov_b64 s[84:85], s[90:91]
	v_add_u32_e32 v4, s23, v217
	ds_read_b128 v[6:9], v4
	ds_read_b128 v[10:13], v4 offset:1024
	ds_read_b128 v[14:17], v4 offset:2048
	ds_read_b128 v[18:21], v4 offset:3072
	s_add_u32 s20, s18, 0x18000
	s_addc_u32 s21, s19, 0
	s_add_i32 s25, s94, 0xc000
	s_add_u32 s18, s18, 0x24000
	ds_read_b128 v[22:25], v218
	ds_read_b128 v[26:29], v218 offset:1024
	ds_read_b128 v[30:33], v218 offset:2048
	ds_read_b128 v[34:37], v218 offset:3072
	ds_read_b128 v[38:41], v218 offset:4096
	ds_read_b128 v[42:45], v218 offset:5120
	ds_read_b128 v[46:49], v218 offset:6144
	ds_read_b128 v[50:53], v218 offset:7168
	s_mov_b32 m0, s25
	v_lshl_add_u64 v[54:55], s[20:21], 0, v[164:165]
	s_addc_u32 s19, s19, 0
	global_load_lds_dwordx4 v[54:55], off
	s_nop 0
	v_lshl_add_u64 v[54:55], s[18:19], 0, v[164:165]
	s_add_i32 s18, s94, 0xe000
	s_mov_b32 m0, s18
	s_nop 0
	global_load_lds_dwordx4 v[54:55], off
	s_waitcnt lgkmcnt(8)
	s_barrier
	s_waitcnt lgkmcnt(0)
	s_setprio 1
	v_mfma_f32_16x16x32_bf16 v[54:57], v[6:9], v[22:25], v[0:3]
	v_mfma_f32_16x16x32_bf16 v[58:61], v[14:17], v[22:25], v[0:3]
	v_mfma_f32_16x16x32_bf16 v[62:65], v[6:9], v[30:33], v[0:3]
	v_mfma_f32_16x16x32_bf16 v[66:69], v[14:17], v[30:33], v[0:3]
	v_mfma_f32_16x16x32_bf16 v[70:73], v[6:9], v[38:41], v[0:3]
	v_mfma_f32_16x16x32_bf16 v[74:77], v[14:17], v[38:41], v[0:3]
	v_mfma_f32_16x16x32_bf16 v[78:81], v[6:9], v[46:49], v[0:3]
	v_mfma_f32_16x16x32_bf16 v[82:85], v[14:17], v[46:49], v[0:3]
	v_mfma_f32_16x16x32_bf16 v[54:57], v[10:13], v[26:29], v[54:57]
	v_mfma_f32_16x16x32_bf16 v[58:61], v[18:21], v[26:29], v[58:61]
	v_mfma_f32_16x16x32_bf16 v[62:65], v[10:13], v[34:37], v[62:65]
	v_mfma_f32_16x16x32_bf16 v[66:69], v[18:21], v[34:37], v[66:69]
	v_mfma_f32_16x16x32_bf16 v[70:73], v[10:13], v[42:45], v[70:73]
	v_mfma_f32_16x16x32_bf16 v[74:77], v[18:21], v[42:45], v[74:77]
	v_mfma_f32_16x16x32_bf16 v[78:81], v[10:13], v[50:53], v[78:81]
	v_mfma_f32_16x16x32_bf16 v[82:85], v[18:21], v[50:53], v[82:85]
	s_setprio 0
	s_barrier
	s_add_i32 s24, 16, 0x14000
	v_add_u32_e32 v5, s24, v217
	s_mov_b64 s[20:21], s[88:89]
	ds_read_b128 v[86:89], v5
	ds_read_b128 v[90:93], v5 offset:1024
	ds_read_b128 v[94:97], v5 offset:2048
	ds_read_b128 v[98:101], v5 offset:3072
	s_add_i32 s23, s23, s59
	v_lshl_add_u64 v[102:103], s[20:21], 0, v[176:177]
	s_add_u32 s20, s88, 0xc000
	s_mov_b32 m0, s23
	s_addc_u32 s21, s89, 0
	s_add_i32 s19, s23, 0x2000
	global_load_lds_dwordx4 v[102:103], off
	s_mov_b32 m0, s19
	v_lshl_add_u64 v[102:103], s[20:21], 0, v[176:177]
	global_load_lds_dwordx4 v[102:103], off
	s_barrier
	s_waitcnt lgkmcnt(0)
	s_setprio 1
	v_mfma_f32_16x16x32_bf16 v[102:105], v[86:89], v[22:25], v[0:3]
	v_mfma_f32_16x16x32_bf16 v[22:25], v[94:97], v[22:25], v[0:3]
	v_mfma_f32_16x16x32_bf16 v[102:105], v[90:93], v[26:29], v[102:105]
	v_mfma_f32_16x16x32_bf16 v[22:25], v[98:101], v[26:29], v[22:25]
	v_mfma_f32_16x16x32_bf16 v[26:29], v[86:89], v[30:33], v[0:3]
	v_mfma_f32_16x16x32_bf16 v[30:33], v[94:97], v[30:33], v[0:3]
	v_mfma_f32_16x16x32_bf16 v[26:29], v[90:93], v[34:37], v[26:29]
	v_mfma_f32_16x16x32_bf16 v[30:33], v[98:101], v[34:37], v[30:33]
	v_mfma_f32_16x16x32_bf16 v[34:37], v[86:89], v[38:41], v[0:3]
	v_mfma_f32_16x16x32_bf16 v[38:41], v[94:97], v[38:41], v[0:3]
	v_mfma_f32_16x16x32_bf16 v[34:37], v[90:93], v[42:45], v[34:37]
	v_mfma_f32_16x16x32_bf16 v[38:41], v[98:101], v[42:45], v[38:41]
	v_mfma_f32_16x16x32_bf16 v[42:45], v[86:89], v[46:49], v[0:3]
	v_mfma_f32_16x16x32_bf16 v[46:49], v[94:97], v[46:49], v[0:3]
	v_mfma_f32_16x16x32_bf16 v[42:45], v[90:93], v[50:53], v[42:45]
	v_mfma_f32_16x16x32_bf16 v[46:49], v[98:101], v[50:53], v[46:49]
	s_setprio 0
	s_mov_b64 s[20:21], s[6:7]
	s_barrier
	ds_read_b128 v[50:53], v218 offset:16384
	ds_read_b128 v[106:109], v218 offset:17408
	ds_read_b128 v[110:113], v218 offset:18432
	ds_read_b128 v[114:117], v218 offset:19456
	ds_read_b128 v[118:121], v218 offset:20480
	ds_read_b128 v[122:125], v218 offset:21504
	ds_read_b128 v[126:129], v218 offset:22528
	ds_read_b128 v[130:133], v218 offset:23552
	s_mov_b32 m0, s94
	v_lshl_add_u64 v[134:135], s[20:21], 0, v[164:165]
	s_add_u32 s20, s6, 0xc000
	s_addc_u32 s21, s7, 0
	global_load_lds_dwordx4 v[134:135], off
	s_mov_b32 m0, s95
	v_lshl_add_u64 v[134:135], s[20:21], 0, v[164:165]
	global_load_lds_dwordx4 v[134:135], off
	s_barrier
	s_waitcnt lgkmcnt(0)
	s_setprio 1
	v_mfma_f32_16x16x32_bf16 v[134:137], v[6:9], v[50:53], v[0:3]
	v_mfma_f32_16x16x32_bf16 v[142:145], v[6:9], v[110:113], v[0:3]
	v_mfma_f32_16x16x32_bf16 v[150:153], v[6:9], v[118:121], v[0:3]
	v_mfma_f32_16x16x32_bf16 v[6:9], v[6:9], v[126:129], v[0:3]
	v_mfma_f32_16x16x32_bf16 v[134:137], v[10:13], v[106:109], v[134:137]
	v_mfma_f32_16x16x32_bf16 v[138:141], v[14:17], v[50:53], v[0:3]
	v_mfma_f32_16x16x32_bf16 v[142:145], v[10:13], v[114:117], v[142:145]
	v_mfma_f32_16x16x32_bf16 v[146:149], v[14:17], v[110:113], v[0:3]
	v_mfma_f32_16x16x32_bf16 v[150:153], v[10:13], v[122:125], v[150:153]
	v_mfma_f32_16x16x32_bf16 v[154:157], v[14:17], v[118:121], v[0:3]
	v_mfma_f32_16x16x32_bf16 v[8:11], v[10:13], v[130:133], v[6:9]
	v_mfma_f32_16x16x32_bf16 v[12:15], v[14:17], v[126:129], v[0:3]
	v_mfma_f32_16x16x32_bf16 v[138:141], v[18:21], v[106:109], v[138:141]
	v_mfma_f32_16x16x32_bf16 v[146:149], v[18:21], v[114:117], v[146:149]
	v_mfma_f32_16x16x32_bf16 v[154:157], v[18:21], v[122:125], v[154:157]
	v_mfma_f32_16x16x32_bf16 v[12:15], v[18:21], v[130:133], v[12:15]
	s_setprio 0
	s_barrier
; #define PG8_STAGE(bufoff, gbase, voff) do { _Pragma("unroll") for (int _i = 0; _i < 2; ++_i) { const char* _gb = (const char*)(gbase) + (size_t)_i * (voff##_q); asm volatile("" : "+s"(_gb)); \
;         __builtin_amdgcn_global_load_lds((const unsigned*)(_gb + (voff)), (LAS unsigned*)(lds + (bufoff) + ldsw + _i * 8192), 16, 0, 0); } } while (0)
; #define PG8_LDA(dst, b, h) do { _Pragma("unroll") for (int m = 0; m < 4; ++m) _Pragma("unroll") for (int k = 0; k < 2; ++k) dst[m][k] = *(const LAS bf16x8*)(lds + PG8_SA(b, h) + aoff + m * 2048 + k * 1024); } while (0)
; #define PG8_LDB(dst, b, h) do { _Pragma("unroll") for (int n = 0; n < 2; ++n) _Pragma("unroll") for (int k = 0; k < 2; ++k) dst[n][k] = *(const LAS bf16x8*)(lds + PG8_SB(b, h) + boff + n * 2048 + k * 1024); } while (0)
; #define PG8_MMA(ai, bj, At, Bt) do { __builtin_amdgcn_s_setprio(1); _Pragma("unroll") for (int m = 0; m < 4; ++m) _Pragma("unroll") for (int n = 0; n < 2; ++n) _Pragma("unroll") for (int k = 0; k < 2; ++k) \
;         acc[ai][bj][m][n] = __builtin_amdgcn_mfma_f32_16x16x32_bf16(Bt[n][k], At[m][k], acc[ai][bj][m][n], 0, 0, 0); __builtin_amdgcn_s_setprio(0); } while (0)
; #define PG8_WAIT_V(n) asm volatile("s_waitcnt vmcnt(" #n ")" ::: "memory")
; #define PG8_WAIT_L(n) asm volatile("s_waitcnt lgkmcnt(" #n ")" ::: "memory")
; #define PG8_BAR __builtin_amdgcn_s_barrier()
; #define PG8_SCHED __builtin_amdgcn_sched_barrier(0)
; template <class Epi, class Sched>
; __device__ __forceinline__ void gemm_phase(int wv, LAS unsigned char* lds, const Gemm g, const Sched& S, const Epi& E) { LIDS
;     ...
;             PG8_STAGE(PG8_SB(0, 1), b2 + hstepB, voffB);
;             PG8_WAIT_V(6); PG8_BAR; PG8_MMA(1, 1, At, B1); PG8_BAR;
;             PG8_LDB(B0, 1, 0); PG8_SCHED; PG8_LDA(At, 1, 0); PG8_STAGE(PG8_SA(0, 1), a2 + hstepA, voffA);
;             PG8_WAIT_L(8); PG8_BAR; PG8_WAIT_L(0); PG8_MMA(0, 0, At, B0); PG8_BAR; PG8_SCHED;
;             PG8_LDB(B1, 1, 1); PG8_STAGE(PG8_SB(1, 0), b3, voffB);
;             PG8_BAR; PG8_WAIT_L(0); PG8_MMA(0, 1, At, B1); PG8_BAR;
;             PG8_LDA(At, 1, 1); PG8_STAGE(PG8_SA(1, 0), a3, voffA);
;             PG8_BAR; PG8_WAIT_L(0); PG8_MMA(1, 0, At, B0); PG8_BAR; PG8_SCHED;
	s_add_u32 s20, s88, 0x18000
	s_addc_u32 s21, s89, 0
	s_add_i32 s24, s24, s59
	v_lshl_add_u64 v[6:7], s[20:21], 0, v[176:177]
	s_add_u32 s20, s88, 0x24000
	s_mov_b32 m0, s24
	s_addc_u32 s21, s89, 0
	global_load_lds_dwordx4 v[6:7], off
	s_nop 0
	v_lshl_add_u64 v[6:7], s[20:21], 0, v[176:177]
	s_add_i32 s20, s24, 0x2000
	s_mov_b32 m0, s20
	s_nop 0
	global_load_lds_dwordx4 v[6:7], off
	s_waitcnt vmcnt(6)
	s_barrier
	s_setprio 1
	v_mfma_f32_16x16x32_bf16 v[16:19], v[86:89], v[50:53], v[0:3]
	v_mfma_f32_16x16x32_bf16 v[50:53], v[94:97], v[50:53], v[0:3]
	v_mfma_f32_16x16x32_bf16 v[16:19], v[90:93], v[106:109], v[16:19]
	v_mfma_f32_16x16x32_bf16 v[50:53], v[98:101], v[106:109], v[50:53]
	v_mfma_f32_16x16x32_bf16 v[106:109], v[86:89], v[110:113], v[0:3]
	v_mfma_f32_16x16x32_bf16 v[110:113], v[94:97], v[110:113], v[0:3]
	v_mfma_f32_16x16x32_bf16 v[106:109], v[90:93], v[114:117], v[106:109]
	v_mfma_f32_16x16x32_bf16 v[110:113], v[98:101], v[114:117], v[110:113]
	v_mfma_f32_16x16x32_bf16 v[114:117], v[86:89], v[118:121], v[0:3]
	v_mfma_f32_16x16x32_bf16 v[86:89], v[86:89], v[126:129], v[0:3]
	v_mfma_f32_16x16x32_bf16 v[114:117], v[90:93], v[122:125], v[114:117]
	v_mfma_f32_16x16x32_bf16 v[118:121], v[94:97], v[118:121], v[0:3]
	v_mfma_f32_16x16x32_bf16 v[86:89], v[90:93], v[130:133], v[86:89]
	v_mfma_f32_16x16x32_bf16 v[90:93], v[94:97], v[126:129], v[0:3]
	v_mfma_f32_16x16x32_bf16 v[118:121], v[98:101], v[122:125], v[118:121]
	v_mfma_f32_16x16x32_bf16 v[90:93], v[98:101], v[130:133], v[90:93]
	s_setprio 0
	s_add_i32 s21, 16, 0x18000
	v_add_u32_e32 v6, s21, v217
	s_barrier
	ds_read_b128 v[94:97], v6
	ds_read_b128 v[98:101], v6 offset:1024
	ds_read_b128 v[122:125], v6 offset:2048
	ds_read_b128 v[126:129], v6 offset:3072
	s_add_u32 s26, s6, 0x18000
	s_addc_u32 s27, s7, 0
	s_add_u32 s6, s6, 0x24000
	s_mov_b32 m0, s56
	ds_read_b128 v[130:133], v218 offset:32768
	ds_read_b128 v[158:161], v218 offset:33792
	ds_read_b128 v[166:169], v218 offset:34816
	ds_read_b128 v[170:173], v218 offset:35840
	ds_read_b128 v[178:181], v218 offset:36864
	ds_read_b128 v[182:185], v218 offset:37888
	ds_read_b128 v[186:189], v218 offset:38912
	ds_read_b128 v[190:193], v218 offset:39936
	s_addc_u32 s7, s7, 0
	v_lshl_add_u64 v[20:21], s[26:27], 0, v[164:165]
	global_load_lds_dwordx4 v[20:21], off
	s_mov_b32 m0, s57
	v_lshl_add_u64 v[20:21], s[6:7], 0, v[164:165]
	global_load_lds_dwordx4 v[20:21], off
	s_waitcnt lgkmcnt(8)
	s_barrier
	s_waitcnt lgkmcnt(0)
	s_setprio 1
	v_mfma_f32_16x16x32_bf16 v[54:57], v[94:97], v[130:133], v[54:57]
	v_mfma_f32_16x16x32_bf16 v[58:61], v[122:125], v[130:133], v[58:61]
	v_mfma_f32_16x16x32_bf16 v[62:65], v[94:97], v[166:169], v[62:65]
	v_mfma_f32_16x16x32_bf16 v[66:69], v[122:125], v[166:169], v[66:69]
	v_mfma_f32_16x16x32_bf16 v[70:73], v[94:97], v[178:181], v[70:73]
	v_mfma_f32_16x16x32_bf16 v[74:77], v[122:125], v[178:181], v[74:77]
	v_mfma_f32_16x16x32_bf16 v[78:81], v[94:97], v[186:189], v[78:81]
	v_mfma_f32_16x16x32_bf16 v[82:85], v[122:125], v[186:189], v[82:85]
	v_mfma_f32_16x16x32_bf16 v[54:57], v[98:101], v[158:161], v[54:57]
	v_mfma_f32_16x16x32_bf16 v[58:61], v[126:129], v[158:161], v[58:61]
	v_mfma_f32_16x16x32_bf16 v[62:65], v[98:101], v[170:173], v[62:65]
	v_mfma_f32_16x16x32_bf16 v[66:69], v[126:129], v[170:173], v[66:69]
	v_mfma_f32_16x16x32_bf16 v[70:73], v[98:101], v[182:185], v[70:73]
	v_mfma_f32_16x16x32_bf16 v[74:77], v[126:129], v[182:185], v[74:77]
	v_mfma_f32_16x16x32_bf16 v[78:81], v[98:101], v[190:193], v[78:81]
	v_mfma_f32_16x16x32_bf16 v[82:85], v[126:129], v[190:193], v[82:85]
	s_setprio 0
	s_barrier
	s_add_i32 s27, 16, 0x1c000
	v_add_u32_e32 v7, s27, v217
	s_mov_b64 s[6:7], s[86:87]
	ds_read_b128 v[194:197], v7
	ds_read_b128 v[198:201], v7 offset:1024
	ds_read_b128 v[202:205], v7 offset:2048
	ds_read_b128 v[206:209], v7 offset:3072
	s_add_i32 s26, s21, s59
	v_lshl_add_u64 v[20:21], s[6:7], 0, v[176:177]
	s_add_u32 s6, s86, 0xc000
	s_mov_b32 m0, s26
	s_addc_u32 s7, s87, 0
	s_add_i32 s21, s26, 0x2000
	global_load_lds_dwordx4 v[20:21], off
	s_mov_b32 m0, s21
	v_lshl_add_u64 v[20:21], s[6:7], 0, v[176:177]
	global_load_lds_dwordx4 v[20:21], off
	s_barrier
	s_waitcnt lgkmcnt(0)
	s_setprio 1
	v_mfma_f32_16x16x32_bf16 v[102:105], v[194:197], v[130:133], v[102:105]
	v_mfma_f32_16x16x32_bf16 v[20:23], v[202:205], v[130:133], v[22:25]
	v_mfma_f32_16x16x32_bf16 v[24:27], v[194:197], v[166:169], v[26:29]
	v_mfma_f32_16x16x32_bf16 v[28:31], v[202:205], v[166:169], v[30:33]
	v_mfma_f32_16x16x32_bf16 v[32:35], v[194:197], v[178:181], v[34:37]
	v_mfma_f32_16x16x32_bf16 v[36:39], v[202:205], v[178:181], v[38:41]
	v_mfma_f32_16x16x32_bf16 v[40:43], v[194:197], v[186:189], v[42:45]
	v_mfma_f32_16x16x32_bf16 v[44:47], v[202:205], v[186:189], v[46:49]
	v_mfma_f32_16x16x32_bf16 v[102:105], v[198:201], v[158:161], v[102:105]
	v_mfma_f32_16x16x32_bf16 v[20:23], v[206:209], v[158:161], v[20:23]
	v_mfma_f32_16x16x32_bf16 v[24:27], v[198:201], v[170:173], v[24:27]
	v_mfma_f32_16x16x32_bf16 v[28:31], v[206:209], v[170:173], v[28:31]
	v_mfma_f32_16x16x32_bf16 v[32:35], v[198:201], v[182:185], v[32:35]
	v_mfma_f32_16x16x32_bf16 v[36:39], v[206:209], v[182:185], v[36:39]
	v_mfma_f32_16x16x32_bf16 v[40:43], v[198:201], v[190:193], v[40:43]
	v_mfma_f32_16x16x32_bf16 v[44:47], v[206:209], v[190:193], v[44:47]
	s_setprio 0
	s_mov_b64 s[6:7], s[84:85]
	s_barrier
; #define PG8_STAGE(bufoff, gbase, voff) do { _Pragma("unroll") for (int _i = 0; _i < 2; ++_i) { const char* _gb = (const char*)(gbase) + (size_t)_i * (voff##_q); asm volatile("" : "+s"(_gb)); \
;         __builtin_amdgcn_global_load_lds((const unsigned*)(_gb + (voff)), (LAS unsigned*)(lds + (bufoff) + ldsw + _i * 8192), 16, 0, 0); } } while (0)
; #define PG8_LDA(dst, b, h) do { _Pragma("unroll") for (int m = 0; m < 4; ++m) _Pragma("unroll") for (int k = 0; k < 2; ++k) dst[m][k] = *(const LAS bf16x8*)(lds + PG8_SA(b, h) + aoff + m * 2048 + k * 1024); } while (0)
; #define PG8_LDB(dst, b, h) do { _Pragma("unroll") for (int n = 0; n < 2; ++n) _Pragma("unroll") for (int k = 0; k < 2; ++k) dst[n][k] = *(const LAS bf16x8*)(lds + PG8_SB(b, h) + boff + n * 2048 + k * 1024); } while (0)
; #define PG8_MMA(ai, bj, At, Bt) do { __builtin_amdgcn_s_setprio(1); _Pragma("unroll") for (int m = 0; m < 4; ++m) _Pragma("unroll") for (int n = 0; n < 2; ++n) _Pragma("unroll") for (int k = 0; k < 2; ++k) \
;         acc[ai][bj][m][n] = __builtin_amdgcn_mfma_f32_16x16x32_bf16(Bt[n][k], At[m][k], acc[ai][bj][m][n], 0, 0, 0); __builtin_amdgcn_s_setprio(0); } while (0)
; template <class Epi, class Sched>
; __device__ __forceinline__ void gemm_phase(int wv, LAS unsigned char* lds, const Gemm g, const Sched& S, const Epi& E) { LIDS
;     ...
;         for (int t = 0; t < nt; t += 2) {
;             const bool last = (t == nt - 2);
;             const char* a1 = cA + (size_t)(t + 1) * kstepA;
;             const char* a2 = last ? nA : cA + (size_t)(t + 2) * kstepA; const char* b2 = last ? nB : cB + (size_t)(t + 2) * kstepB;
;             const char* a3 = a2 + kstepA; const char* b3 = b2 + kstepB;
;             asm volatile("" : "+s"(a1), "+s"(a2), "+s"(b2), "+s"(a3), "+s"(b3));
;             PG8_LDB(B0, 0, 0); PG8_SCHED; PG8_LDA(At, 0, 0); PG8_STAGE(PG8_SA(1, 1), a1 + hstepA, voffA);
;             PG8_WAIT_L(8); PG8_BAR; PG8_WAIT_L(0); PG8_MMA(0, 0, At, B0); PG8_BAR; PG8_SCHED;
;     ...
;             PG8_LDB(B1, 1, 1); PG8_STAGE(PG8_SB(1, 0), b3, voffB);
;             PG8_BAR; PG8_WAIT_L(0); PG8_MMA(0, 1, At, B1); PG8_BAR;
;             PG8_LDA(At, 1, 1); PG8_STAGE(PG8_SA(1, 0), a3, voffA);
;             PG8_BAR; PG8_WAIT_L(0); PG8_MMA(1, 0, At, B0); PG8_BAR; PG8_SCHED;
;             PG8_STAGE(PG8_SB(1, 1), b3 + hstepB, voffB);
;             PG8_WAIT_V(6); PG8_BAR; PG8_MMA(1, 1, At, B1); PG8_BAR;
	ds_read_b128 v[130:133], v218 offset:49152
	ds_read_b128 v[158:161], v218 offset:50176
	ds_read_b128 v[166:169], v218 offset:51200
	ds_read_b128 v[170:173], v218 offset:52224
	ds_read_b128 v[178:181], v218 offset:53248
	ds_read_b128 v[182:185], v218 offset:54272
	ds_read_b128 v[186:189], v218 offset:55296
	ds_read_b128 v[190:193], v218 offset:56320
	s_mov_b32 m0, s4
	v_lshl_add_u64 v[48:49], s[6:7], 0, v[164:165]
	s_add_u32 s6, s84, 0xc000
	s_addc_u32 s7, s85, 0
	global_load_lds_dwordx4 v[48:49], off
	s_mov_b32 m0, s5
	v_lshl_add_u64 v[48:49], s[6:7], 0, v[164:165]
	global_load_lds_dwordx4 v[48:49], off
	s_barrier
	s_waitcnt lgkmcnt(0)
	s_setprio 1
	v_mfma_f32_16x16x32_bf16 v[134:137], v[94:97], v[130:133], v[134:137]
	v_mfma_f32_16x16x32_bf16 v[138:141], v[122:125], v[130:133], v[138:141]
	v_mfma_f32_16x16x32_bf16 v[142:145], v[94:97], v[166:169], v[142:145]
	v_mfma_f32_16x16x32_bf16 v[146:149], v[122:125], v[166:169], v[146:149]
	v_mfma_f32_16x16x32_bf16 v[150:153], v[94:97], v[178:181], v[150:153]
	v_mfma_f32_16x16x32_bf16 v[154:157], v[122:125], v[178:181], v[154:157]
	v_mfma_f32_16x16x32_bf16 v[8:11], v[94:97], v[186:189], v[8:11]
	v_mfma_f32_16x16x32_bf16 v[12:15], v[122:125], v[186:189], v[12:15]
	v_mfma_f32_16x16x32_bf16 v[134:137], v[98:101], v[158:161], v[134:137]
	v_mfma_f32_16x16x32_bf16 v[138:141], v[126:129], v[158:161], v[138:141]
	v_mfma_f32_16x16x32_bf16 v[142:145], v[98:101], v[170:173], v[142:145]
	v_mfma_f32_16x16x32_bf16 v[146:149], v[126:129], v[170:173], v[146:149]
	v_mfma_f32_16x16x32_bf16 v[150:153], v[98:101], v[182:185], v[150:153]
	v_mfma_f32_16x16x32_bf16 v[154:157], v[126:129], v[182:185], v[154:157]
	v_mfma_f32_16x16x32_bf16 v[8:11], v[98:101], v[190:193], v[8:11]
	v_mfma_f32_16x16x32_bf16 v[12:15], v[126:129], v[190:193], v[12:15]
	s_setprio 0
	s_barrier
	s_add_u32 s6, s86, 0x18000
	s_addc_u32 s7, s87, 0
	s_add_i32 s27, s27, s59
	v_lshl_add_u64 v[48:49], s[6:7], 0, v[176:177]
	s_add_u32 s6, s86, 0x24000
	s_mov_b32 m0, s27
	s_addc_u32 s7, s87, 0
	s_add_i32 s22, s27, 0x2000
	global_load_lds_dwordx4 v[48:49], off
	s_mov_b32 m0, s22
	v_lshl_add_u64 v[48:49], s[6:7], 0, v[176:177]
	global_load_lds_dwordx4 v[48:49], off
	s_waitcnt vmcnt(6)
	s_barrier
	s_setprio 1
	v_mfma_f32_16x16x32_bf16 v[16:19], v[194:197], v[130:133], v[16:19]
	v_mfma_f32_16x16x32_bf16 v[48:51], v[202:205], v[130:133], v[50:53]
	v_mfma_f32_16x16x32_bf16 v[94:97], v[194:197], v[166:169], v[106:109]
	v_mfma_f32_16x16x32_bf16 v[98:101], v[202:205], v[166:169], v[110:113]
	v_mfma_f32_16x16x32_bf16 v[106:109], v[194:197], v[178:181], v[114:117]
	v_mfma_f32_16x16x32_bf16 v[110:113], v[202:205], v[178:181], v[118:121]
	v_mfma_f32_16x16x32_bf16 v[86:89], v[194:197], v[186:189], v[86:89]
	v_mfma_f32_16x16x32_bf16 v[90:93], v[202:205], v[186:189], v[90:93]
	v_mfma_f32_16x16x32_bf16 v[16:19], v[198:201], v[158:161], v[16:19]
	v_mfma_f32_16x16x32_bf16 v[48:51], v[206:209], v[158:161], v[48:51]
	v_mfma_f32_16x16x32_bf16 v[94:97], v[198:201], v[170:173], v[94:97]
	v_mfma_f32_16x16x32_bf16 v[98:101], v[206:209], v[170:173], v[98:101]
	v_mfma_f32_16x16x32_bf16 v[106:109], v[198:201], v[182:185], v[106:109]
	v_mfma_f32_16x16x32_bf16 v[110:113], v[206:209], v[182:185], v[110:113]
	v_mfma_f32_16x16x32_bf16 v[86:89], v[198:201], v[190:193], v[86:89]
	v_mfma_f32_16x16x32_bf16 v[90:93], v[206:209], v[190:193], v[90:93]
	s_setprio 0
	s_add_u32 s6, s78, 0x200
	s_addc_u32 s7, s79, 0
	s_add_u32 s86, s72, 0x200
	s_addc_u32 s87, s73, 0
	s_add_u32 s78, s78, 0x280
	s_addc_u32 s79, s79, 0
	s_add_u32 s72, s72, 0x280
	s_addc_u32 s73, s73, 0
	s_mov_b64 s[84:85], s[78:79]
	s_barrier
	ds_read_b128 v[114:117], v4
	ds_read_b128 v[118:121], v4 offset:1024
	ds_read_b128 v[122:125], v4 offset:2048
	ds_read_b128 v[126:129], v4 offset:3072
	s_add_u32 s28, s90, 0x18000
	s_addc_u32 s29, s91, 0
	ds_read_b128 v[130:133], v218
	ds_read_b128 v[158:161], v218 offset:1024
	ds_read_b128 v[166:169], v218 offset:2048
	ds_read_b128 v[170:173], v218 offset:3072
	ds_read_b128 v[178:181], v218 offset:4096
	ds_read_b128 v[182:185], v218 offset:5120
	ds_read_b128 v[186:189], v218 offset:6144
	ds_read_b128 v[190:193], v218 offset:7168
	s_mov_b32 m0, s25
	v_lshl_add_u64 v[52:53], s[28:29], 0, v[164:165]
	s_add_u32 s28, s90, 0x24000
	s_addc_u32 s29, s91, 0
	global_load_lds_dwordx4 v[52:53], off
	s_mov_b32 m0, s18
	v_lshl_add_u64 v[52:53], s[28:29], 0, v[164:165]
	global_load_lds_dwordx4 v[52:53], off
	s_waitcnt lgkmcnt(8)
	s_barrier
	s_waitcnt lgkmcnt(0)
	s_setprio 1
	v_mfma_f32_16x16x32_bf16 v[52:55], v[114:117], v[130:133], v[54:57]
	v_mfma_f32_16x16x32_bf16 v[56:59], v[122:125], v[130:133], v[58:61]
	v_mfma_f32_16x16x32_bf16 v[60:63], v[114:117], v[166:169], v[62:65]
	v_mfma_f32_16x16x32_bf16 v[64:67], v[122:125], v[166:169], v[66:69]
	v_mfma_f32_16x16x32_bf16 v[68:71], v[114:117], v[178:181], v[70:73]
	v_mfma_f32_16x16x32_bf16 v[72:75], v[122:125], v[178:181], v[74:77]
	v_mfma_f32_16x16x32_bf16 v[76:79], v[114:117], v[186:189], v[78:81]
	v_mfma_f32_16x16x32_bf16 v[80:83], v[122:125], v[186:189], v[82:85]
	v_mfma_f32_16x16x32_bf16 v[52:55], v[118:121], v[158:161], v[52:55]
	v_mfma_f32_16x16x32_bf16 v[56:59], v[126:129], v[158:161], v[56:59]
	v_mfma_f32_16x16x32_bf16 v[60:63], v[118:121], v[170:173], v[60:63]
	v_mfma_f32_16x16x32_bf16 v[64:67], v[126:129], v[170:173], v[64:67]
	v_mfma_f32_16x16x32_bf16 v[68:71], v[118:121], v[182:185], v[68:71]
	v_mfma_f32_16x16x32_bf16 v[72:75], v[126:129], v[182:185], v[72:75]
	v_mfma_f32_16x16x32_bf16 v[76:79], v[118:121], v[190:193], v[76:79]
	v_mfma_f32_16x16x32_bf16 v[80:83], v[126:129], v[190:193], v[80:83]
	s_setprio 0
	s_barrier
; #define PG8_STAGE(bufoff, gbase, voff) do { _Pragma("unroll") for (int _i = 0; _i < 2; ++_i) { const char* _gb = (const char*)(gbase) + (size_t)_i * (voff##_q); asm volatile("" : "+s"(_gb)); \
;         __builtin_amdgcn_global_load_lds((const unsigned*)(_gb + (voff)), (LAS unsigned*)(lds + (bufoff) + ldsw + _i * 8192), 16, 0, 0); } } while (0)
; #define PG8_LDA(dst, b, h) do { _Pragma("unroll") for (int m = 0; m < 4; ++m) _Pragma("unroll") for (int k = 0; k < 2; ++k) dst[m][k] = *(const LAS bf16x8*)(lds + PG8_SA(b, h) + aoff + m * 2048 + k * 1024); } while (0)
; #define PG8_LDB(dst, b, h) do { _Pragma("unroll") for (int n = 0; n < 2; ++n) _Pragma("unroll") for (int k = 0; k < 2; ++k) dst[n][k] = *(const LAS bf16x8*)(lds + PG8_SB(b, h) + boff + n * 2048 + k * 1024); } while (0)
; #define PG8_MMA(ai, bj, At, Bt) do { __builtin_amdgcn_s_setprio(1); _Pragma("unroll") for (int m = 0; m < 4; ++m) _Pragma("unroll") for (int n = 0; n < 2; ++n) _Pragma("unroll") for (int k = 0; k < 2; ++k) \
;         acc[ai][bj][m][n] = __builtin_amdgcn_mfma_f32_16x16x32_bf16(Bt[n][k], At[m][k], acc[ai][bj][m][n], 0, 0, 0); __builtin_amdgcn_s_setprio(0); } while (0)
; #define PG8_WAIT_V(n) asm volatile("s_waitcnt vmcnt(" #n ")" ::: "memory")
; #define PG8_WAIT_L(n) asm volatile("s_waitcnt lgkmcnt(" #n ")" ::: "memory")
; template <class Epi, class Sched>
; __device__ __forceinline__ void gemm_phase(int wv, LAS unsigned char* lds, const Gemm g, const Sched& S, const Epi& E) { LIDS
;     ...
;             PG8_LDB(B1, 0, 1); PG8_STAGE(PG8_SB(0, 0), b2, voffB);
;             PG8_BAR; PG8_WAIT_L(0); PG8_MMA(0, 1, At, B1); PG8_BAR;
;             PG8_LDA(At, 0, 1); PG8_STAGE(PG8_SA(0, 0), a2, voffA);
;             PG8_BAR; PG8_WAIT_L(0); PG8_MMA(1, 0, At, B0); PG8_BAR; PG8_SCHED;
;             PG8_STAGE(PG8_SB(0, 1), b2 + hstepB, voffB);
;             PG8_WAIT_V(6); PG8_BAR; PG8_MMA(1, 1, At, B1); PG8_BAR;
;             PG8_LDB(B0, 1, 0); PG8_SCHED; PG8_LDA(At, 1, 0); PG8_STAGE(PG8_SA(0, 1), a2 + hstepA, voffA);
;             PG8_WAIT_L(8); PG8_BAR; PG8_WAIT_L(0); PG8_MMA(0, 0, At, B0); PG8_BAR; PG8_SCHED;
;             PG8_LDB(B1, 1, 1); PG8_STAGE(PG8_SB(1, 0), b3, voffB);
;             PG8_BAR; PG8_WAIT_L(0); PG8_MMA(0, 1, At, B1); PG8_BAR;
;             PG8_LDA(At, 1, 1); PG8_STAGE(PG8_SA(1, 0), a3, voffA);
;             PG8_BAR; PG8_WAIT_L(0); PG8_MMA(1, 0, At, B0); PG8_BAR; PG8_SCHED;
	s_mov_b64 s[28:29], s[86:87]
	ds_read_b128 v[194:197], v5
	ds_read_b128 v[198:201], v5 offset:1024
	ds_read_b128 v[202:205], v5 offset:2048
	ds_read_b128 v[206:209], v5 offset:3072
	s_mov_b32 m0, s23
	v_lshl_add_u64 v[84:85], s[28:29], 0, v[176:177]
	s_add_u32 s28, s86, 0xc000
	s_addc_u32 s29, s87, 0
	global_load_lds_dwordx4 v[84:85], off
	s_mov_b32 m0, s19
	v_lshl_add_u64 v[84:85], s[28:29], 0, v[176:177]
	global_load_lds_dwordx4 v[84:85], off
	s_barrier
	s_waitcnt lgkmcnt(0)
	s_setprio 1
	v_mfma_f32_16x16x32_bf16 v[102:105], v[194:197], v[130:133], v[102:105]
	v_mfma_f32_16x16x32_bf16 v[20:23], v[202:205], v[130:133], v[20:23]
	v_mfma_f32_16x16x32_bf16 v[24:27], v[194:197], v[166:169], v[24:27]
	v_mfma_f32_16x16x32_bf16 v[28:31], v[202:205], v[166:169], v[28:31]
	v_mfma_f32_16x16x32_bf16 v[32:35], v[194:197], v[178:181], v[32:35]
	v_mfma_f32_16x16x32_bf16 v[36:39], v[202:205], v[178:181], v[36:39]
	v_mfma_f32_16x16x32_bf16 v[40:43], v[194:197], v[186:189], v[40:43]
	v_mfma_f32_16x16x32_bf16 v[44:47], v[202:205], v[186:189], v[44:47]
	v_mfma_f32_16x16x32_bf16 v[102:105], v[198:201], v[158:161], v[102:105]
	v_mfma_f32_16x16x32_bf16 v[20:23], v[206:209], v[158:161], v[20:23]
	v_mfma_f32_16x16x32_bf16 v[24:27], v[198:201], v[170:173], v[24:27]
	v_mfma_f32_16x16x32_bf16 v[28:31], v[206:209], v[170:173], v[28:31]
	v_mfma_f32_16x16x32_bf16 v[32:35], v[198:201], v[182:185], v[32:35]
	v_mfma_f32_16x16x32_bf16 v[36:39], v[206:209], v[182:185], v[36:39]
	v_mfma_f32_16x16x32_bf16 v[40:43], v[198:201], v[190:193], v[40:43]
	v_mfma_f32_16x16x32_bf16 v[44:47], v[206:209], v[190:193], v[44:47]
	s_setprio 0
	s_mov_b64 s[28:29], s[6:7]
	s_barrier
	ds_read_b128 v[130:133], v218 offset:16384
	ds_read_b128 v[158:161], v218 offset:17408
	ds_read_b128 v[166:169], v218 offset:18432
	ds_read_b128 v[170:173], v218 offset:19456
	ds_read_b128 v[178:181], v218 offset:20480
	ds_read_b128 v[182:185], v218 offset:21504
	ds_read_b128 v[186:189], v218 offset:22528
	ds_read_b128 v[190:193], v218 offset:23552
	s_mov_b32 m0, s94
	v_lshl_add_u64 v[84:85], s[28:29], 0, v[164:165]
	s_add_u32 s28, s6, 0xc000
	s_addc_u32 s29, s7, 0
	global_load_lds_dwordx4 v[84:85], off
	s_mov_b32 m0, s95
	v_lshl_add_u64 v[84:85], s[28:29], 0, v[164:165]
	global_load_lds_dwordx4 v[84:85], off
	s_barrier
	s_waitcnt lgkmcnt(0)
	s_setprio 1
	v_mfma_f32_16x16x32_bf16 v[134:137], v[114:117], v[130:133], v[134:137]
	v_mfma_f32_16x16x32_bf16 v[138:141], v[122:125], v[130:133], v[138:141]
	v_mfma_f32_16x16x32_bf16 v[142:145], v[114:117], v[166:169], v[142:145]
	v_mfma_f32_16x16x32_bf16 v[146:149], v[122:125], v[166:169], v[146:149]
	v_mfma_f32_16x16x32_bf16 v[150:153], v[114:117], v[178:181], v[150:153]
	v_mfma_f32_16x16x32_bf16 v[154:157], v[122:125], v[178:181], v[154:157]
	v_mfma_f32_16x16x32_bf16 v[8:11], v[114:117], v[186:189], v[8:11]
	v_mfma_f32_16x16x32_bf16 v[12:15], v[122:125], v[186:189], v[12:15]
	v_mfma_f32_16x16x32_bf16 v[134:137], v[118:121], v[158:161], v[134:137]
	v_mfma_f32_16x16x32_bf16 v[138:141], v[126:129], v[158:161], v[138:141]
	v_mfma_f32_16x16x32_bf16 v[142:145], v[118:121], v[170:173], v[142:145]
	v_mfma_f32_16x16x32_bf16 v[146:149], v[126:129], v[170:173], v[146:149]
	v_mfma_f32_16x16x32_bf16 v[150:153], v[118:121], v[182:185], v[150:153]
	v_mfma_f32_16x16x32_bf16 v[154:157], v[126:129], v[182:185], v[154:157]
	v_mfma_f32_16x16x32_bf16 v[8:11], v[118:121], v[190:193], v[8:11]
	v_mfma_f32_16x16x32_bf16 v[12:15], v[126:129], v[190:193], v[12:15]
	s_setprio 0
	s_barrier
	s_add_u32 s28, s86, 0x18000
	s_addc_u32 s29, s87, 0
	s_mov_b32 m0, s24
	v_lshl_add_u64 v[84:85], s[28:29], 0, v[176:177]
	s_add_u32 s28, s86, 0x24000
	s_addc_u32 s29, s87, 0
	global_load_lds_dwordx4 v[84:85], off
	s_mov_b32 m0, s20
	v_lshl_add_u64 v[84:85], s[28:29], 0, v[176:177]
	global_load_lds_dwordx4 v[84:85], off
	s_waitcnt vmcnt(6)
	s_barrier
	s_setprio 1
	v_mfma_f32_16x16x32_bf16 v[16:19], v[194:197], v[130:133], v[16:19]
	v_mfma_f32_16x16x32_bf16 v[48:51], v[202:205], v[130:133], v[48:51]
	v_mfma_f32_16x16x32_bf16 v[94:97], v[194:197], v[166:169], v[94:97]
	v_mfma_f32_16x16x32_bf16 v[98:101], v[202:205], v[166:169], v[98:101]
	v_mfma_f32_16x16x32_bf16 v[106:109], v[194:197], v[178:181], v[106:109]
	v_mfma_f32_16x16x32_bf16 v[110:113], v[202:205], v[178:181], v[110:113]
	v_mfma_f32_16x16x32_bf16 v[84:87], v[194:197], v[186:189], v[86:89]
	v_mfma_f32_16x16x32_bf16 v[88:91], v[202:205], v[186:189], v[90:93]
	v_mfma_f32_16x16x32_bf16 v[16:19], v[198:201], v[158:161], v[16:19]
	v_mfma_f32_16x16x32_bf16 v[48:51], v[206:209], v[158:161], v[48:51]
	v_mfma_f32_16x16x32_bf16 v[94:97], v[198:201], v[170:173], v[94:97]
	v_mfma_f32_16x16x32_bf16 v[98:101], v[206:209], v[170:173], v[98:101]
	v_mfma_f32_16x16x32_bf16 v[106:109], v[198:201], v[182:185], v[106:109]
	v_mfma_f32_16x16x32_bf16 v[110:113], v[206:209], v[182:185], v[110:113]
	v_mfma_f32_16x16x32_bf16 v[84:87], v[198:201], v[190:193], v[84:87]
	v_mfma_f32_16x16x32_bf16 v[88:91], v[206:209], v[190:193], v[88:91]
	s_setprio 0
	s_barrier
	ds_read_b128 v[114:117], v6
	ds_read_b128 v[118:121], v6 offset:1024
	ds_read_b128 v[122:125], v6 offset:2048
	ds_read_b128 v[126:129], v6 offset:3072
	s_add_u32 s28, s6, 0x18000
	s_addc_u32 s29, s7, 0
	s_add_u32 s6, s6, 0x24000
	s_mov_b32 m0, s56
	ds_read_b128 v[130:133], v218 offset:32768
	ds_read_b128 v[158:161], v218 offset:33792
	ds_read_b128 v[166:169], v218 offset:34816
	ds_read_b128 v[170:173], v218 offset:35840
	ds_read_b128 v[178:181], v218 offset:36864
	ds_read_b128 v[182:185], v218 offset:37888
	ds_read_b128 v[186:189], v218 offset:38912
	ds_read_b128 v[190:193], v218 offset:39936
	s_addc_u32 s7, s7, 0
	v_lshl_add_u64 v[92:93], s[28:29], 0, v[164:165]
	global_load_lds_dwordx4 v[92:93], off
	s_mov_b32 m0, s57
	v_lshl_add_u64 v[92:93], s[6:7], 0, v[164:165]
	global_load_lds_dwordx4 v[92:93], off
	s_waitcnt lgkmcnt(8)
	s_barrier
; #define PG8_STAGE(bufoff, gbase, voff) do { _Pragma("unroll") for (int _i = 0; _i < 2; ++_i) { const char* _gb = (const char*)(gbase) + (size_t)_i * (voff##_q); asm volatile("" : "+s"(_gb)); \
;         __builtin_amdgcn_global_load_lds((const unsigned*)(_gb + (voff)), (LAS unsigned*)(lds + (bufoff) + ldsw + _i * 8192), 16, 0, 0); } } while (0)
; #define PG8_LDA(dst, b, h) do { _Pragma("unroll") for (int m = 0; m < 4; ++m) _Pragma("unroll") for (int k = 0; k < 2; ++k) dst[m][k] = *(const LAS bf16x8*)(lds + PG8_SA(b, h) + aoff + m * 2048 + k * 1024); } while (0)
; #define PG8_LDB(dst, b, h) do { _Pragma("unroll") for (int n = 0; n < 2; ++n) _Pragma("unroll") for (int k = 0; k < 2; ++k) dst[n][k] = *(const LAS bf16x8*)(lds + PG8_SB(b, h) + boff + n * 2048 + k * 1024); } while (0)
; #define PG8_MMA(ai, bj, At, Bt) do { __builtin_amdgcn_s_setprio(1); _Pragma("unroll") for (int m = 0; m < 4; ++m) _Pragma("unroll") for (int n = 0; n < 2; ++n) _Pragma("unroll") for (int k = 0; k < 2; ++k) \
;         acc[ai][bj][m][n] = __builtin_amdgcn_mfma_f32_16x16x32_bf16(Bt[n][k], At[m][k], acc[ai][bj][m][n], 0, 0, 0); __builtin_amdgcn_s_setprio(0); } while (0)
; #define PG8_WAIT_V(n) asm volatile("s_waitcnt vmcnt(" #n ")" ::: "memory")
; #define PG8_WAIT_L(n) asm volatile("s_waitcnt lgkmcnt(" #n ")" ::: "memory")
; #define PG8_BAR __builtin_amdgcn_s_barrier()
; #define PG8_SCHED __builtin_amdgcn_sched_barrier(0)
; template <class Epi, class Sched>
; __device__ __forceinline__ void gemm_phase(int wv, LAS unsigned char* lds, const Gemm g, const Sched& S, const Epi& E) { LIDS
;     ...
;             PG8_WAIT_L(8); PG8_BAR; PG8_WAIT_L(0); PG8_MMA(0, 0, At, B0); PG8_BAR; PG8_SCHED;
;             PG8_LDB(B1, 1, 1); PG8_STAGE(PG8_SB(1, 0), b3, voffB);
;             PG8_BAR; PG8_WAIT_L(0); PG8_MMA(0, 1, At, B1); PG8_BAR;
;             PG8_LDA(At, 1, 1); PG8_STAGE(PG8_SA(1, 0), a3, voffA);
;             PG8_BAR; PG8_WAIT_L(0); PG8_MMA(1, 0, At, B0); PG8_BAR; PG8_SCHED;
;             PG8_STAGE(PG8_SB(1, 1), b3 + hstepB, voffB);
;             PG8_WAIT_V(6); PG8_BAR; PG8_MMA(1, 1, At, B1); PG8_BAR;
	s_waitcnt lgkmcnt(0)
	s_setprio 1
	v_mfma_f32_16x16x32_bf16 v[52:55], v[114:117], v[130:133], v[52:55]
	v_mfma_f32_16x16x32_bf16 v[56:59], v[122:125], v[130:133], v[56:59]
	v_mfma_f32_16x16x32_bf16 v[60:63], v[114:117], v[166:169], v[60:63]
	v_mfma_f32_16x16x32_bf16 v[64:67], v[122:125], v[166:169], v[64:67]
	v_mfma_f32_16x16x32_bf16 v[68:71], v[114:117], v[178:181], v[68:71]
	v_mfma_f32_16x16x32_bf16 v[72:75], v[122:125], v[178:181], v[72:75]
	v_mfma_f32_16x16x32_bf16 v[76:79], v[114:117], v[186:189], v[76:79]
	v_mfma_f32_16x16x32_bf16 v[80:83], v[122:125], v[186:189], v[80:83]
	v_mfma_f32_16x16x32_bf16 v[52:55], v[118:121], v[158:161], v[52:55]
	v_mfma_f32_16x16x32_bf16 v[56:59], v[126:129], v[158:161], v[56:59]
	v_mfma_f32_16x16x32_bf16 v[60:63], v[118:121], v[170:173], v[60:63]
	v_mfma_f32_16x16x32_bf16 v[64:67], v[126:129], v[170:173], v[64:67]
	v_mfma_f32_16x16x32_bf16 v[68:71], v[118:121], v[182:185], v[68:71]
	v_mfma_f32_16x16x32_bf16 v[72:75], v[126:129], v[182:185], v[72:75]
	v_mfma_f32_16x16x32_bf16 v[76:79], v[118:121], v[190:193], v[76:79]
	v_mfma_f32_16x16x32_bf16 v[80:83], v[126:129], v[190:193], v[80:83]
	s_setprio 0
	s_barrier
	s_mov_b64 s[6:7], s[72:73]
	ds_read_b128 v[194:197], v7
	ds_read_b128 v[198:201], v7 offset:1024
	ds_read_b128 v[202:205], v7 offset:2048
	ds_read_b128 v[206:209], v7 offset:3072
	s_mov_b32 m0, s26
	v_lshl_add_u64 v[92:93], s[6:7], 0, v[176:177]
	s_add_u32 s6, s72, 0xc000
	s_addc_u32 s7, s73, 0
	global_load_lds_dwordx4 v[92:93], off
	s_mov_b32 m0, s21
	v_lshl_add_u64 v[92:93], s[6:7], 0, v[176:177]
	global_load_lds_dwordx4 v[92:93], off
	s_barrier
	s_waitcnt lgkmcnt(0)
	s_setprio 1
	v_mfma_f32_16x16x32_bf16 v[102:105], v[194:197], v[130:133], v[102:105]
	v_mfma_f32_16x16x32_bf16 v[20:23], v[202:205], v[130:133], v[20:23]
	v_mfma_f32_16x16x32_bf16 v[24:27], v[194:197], v[166:169], v[24:27]
	v_mfma_f32_16x16x32_bf16 v[28:31], v[202:205], v[166:169], v[28:31]
	v_mfma_f32_16x16x32_bf16 v[32:35], v[194:197], v[178:181], v[32:35]
	v_mfma_f32_16x16x32_bf16 v[36:39], v[202:205], v[178:181], v[36:39]
	v_mfma_f32_16x16x32_bf16 v[40:43], v[194:197], v[186:189], v[40:43]
	v_mfma_f32_16x16x32_bf16 v[44:47], v[202:205], v[186:189], v[44:47]
	v_mfma_f32_16x16x32_bf16 v[102:105], v[198:201], v[158:161], v[102:105]
	v_mfma_f32_16x16x32_bf16 v[20:23], v[206:209], v[158:161], v[20:23]
	v_mfma_f32_16x16x32_bf16 v[24:27], v[198:201], v[170:173], v[24:27]
	v_mfma_f32_16x16x32_bf16 v[28:31], v[206:209], v[170:173], v[28:31]
	v_mfma_f32_16x16x32_bf16 v[32:35], v[198:201], v[182:185], v[32:35]
	v_mfma_f32_16x16x32_bf16 v[36:39], v[206:209], v[182:185], v[36:39]
	v_mfma_f32_16x16x32_bf16 v[40:43], v[198:201], v[190:193], v[40:43]
	v_mfma_f32_16x16x32_bf16 v[44:47], v[206:209], v[190:193], v[44:47]
	s_setprio 0
	s_mov_b64 s[6:7], s[84:85]
	s_barrier
	ds_read_b128 v[130:133], v218 offset:49152
	ds_read_b128 v[158:161], v218 offset:50176
	ds_read_b128 v[166:169], v218 offset:51200
	ds_read_b128 v[170:173], v218 offset:52224
	ds_read_b128 v[178:181], v218 offset:53248
	ds_read_b128 v[182:185], v218 offset:54272
	ds_read_b128 v[186:189], v218 offset:55296
	ds_read_b128 v[190:193], v218 offset:56320
	s_mov_b32 m0, s4
	v_lshl_add_u64 v[92:93], s[6:7], 0, v[164:165]
	s_add_u32 s6, s84, 0xc000
	s_addc_u32 s7, s85, 0
	global_load_lds_dwordx4 v[92:93], off
	s_mov_b32 m0, s5
	v_lshl_add_u64 v[92:93], s[6:7], 0, v[164:165]
	global_load_lds_dwordx4 v[92:93], off
	s_barrier
	s_waitcnt lgkmcnt(0)
	s_setprio 1
	v_mfma_f32_16x16x32_bf16 v[134:137], v[114:117], v[130:133], v[134:137]
	v_mfma_f32_16x16x32_bf16 v[138:141], v[122:125], v[130:133], v[138:141]
	v_mfma_f32_16x16x32_bf16 v[142:145], v[114:117], v[166:169], v[142:145]
	v_mfma_f32_16x16x32_bf16 v[146:149], v[122:125], v[166:169], v[146:149]
	v_mfma_f32_16x16x32_bf16 v[150:153], v[114:117], v[178:181], v[150:153]
	v_mfma_f32_16x16x32_bf16 v[154:157], v[122:125], v[178:181], v[154:157]
	v_mfma_f32_16x16x32_bf16 v[8:11], v[114:117], v[186:189], v[8:11]
	v_mfma_f32_16x16x32_bf16 v[12:15], v[122:125], v[186:189], v[12:15]
	v_mfma_f32_16x16x32_bf16 v[134:137], v[118:121], v[158:161], v[134:137]
	v_mfma_f32_16x16x32_bf16 v[138:141], v[126:129], v[158:161], v[138:141]
	v_mfma_f32_16x16x32_bf16 v[142:145], v[118:121], v[170:173], v[142:145]
	v_mfma_f32_16x16x32_bf16 v[146:149], v[126:129], v[170:173], v[146:149]
	v_mfma_f32_16x16x32_bf16 v[150:153], v[118:121], v[182:185], v[150:153]
	v_mfma_f32_16x16x32_bf16 v[154:157], v[126:129], v[182:185], v[154:157]
	v_mfma_f32_16x16x32_bf16 v[8:11], v[118:121], v[190:193], v[8:11]
	v_mfma_f32_16x16x32_bf16 v[12:15], v[126:129], v[190:193], v[12:15]
	s_setprio 0
	s_barrier
	s_add_u32 s6, s72, 0x18000
	s_addc_u32 s7, s73, 0
	s_mov_b32 m0, s27
	v_lshl_add_u64 v[92:93], s[6:7], 0, v[176:177]
	s_add_u32 s6, s72, 0x24000
	s_addc_u32 s7, s73, 0
	global_load_lds_dwordx4 v[92:93], off
	s_mov_b32 m0, s22
	v_lshl_add_u64 v[92:93], s[6:7], 0, v[176:177]
	global_load_lds_dwordx4 v[92:93], off
	s_waitcnt vmcnt(6)
	s_barrier
	s_setprio 1
	v_mfma_f32_16x16x32_bf16 v[16:19], v[194:197], v[130:133], v[16:19]
	v_mfma_f32_16x16x32_bf16 v[48:51], v[202:205], v[130:133], v[48:51]
	v_mfma_f32_16x16x32_bf16 v[92:95], v[194:197], v[166:169], v[94:97]
	v_mfma_f32_16x16x32_bf16 v[96:99], v[202:205], v[166:169], v[98:101]
	v_mfma_f32_16x16x32_bf16 v[106:109], v[194:197], v[178:181], v[106:109]
	v_mfma_f32_16x16x32_bf16 v[110:113], v[202:205], v[178:181], v[110:113]
	v_mfma_f32_16x16x32_bf16 v[84:87], v[194:197], v[186:189], v[84:87]
	v_mfma_f32_16x16x32_bf16 v[88:91], v[202:205], v[186:189], v[88:91]
	v_mfma_f32_16x16x32_bf16 v[16:19], v[198:201], v[158:161], v[16:19]
	v_mfma_f32_16x16x32_bf16 v[48:51], v[206:209], v[158:161], v[48:51]
	v_mfma_f32_16x16x32_bf16 v[92:95], v[198:201], v[170:173], v[92:95]
	v_mfma_f32_16x16x32_bf16 v[96:99], v[206:209], v[170:173], v[96:99]
	v_mfma_f32_16x16x32_bf16 v[106:109], v[198:201], v[182:185], v[106:109]
	v_mfma_f32_16x16x32_bf16 v[110:113], v[206:209], v[182:185], v[110:113]
	v_mfma_f32_16x16x32_bf16 v[84:87], v[198:201], v[190:193], v[84:87]
	v_mfma_f32_16x16x32_bf16 v[88:91], v[206:209], v[190:193], v[88:91]
	s_setprio 0
	s_add_u32 s86, s62, 0x80
	s_addc_u32 s87, s63, 0
	s_add_u32 s72, s68, 0x80
	s_addc_u32 s73, s69, 0
	s_barrier
; #define PG8_STAGE(bufoff, gbase, voff) do { _Pragma("unroll") for (int _i = 0; _i < 2; ++_i) { const char* _gb = (const char*)(gbase) + (size_t)_i * (voff##_q); asm volatile("" : "+s"(_gb)); \
;         __builtin_amdgcn_global_load_lds((const unsigned*)(_gb + (voff)), (LAS unsigned*)(lds + (bufoff) + ldsw + _i * 8192), 16, 0, 0); } } while (0)
; #define PG8_LDA(dst, b, h) do { _Pragma("unroll") for (int m = 0; m < 4; ++m) _Pragma("unroll") for (int k = 0; k < 2; ++k) dst[m][k] = *(const LAS bf16x8*)(lds + PG8_SA(b, h) + aoff + m * 2048 + k * 1024); } while (0)
; #define PG8_LDB(dst, b, h) do { _Pragma("unroll") for (int n = 0; n < 2; ++n) _Pragma("unroll") for (int k = 0; k < 2; ++k) dst[n][k] = *(const LAS bf16x8*)(lds + PG8_SB(b, h) + boff + n * 2048 + k * 1024); } while (0)
; #define PG8_WAIT_V(n) asm volatile("s_waitcnt vmcnt(" #n ")" ::: "memory")
; #define PG8_WAIT_L(n) asm volatile("s_waitcnt lgkmcnt(" #n ")" ::: "memory")
; #define PG8_BAR __builtin_amdgcn_s_barrier()
; #define PG8_SCHED __builtin_amdgcn_sched_barrier(0)
; template <class Epi, class Sched>
; __device__ __forceinline__ void gemm_phase(int wv, LAS unsigned char* lds, const Gemm g, const Sched& S, const Epi& E) { LIDS
;     ...
;             PG8_LDB(B0, 0, 0); PG8_SCHED; PG8_LDA(At, 0, 0); PG8_STAGE(PG8_SA(1, 1), a1 + hstepA, voffA);
;             PG8_WAIT_L(8); PG8_BAR; PG8_WAIT_L(0); PG8_MMA(0, 0, At, B0); PG8_BAR; PG8_SCHED;
;             PG8_LDB(B1, 0, 1); PG8_STAGE(PG8_SB(0, 0), b2, voffB);
;             PG8_BAR; PG8_WAIT_L(0); PG8_MMA(0, 1, At, B1); PG8_BAR;
;             PG8_LDA(At, 0, 1); PG8_STAGE(PG8_SA(0, 0), a2, voffA);
;             PG8_BAR; PG8_WAIT_L(0); PG8_MMA(1, 0, At, B0); PG8_BAR; PG8_SCHED;
;             PG8_STAGE(PG8_SB(0, 1), b2 + hstepB, voffB);
;             PG8_WAIT_V(6); PG8_BAR; PG8_MMA(1, 1, At, B1); PG8_BAR;
;             PG8_LDB(B0, 1, 0); PG8_SCHED; PG8_LDA(At, 1, 0); PG8_STAGE(PG8_SA(0, 1), a2 + hstepA, voffA);
;             PG8_WAIT_L(8); PG8_BAR; PG8_WAIT_L(0); PG8_MMA(0, 0, At, B0); PG8_BAR; PG8_SCHED;
;             PG8_LDB(B1, 1, 1); PG8_STAGE(PG8_SB(1, 0), b3, voffB);
;             PG8_BAR; PG8_WAIT_L(0); PG8_MMA(0, 1, At, B1); PG8_BAR;
;             PG8_LDA(At, 1, 1); PG8_STAGE(PG8_SA(1, 0), a3, voffA);
;             PG8_BAR; PG8_WAIT_L(0); PG8_MMA(1, 0, At, B0); PG8_BAR; PG8_SCHED;
	ds_read_b128 v[114:117], v4
	ds_read_b128 v[118:121], v4 offset:1024
	ds_read_b128 v[122:125], v4 offset:2048
	ds_read_b128 v[126:129], v4 offset:3072
	s_add_u32 s6, s78, 0x18000
	s_addc_u32 s7, s79, 0
	ds_read_b128 v[130:133], v218
	ds_read_b128 v[158:161], v218 offset:1024
	ds_read_b128 v[166:169], v218 offset:2048
	ds_read_b128 v[170:173], v218 offset:3072
	ds_read_b128 v[178:181], v218 offset:4096
	ds_read_b128 v[182:185], v218 offset:5120
	ds_read_b128 v[186:189], v218 offset:6144
	ds_read_b128 v[190:193], v218 offset:7168
	s_mov_b32 m0, s25
	v_lshl_add_u64 v[100:101], s[6:7], 0, v[164:165]
	s_add_u32 s6, s78, 0x24000
	s_addc_u32 s7, s79, 0
	global_load_lds_dwordx4 v[100:101], off
	s_mov_b32 m0, s18
	v_lshl_add_u64 v[100:101], s[6:7], 0, v[164:165]
	global_load_lds_dwordx4 v[100:101], off
	s_waitcnt lgkmcnt(8)
	s_barrier
	s_waitcnt lgkmcnt(0)
	s_setprio 1
	v_mfma_f32_16x16x32_bf16 v[52:55], v[114:117], v[130:133], v[52:55]
	v_mfma_f32_16x16x32_bf16 v[56:59], v[122:125], v[130:133], v[56:59]
	v_mfma_f32_16x16x32_bf16 v[60:63], v[114:117], v[166:169], v[60:63]
	v_mfma_f32_16x16x32_bf16 v[64:67], v[122:125], v[166:169], v[64:67]
	v_mfma_f32_16x16x32_bf16 v[68:71], v[114:117], v[178:181], v[68:71]
	v_mfma_f32_16x16x32_bf16 v[72:75], v[122:125], v[178:181], v[72:75]
	v_mfma_f32_16x16x32_bf16 v[76:79], v[114:117], v[186:189], v[76:79]
	v_mfma_f32_16x16x32_bf16 v[80:83], v[122:125], v[186:189], v[80:83]
	v_mfma_f32_16x16x32_bf16 v[52:55], v[118:121], v[158:161], v[52:55]
	v_mfma_f32_16x16x32_bf16 v[56:59], v[126:129], v[158:161], v[56:59]
	v_mfma_f32_16x16x32_bf16 v[60:63], v[118:121], v[170:173], v[60:63]
	v_mfma_f32_16x16x32_bf16 v[64:67], v[126:129], v[170:173], v[64:67]
	v_mfma_f32_16x16x32_bf16 v[68:71], v[118:121], v[182:185], v[68:71]
	v_mfma_f32_16x16x32_bf16 v[72:75], v[126:129], v[182:185], v[72:75]
	v_mfma_f32_16x16x32_bf16 v[76:79], v[118:121], v[190:193], v[76:79]
	v_mfma_f32_16x16x32_bf16 v[80:83], v[126:129], v[190:193], v[80:83]
	s_setprio 0
	s_barrier
	s_mov_b64 s[6:7], s[68:69]
	ds_read_b128 v[194:197], v5
	ds_read_b128 v[198:201], v5 offset:1024
	ds_read_b128 v[202:205], v5 offset:2048
	ds_read_b128 v[206:209], v5 offset:3072
	s_mov_b32 m0, s23
	v_lshl_add_u64 v[4:5], s[6:7], 0, v[176:177]
	s_add_u32 s6, s68, 0xc000
	s_addc_u32 s7, s69, 0
	global_load_lds_dwordx4 v[4:5], off
	s_mov_b32 m0, s19
	v_lshl_add_u64 v[4:5], s[6:7], 0, v[176:177]
	global_load_lds_dwordx4 v[4:5], off
	s_barrier
	s_waitcnt lgkmcnt(0)
	s_setprio 1
	v_mfma_f32_16x16x32_bf16 v[100:103], v[194:197], v[130:133], v[102:105]
	v_mfma_f32_16x16x32_bf16 v[20:23], v[202:205], v[130:133], v[20:23]
	v_mfma_f32_16x16x32_bf16 v[24:27], v[194:197], v[166:169], v[24:27]
	v_mfma_f32_16x16x32_bf16 v[28:31], v[202:205], v[166:169], v[28:31]
	v_mfma_f32_16x16x32_bf16 v[32:35], v[194:197], v[178:181], v[32:35]
	v_mfma_f32_16x16x32_bf16 v[36:39], v[202:205], v[178:181], v[36:39]
	v_mfma_f32_16x16x32_bf16 v[40:43], v[194:197], v[186:189], v[40:43]
	v_mfma_f32_16x16x32_bf16 v[44:47], v[202:205], v[186:189], v[44:47]
	v_mfma_f32_16x16x32_bf16 v[100:103], v[198:201], v[158:161], v[100:103]
	v_mfma_f32_16x16x32_bf16 v[20:23], v[206:209], v[158:161], v[20:23]
	v_mfma_f32_16x16x32_bf16 v[24:27], v[198:201], v[170:173], v[24:27]
	v_mfma_f32_16x16x32_bf16 v[28:31], v[206:209], v[170:173], v[28:31]
	v_mfma_f32_16x16x32_bf16 v[32:35], v[198:201], v[182:185], v[32:35]
	v_mfma_f32_16x16x32_bf16 v[36:39], v[206:209], v[182:185], v[36:39]
	v_mfma_f32_16x16x32_bf16 v[40:43], v[198:201], v[190:193], v[40:43]
	v_mfma_f32_16x16x32_bf16 v[160:163], v[206:209], v[190:193], v[44:47]
	s_setprio 0
	s_mov_b64 s[6:7], s[62:63]
	s_barrier
	ds_read_b128 v[44:47], v218 offset:16384
	ds_read_b128 v[130:133], v218 offset:17408
	ds_read_b128 v[166:169], v218 offset:18432
	ds_read_b128 v[170:173], v218 offset:19456
	ds_read_b128 v[178:181], v218 offset:20480
	ds_read_b128 v[182:185], v218 offset:21504
	ds_read_b128 v[186:189], v218 offset:22528
	ds_read_b128 v[190:193], v218 offset:23552
	s_mov_b32 m0, s94
	v_lshl_add_u64 v[4:5], s[6:7], 0, v[164:165]
	s_add_u32 s6, s62, 0xc000
	s_addc_u32 s7, s63, 0
	global_load_lds_dwordx4 v[4:5], off
	s_mov_b32 m0, s95
	v_lshl_add_u64 v[4:5], s[6:7], 0, v[164:165]
	global_load_lds_dwordx4 v[4:5], off
	s_barrier
	s_waitcnt lgkmcnt(0)
	s_setprio 1
	v_mfma_f32_16x16x32_bf16 v[134:137], v[114:117], v[44:47], v[134:137]
	v_mfma_f32_16x16x32_bf16 v[210:213], v[118:121], v[130:133], v[134:137]
	v_mfma_f32_16x16x32_bf16 v[134:137], v[122:125], v[44:47], v[138:141]
	v_mfma_f32_16x16x32_bf16 v[140:143], v[114:117], v[166:169], v[142:145]
	v_mfma_f32_16x16x32_bf16 v[220:223], v[118:121], v[170:173], v[140:143]
	v_mfma_f32_16x16x32_bf16 v[140:143], v[122:125], v[166:169], v[146:149]
	v_mfma_f32_16x16x32_bf16 v[224:227], v[126:129], v[170:173], v[140:143]
	v_mfma_f32_16x16x32_bf16 v[140:143], v[114:117], v[178:181], v[150:153]
	v_mfma_f32_16x16x32_bf16 v[148:151], v[118:121], v[182:185], v[140:143]
	v_mfma_f32_16x16x32_bf16 v[140:143], v[122:125], v[178:181], v[154:157]
	v_mfma_f32_16x16x32_bf16 v[8:11], v[114:117], v[186:189], v[8:11]
	v_mfma_f32_16x16x32_bf16 v[12:15], v[122:125], v[186:189], v[12:15]
	v_mfma_f32_16x16x32_bf16 v[136:139], v[126:129], v[130:133], v[134:137]
	v_mfma_f32_16x16x32_bf16 v[228:231], v[126:129], v[182:185], v[140:143]
	v_mfma_f32_16x16x32_bf16 v[8:11], v[118:121], v[190:193], v[8:11]
	v_mfma_f32_16x16x32_bf16 v[12:15], v[126:129], v[190:193], v[12:15]
	s_setprio 0
	s_barrier
	s_add_u32 s6, s68, 0x18000
	s_addc_u32 s7, s69, 0
	s_mov_b32 m0, s24
	v_lshl_add_u64 v[4:5], s[6:7], 0, v[176:177]
	s_add_u32 s6, s68, 0x24000
	s_addc_u32 s7, s69, 0
	global_load_lds_dwordx4 v[4:5], off
	s_mov_b32 m0, s20
	v_lshl_add_u64 v[4:5], s[6:7], 0, v[176:177]
	global_load_lds_dwordx4 v[4:5], off
	s_waitcnt vmcnt(6)
	s_barrier
; #define PG8_STAGE(bufoff, gbase, voff) do { _Pragma("unroll") for (int _i = 0; _i < 2; ++_i) { const char* _gb = (const char*)(gbase) + (size_t)_i * (voff##_q); asm volatile("" : "+s"(_gb)); \
;         __builtin_amdgcn_global_load_lds((const unsigned*)(_gb + (voff)), (LAS unsigned*)(lds + (bufoff) + ldsw + _i * 8192), 16, 0, 0); } } while (0)
; #define PG8_LDA(dst, b, h) do { _Pragma("unroll") for (int m = 0; m < 4; ++m) _Pragma("unroll") for (int k = 0; k < 2; ++k) dst[m][k] = *(const LAS bf16x8*)(lds + PG8_SA(b, h) + aoff + m * 2048 + k * 1024); } while (0)
; #define PG8_LDB(dst, b, h) do { _Pragma("unroll") for (int n = 0; n < 2; ++n) _Pragma("unroll") for (int k = 0; k < 2; ++k) dst[n][k] = *(const LAS bf16x8*)(lds + PG8_SB(b, h) + boff + n * 2048 + k * 1024); } while (0)
; #define PG8_MMA(ai, bj, At, Bt) do { __builtin_amdgcn_s_setprio(1); _Pragma("unroll") for (int m = 0; m < 4; ++m) _Pragma("unroll") for (int n = 0; n < 2; ++n) _Pragma("unroll") for (int k = 0; k < 2; ++k) \
;         acc[ai][bj][m][n] = __builtin_amdgcn_mfma_f32_16x16x32_bf16(Bt[n][k], At[m][k], acc[ai][bj][m][n], 0, 0, 0); __builtin_amdgcn_s_setprio(0); } while (0)
; #define PG8_WAIT_V(n) asm volatile("s_waitcnt vmcnt(" #n ")" ::: "memory")
; #define PG8_WAIT_L(n) asm volatile("s_waitcnt lgkmcnt(" #n ")" ::: "memory")
; #define PG8_BAR __builtin_amdgcn_s_barrier()
; #define PG8_SCHED __builtin_amdgcn_sched_barrier(0)
; template <class Epi, class Sched>
; __device__ __forceinline__ void gemm_phase(int wv, LAS unsigned char* lds, const Gemm g, const Sched& S, const Epi& E) { LIDS
;     ...
;             PG8_WAIT_V(6); PG8_BAR; PG8_MMA(1, 1, At, B1); PG8_BAR;
;             PG8_LDB(B0, 1, 0); PG8_SCHED; PG8_LDA(At, 1, 0); PG8_STAGE(PG8_SA(0, 1), a2 + hstepA, voffA);
;             PG8_WAIT_L(8); PG8_BAR; PG8_WAIT_L(0); PG8_MMA(0, 0, At, B0); PG8_BAR; PG8_SCHED;
;             PG8_LDB(B1, 1, 1); PG8_STAGE(PG8_SB(1, 0), b3, voffB);
;             PG8_BAR; PG8_WAIT_L(0); PG8_MMA(0, 1, At, B1); PG8_BAR;
;             PG8_LDA(At, 1, 1); PG8_STAGE(PG8_SA(1, 0), a3, voffA);
;             PG8_BAR; PG8_WAIT_L(0); PG8_MMA(1, 0, At, B0); PG8_BAR; PG8_SCHED;
	s_setprio 1
	v_mfma_f32_16x16x32_bf16 v[16:19], v[194:197], v[44:47], v[16:19]
	v_mfma_f32_16x16x32_bf16 v[44:47], v[202:205], v[44:47], v[48:51]
	v_mfma_f32_16x16x32_bf16 v[124:127], v[206:209], v[130:133], v[44:47]
	v_mfma_f32_16x16x32_bf16 v[44:47], v[194:197], v[166:169], v[92:95]
	v_mfma_f32_16x16x32_bf16 v[92:95], v[198:201], v[170:173], v[44:47]
	v_mfma_f32_16x16x32_bf16 v[44:47], v[202:205], v[166:169], v[96:99]
	v_mfma_f32_16x16x32_bf16 v[166:169], v[206:209], v[170:173], v[44:47]
	v_mfma_f32_16x16x32_bf16 v[44:47], v[194:197], v[178:181], v[106:109]
	v_mfma_f32_16x16x32_bf16 v[104:107], v[198:201], v[182:185], v[44:47]
	v_mfma_f32_16x16x32_bf16 v[44:47], v[202:205], v[178:181], v[110:113]
	v_mfma_f32_16x16x32_bf16 v[170:173], v[206:209], v[182:185], v[44:47]
	v_mfma_f32_16x16x32_bf16 v[44:47], v[194:197], v[186:189], v[84:87]
	v_mfma_f32_16x16x32_bf16 v[84:87], v[198:201], v[190:193], v[44:47]
	v_mfma_f32_16x16x32_bf16 v[44:47], v[202:205], v[186:189], v[88:91]
	v_mfma_f32_16x16x32_bf16 v[16:19], v[198:201], v[130:133], v[16:19]
	v_mfma_f32_16x16x32_bf16 v[88:91], v[206:209], v[190:193], v[44:47]
	s_setprio 0
	s_barrier
	ds_read_b128 v[178:181], v6
	ds_read_b128 v[182:185], v6 offset:1024
	ds_read_b128 v[186:189], v6 offset:2048
	ds_read_b128 v[190:193], v6 offset:3072
	s_add_u32 s6, s62, 0x18000
	s_addc_u32 s7, s63, 0
	ds_read_b128 v[44:47], v218 offset:32768
	ds_read_b128 v[48:51], v218 offset:33792
	ds_read_b128 v[96:99], v218 offset:34816
	ds_read_b128 v[108:111], v218 offset:35840
	ds_read_b128 v[112:115], v218 offset:36864
	ds_read_b128 v[194:197], v218 offset:37888
	ds_read_b128 v[198:201], v218 offset:38912
	ds_read_b128 v[202:205], v218 offset:39936
	s_mov_b32 m0, s56
	v_lshl_add_u64 v[4:5], s[6:7], 0, v[164:165]
	s_add_u32 s6, s62, 0x24000
	s_addc_u32 s7, s63, 0
	global_load_lds_dwordx4 v[4:5], off
	s_mov_b32 m0, s57
	v_lshl_add_u64 v[4:5], s[6:7], 0, v[164:165]
	global_load_lds_dwordx4 v[4:5], off
	s_waitcnt lgkmcnt(8)
	s_barrier
	s_waitcnt lgkmcnt(0)
	s_setprio 1
	v_mfma_f32_16x16x32_bf16 v[52:55], v[178:181], v[44:47], v[52:55]
	v_mfma_f32_16x16x32_bf16 v[152:155], v[182:185], v[48:51], v[52:55]
	v_mfma_f32_16x16x32_bf16 v[52:55], v[186:189], v[44:47], v[56:59]
	v_mfma_f32_16x16x32_bf16 v[156:159], v[190:193], v[48:51], v[52:55]
	v_mfma_f32_16x16x32_bf16 v[52:55], v[178:181], v[96:99], v[60:63]
	v_mfma_f32_16x16x32_bf16 v[140:143], v[182:185], v[108:111], v[52:55]
	v_mfma_f32_16x16x32_bf16 v[52:55], v[186:189], v[96:99], v[64:67]
	v_mfma_f32_16x16x32_bf16 v[144:147], v[190:193], v[108:111], v[52:55]
	v_mfma_f32_16x16x32_bf16 v[52:55], v[178:181], v[112:115], v[68:71]
	v_mfma_f32_16x16x32_bf16 v[128:131], v[182:185], v[194:197], v[52:55]
	v_mfma_f32_16x16x32_bf16 v[52:55], v[186:189], v[112:115], v[72:75]
	v_mfma_f32_16x16x32_bf16 v[132:135], v[190:193], v[194:197], v[52:55]
	v_mfma_f32_16x16x32_bf16 v[52:55], v[178:181], v[198:201], v[76:79]
	v_mfma_f32_16x16x32_bf16 v[116:119], v[182:185], v[202:205], v[52:55]
	v_mfma_f32_16x16x32_bf16 v[52:55], v[186:189], v[198:201], v[80:83]
	v_mfma_f32_16x16x32_bf16 v[120:123], v[190:193], v[202:205], v[52:55]
	s_setprio 0
	s_barrier
	s_mov_b64 s[6:7], s[72:73]
	ds_read_b128 v[206:209], v7
	ds_read_b128 v[232:235], v7 offset:1024
	ds_read_b128 v[236:239], v7 offset:2048
	ds_read_b128 v[240:243], v7 offset:3072
	s_mov_b32 m0, s26
	v_lshl_add_u64 v[4:5], s[6:7], 0, v[176:177]
	s_add_u32 s6, s72, 0xc000
	s_addc_u32 s7, s73, 0
	global_load_lds_dwordx4 v[4:5], off
	s_mov_b32 m0, s21
	v_lshl_add_u64 v[4:5], s[6:7], 0, v[176:177]
	global_load_lds_dwordx4 v[4:5], off
	s_barrier
	s_waitcnt lgkmcnt(0)
	s_setprio 1
	v_mfma_f32_16x16x32_bf16 v[4:7], v[206:209], v[44:47], v[100:103]
	v_mfma_f32_16x16x32_bf16 v[60:63], v[232:235], v[48:51], v[4:7]
	v_mfma_f32_16x16x32_bf16 v[4:7], v[236:239], v[44:47], v[20:23]
	v_mfma_f32_16x16x32_bf16 v[64:67], v[240:243], v[48:51], v[4:7]
	v_mfma_f32_16x16x32_bf16 v[4:7], v[206:209], v[96:99], v[24:27]
	v_mfma_f32_16x16x32_bf16 v[52:55], v[232:235], v[108:111], v[4:7]
	v_mfma_f32_16x16x32_bf16 v[4:7], v[236:239], v[96:99], v[28:31]
	v_mfma_f32_16x16x32_bf16 v[56:59], v[240:243], v[108:111], v[4:7]
	v_mfma_f32_16x16x32_bf16 v[4:7], v[206:209], v[112:115], v[32:35]
	v_mfma_f32_16x16x32_bf16 v[44:47], v[232:235], v[194:197], v[4:7]
	v_mfma_f32_16x16x32_bf16 v[4:7], v[236:239], v[112:115], v[36:39]
	v_mfma_f32_16x16x32_bf16 v[48:51], v[240:243], v[194:197], v[4:7]
	v_mfma_f32_16x16x32_bf16 v[4:7], v[206:209], v[198:201], v[40:43]
	v_mfma_f32_16x16x32_bf16 v[36:39], v[232:235], v[202:205], v[4:7]
	v_mfma_f32_16x16x32_bf16 v[4:7], v[236:239], v[198:201], v[160:163]
	v_mfma_f32_16x16x32_bf16 v[40:43], v[240:243], v[202:205], v[4:7]
	s_setprio 0
	s_mov_b64 s[6:7], s[86:87]
	s_barrier
	s_nop 3
	ds_read_b128 v[4:7], v218 offset:49152
	ds_read_b128 v[20:23], v218 offset:50176
	ds_read_b128 v[24:27], v218 offset:51200
	ds_read_b128 v[160:163], v218 offset:52224
	ds_read_b128 v[194:197], v218 offset:53248
	ds_read_b128 v[198:201], v218 offset:54272
	ds_read_b128 v[202:205], v218 offset:55296
	ds_read_b128 v[244:247], v218 offset:56320
	s_mov_b32 m0, s4
	v_lshl_add_u64 v[28:29], s[6:7], 0, v[164:165]
	s_add_u32 s6, s86, 0xc000
	s_addc_u32 s7, s87, 0
	global_load_lds_dwordx4 v[28:29], off
	s_mov_b32 m0, s5
	v_lshl_add_u64 v[28:29], s[6:7], 0, v[164:165]
	global_load_lds_dwordx4 v[28:29], off
	s_barrier
; __device__ __forceinline__ int lane_id_asm() { int x; asm volatile("v_mbcnt_lo_u32_b32 %0, -1, 0\n\tv_mbcnt_hi_u32_b32 %0, -1, %0" : "=&v"(x)); return x; }
; #define PG8_STAGE(bufoff, gbase, voff) do { _Pragma("unroll") for (int _i = 0; _i < 2; ++_i) { const char* _gb = (const char*)(gbase) + (size_t)_i * (voff##_q); asm volatile("" : "+s"(_gb)); \
;         __builtin_amdgcn_global_load_lds((const unsigned*)(_gb + (voff)), (LAS unsigned*)(lds + (bufoff) + ldsw + _i * 8192), 16, 0, 0); } } while (0)
; #define PG8_MMA(ai, bj, At, Bt) do { __builtin_amdgcn_s_setprio(1); _Pragma("unroll") for (int m = 0; m < 4; ++m) _Pragma("unroll") for (int n = 0; n < 2; ++n) _Pragma("unroll") for (int k = 0; k < 2; ++k) \
;         acc[ai][bj][m][n] = __builtin_amdgcn_mfma_f32_16x16x32_bf16(Bt[n][k], At[m][k], acc[ai][bj][m][n], 0, 0, 0); __builtin_amdgcn_s_setprio(0); } while (0)
; #define PG8_WAIT_V(n) asm volatile("s_waitcnt vmcnt(" #n ")" ::: "memory")
; #define PG8_WAIT_L(n) asm volatile("s_waitcnt lgkmcnt(" #n ")" ::: "memory")
; #define PG8_BAR __builtin_amdgcn_s_barrier()
; #define PG8_SCHED __builtin_amdgcn_sched_barrier(0)
; template <class Epi, class Sched>
; __device__ __forceinline__ void gemm_phase(int wv, LAS unsigned char* lds, const Gemm g, const Sched& S, const Epi& E) { LIDS
;     ...
;             PG8_BAR; PG8_WAIT_L(0); PG8_MMA(1, 0, At, B0); PG8_BAR; PG8_SCHED;
;             PG8_STAGE(PG8_SB(1, 1), b3 + hstepB, voffB);
;             PG8_WAIT_V(6); PG8_BAR; PG8_MMA(1, 1, At, B1); PG8_BAR;
;         }
;         { const int l2 = lane_id_asm(); E(acc, cur, wr, wc, l2 & 15, l2 >> 4); }
;     __device__ __forceinline__ void operator()(const AccT& acc, const Unit& u, int wr, int wc, int fr, int fq) const {
;         const int row0 = u.pm * BM + wr * 64 + fr, g = u.pn;
; #pragma unroll
;         for (int bj = 0; bj < 2; ++bj) {
;             const int n = bj * HALF + wc * 32 + 8 * fq, t = n >> 4, hh = n & 15;
;             const f32x4 d0 = *(const f32x4*)(dskip + g * 16 + hh), d1 = *(const f32x4*)(dskip + g * 16 + hh + 4);
;             u32x4 uv[8];
; #pragma unroll
;             for (int rr = 0; rr < 8; ++rr) uv[rr] = *(const u32x4*)(ucat + (size_t)(row0 + (rr >> 2) * HALF + (rr & 3) * 16) * KCAT + n);
;             __builtin_amdgcn_sched_barrier(0);
	s_waitcnt lgkmcnt(0)
	s_setprio 1
	v_mfma_f32_16x16x32_bf16 v[28:31], v[178:181], v[4:7], v[210:213]
	v_mfma_f32_16x16x32_bf16 v[108:111], v[182:185], v[20:23], v[28:31]
	v_mfma_f32_16x16x32_bf16 v[28:31], v[186:189], v[4:7], v[136:139]
	v_mfma_f32_16x16x32_bf16 v[112:115], v[190:193], v[20:23], v[28:31]
	v_mfma_f32_16x16x32_bf16 v[28:31], v[178:181], v[24:27], v[220:223]
	v_mfma_f32_16x16x32_bf16 v[96:99], v[182:185], v[160:163], v[28:31]
	v_mfma_f32_16x16x32_bf16 v[28:31], v[186:189], v[24:27], v[224:227]
	v_mfma_f32_16x16x32_bf16 v[100:103], v[190:193], v[160:163], v[28:31]
	v_mfma_f32_16x16x32_bf16 v[28:31], v[178:181], v[194:197], v[148:151]
	v_mfma_f32_16x16x32_bf16 v[8:11], v[178:181], v[202:205], v[8:11]
	v_mfma_f32_16x16x32_bf16 v[76:79], v[182:185], v[198:201], v[28:31]
	v_mfma_f32_16x16x32_bf16 v[28:31], v[186:189], v[194:197], v[228:231]
	v_mfma_f32_16x16x32_bf16 v[68:71], v[182:185], v[244:247], v[8:11]
	v_mfma_f32_16x16x32_bf16 v[8:11], v[186:189], v[202:205], v[12:15]
	v_mfma_f32_16x16x32_bf16 v[80:83], v[190:193], v[198:201], v[28:31]
	v_mfma_f32_16x16x32_bf16 v[72:75], v[190:193], v[244:247], v[8:11]
	s_setprio 0
	s_barrier
	s_add_u32 s6, s72, 0x18000
	s_addc_u32 s7, s73, 0
	s_mov_b32 m0, s27
	s_nop 0
	v_lshl_add_u64 v[8:9], s[6:7], 0, v[176:177]
	s_add_u32 s6, s72, 0x24000
	s_addc_u32 s7, s73, 0
	global_load_lds_dwordx4 v[8:9], off
	s_mov_b32 m0, s22
	v_lshl_add_u64 v[8:9], s[6:7], 0, v[176:177]
	global_load_lds_dwordx4 v[8:9], off
	s_waitcnt vmcnt(6)
	s_barrier
	s_setprio 1
	v_mfma_f32_16x16x32_bf16 v[8:11], v[206:209], v[4:7], v[16:19]
	v_mfma_f32_16x16x32_bf16 v[4:7], v[236:239], v[4:7], v[124:127]
	v_mfma_f32_16x16x32_bf16 v[32:35], v[240:243], v[20:23], v[4:7]
	v_mfma_f32_16x16x32_bf16 v[4:7], v[206:209], v[24:27], v[92:95]
	v_mfma_f32_16x16x32_bf16 v[28:31], v[232:235], v[20:23], v[8:11]
	v_mfma_f32_16x16x32_bf16 v[20:23], v[232:235], v[160:163], v[4:7]
	v_mfma_f32_16x16x32_bf16 v[4:7], v[236:239], v[24:27], v[166:169]
	v_mfma_f32_16x16x32_bf16 v[24:27], v[240:243], v[160:163], v[4:7]
	v_mfma_f32_16x16x32_bf16 v[4:7], v[206:209], v[194:197], v[104:107]
	v_mfma_f32_16x16x32_bf16 v[12:15], v[232:235], v[198:201], v[4:7]
	v_mfma_f32_16x16x32_bf16 v[4:7], v[236:239], v[194:197], v[170:173]
	v_mfma_f32_16x16x32_bf16 v[16:19], v[240:243], v[198:201], v[4:7]
	v_mfma_f32_16x16x32_bf16 v[4:7], v[206:209], v[202:205], v[84:87]
	v_mfma_f32_16x16x32_bf16 v[8:11], v[236:239], v[202:205], v[88:91]
	v_mfma_f32_16x16x32_bf16 v[4:7], v[232:235], v[244:247], v[4:7]
	v_mfma_f32_16x16x32_bf16 v[8:11], v[240:243], v[244:247], v[8:11]
	s_setprio 0
	s_lshl_b32 s6, s16, 8
	v_readlane_b32 s7, v255, 3
	s_add_i32 s6, s6, s7
	s_barrier
	v_mbcnt_lo_u32_b32 v84, -1, 0
	v_mbcnt_hi_u32_b32 v84, -1, v84
	v_readlane_b32 s16, v255, 1
	v_and_or_b32 v186, v84, 15, s6
	s_lshl_b32 s6, s17, 4
	v_ashrrev_i32_e32 v84, 1, v84
	s_ashr_i32 s7, s6, 31
	v_and_b32_e32 v85, -8, v84
	s_lshl_b64 s[6:7], s[6:7], 2
	v_add_u32_e32 v92, s80, v85
	s_add_u32 s62, s16, s6
	v_readlane_b32 s6, v255, 2
	s_addc_u32 s63, s6, s7
	v_ashrrev_i32_e32 v93, 31, v92
	v_readlane_b32 s6, v253, 6
	v_lshlrev_b64 v[200:201], 1, v[92:93]
	v_readlane_b32 s7, v253, 7
	s_movk_i32 s16, 0x300
	v_add_u32_e32 v94, 0x90, v186
	v_lshl_add_u64 v[92:93], s[6:7], 0, v[200:201]
	v_lshlrev_b32_e32 v84, 2, v84
	v_or_b32_e32 v206, 32, v186
	v_add_u32_e32 v202, 0x80, v186
	v_mad_i64_i32 v[194:195], s[6:7], v94, s16, v[92:93]
	v_add_u32_e32 v94, 0xa0, v186
	v_and_b32_e32 v219, 32, v84
	v_mad_i64_i32 v[166:167], s[6:7], v186, s16, v[92:93]
	v_or_b32_e32 v208, 16, v186
	v_mad_i64_i32 v[170:171], s[6:7], v206, s16, v[92:93]
	v_or_b32_e32 v204, 48, v186
	v_mad_i64_i32 v[174:175], s[6:7], v202, s16, v[92:93]
	v_mad_i64_i32 v[196:197], s[6:7], v94, s16, v[92:93]
	v_add_u32_e32 v94, 0xb0, v186
	global_load_dwordx4 v[84:87], v219, s[62:63] offset:16
	global_load_dwordx4 v[88:91], v219, s[62:63]
	v_mad_i64_i32 v[168:169], s[6:7], v208, s16, v[92:93]
	global_load_dwordx4 v[178:181], v[166:167], off
	global_load_dwordx4 v[182:185], v[168:169], off
	v_mad_i64_i32 v[172:173], s[6:7], v204, s16, v[92:93]
	global_load_dwordx4 v[160:163], v[170:171], off
	global_load_dwordx4 v[148:151], v[172:173], off
	global_load_dwordx4 v[136:139], v[174:175], off
	global_load_dwordx4 v[124:127], v[194:195], off
	v_mad_i64_i32 v[198:199], s[6:7], v94, s16, v[92:93]
	global_load_dwordx4 v[104:107], v[196:197], off
	global_load_dwordx4 v[92:95], v[198:199], off
	v_ashrrev_i32_e32 v187, 31, v186
	v_ashrrev_i32_e32 v209, 31, v208
	v_ashrrev_i32_e32 v207, 31, v206
	v_ashrrev_i32_e32 v205, 31, v204
	v_ashrrev_i32_e32 v203, 31, v202
	s_waitcnt vmcnt(0)
; __device__ __forceinline__ float bflo(unsigned w) { return __uint_as_float(w << 16); }
; __device__ __forceinline__ float bfhi(unsigned w) { return __uint_as_float(w & 0xffff0000u); }
; __device__ __forceinline__ u32x4 pack8(f32x4 a, f32x4 b) { u32x4 r; r[0] = cvt_pk_bf16(a[0], a[1]); r[1] = cvt_pk_bf16(a[2], a[3]); r[2] = cvt_pk_bf16(b[0], b[1]); r[3] = cvt_pk_bf16(b[2], b[3]); return r; }
; __device__ __forceinline__ float sigmoidf_(float x) { return fast_rcp(1.0f + fast_exp2(-1.4426950408889634f * x)); }
; __device__ __forceinline__ float gelu_tanh(float x) {
;     const float u = 0.7978845608028654f * (x + 0.044715f * x * x * x);
;     return x * sigmoidf_(2.0f * u);
;     __device__ __forceinline__ void operator()(const AccT& acc, const Unit& u, int wr, int wc, int fr, int fq) const {
;     ...
;             for (int ai = 0; ai < 2; ++ai)
; #pragma unroll
;                 for (int m = 0; m < 4; ++m) {
;                     const int R = row0 + ai * HALF + m * 16;
;                     const u32x4 uu = uv[ai * 4 + m];
;                     f32x4 y0 = acc[ai][bj][m][0], y1 = acc[ai][bj][m][1];
;                     y0[0] += d0[0] * bflo(uu[0]); y0[1] += d0[1] * bfhi(uu[0]); y0[2] += d0[2] * bflo(uu[1]); y0[3] += d0[3] * bfhi(uu[1]);
;                     y1[0] += d1[0] * bflo(uu[2]); y1[1] += d1[1] * bfhi(uu[2]); y1[2] += d1[2] * bflo(uu[3]); y1[3] += d1[3] * bfhi(uu[3]);
; #pragma unroll
;                     for (int j = 0; j < 4; ++j) { y0[j] = gelu_tanh(y0[j]); y1[j] = gelu_tanh(y1[j]); }
;                     *(u32x4*)(Yact + (size_t)R * 256 + n) = pack8(y0, y1); __builtin_amdgcn_sched_barrier(0);
	v_lshlrev_b32_e32 v188, 16, v178
	v_and_b32_e32 v178, 0xffff0000, v178
	v_fma_f32 v152, v88, v188, v152
	v_fma_f32 v153, v89, v178, v153
	v_lshlrev_b32_e32 v178, 16, v179
	v_fma_f32 v154, v90, v178, v154
	v_and_b32_e32 v178, 0xffff0000, v179
	v_mul_f32_e32 v179, 0x3d372713, v152
	v_mul_f32_e32 v179, v152, v179
	v_fma_f32 v179, v152, v179, v152
	v_mul_f32_e32 v179, 0x3f4c422a, v179
	v_add_f32_e32 v179, v179, v179
	v_mul_f32_e32 v179, 0xbfb8aa3b, v179
	v_fmac_f32_e32 v155, v91, v178
	v_lshlrev_b32_e32 v178, 16, v180
	v_exp_f32_e32 v179, v179
	v_fma_f32 v156, v84, v178, v156
	v_and_b32_e32 v178, 0xffff0000, v180
	v_fma_f32 v157, v85, v178, v157
	v_lshlrev_b32_e32 v178, 16, v181
	v_fma_f32 v158, v86, v178, v158
	v_and_b32_e32 v178, 0xffff0000, v181
	v_fmac_f32_e32 v159, v87, v178
	v_add_f32_e32 v178, 1.0, v179
	v_mul_f32_e32 v179, 0x3d372713, v156
	v_mul_f32_e32 v180, 0x3d372713, v153
	v_mul_f32_e32 v179, v156, v179
	v_mul_f32_e32 v180, v153, v180
	v_fma_f32 v179, v156, v179, v156
	v_fma_f32 v180, v153, v180, v153
	v_mul_f32_e32 v179, 0x3f4c422a, v179
	v_mul_f32_e32 v180, 0x3f4c422a, v180
	v_add_f32_e32 v179, v179, v179
	v_add_f32_e32 v180, v180, v180
	v_mul_f32_e32 v179, 0xbfb8aa3b, v179
	v_mul_f32_e32 v180, 0xbfb8aa3b, v180
	v_exp_f32_e32 v179, v179
	v_exp_f32_e32 v180, v180
	v_mul_f32_e32 v181, 0x3d372713, v157
	v_mul_f32_e32 v181, v157, v181
	v_add_f32_e32 v179, 1.0, v179
	v_add_f32_e32 v180, 1.0, v180
	v_rcp_f32_e32 v179, v179
	v_rcp_f32_e32 v180, v180
	v_fma_f32 v181, v157, v181, v157
	v_mul_f32_e32 v181, 0x3f4c422a, v181
	v_add_f32_e32 v181, v181, v181
	v_mul_f32_e32 v181, 0xbfb8aa3b, v181
	v_mul_f32_e32 v156, v156, v179
	v_mul_f32_e32 v153, v153, v180
	v_mul_f32_e32 v179, 0x3d372713, v154
	v_mul_f32_e32 v180, 0x3d372713, v158
	v_rcp_f32_e32 v178, v178
	v_exp_f32_e32 v181, v181
	v_mul_f32_e32 v179, v154, v179
	v_mul_f32_e32 v180, v158, v180
	v_fma_f32 v179, v154, v179, v154
	v_fma_f32 v180, v158, v180, v158
	v_mul_f32_e32 v179, 0x3f4c422a, v179
	v_mul_f32_e32 v180, 0x3f4c422a, v180
	v_add_f32_e32 v179, v179, v179
	v_add_f32_e32 v180, v180, v180
	v_mul_f32_e32 v152, v152, v178
	v_add_f32_e32 v178, 1.0, v181
	v_mul_f32_e32 v179, 0xbfb8aa3b, v179
	v_mul_f32_e32 v180, 0xbfb8aa3b, v180
	v_rcp_f32_e32 v178, v178
	v_exp_f32_e32 v179, v179
	v_exp_f32_e32 v180, v180
	v_mul_f32_e32 v181, 0x3d372713, v159
	v_mul_f32_e32 v157, v157, v178
	v_add_f32_e32 v178, 1.0, v179
	v_add_f32_e32 v179, 1.0, v180
	v_mul_f32_e32 v180, 0x3d372713, v155
	v_mul_f32_e32 v180, v155, v180
	v_fma_f32 v180, v155, v180, v155
	v_mul_f32_e32 v181, v159, v181
	v_mul_f32_e32 v180, 0x3f4c422a, v180
	v_fma_f32 v181, v159, v181, v159
	v_add_f32_e32 v180, v180, v180
	v_mul_f32_e32 v181, 0x3f4c422a, v181
	v_mul_f32_e32 v180, 0xbfb8aa3b, v180
	v_add_f32_e32 v181, v181, v181
	v_exp_f32_e32 v180, v180
	v_mul_f32_e32 v181, 0xbfb8aa3b, v181
	v_exp_f32_e32 v181, v181
	v_rcp_f32_e32 v178, v178
	v_add_f32_e32 v180, 1.0, v180
	v_rcp_f32_e32 v180, v180
	v_add_f32_e32 v181, 1.0, v181
	v_rcp_f32_e32 v179, v179
	v_rcp_f32_e32 v181, v181
	v_readlane_b32 s28, v254, 44
	v_mul_f32_e32 v178, v154, v178
	v_cvt_pk_bf16_f32 v154, v152, v153
	v_lshlrev_b64 v[152:153], 9, v[186:187]
	v_readlane_b32 s29, v254, 45
	v_mul_f32_e32 v155, v155, v180
	v_mul_f32_e32 v158, v158, v179
	v_lshl_add_u64 v[152:153], s[28:29], 0, v[152:153]
	v_lshl_add_u64 v[152:153], v[152:153], 0, v[200:201]
	v_mul_f32_e32 v159, v159, v181
	v_cvt_pk_bf16_f32 v155, v178, v155
	v_cvt_pk_bf16_f32 v156, v156, v157
	v_cvt_pk_bf16_f32 v157, v158, v159
	global_store_dwordx4 v[152:153], v[154:157], off
	s_nop 1
	v_lshlrev_b32_e32 v154, 16, v182
	v_fma_f32 v140, v88, v154, v140
	v_mul_f32_e32 v155, 0x3d372713, v140
	v_mul_f32_e32 v155, v140, v155
	v_fma_f32 v155, v140, v155, v140
	v_and_b32_e32 v154, 0xffff0000, v182
	v_mul_f32_e32 v155, 0x3f4c422a, v155
	v_fma_f32 v141, v89, v154, v141
	v_lshlrev_b32_e32 v154, 16, v183
	v_add_f32_e32 v155, v155, v155
	v_fma_f32 v142, v90, v154, v142
	v_and_b32_e32 v154, 0xffff0000, v183
	v_mul_f32_e32 v155, 0xbfb8aa3b, v155
	v_fmac_f32_e32 v143, v91, v154
	v_lshlrev_b32_e32 v154, 16, v184
	v_exp_f32_e32 v155, v155
	v_fma_f32 v144, v84, v154, v144
	v_and_b32_e32 v154, 0xffff0000, v184
	v_fma_f32 v145, v85, v154, v145
	v_lshlrev_b32_e32 v154, 16, v185
	v_fma_f32 v146, v86, v154, v146
	v_and_b32_e32 v154, 0xffff0000, v185
	v_fmac_f32_e32 v147, v87, v154
	v_add_f32_e32 v154, 1.0, v155
	v_mul_f32_e32 v155, 0x3d372713, v144
	v_mul_f32_e32 v156, 0x3d372713, v141
	v_mul_f32_e32 v155, v144, v155
	v_mul_f32_e32 v156, v141, v156
	v_fma_f32 v155, v144, v155, v144
	v_fma_f32 v156, v141, v156, v141
	v_mul_f32_e32 v155, 0x3f4c422a, v155
	v_mul_f32_e32 v156, 0x3f4c422a, v156
	v_add_f32_e32 v155, v155, v155
	v_add_f32_e32 v156, v156, v156
	v_mul_f32_e32 v155, 0xbfb8aa3b, v155
	v_mul_f32_e32 v156, 0xbfb8aa3b, v156
	v_exp_f32_e32 v155, v155
	v_exp_f32_e32 v156, v156
	v_mul_f32_e32 v157, 0x3d372713, v145
	v_mul_f32_e32 v157, v145, v157
	v_add_f32_e32 v155, 1.0, v155
	v_add_f32_e32 v156, 1.0, v156
	v_rcp_f32_e32 v155, v155
	v_rcp_f32_e32 v156, v156
	v_fma_f32 v157, v145, v157, v145
	v_mul_f32_e32 v157, 0x3f4c422a, v157
	v_add_f32_e32 v157, v157, v157
	v_mul_f32_e32 v157, 0xbfb8aa3b, v157
	v_mul_f32_e32 v144, v144, v155
	v_mul_f32_e32 v141, v141, v156
	v_mul_f32_e32 v155, 0x3d372713, v142
	v_mul_f32_e32 v156, 0x3d372713, v146
	v_rcp_f32_e32 v154, v154
	v_exp_f32_e32 v157, v157
	v_mul_f32_e32 v155, v142, v155
	v_mul_f32_e32 v156, v146, v156
	v_fma_f32 v155, v142, v155, v142
	v_fma_f32 v156, v146, v156, v146
	v_mul_f32_e32 v155, 0x3f4c422a, v155
	v_mul_f32_e32 v156, 0x3f4c422a, v156
	v_add_f32_e32 v155, v155, v155
; __device__ __forceinline__ float bflo(unsigned w) { return __uint_as_float(w << 16); }
; __device__ __forceinline__ float bfhi(unsigned w) { return __uint_as_float(w & 0xffff0000u); }
; __device__ __forceinline__ u32x4 pack8(f32x4 a, f32x4 b) { u32x4 r; r[0] = cvt_pk_bf16(a[0], a[1]); r[1] = cvt_pk_bf16(a[2], a[3]); r[2] = cvt_pk_bf16(b[0], b[1]); r[3] = cvt_pk_bf16(b[2], b[3]); return r; }
; __device__ __forceinline__ float sigmoidf_(float x) { return fast_rcp(1.0f + fast_exp2(-1.4426950408889634f * x)); }
; __device__ __forceinline__ float gelu_tanh(float x) {
;     const float u = 0.7978845608028654f * (x + 0.044715f * x * x * x);
;     return x * sigmoidf_(2.0f * u);
;     __device__ __forceinline__ void operator()(const AccT& acc, const Unit& u, int wr, int wc, int fr, int fq) const {
;     ...
;             for (int ai = 0; ai < 2; ++ai)
; #pragma unroll
;                 for (int m = 0; m < 4; ++m) {
;                     const int R = row0 + ai * HALF + m * 16;
;                     const u32x4 uu = uv[ai * 4 + m];
;                     f32x4 y0 = acc[ai][bj][m][0], y1 = acc[ai][bj][m][1];
;                     y0[0] += d0[0] * bflo(uu[0]); y0[1] += d0[1] * bfhi(uu[0]); y0[2] += d0[2] * bflo(uu[1]); y0[3] += d0[3] * bfhi(uu[1]);
;                     y1[0] += d1[0] * bflo(uu[2]); y1[1] += d1[1] * bfhi(uu[2]); y1[2] += d1[2] * bflo(uu[3]); y1[3] += d1[3] * bfhi(uu[3]);
; #pragma unroll
;                     for (int j = 0; j < 4; ++j) { y0[j] = gelu_tanh(y0[j]); y1[j] = gelu_tanh(y1[j]); }
;                     *(u32x4*)(Yact + (size_t)R * 256 + n) = pack8(y0, y1); __builtin_amdgcn_sched_barrier(0);
	v_add_f32_e32 v156, v156, v156
	v_mul_f32_e32 v140, v140, v154
	v_add_f32_e32 v154, 1.0, v157
	v_mul_f32_e32 v155, 0xbfb8aa3b, v155
	v_mul_f32_e32 v156, 0xbfb8aa3b, v156
	v_rcp_f32_e32 v154, v154
	v_exp_f32_e32 v155, v155
	v_exp_f32_e32 v156, v156
	v_mul_f32_e32 v157, 0x3d372713, v147
	v_mul_f32_e32 v145, v145, v154
	v_add_f32_e32 v154, 1.0, v155
	v_add_f32_e32 v155, 1.0, v156
	v_mul_f32_e32 v156, 0x3d372713, v143
	v_mul_f32_e32 v156, v143, v156
	v_fma_f32 v156, v143, v156, v143
	v_mul_f32_e32 v157, v147, v157
	v_mul_f32_e32 v156, 0x3f4c422a, v156
	v_fma_f32 v157, v147, v157, v147
	v_add_f32_e32 v156, v156, v156
	v_mul_f32_e32 v157, 0x3f4c422a, v157
	v_mul_f32_e32 v156, 0xbfb8aa3b, v156
	v_add_f32_e32 v157, v157, v157
	v_exp_f32_e32 v156, v156
	v_mul_f32_e32 v157, 0xbfb8aa3b, v157
	v_exp_f32_e32 v157, v157
	v_rcp_f32_e32 v154, v154
	v_add_f32_e32 v156, 1.0, v156
	v_rcp_f32_e32 v156, v156
	v_add_f32_e32 v157, 1.0, v157
	v_rcp_f32_e32 v155, v155
	v_rcp_f32_e32 v157, v157
	v_mul_f32_e32 v154, v142, v154
	v_cvt_pk_bf16_f32 v142, v140, v141
	v_lshlrev_b64 v[140:141], 9, v[208:209]
	v_lshl_add_u64 v[140:141], s[28:29], 0, v[140:141]
	v_mul_f32_e32 v143, v143, v156
	v_lshl_add_u64 v[140:141], v[140:141], 0, v[200:201]
	v_mul_f32_e32 v146, v146, v155
	v_mul_f32_e32 v147, v147, v157
	v_cvt_pk_bf16_f32 v143, v154, v143
	v_cvt_pk_bf16_f32 v144, v144, v145
	v_cvt_pk_bf16_f32 v145, v146, v147
	global_store_dwordx4 v[140:141], v[142:145], off
	s_nop 1
	v_lshlrev_b32_e32 v142, 16, v160
	v_fma_f32 v128, v88, v142, v128
	v_mul_f32_e32 v143, 0x3d372713, v128
	v_mul_f32_e32 v143, v128, v143
	v_fma_f32 v143, v128, v143, v128
	v_and_b32_e32 v142, 0xffff0000, v160
	v_mul_f32_e32 v143, 0x3f4c422a, v143
	v_fma_f32 v129, v89, v142, v129
	v_lshlrev_b32_e32 v142, 16, v161
	v_add_f32_e32 v143, v143, v143
	v_fma_f32 v130, v90, v142, v130
	v_and_b32_e32 v142, 0xffff0000, v161
	v_mul_f32_e32 v143, 0xbfb8aa3b, v143
	v_fmac_f32_e32 v131, v91, v142
	v_lshlrev_b32_e32 v142, 16, v162
	v_exp_f32_e32 v143, v143
	v_fma_f32 v132, v84, v142, v132
	v_and_b32_e32 v142, 0xffff0000, v162
	v_fma_f32 v133, v85, v142, v133
	v_lshlrev_b32_e32 v142, 16, v163
	v_fma_f32 v134, v86, v142, v134
	v_and_b32_e32 v142, 0xffff0000, v163
	v_fmac_f32_e32 v135, v87, v142
	v_add_f32_e32 v142, 1.0, v143
	v_mul_f32_e32 v143, 0x3d372713, v132
	v_mul_f32_e32 v144, 0x3d372713, v129
	v_mul_f32_e32 v143, v132, v143
	v_mul_f32_e32 v144, v129, v144
	v_fma_f32 v143, v132, v143, v132
	v_fma_f32 v144, v129, v144, v129
	v_mul_f32_e32 v143, 0x3f4c422a, v143
	v_mul_f32_e32 v144, 0x3f4c422a, v144
	v_add_f32_e32 v143, v143, v143
	v_add_f32_e32 v144, v144, v144
	v_mul_f32_e32 v143, 0xbfb8aa3b, v143
	v_mul_f32_e32 v144, 0xbfb8aa3b, v144
	v_exp_f32_e32 v143, v143
	v_exp_f32_e32 v144, v144
	v_mul_f32_e32 v145, 0x3d372713, v133
	v_mul_f32_e32 v145, v133, v145
	v_add_f32_e32 v143, 1.0, v143
	v_add_f32_e32 v144, 1.0, v144
	v_rcp_f32_e32 v143, v143
	v_rcp_f32_e32 v144, v144
	v_fma_f32 v145, v133, v145, v133
	v_mul_f32_e32 v145, 0x3f4c422a, v145
	v_add_f32_e32 v145, v145, v145
	v_mul_f32_e32 v145, 0xbfb8aa3b, v145
	v_mul_f32_e32 v132, v132, v143
	v_mul_f32_e32 v129, v129, v144
	v_mul_f32_e32 v143, 0x3d372713, v130
	v_mul_f32_e32 v144, 0x3d372713, v134
	v_rcp_f32_e32 v142, v142
	v_exp_f32_e32 v145, v145
	v_mul_f32_e32 v143, v130, v143
	v_mul_f32_e32 v144, v134, v144
	v_fma_f32 v143, v130, v143, v130
	v_fma_f32 v144, v134, v144, v134
	v_mul_f32_e32 v143, 0x3f4c422a, v143
	v_mul_f32_e32 v144, 0x3f4c422a, v144
	v_add_f32_e32 v143, v143, v143
	v_add_f32_e32 v144, v144, v144
	v_mul_f32_e32 v128, v128, v142
	v_add_f32_e32 v142, 1.0, v145
	v_mul_f32_e32 v143, 0xbfb8aa3b, v143
	v_mul_f32_e32 v144, 0xbfb8aa3b, v144
	v_rcp_f32_e32 v142, v142
	v_exp_f32_e32 v143, v143
	v_exp_f32_e32 v144, v144
	v_mul_f32_e32 v145, 0x3d372713, v135
	v_mul_f32_e32 v133, v133, v142
	v_add_f32_e32 v142, 1.0, v143
	v_add_f32_e32 v143, 1.0, v144
	v_mul_f32_e32 v144, 0x3d372713, v131
	v_mul_f32_e32 v144, v131, v144
	v_fma_f32 v144, v131, v144, v131
	v_mul_f32_e32 v145, v135, v145
	v_mul_f32_e32 v144, 0x3f4c422a, v144
	v_fma_f32 v145, v135, v145, v135
	v_add_f32_e32 v144, v144, v144
	v_mul_f32_e32 v145, 0x3f4c422a, v145
	v_mul_f32_e32 v144, 0xbfb8aa3b, v144
	v_add_f32_e32 v145, v145, v145
	v_exp_f32_e32 v144, v144
	v_mul_f32_e32 v145, 0xbfb8aa3b, v145
	v_exp_f32_e32 v145, v145
	v_rcp_f32_e32 v142, v142
	v_add_f32_e32 v144, 1.0, v144
	v_rcp_f32_e32 v144, v144
	v_add_f32_e32 v145, 1.0, v145
	v_rcp_f32_e32 v143, v143
	v_rcp_f32_e32 v145, v145
	v_mul_f32_e32 v142, v130, v142
	v_cvt_pk_bf16_f32 v130, v128, v129
	v_lshlrev_b64 v[128:129], 9, v[206:207]
	v_lshl_add_u64 v[128:129], s[28:29], 0, v[128:129]
	v_mul_f32_e32 v131, v131, v144
	v_lshl_add_u64 v[128:129], v[128:129], 0, v[200:201]
	v_mul_f32_e32 v134, v134, v143
	v_mul_f32_e32 v135, v135, v145
	v_cvt_pk_bf16_f32 v131, v142, v131
	v_cvt_pk_bf16_f32 v132, v132, v133
	v_cvt_pk_bf16_f32 v133, v134, v135
	global_store_dwordx4 v[128:129], v[130:133], off
	s_nop 1
	v_lshlrev_b32_e32 v130, 16, v148
	v_fma_f32 v116, v88, v130, v116
	v_mul_f32_e32 v131, 0x3d372713, v116
	v_mul_f32_e32 v131, v116, v131
	v_fma_f32 v131, v116, v131, v116
	v_and_b32_e32 v130, 0xffff0000, v148
	v_mul_f32_e32 v131, 0x3f4c422a, v131
	v_fma_f32 v117, v89, v130, v117
	v_lshlrev_b32_e32 v130, 16, v149
	v_add_f32_e32 v131, v131, v131
	v_fma_f32 v118, v90, v130, v118
	v_and_b32_e32 v130, 0xffff0000, v149
	v_mul_f32_e32 v131, 0xbfb8aa3b, v131
	v_fmac_f32_e32 v119, v91, v130
	v_lshlrev_b32_e32 v130, 16, v150
	v_exp_f32_e32 v131, v131
	v_fma_f32 v120, v84, v130, v120
	v_and_b32_e32 v130, 0xffff0000, v150
	v_fma_f32 v121, v85, v130, v121
; __device__ __forceinline__ float bflo(unsigned w) { return __uint_as_float(w << 16); }
; __device__ __forceinline__ float bfhi(unsigned w) { return __uint_as_float(w & 0xffff0000u); }
; __device__ __forceinline__ u32x4 pack8(f32x4 a, f32x4 b) { u32x4 r; r[0] = cvt_pk_bf16(a[0], a[1]); r[1] = cvt_pk_bf16(a[2], a[3]); r[2] = cvt_pk_bf16(b[0], b[1]); r[3] = cvt_pk_bf16(b[2], b[3]); return r; }
; __device__ __forceinline__ float sigmoidf_(float x) { return fast_rcp(1.0f + fast_exp2(-1.4426950408889634f * x)); }
; __device__ __forceinline__ float gelu_tanh(float x) {
;     const float u = 0.7978845608028654f * (x + 0.044715f * x * x * x);
;     return x * sigmoidf_(2.0f * u);
; }
;     __device__ __forceinline__ void operator()(const AccT& acc, const Unit& u, int wr, int wc, int fr, int fq) const {
;     ...
;                 for (int m = 0; m < 4; ++m) {
;                     const int R = row0 + ai * HALF + m * 16;
;                     const u32x4 uu = uv[ai * 4 + m];
;                     f32x4 y0 = acc[ai][bj][m][0], y1 = acc[ai][bj][m][1];
;                     y0[0] += d0[0] * bflo(uu[0]); y0[1] += d0[1] * bfhi(uu[0]); y0[2] += d0[2] * bflo(uu[1]); y0[3] += d0[3] * bfhi(uu[1]);
;                     y1[0] += d1[0] * bflo(uu[2]); y1[1] += d1[1] * bfhi(uu[2]); y1[2] += d1[2] * bflo(uu[3]); y1[3] += d1[3] * bfhi(uu[3]);
; #pragma unroll
;                     for (int j = 0; j < 4; ++j) { y0[j] = gelu_tanh(y0[j]); y1[j] = gelu_tanh(y1[j]); }
;                     *(u32x4*)(Yact + (size_t)R * 256 + n) = pack8(y0, y1); __builtin_amdgcn_sched_barrier(0);
	v_lshlrev_b32_e32 v130, 16, v151
	v_fma_f32 v122, v86, v130, v122
	v_and_b32_e32 v130, 0xffff0000, v151
	v_fmac_f32_e32 v123, v87, v130
	v_add_f32_e32 v130, 1.0, v131
	v_mul_f32_e32 v131, 0x3d372713, v120
	v_mul_f32_e32 v132, 0x3d372713, v117
	v_mul_f32_e32 v131, v120, v131
	v_mul_f32_e32 v132, v117, v132
	v_fma_f32 v131, v120, v131, v120
	v_fma_f32 v132, v117, v132, v117
	v_mul_f32_e32 v131, 0x3f4c422a, v131
	v_mul_f32_e32 v132, 0x3f4c422a, v132
	v_add_f32_e32 v131, v131, v131
	v_add_f32_e32 v132, v132, v132
	v_mul_f32_e32 v131, 0xbfb8aa3b, v131
	v_mul_f32_e32 v132, 0xbfb8aa3b, v132
	v_exp_f32_e32 v131, v131
	v_exp_f32_e32 v132, v132
	v_mul_f32_e32 v133, 0x3d372713, v121
	v_mul_f32_e32 v133, v121, v133
	v_add_f32_e32 v131, 1.0, v131
	v_add_f32_e32 v132, 1.0, v132
	v_rcp_f32_e32 v131, v131
	v_rcp_f32_e32 v132, v132
	v_fma_f32 v133, v121, v133, v121
	v_mul_f32_e32 v133, 0x3f4c422a, v133
	v_add_f32_e32 v133, v133, v133
	v_mul_f32_e32 v133, 0xbfb8aa3b, v133
	v_mul_f32_e32 v120, v120, v131
	v_mul_f32_e32 v117, v117, v132
	v_mul_f32_e32 v131, 0x3d372713, v118
	v_mul_f32_e32 v132, 0x3d372713, v122
	v_rcp_f32_e32 v130, v130
	v_exp_f32_e32 v133, v133
	v_mul_f32_e32 v131, v118, v131
	v_mul_f32_e32 v132, v122, v132
	v_fma_f32 v131, v118, v131, v118
	v_fma_f32 v132, v122, v132, v122
	v_mul_f32_e32 v131, 0x3f4c422a, v131
	v_mul_f32_e32 v132, 0x3f4c422a, v132
	v_add_f32_e32 v131, v131, v131
	v_add_f32_e32 v132, v132, v132
	v_mul_f32_e32 v116, v116, v130
	v_add_f32_e32 v130, 1.0, v133
	v_mul_f32_e32 v131, 0xbfb8aa3b, v131
	v_mul_f32_e32 v132, 0xbfb8aa3b, v132
	v_rcp_f32_e32 v130, v130
	v_exp_f32_e32 v131, v131
	v_exp_f32_e32 v132, v132
	v_mul_f32_e32 v133, 0x3d372713, v123
	v_mul_f32_e32 v121, v121, v130
	v_add_f32_e32 v130, 1.0, v131
	v_add_f32_e32 v131, 1.0, v132
	v_mul_f32_e32 v132, 0x3d372713, v119
	v_mul_f32_e32 v132, v119, v132
	v_fma_f32 v132, v119, v132, v119
	v_mul_f32_e32 v133, v123, v133
	v_mul_f32_e32 v132, 0x3f4c422a, v132
	v_fma_f32 v133, v123, v133, v123
	v_add_f32_e32 v132, v132, v132
	v_mul_f32_e32 v133, 0x3f4c422a, v133
	v_mul_f32_e32 v132, 0xbfb8aa3b, v132
	v_add_f32_e32 v133, v133, v133
	v_exp_f32_e32 v132, v132
	v_mul_f32_e32 v133, 0xbfb8aa3b, v133
	v_exp_f32_e32 v133, v133
	v_rcp_f32_e32 v130, v130
	v_add_f32_e32 v132, 1.0, v132
	v_rcp_f32_e32 v132, v132
	v_add_f32_e32 v133, 1.0, v133
	v_rcp_f32_e32 v131, v131
	v_rcp_f32_e32 v133, v133
	v_mul_f32_e32 v130, v118, v130
	v_cvt_pk_bf16_f32 v118, v116, v117
	v_lshlrev_b64 v[116:117], 9, v[204:205]
	v_lshl_add_u64 v[116:117], s[28:29], 0, v[116:117]
	v_mul_f32_e32 v119, v119, v132
	v_lshl_add_u64 v[116:117], v[116:117], 0, v[200:201]
	v_mul_f32_e32 v122, v122, v131
	v_mul_f32_e32 v123, v123, v133
	v_cvt_pk_bf16_f32 v119, v130, v119
	v_cvt_pk_bf16_f32 v120, v120, v121
	v_cvt_pk_bf16_f32 v121, v122, v123
	global_store_dwordx4 v[116:117], v[118:121], off
	s_nop 1
	v_lshlrev_b32_e32 v118, 16, v136
	v_fma_f32 v108, v88, v118, v108
	v_mul_f32_e32 v119, 0x3d372713, v108
	v_mul_f32_e32 v119, v108, v119
	v_fma_f32 v119, v108, v119, v108
	v_and_b32_e32 v118, 0xffff0000, v136
	v_mul_f32_e32 v119, 0x3f4c422a, v119
	v_fma_f32 v109, v89, v118, v109
	v_lshlrev_b32_e32 v118, 16, v137
	v_add_f32_e32 v119, v119, v119
	v_fma_f32 v110, v90, v118, v110
	v_and_b32_e32 v118, 0xffff0000, v137
	v_mul_f32_e32 v119, 0xbfb8aa3b, v119
	v_fmac_f32_e32 v111, v91, v118
	v_lshlrev_b32_e32 v118, 16, v138
	v_exp_f32_e32 v119, v119
	v_fma_f32 v112, v84, v118, v112
	v_and_b32_e32 v118, 0xffff0000, v138
	v_fma_f32 v113, v85, v118, v113
	v_lshlrev_b32_e32 v118, 16, v139
	v_fma_f32 v114, v86, v118, v114
	v_and_b32_e32 v118, 0xffff0000, v139
	v_fmac_f32_e32 v115, v87, v118
	v_add_f32_e32 v118, 1.0, v119
	v_mul_f32_e32 v119, 0x3d372713, v112
	v_mul_f32_e32 v120, 0x3d372713, v109
	v_mul_f32_e32 v119, v112, v119
	v_mul_f32_e32 v120, v109, v120
	v_fma_f32 v119, v112, v119, v112
	v_fma_f32 v120, v109, v120, v109
	v_mul_f32_e32 v119, 0x3f4c422a, v119
	v_mul_f32_e32 v120, 0x3f4c422a, v120
	v_add_f32_e32 v119, v119, v119
	v_add_f32_e32 v120, v120, v120
	v_mul_f32_e32 v119, 0xbfb8aa3b, v119
	v_mul_f32_e32 v120, 0xbfb8aa3b, v120
	v_exp_f32_e32 v119, v119
	v_exp_f32_e32 v120, v120
	v_mul_f32_e32 v121, 0x3d372713, v113
	v_mul_f32_e32 v121, v113, v121
	v_add_f32_e32 v119, 1.0, v119
	v_add_f32_e32 v120, 1.0, v120
	v_rcp_f32_e32 v119, v119
	v_rcp_f32_e32 v120, v120
	v_fma_f32 v121, v113, v121, v113
	v_mul_f32_e32 v121, 0x3f4c422a, v121
	v_add_f32_e32 v121, v121, v121
	v_mul_f32_e32 v121, 0xbfb8aa3b, v121
	v_mul_f32_e32 v112, v112, v119
	v_mul_f32_e32 v109, v109, v120
	v_mul_f32_e32 v119, 0x3d372713, v110
	v_mul_f32_e32 v120, 0x3d372713, v114
	v_rcp_f32_e32 v118, v118
	v_exp_f32_e32 v121, v121
	v_mul_f32_e32 v119, v110, v119
	v_mul_f32_e32 v120, v114, v120
	v_fma_f32 v119, v110, v119, v110
	v_fma_f32 v120, v114, v120, v114
	v_mul_f32_e32 v119, 0x3f4c422a, v119
	v_mul_f32_e32 v120, 0x3f4c422a, v120
	v_add_f32_e32 v119, v119, v119
	v_add_f32_e32 v120, v120, v120
	v_mul_f32_e32 v108, v108, v118
	v_add_f32_e32 v118, 1.0, v121
	v_mul_f32_e32 v119, 0xbfb8aa3b, v119
	v_mul_f32_e32 v120, 0xbfb8aa3b, v120
	v_rcp_f32_e32 v118, v118
	v_exp_f32_e32 v119, v119
	v_exp_f32_e32 v120, v120
	v_mul_f32_e32 v121, 0x3d372713, v115
	v_mul_f32_e32 v113, v113, v118
	v_add_f32_e32 v118, 1.0, v119
	v_add_f32_e32 v119, 1.0, v120
	v_mul_f32_e32 v120, 0x3d372713, v111
	v_mul_f32_e32 v120, v111, v120
	v_fma_f32 v120, v111, v120, v111
	v_mul_f32_e32 v121, v115, v121
	v_mul_f32_e32 v120, 0x3f4c422a, v120
	v_fma_f32 v121, v115, v121, v115
	v_add_f32_e32 v120, v120, v120
	v_mul_f32_e32 v121, 0x3f4c422a, v121
	v_mul_f32_e32 v120, 0xbfb8aa3b, v120
	v_add_f32_e32 v121, v121, v121
; __device__ __forceinline__ float bflo(unsigned w) { return __uint_as_float(w << 16); }
; __device__ __forceinline__ float bfhi(unsigned w) { return __uint_as_float(w & 0xffff0000u); }
; __device__ __forceinline__ u32x4 pack8(f32x4 a, f32x4 b) { u32x4 r; r[0] = cvt_pk_bf16(a[0], a[1]); r[1] = cvt_pk_bf16(a[2], a[3]); r[2] = cvt_pk_bf16(b[0], b[1]); r[3] = cvt_pk_bf16(b[2], b[3]); return r; }
; __device__ __forceinline__ float sigmoidf_(float x) { return fast_rcp(1.0f + fast_exp2(-1.4426950408889634f * x)); }
; __device__ __forceinline__ float gelu_tanh(float x) {
;     const float u = 0.7978845608028654f * (x + 0.044715f * x * x * x);
;     return x * sigmoidf_(2.0f * u);
; }
;     __device__ __forceinline__ void operator()(const AccT& acc, const Unit& u, int wr, int wc, int fr, int fq) const {
;     ...
;                 for (int m = 0; m < 4; ++m) {
;                     const int R = row0 + ai * HALF + m * 16;
;                     const u32x4 uu = uv[ai * 4 + m];
;                     f32x4 y0 = acc[ai][bj][m][0], y1 = acc[ai][bj][m][1];
;                     y0[0] += d0[0] * bflo(uu[0]); y0[1] += d0[1] * bfhi(uu[0]); y0[2] += d0[2] * bflo(uu[1]); y0[3] += d0[3] * bfhi(uu[1]);
;                     y1[0] += d1[0] * bflo(uu[2]); y1[1] += d1[1] * bfhi(uu[2]); y1[2] += d1[2] * bflo(uu[3]); y1[3] += d1[3] * bfhi(uu[3]);
; #pragma unroll
;                     for (int j = 0; j < 4; ++j) { y0[j] = gelu_tanh(y0[j]); y1[j] = gelu_tanh(y1[j]); }
;                     *(u32x4*)(Yact + (size_t)R * 256 + n) = pack8(y0, y1); __builtin_amdgcn_sched_barrier(0);
	v_exp_f32_e32 v120, v120
	v_mul_f32_e32 v121, 0xbfb8aa3b, v121
	v_exp_f32_e32 v121, v121
	v_rcp_f32_e32 v118, v118
	v_add_f32_e32 v120, 1.0, v120
	v_rcp_f32_e32 v120, v120
	v_add_f32_e32 v121, 1.0, v121
	v_rcp_f32_e32 v119, v119
	v_rcp_f32_e32 v121, v121
	v_mul_f32_e32 v118, v110, v118
	v_cvt_pk_bf16_f32 v110, v108, v109
	v_lshlrev_b64 v[108:109], 9, v[202:203]
	v_lshl_add_u64 v[108:109], s[28:29], 0, v[108:109]
	v_mul_f32_e32 v111, v111, v120
	v_lshl_add_u64 v[108:109], v[108:109], 0, v[200:201]
	v_mul_f32_e32 v114, v114, v119
	v_mul_f32_e32 v115, v115, v121
	v_cvt_pk_bf16_f32 v111, v118, v111
	v_cvt_pk_bf16_f32 v112, v112, v113
	v_cvt_pk_bf16_f32 v113, v114, v115
	global_store_dwordx4 v[108:109], v[110:113], off
	s_nop 1
	v_lshlrev_b32_e32 v110, 16, v124
	v_fma_f32 v96, v88, v110, v96
	v_mul_f32_e32 v111, 0x3d372713, v96
	v_mul_f32_e32 v111, v96, v111
	v_fma_f32 v111, v96, v111, v96
	v_and_b32_e32 v110, 0xffff0000, v124
	v_mul_f32_e32 v111, 0x3f4c422a, v111
	v_fma_f32 v97, v89, v110, v97
	v_lshlrev_b32_e32 v110, 16, v125
	v_add_f32_e32 v111, v111, v111
	v_fma_f32 v98, v90, v110, v98
	v_and_b32_e32 v110, 0xffff0000, v125
	v_mul_f32_e32 v111, 0xbfb8aa3b, v111
	v_fmac_f32_e32 v99, v91, v110
	v_lshlrev_b32_e32 v110, 16, v126
	v_exp_f32_e32 v111, v111
	v_fma_f32 v100, v84, v110, v100
	v_and_b32_e32 v110, 0xffff0000, v126
	v_fma_f32 v101, v85, v110, v101
	v_lshlrev_b32_e32 v110, 16, v127
	v_fma_f32 v102, v86, v110, v102
	v_and_b32_e32 v110, 0xffff0000, v127
	v_fmac_f32_e32 v103, v87, v110
	v_add_f32_e32 v110, 1.0, v111
	v_mul_f32_e32 v111, 0x3d372713, v100
	v_mul_f32_e32 v112, 0x3d372713, v97
	v_mul_f32_e32 v111, v100, v111
	v_mul_f32_e32 v112, v97, v112
	v_fma_f32 v111, v100, v111, v100
	v_fma_f32 v112, v97, v112, v97
	v_mul_f32_e32 v111, 0x3f4c422a, v111
	v_mul_f32_e32 v112, 0x3f4c422a, v112
	v_add_f32_e32 v111, v111, v111
	v_add_f32_e32 v112, v112, v112
	v_mul_f32_e32 v111, 0xbfb8aa3b, v111
	v_mul_f32_e32 v112, 0xbfb8aa3b, v112
	v_exp_f32_e32 v111, v111
	v_exp_f32_e32 v112, v112
	v_mul_f32_e32 v113, 0x3d372713, v101
	v_mul_f32_e32 v113, v101, v113
	v_add_f32_e32 v111, 1.0, v111
	v_add_f32_e32 v112, 1.0, v112
	v_rcp_f32_e32 v111, v111
	v_rcp_f32_e32 v112, v112
	v_fma_f32 v113, v101, v113, v101
	v_mul_f32_e32 v113, 0x3f4c422a, v113
	v_add_f32_e32 v113, v113, v113
	v_mul_f32_e32 v113, 0xbfb8aa3b, v113
	v_mul_f32_e32 v100, v100, v111
	v_mul_f32_e32 v97, v97, v112
	v_mul_f32_e32 v111, 0x3d372713, v98
	v_mul_f32_e32 v112, 0x3d372713, v102
	v_rcp_f32_e32 v110, v110
	v_exp_f32_e32 v113, v113
	v_mul_f32_e32 v111, v98, v111
	v_mul_f32_e32 v112, v102, v112
	v_fma_f32 v111, v98, v111, v98
	v_fma_f32 v112, v102, v112, v102
	v_mul_f32_e32 v111, 0x3f4c422a, v111
	v_mul_f32_e32 v112, 0x3f4c422a, v112
	v_add_f32_e32 v111, v111, v111
	v_add_f32_e32 v112, v112, v112
	v_mul_f32_e32 v96, v96, v110
	v_add_f32_e32 v110, 1.0, v113
	v_mul_f32_e32 v111, 0xbfb8aa3b, v111
	v_mul_f32_e32 v112, 0xbfb8aa3b, v112
	v_rcp_f32_e32 v110, v110
	v_exp_f32_e32 v111, v111
	v_exp_f32_e32 v112, v112
	v_mul_f32_e32 v113, 0x3d372713, v103
	v_mul_f32_e32 v101, v101, v110
	v_add_f32_e32 v110, 1.0, v111
	v_add_f32_e32 v111, 1.0, v112
	v_mul_f32_e32 v112, 0x3d372713, v99
	v_mul_f32_e32 v112, v99, v112
	v_fma_f32 v112, v99, v112, v99
	v_mul_f32_e32 v113, v103, v113
	v_mul_f32_e32 v112, 0x3f4c422a, v112
	v_fma_f32 v113, v103, v113, v103
	v_add_f32_e32 v112, v112, v112
	v_mul_f32_e32 v113, 0x3f4c422a, v113
	v_mul_f32_e32 v112, 0xbfb8aa3b, v112
	v_add_f32_e32 v113, v113, v113
	v_exp_f32_e32 v112, v112
	v_mul_f32_e32 v113, 0xbfb8aa3b, v113
	v_exp_f32_e32 v113, v113
	v_rcp_f32_e32 v110, v110
	v_add_f32_e32 v112, 1.0, v112
	v_rcp_f32_e32 v111, v111
	v_rcp_f32_e32 v112, v112
	v_add_f32_e32 v113, 1.0, v113
	v_rcp_f32_e32 v113, v113
	v_mul_f32_e32 v98, v98, v110
	s_mov_b64 s[6:7], 0x12000
	v_mul_f32_e32 v102, v102, v111
	v_mul_f32_e32 v99, v99, v112
	v_cvt_pk_bf16_f32 v96, v96, v97
	v_cvt_pk_bf16_f32 v97, v98, v99
	v_cvt_pk_bf16_f32 v98, v100, v101
	v_lshl_add_u64 v[100:101], v[152:153], 0, s[6:7]
	s_mov_b32 s6, 0x12000
	v_mul_f32_e32 v103, v103, v113
	v_cvt_pk_bf16_f32 v99, v102, v103
	v_add_co_u32_e32 v102, vcc, s6, v152
	s_nop 1
	v_addc_co_u32_e32 v103, vcc, 0, v153, vcc
	global_store_dwordx4 v[102:103], v[96:99], off
	s_nop 1
	v_lshlrev_b32_e32 v96, 16, v104
	v_fma_f32 v76, v88, v96, v76
	v_mul_f32_e32 v97, 0x3d372713, v76
	v_mul_f32_e32 v97, v76, v97
	v_fma_f32 v97, v76, v97, v76
	v_and_b32_e32 v96, 0xffff0000, v104
	v_mul_f32_e32 v97, 0x3f4c422a, v97
	v_fma_f32 v77, v89, v96, v77
	v_lshlrev_b32_e32 v96, 16, v105
	v_add_f32_e32 v97, v97, v97
	v_fma_f32 v78, v90, v96, v78
	v_and_b32_e32 v96, 0xffff0000, v105
	v_mul_f32_e32 v97, 0xbfb8aa3b, v97
	v_fmac_f32_e32 v79, v91, v96
	v_lshlrev_b32_e32 v96, 16, v106
	v_exp_f32_e32 v97, v97
	v_fma_f32 v80, v84, v96, v80
	v_and_b32_e32 v96, 0xffff0000, v106
	v_fma_f32 v81, v85, v96, v81
	v_lshlrev_b32_e32 v96, 16, v107
	v_fma_f32 v82, v86, v96, v82
	v_and_b32_e32 v96, 0xffff0000, v107
	v_fmac_f32_e32 v83, v87, v96
	v_add_f32_e32 v96, 1.0, v97
	v_mul_f32_e32 v97, 0x3d372713, v80
	v_mul_f32_e32 v98, 0x3d372713, v77
	v_mul_f32_e32 v97, v80, v97
	v_mul_f32_e32 v98, v77, v98
	v_fma_f32 v97, v80, v97, v80
	v_fma_f32 v98, v77, v98, v77
	v_mul_f32_e32 v97, 0x3f4c422a, v97
	v_mul_f32_e32 v98, 0x3f4c422a, v98
	v_add_f32_e32 v97, v97, v97
	v_add_f32_e32 v98, v98, v98
	v_mul_f32_e32 v97, 0xbfb8aa3b, v97
	v_mul_f32_e32 v98, 0xbfb8aa3b, v98
	v_exp_f32_e32 v97, v97
	v_exp_f32_e32 v98, v98
	v_mul_f32_e32 v99, 0x3d372713, v81
	v_mul_f32_e32 v99, v81, v99
	v_add_f32_e32 v97, 1.0, v97
	v_add_f32_e32 v98, 1.0, v98
	v_rcp_f32_e32 v97, v97
	v_rcp_f32_e32 v98, v98
; __device__ __forceinline__ float bflo(unsigned w) { return __uint_as_float(w << 16); }
; __device__ __forceinline__ float bfhi(unsigned w) { return __uint_as_float(w & 0xffff0000u); }
; __device__ __forceinline__ u32x4 pack8(f32x4 a, f32x4 b) { u32x4 r; r[0] = cvt_pk_bf16(a[0], a[1]); r[1] = cvt_pk_bf16(a[2], a[3]); r[2] = cvt_pk_bf16(b[0], b[1]); r[3] = cvt_pk_bf16(b[2], b[3]); return r; }
;     __device__ __forceinline__ void operator()(const AccT& acc, const Unit& u, int wr, int wc, int fr, int fq) const {
;     ...
;         for (int bj = 0; bj < 2; ++bj) {
;             const int n = bj * HALF + wc * 32 + 8 * fq, t = n >> 4, hh = n & 15;
;             const f32x4 d0 = *(const f32x4*)(dskip + g * 16 + hh), d1 = *(const f32x4*)(dskip + g * 16 + hh + 4);
;             u32x4 uv[8];
; #pragma unroll
;             for (int rr = 0; rr < 8; ++rr) uv[rr] = *(const u32x4*)(ucat + (size_t)(row0 + (rr >> 2) * HALF + (rr & 3) * 16) * KCAT + n);
;             __builtin_amdgcn_sched_barrier(0);
; #pragma unroll
;             for (int ai = 0; ai < 2; ++ai)
; #pragma unroll
;                 for (int m = 0; m < 4; ++m) {
;                     const int R = row0 + ai * HALF + m * 16;
;                     const u32x4 uu = uv[ai * 4 + m];
;                     f32x4 y0 = acc[ai][bj][m][0], y1 = acc[ai][bj][m][1];
;                     y0[0] += d0[0] * bflo(uu[0]); y0[1] += d0[1] * bfhi(uu[0]); y0[2] += d0[2] * bflo(uu[1]); y0[3] += d0[3] * bfhi(uu[1]);
;                     y1[0] += d1[0] * bflo(uu[2]); y1[1] += d1[1] * bfhi(uu[2]); y1[2] += d1[2] * bflo(uu[3]); y1[3] += d1[3] * bfhi(uu[3]);
; #pragma unroll
;                     for (int j = 0; j < 4; ++j) { y0[j] = gelu_tanh(y0[j]); y1[j] = gelu_tanh(y1[j]); }
;                     *(u32x4*)(Yact + (size_t)R * 256 + n) = pack8(y0, y1); __builtin_amdgcn_sched_barrier(0);
	v_fma_f32 v99, v81, v99, v81
	v_mul_f32_e32 v99, 0x3f4c422a, v99
	v_add_f32_e32 v99, v99, v99
	v_mul_f32_e32 v99, 0xbfb8aa3b, v99
	v_mul_f32_e32 v80, v80, v97
	v_mul_f32_e32 v77, v77, v98
	v_mul_f32_e32 v97, 0x3d372713, v78
	v_mul_f32_e32 v98, 0x3d372713, v82
	v_rcp_f32_e32 v96, v96
	v_exp_f32_e32 v99, v99
	v_mul_f32_e32 v97, v78, v97
	v_mul_f32_e32 v98, v82, v98
	v_fma_f32 v97, v78, v97, v78
	v_fma_f32 v98, v82, v98, v82
	v_mul_f32_e32 v97, 0x3f4c422a, v97
	v_mul_f32_e32 v98, 0x3f4c422a, v98
	v_add_f32_e32 v97, v97, v97
	v_add_f32_e32 v98, v98, v98
	v_mul_f32_e32 v76, v76, v96
	v_add_f32_e32 v96, 1.0, v99
	v_mul_f32_e32 v97, 0xbfb8aa3b, v97
	v_mul_f32_e32 v98, 0xbfb8aa3b, v98
	v_rcp_f32_e32 v96, v96
	v_exp_f32_e32 v97, v97
	v_exp_f32_e32 v98, v98
	v_mul_f32_e32 v99, 0x3d372713, v83
	v_mul_f32_e32 v81, v81, v96
	v_add_f32_e32 v96, 1.0, v97
	v_add_f32_e32 v97, 1.0, v98
	v_mul_f32_e32 v98, 0x3d372713, v79
	v_mul_f32_e32 v98, v79, v98
	v_fma_f32 v98, v79, v98, v79
	v_mul_f32_e32 v98, 0x3f4c422a, v98
	v_mul_f32_e32 v99, v83, v99
	v_add_f32_e32 v98, v98, v98
	v_fma_f32 v99, v83, v99, v83
	v_mul_f32_e32 v98, 0xbfb8aa3b, v98
	v_mul_f32_e32 v99, 0x3f4c422a, v99
	v_exp_f32_e32 v98, v98
	v_add_f32_e32 v99, v99, v99
	v_mul_f32_e32 v99, 0xbfb8aa3b, v99
	v_exp_f32_e32 v99, v99
	v_rcp_f32_e32 v96, v96
	v_add_f32_e32 v98, 1.0, v98
	v_rcp_f32_e32 v98, v98
	v_add_f32_e32 v99, 1.0, v99
	v_rcp_f32_e32 v97, v97
	v_rcp_f32_e32 v99, v99
	s_mov_b64 s[6:7], 0x14000
	v_mul_f32_e32 v78, v78, v96
	v_lshl_add_u64 v[102:103], v[152:153], 0, s[6:7]
	s_mov_b32 s6, 0x14000
	v_mul_f32_e32 v79, v79, v98
	v_cvt_pk_bf16_f32 v76, v76, v77
	v_cvt_pk_bf16_f32 v77, v78, v79
	v_cvt_pk_bf16_f32 v78, v80, v81
	v_add_co_u32_e32 v80, vcc, s6, v152
	v_mul_f32_e32 v82, v82, v97
	s_nop 0
	v_addc_co_u32_e32 v81, vcc, 0, v153, vcc
	v_mul_f32_e32 v83, v83, v99
	v_cvt_pk_bf16_f32 v79, v82, v83
	global_store_dwordx4 v[80:81], v[76:79], off
	s_nop 1
	v_lshlrev_b32_e32 v76, 16, v92
	v_fma_f32 v68, v88, v76, v68
	v_mul_f32_e32 v77, 0x3d372713, v68
	v_mul_f32_e32 v77, v68, v77
	v_fma_f32 v77, v68, v77, v68
	v_and_b32_e32 v76, 0xffff0000, v92
	v_mul_f32_e32 v77, 0x3f4c422a, v77
	v_fma_f32 v69, v89, v76, v69
	v_lshlrev_b32_e32 v76, 16, v93
	v_add_f32_e32 v77, v77, v77
	v_fma_f32 v70, v90, v76, v70
	v_and_b32_e32 v76, 0xffff0000, v93
	v_mul_f32_e32 v77, 0xbfb8aa3b, v77
	v_fmac_f32_e32 v71, v91, v76
	v_lshlrev_b32_e32 v76, 16, v94
	v_exp_f32_e32 v77, v77
	v_fma_f32 v72, v84, v76, v72
	v_and_b32_e32 v76, 0xffff0000, v94
	v_fma_f32 v73, v85, v76, v73
	v_lshlrev_b32_e32 v76, 16, v95
	v_fma_f32 v74, v86, v76, v74
	v_and_b32_e32 v76, 0xffff0000, v95
	v_fmac_f32_e32 v75, v87, v76
	v_add_f32_e32 v76, 1.0, v77
	v_mul_f32_e32 v77, 0x3d372713, v72
	v_mul_f32_e32 v78, 0x3d372713, v69
	v_mul_f32_e32 v77, v72, v77
	v_mul_f32_e32 v78, v69, v78
	v_fma_f32 v77, v72, v77, v72
	v_fma_f32 v78, v69, v78, v69
	v_mul_f32_e32 v77, 0x3f4c422a, v77
	v_mul_f32_e32 v78, 0x3f4c422a, v78
	v_add_f32_e32 v77, v77, v77
	v_add_f32_e32 v78, v78, v78
	v_mul_f32_e32 v77, 0xbfb8aa3b, v77
	v_mul_f32_e32 v78, 0xbfb8aa3b, v78
	v_exp_f32_e32 v77, v77
	v_exp_f32_e32 v78, v78
	v_mul_f32_e32 v79, 0x3d372713, v73
	v_mul_f32_e32 v79, v73, v79
	v_add_f32_e32 v77, 1.0, v77
	v_add_f32_e32 v78, 1.0, v78
	v_rcp_f32_e32 v77, v77
	v_rcp_f32_e32 v78, v78
	v_fma_f32 v79, v73, v79, v73
	v_mul_f32_e32 v79, 0x3f4c422a, v79
	v_add_f32_e32 v79, v79, v79
	v_mul_f32_e32 v79, 0xbfb8aa3b, v79
	v_mul_f32_e32 v72, v72, v77
	v_mul_f32_e32 v69, v69, v78
	v_mul_f32_e32 v77, 0x3d372713, v70
	v_mul_f32_e32 v78, 0x3d372713, v74
	v_rcp_f32_e32 v76, v76
	v_exp_f32_e32 v79, v79
	v_mul_f32_e32 v77, v70, v77
	v_mul_f32_e32 v78, v74, v78
	v_fma_f32 v77, v70, v77, v70
	v_fma_f32 v78, v74, v78, v74
	v_mul_f32_e32 v77, 0x3f4c422a, v77
	v_mul_f32_e32 v78, 0x3f4c422a, v78
	v_add_f32_e32 v77, v77, v77
	v_add_f32_e32 v78, v78, v78
	v_mul_f32_e32 v68, v68, v76
	v_add_f32_e32 v76, 1.0, v79
	v_mul_f32_e32 v77, 0xbfb8aa3b, v77
	v_mul_f32_e32 v78, 0xbfb8aa3b, v78
	v_rcp_f32_e32 v76, v76
	v_exp_f32_e32 v77, v77
	v_exp_f32_e32 v78, v78
	v_mul_f32_e32 v79, 0x3d372713, v75
	v_mul_f32_e32 v73, v73, v76
	v_add_f32_e32 v76, 1.0, v77
	v_add_f32_e32 v77, 1.0, v78
	v_mul_f32_e32 v78, 0x3d372713, v71
	v_mul_f32_e32 v78, v71, v78
	v_fma_f32 v78, v71, v78, v71
	v_mul_f32_e32 v78, 0x3f4c422a, v78
	v_mul_f32_e32 v79, v75, v79
	v_add_f32_e32 v78, v78, v78
	v_fma_f32 v79, v75, v79, v75
	v_mul_f32_e32 v78, 0xbfb8aa3b, v78
	v_mul_f32_e32 v79, 0x3f4c422a, v79
	v_exp_f32_e32 v78, v78
	v_add_f32_e32 v79, v79, v79
	v_mul_f32_e32 v79, 0xbfb8aa3b, v79
	v_exp_f32_e32 v79, v79
	v_rcp_f32_e32 v76, v76
	v_add_f32_e32 v78, 1.0, v78
	v_rcp_f32_e32 v78, v78
	v_add_f32_e32 v79, 1.0, v79
	v_rcp_f32_e32 v77, v77
	v_rcp_f32_e32 v79, v79
	s_mov_b64 s[6:7], 0x16000
	v_mul_f32_e32 v70, v70, v76
	v_lshl_add_u64 v[104:105], v[152:153], 0, s[6:7]
	s_mov_b32 s6, 0x16000
	v_mul_f32_e32 v71, v71, v78
	v_cvt_pk_bf16_f32 v68, v68, v69
	v_cvt_pk_bf16_f32 v69, v70, v71
	v_cvt_pk_bf16_f32 v70, v72, v73
	v_add_co_u32_e32 v72, vcc, s6, v152
	v_mul_f32_e32 v74, v74, v77
	s_nop 0
	v_addc_co_u32_e32 v73, vcc, 0, v153, vcc
	v_mul_f32_e32 v75, v75, v79
	v_cvt_pk_bf16_f32 v71, v74, v75
	global_store_dwordx4 v[72:73], v[68:71], off
	global_load_dwordx4 v[68:71], v219, s[62:63] offset:16
	s_nop 0
	global_load_dwordx4 v[76:79], v219, s[62:63]
	global_load_dwordx4 v[110:113], v[166:167], off offset:256
	global_load_dwordx4 v[118:121], v[168:169], off offset:256
	global_load_dwordx4 v[96:99], v[170:171], off offset:256
	global_load_dwordx4 v[92:95], v[172:173], off offset:256
	global_load_dwordx4 v[88:91], v[174:175], off offset:256
	global_load_dwordx4 v[84:87], v[194:195], off offset:256
	global_load_dwordx4 v[80:83], v[196:197], off offset:256
	global_load_dwordx4 v[72:75], v[198:199], off offset:256
	s_waitcnt vmcnt(0)
; __device__ __forceinline__ float bflo(unsigned w) { return __uint_as_float(w << 16); }
; __device__ __forceinline__ float bfhi(unsigned w) { return __uint_as_float(w & 0xffff0000u); }
; __device__ __forceinline__ u32x4 pack8(f32x4 a, f32x4 b) { u32x4 r; r[0] = cvt_pk_bf16(a[0], a[1]); r[1] = cvt_pk_bf16(a[2], a[3]); r[2] = cvt_pk_bf16(b[0], b[1]); r[3] = cvt_pk_bf16(b[2], b[3]); return r; }
; __device__ __forceinline__ float sigmoidf_(float x) { return fast_rcp(1.0f + fast_exp2(-1.4426950408889634f * x)); }
; __device__ __forceinline__ float gelu_tanh(float x) {
;     const float u = 0.7978845608028654f * (x + 0.044715f * x * x * x);
;     return x * sigmoidf_(2.0f * u);
; }
;     __device__ __forceinline__ void operator()(const AccT& acc, const Unit& u, int wr, int wc, int fr, int fq) const {
;     ...
;             for (int ai = 0; ai < 2; ++ai)
; #pragma unroll
;                 for (int m = 0; m < 4; ++m) {
;                     const int R = row0 + ai * HALF + m * 16;
;                     const u32x4 uu = uv[ai * 4 + m];
;                     f32x4 y0 = acc[ai][bj][m][0], y1 = acc[ai][bj][m][1];
;                     y0[0] += d0[0] * bflo(uu[0]); y0[1] += d0[1] * bfhi(uu[0]); y0[2] += d0[2] * bflo(uu[1]); y0[3] += d0[3] * bfhi(uu[1]);
;                     y1[0] += d1[0] * bflo(uu[2]); y1[1] += d1[1] * bfhi(uu[2]); y1[2] += d1[2] * bflo(uu[3]); y1[3] += d1[3] * bfhi(uu[3]);
; #pragma unroll
;                     for (int j = 0; j < 4; ++j) { y0[j] = gelu_tanh(y0[j]); y1[j] = gelu_tanh(y1[j]); }
;                     *(u32x4*)(Yact + (size_t)R * 256 + n) = pack8(y0, y1); __builtin_amdgcn_sched_barrier(0);
	v_lshlrev_b32_e32 v106, 16, v110
	v_fma_f32 v60, v76, v106, v60
	v_mul_f32_e32 v107, 0x3d372713, v60
	v_mul_f32_e32 v107, v60, v107
	v_fma_f32 v107, v60, v107, v60
	v_and_b32_e32 v106, 0xffff0000, v110
	v_mul_f32_e32 v107, 0x3f4c422a, v107
	v_fma_f32 v61, v77, v106, v61
	v_lshlrev_b32_e32 v106, 16, v111
	v_add_f32_e32 v107, v107, v107
	v_fma_f32 v62, v78, v106, v62
	v_and_b32_e32 v106, 0xffff0000, v111
	v_mul_f32_e32 v107, 0xbfb8aa3b, v107
	v_fmac_f32_e32 v63, v79, v106
	v_lshlrev_b32_e32 v106, 16, v112
	v_exp_f32_e32 v107, v107
	v_fma_f32 v64, v68, v106, v64
	v_and_b32_e32 v106, 0xffff0000, v112
	v_fma_f32 v65, v69, v106, v65
	v_lshlrev_b32_e32 v106, 16, v113
	v_fma_f32 v66, v70, v106, v66
	v_and_b32_e32 v106, 0xffff0000, v113
	v_fmac_f32_e32 v67, v71, v106
	v_add_f32_e32 v106, 1.0, v107
	v_mul_f32_e32 v107, 0x3d372713, v64
	v_mul_f32_e32 v110, 0x3d372713, v61
	v_mul_f32_e32 v107, v64, v107
	v_mul_f32_e32 v110, v61, v110
	v_fma_f32 v107, v64, v107, v64
	v_fma_f32 v110, v61, v110, v61
	v_mul_f32_e32 v107, 0x3f4c422a, v107
	v_mul_f32_e32 v110, 0x3f4c422a, v110
	v_add_f32_e32 v107, v107, v107
	v_add_f32_e32 v110, v110, v110
	v_mul_f32_e32 v107, 0xbfb8aa3b, v107
	v_mul_f32_e32 v110, 0xbfb8aa3b, v110
	v_exp_f32_e32 v107, v107
	v_exp_f32_e32 v110, v110
	v_mul_f32_e32 v111, 0x3d372713, v65
	v_mul_f32_e32 v111, v65, v111
	v_add_f32_e32 v107, 1.0, v107
	v_add_f32_e32 v110, 1.0, v110
	v_rcp_f32_e32 v107, v107
	v_rcp_f32_e32 v110, v110
	v_fma_f32 v111, v65, v111, v65
	v_mul_f32_e32 v111, 0x3f4c422a, v111
	v_add_f32_e32 v111, v111, v111
	v_mul_f32_e32 v111, 0xbfb8aa3b, v111
	v_mul_f32_e32 v64, v64, v107
	v_mul_f32_e32 v61, v61, v110
	v_mul_f32_e32 v107, 0x3d372713, v62
	v_mul_f32_e32 v110, 0x3d372713, v66
	v_rcp_f32_e32 v106, v106
	v_exp_f32_e32 v111, v111
	v_mul_f32_e32 v107, v62, v107
	v_mul_f32_e32 v110, v66, v110
	v_fma_f32 v107, v62, v107, v62
	v_fma_f32 v110, v66, v110, v66
	v_mul_f32_e32 v107, 0x3f4c422a, v107
	v_mul_f32_e32 v110, 0x3f4c422a, v110
	v_add_f32_e32 v107, v107, v107
	v_add_f32_e32 v110, v110, v110
	v_mul_f32_e32 v60, v60, v106
	v_add_f32_e32 v106, 1.0, v111
	v_mul_f32_e32 v107, 0xbfb8aa3b, v107
	v_mul_f32_e32 v110, 0xbfb8aa3b, v110
	v_rcp_f32_e32 v106, v106
	v_exp_f32_e32 v107, v107
	v_exp_f32_e32 v110, v110
	v_mul_f32_e32 v111, 0x3d372713, v67
	v_mul_f32_e32 v65, v65, v106
	v_add_f32_e32 v106, 1.0, v107
	v_add_f32_e32 v107, 1.0, v110
	v_mul_f32_e32 v110, 0x3d372713, v63
	v_mul_f32_e32 v110, v63, v110
	v_fma_f32 v110, v63, v110, v63
	v_mul_f32_e32 v111, v67, v111
	v_mul_f32_e32 v110, 0x3f4c422a, v110
	v_fma_f32 v111, v67, v111, v67
	v_add_f32_e32 v110, v110, v110
	v_mul_f32_e32 v111, 0x3f4c422a, v111
	v_mul_f32_e32 v110, 0xbfb8aa3b, v110
	v_add_f32_e32 v111, v111, v111
	v_exp_f32_e32 v110, v110
	v_mul_f32_e32 v111, 0xbfb8aa3b, v111
	v_exp_f32_e32 v111, v111
	v_rcp_f32_e32 v106, v106
	v_add_f32_e32 v110, 1.0, v110
	v_rcp_f32_e32 v110, v110
	v_add_f32_e32 v111, 1.0, v111
	v_rcp_f32_e32 v107, v107
	v_rcp_f32_e32 v111, v111
	v_mul_f32_e32 v62, v62, v106
	v_mul_f32_e32 v63, v63, v110
	v_mul_f32_e32 v66, v66, v107
	v_mul_f32_e32 v67, v67, v111
	v_cvt_pk_bf16_f32 v60, v60, v61
	v_cvt_pk_bf16_f32 v61, v62, v63
	v_cvt_pk_bf16_f32 v62, v64, v65
	v_cvt_pk_bf16_f32 v63, v66, v67
	global_store_dwordx4 v[152:153], v[60:63], off offset:256
	s_nop 1
	v_lshlrev_b32_e32 v60, 16, v118
	v_fma_f32 v52, v76, v60, v52
	v_mul_f32_e32 v61, 0x3d372713, v52
	v_mul_f32_e32 v61, v52, v61
	v_fma_f32 v61, v52, v61, v52
	v_and_b32_e32 v60, 0xffff0000, v118
	v_mul_f32_e32 v61, 0x3f4c422a, v61
	v_fma_f32 v53, v77, v60, v53
	v_lshlrev_b32_e32 v60, 16, v119
	v_add_f32_e32 v61, v61, v61
	v_fma_f32 v54, v78, v60, v54
	v_and_b32_e32 v60, 0xffff0000, v119
	v_mul_f32_e32 v61, 0xbfb8aa3b, v61
	v_fmac_f32_e32 v55, v79, v60
	v_lshlrev_b32_e32 v60, 16, v120
	v_exp_f32_e32 v61, v61
	v_fma_f32 v56, v68, v60, v56
	v_and_b32_e32 v60, 0xffff0000, v120
	v_fma_f32 v57, v69, v60, v57
	v_lshlrev_b32_e32 v60, 16, v121
	v_fma_f32 v58, v70, v60, v58
	v_and_b32_e32 v60, 0xffff0000, v121
	v_fmac_f32_e32 v59, v71, v60
	v_add_f32_e32 v60, 1.0, v61
	v_mul_f32_e32 v61, 0x3d372713, v56
	v_mul_f32_e32 v62, 0x3d372713, v53
	v_mul_f32_e32 v61, v56, v61
	v_mul_f32_e32 v62, v53, v62
	v_fma_f32 v61, v56, v61, v56
	v_fma_f32 v62, v53, v62, v53
	v_mul_f32_e32 v61, 0x3f4c422a, v61
	v_mul_f32_e32 v62, 0x3f4c422a, v62
	v_add_f32_e32 v61, v61, v61
	v_add_f32_e32 v62, v62, v62
	v_mul_f32_e32 v61, 0xbfb8aa3b, v61
	v_mul_f32_e32 v62, 0xbfb8aa3b, v62
	v_exp_f32_e32 v61, v61
	v_exp_f32_e32 v62, v62
	v_mul_f32_e32 v63, 0x3d372713, v57
	v_mul_f32_e32 v63, v57, v63
	v_add_f32_e32 v61, 1.0, v61
	v_add_f32_e32 v62, 1.0, v62
	v_rcp_f32_e32 v61, v61
	v_rcp_f32_e32 v62, v62
	v_fma_f32 v63, v57, v63, v57
	v_mul_f32_e32 v63, 0x3f4c422a, v63
	v_add_f32_e32 v63, v63, v63
	v_mul_f32_e32 v63, 0xbfb8aa3b, v63
	v_mul_f32_e32 v56, v56, v61
	v_mul_f32_e32 v53, v53, v62
	v_mul_f32_e32 v61, 0x3d372713, v54
	v_mul_f32_e32 v62, 0x3d372713, v58
	v_rcp_f32_e32 v60, v60
	v_exp_f32_e32 v63, v63
	v_mul_f32_e32 v61, v54, v61
	v_mul_f32_e32 v62, v58, v62
	v_fma_f32 v61, v54, v61, v54
	v_fma_f32 v62, v58, v62, v58
	v_mul_f32_e32 v61, 0x3f4c422a, v61
	v_mul_f32_e32 v62, 0x3f4c422a, v62
	v_add_f32_e32 v61, v61, v61
	v_add_f32_e32 v62, v62, v62
	v_mul_f32_e32 v52, v52, v60
	v_add_f32_e32 v60, 1.0, v63
	v_mul_f32_e32 v61, 0xbfb8aa3b, v61
	v_mul_f32_e32 v62, 0xbfb8aa3b, v62
	v_rcp_f32_e32 v60, v60
	v_exp_f32_e32 v61, v61
	v_exp_f32_e32 v62, v62
	v_mul_f32_e32 v63, 0x3d372713, v59
	v_mul_f32_e32 v57, v57, v60
	v_add_f32_e32 v60, 1.0, v61
	v_add_f32_e32 v61, 1.0, v62
	v_mul_f32_e32 v62, 0x3d372713, v55
	v_mul_f32_e32 v62, v55, v62
; __device__ __forceinline__ float bflo(unsigned w) { return __uint_as_float(w << 16); }
; __device__ __forceinline__ float bfhi(unsigned w) { return __uint_as_float(w & 0xffff0000u); }
; __device__ __forceinline__ u32x4 pack8(f32x4 a, f32x4 b) { u32x4 r; r[0] = cvt_pk_bf16(a[0], a[1]); r[1] = cvt_pk_bf16(a[2], a[3]); r[2] = cvt_pk_bf16(b[0], b[1]); r[3] = cvt_pk_bf16(b[2], b[3]); return r; }
; __device__ __forceinline__ float sigmoidf_(float x) { return fast_rcp(1.0f + fast_exp2(-1.4426950408889634f * x)); }
; __device__ __forceinline__ float gelu_tanh(float x) {
;     const float u = 0.7978845608028654f * (x + 0.044715f * x * x * x);
;     return x * sigmoidf_(2.0f * u);
; }
;     __device__ __forceinline__ void operator()(const AccT& acc, const Unit& u, int wr, int wc, int fr, int fq) const {
;     ...
;             for (int ai = 0; ai < 2; ++ai)
; #pragma unroll
;                 for (int m = 0; m < 4; ++m) {
;                     const int R = row0 + ai * HALF + m * 16;
;                     const u32x4 uu = uv[ai * 4 + m];
;                     f32x4 y0 = acc[ai][bj][m][0], y1 = acc[ai][bj][m][1];
;                     y0[0] += d0[0] * bflo(uu[0]); y0[1] += d0[1] * bfhi(uu[0]); y0[2] += d0[2] * bflo(uu[1]); y0[3] += d0[3] * bfhi(uu[1]);
;                     y1[0] += d1[0] * bflo(uu[2]); y1[1] += d1[1] * bfhi(uu[2]); y1[2] += d1[2] * bflo(uu[3]); y1[3] += d1[3] * bfhi(uu[3]);
; #pragma unroll
;                     for (int j = 0; j < 4; ++j) { y0[j] = gelu_tanh(y0[j]); y1[j] = gelu_tanh(y1[j]); }
;                     *(u32x4*)(Yact + (size_t)R * 256 + n) = pack8(y0, y1); __builtin_amdgcn_sched_barrier(0);
	v_fma_f32 v62, v55, v62, v55
	v_mul_f32_e32 v63, v59, v63
	v_mul_f32_e32 v62, 0x3f4c422a, v62
	v_fma_f32 v63, v59, v63, v59
	v_add_f32_e32 v62, v62, v62
	v_mul_f32_e32 v63, 0x3f4c422a, v63
	v_mul_f32_e32 v62, 0xbfb8aa3b, v62
	v_add_f32_e32 v63, v63, v63
	v_exp_f32_e32 v62, v62
	v_mul_f32_e32 v63, 0xbfb8aa3b, v63
	v_exp_f32_e32 v63, v63
	v_rcp_f32_e32 v60, v60
	v_add_f32_e32 v62, 1.0, v62
	v_rcp_f32_e32 v62, v62
	v_add_f32_e32 v63, 1.0, v63
	v_rcp_f32_e32 v61, v61
	v_rcp_f32_e32 v63, v63
	v_mul_f32_e32 v54, v54, v60
	v_mul_f32_e32 v55, v55, v62
	v_mul_f32_e32 v58, v58, v61
	v_mul_f32_e32 v59, v59, v63
	v_cvt_pk_bf16_f32 v52, v52, v53
	v_cvt_pk_bf16_f32 v53, v54, v55
	v_cvt_pk_bf16_f32 v54, v56, v57
	v_cvt_pk_bf16_f32 v55, v58, v59
	global_store_dwordx4 v[140:141], v[52:55], off offset:256
	s_nop 1
	v_lshlrev_b32_e32 v52, 16, v96
	v_fma_f32 v44, v76, v52, v44
	v_mul_f32_e32 v53, 0x3d372713, v44
	v_mul_f32_e32 v53, v44, v53
	v_fma_f32 v53, v44, v53, v44
	v_and_b32_e32 v52, 0xffff0000, v96
	v_mul_f32_e32 v53, 0x3f4c422a, v53
	v_fma_f32 v45, v77, v52, v45
	v_lshlrev_b32_e32 v52, 16, v97
	v_add_f32_e32 v53, v53, v53
	v_fma_f32 v46, v78, v52, v46
	v_and_b32_e32 v52, 0xffff0000, v97
	v_mul_f32_e32 v53, 0xbfb8aa3b, v53
	v_fmac_f32_e32 v47, v79, v52
	v_lshlrev_b32_e32 v52, 16, v98
	v_exp_f32_e32 v53, v53
	v_fma_f32 v48, v68, v52, v48
	v_and_b32_e32 v52, 0xffff0000, v98
	v_fma_f32 v49, v69, v52, v49
	v_lshlrev_b32_e32 v52, 16, v99
	v_fma_f32 v50, v70, v52, v50
	v_and_b32_e32 v52, 0xffff0000, v99
	v_fmac_f32_e32 v51, v71, v52
	v_add_f32_e32 v52, 1.0, v53
	v_mul_f32_e32 v53, 0x3d372713, v48
	v_mul_f32_e32 v54, 0x3d372713, v45
	v_mul_f32_e32 v53, v48, v53
	v_mul_f32_e32 v54, v45, v54
	v_fma_f32 v53, v48, v53, v48
	v_fma_f32 v54, v45, v54, v45
	v_mul_f32_e32 v53, 0x3f4c422a, v53
	v_mul_f32_e32 v54, 0x3f4c422a, v54
	v_add_f32_e32 v53, v53, v53
	v_add_f32_e32 v54, v54, v54
	v_mul_f32_e32 v53, 0xbfb8aa3b, v53
	v_mul_f32_e32 v54, 0xbfb8aa3b, v54
	v_exp_f32_e32 v53, v53
	v_exp_f32_e32 v54, v54
	v_mul_f32_e32 v55, 0x3d372713, v49
	v_mul_f32_e32 v55, v49, v55
	v_add_f32_e32 v53, 1.0, v53
	v_add_f32_e32 v54, 1.0, v54
	v_rcp_f32_e32 v53, v53
	v_rcp_f32_e32 v54, v54
	v_fma_f32 v55, v49, v55, v49
	v_mul_f32_e32 v55, 0x3f4c422a, v55
	v_add_f32_e32 v55, v55, v55
	v_mul_f32_e32 v55, 0xbfb8aa3b, v55
	v_mul_f32_e32 v48, v48, v53
	v_mul_f32_e32 v45, v45, v54
	v_mul_f32_e32 v53, 0x3d372713, v46
	v_mul_f32_e32 v54, 0x3d372713, v50
	v_rcp_f32_e32 v52, v52
	v_exp_f32_e32 v55, v55
	v_mul_f32_e32 v53, v46, v53
	v_mul_f32_e32 v54, v50, v54
	v_fma_f32 v53, v46, v53, v46
	v_fma_f32 v54, v50, v54, v50
	v_mul_f32_e32 v53, 0x3f4c422a, v53
	v_mul_f32_e32 v54, 0x3f4c422a, v54
	v_add_f32_e32 v53, v53, v53
	v_add_f32_e32 v54, v54, v54
	v_mul_f32_e32 v44, v44, v52
	v_add_f32_e32 v52, 1.0, v55
	v_mul_f32_e32 v53, 0xbfb8aa3b, v53
	v_mul_f32_e32 v54, 0xbfb8aa3b, v54
	v_rcp_f32_e32 v52, v52
	v_exp_f32_e32 v53, v53
	v_exp_f32_e32 v54, v54
	v_mul_f32_e32 v55, 0x3d372713, v51
	v_mul_f32_e32 v49, v49, v52
	v_add_f32_e32 v52, 1.0, v53
	v_add_f32_e32 v53, 1.0, v54
	v_mul_f32_e32 v54, 0x3d372713, v47
	v_mul_f32_e32 v54, v47, v54
	v_fma_f32 v54, v47, v54, v47
	v_mul_f32_e32 v55, v51, v55
	v_mul_f32_e32 v54, 0x3f4c422a, v54
	v_fma_f32 v55, v51, v55, v51
	v_add_f32_e32 v54, v54, v54
	v_mul_f32_e32 v55, 0x3f4c422a, v55
	v_mul_f32_e32 v54, 0xbfb8aa3b, v54
	v_add_f32_e32 v55, v55, v55
	v_exp_f32_e32 v54, v54
	v_mul_f32_e32 v55, 0xbfb8aa3b, v55
	v_exp_f32_e32 v55, v55
	v_rcp_f32_e32 v52, v52
	v_add_f32_e32 v54, 1.0, v54
	v_rcp_f32_e32 v54, v54
	v_add_f32_e32 v55, 1.0, v55
	v_rcp_f32_e32 v53, v53
	v_rcp_f32_e32 v55, v55
	v_mul_f32_e32 v46, v46, v52
	v_mul_f32_e32 v47, v47, v54
	v_mul_f32_e32 v50, v50, v53
	v_mul_f32_e32 v51, v51, v55
	v_cvt_pk_bf16_f32 v44, v44, v45
	v_cvt_pk_bf16_f32 v45, v46, v47
	v_cvt_pk_bf16_f32 v46, v48, v49
	v_cvt_pk_bf16_f32 v47, v50, v51
	global_store_dwordx4 v[128:129], v[44:47], off offset:256
	s_nop 1
	v_lshlrev_b32_e32 v44, 16, v92
	v_fma_f32 v36, v76, v44, v36
	v_mul_f32_e32 v45, 0x3d372713, v36
	v_mul_f32_e32 v45, v36, v45
	v_fma_f32 v45, v36, v45, v36
	v_and_b32_e32 v44, 0xffff0000, v92
	v_mul_f32_e32 v45, 0x3f4c422a, v45
	v_fma_f32 v37, v77, v44, v37
	v_lshlrev_b32_e32 v44, 16, v93
	v_add_f32_e32 v45, v45, v45
	v_fma_f32 v38, v78, v44, v38
	v_and_b32_e32 v44, 0xffff0000, v93
	v_mul_f32_e32 v45, 0xbfb8aa3b, v45
	v_fmac_f32_e32 v39, v79, v44
	v_lshlrev_b32_e32 v44, 16, v94
	v_exp_f32_e32 v45, v45
	v_fma_f32 v40, v68, v44, v40
	v_and_b32_e32 v44, 0xffff0000, v94
	v_fma_f32 v41, v69, v44, v41
	v_lshlrev_b32_e32 v44, 16, v95
	v_fma_f32 v42, v70, v44, v42
	v_and_b32_e32 v44, 0xffff0000, v95
	v_fmac_f32_e32 v43, v71, v44
	v_add_f32_e32 v44, 1.0, v45
	v_mul_f32_e32 v45, 0x3d372713, v40
	v_mul_f32_e32 v46, 0x3d372713, v37
	v_mul_f32_e32 v45, v40, v45
	v_mul_f32_e32 v46, v37, v46
	v_fma_f32 v45, v40, v45, v40
	v_fma_f32 v46, v37, v46, v37
	v_mul_f32_e32 v45, 0x3f4c422a, v45
	v_mul_f32_e32 v46, 0x3f4c422a, v46
	v_add_f32_e32 v45, v45, v45
	v_add_f32_e32 v46, v46, v46
	v_mul_f32_e32 v45, 0xbfb8aa3b, v45
	v_mul_f32_e32 v46, 0xbfb8aa3b, v46
	v_exp_f32_e32 v45, v45
	v_exp_f32_e32 v46, v46
	v_mul_f32_e32 v47, 0x3d372713, v41
	v_mul_f32_e32 v47, v41, v47
	v_add_f32_e32 v45, 1.0, v45
	v_add_f32_e32 v46, 1.0, v46
	v_rcp_f32_e32 v45, v45
	v_rcp_f32_e32 v46, v46
	v_fma_f32 v47, v41, v47, v41
	v_mul_f32_e32 v47, 0x3f4c422a, v47
	v_add_f32_e32 v47, v47, v47
	v_mul_f32_e32 v47, 0xbfb8aa3b, v47
	v_mul_f32_e32 v40, v40, v45
	v_mul_f32_e32 v37, v37, v46
	v_mul_f32_e32 v45, 0x3d372713, v38
	v_mul_f32_e32 v46, 0x3d372713, v42
	v_rcp_f32_e32 v44, v44
	v_exp_f32_e32 v47, v47
	v_mul_f32_e32 v45, v38, v45
; __device__ __forceinline__ float bflo(unsigned w) { return __uint_as_float(w << 16); }
; __device__ __forceinline__ float bfhi(unsigned w) { return __uint_as_float(w & 0xffff0000u); }
; __device__ __forceinline__ u32x4 pack8(f32x4 a, f32x4 b) { u32x4 r; r[0] = cvt_pk_bf16(a[0], a[1]); r[1] = cvt_pk_bf16(a[2], a[3]); r[2] = cvt_pk_bf16(b[0], b[1]); r[3] = cvt_pk_bf16(b[2], b[3]); return r; }
; __device__ __forceinline__ float sigmoidf_(float x) { return fast_rcp(1.0f + fast_exp2(-1.4426950408889634f * x)); }
; __device__ __forceinline__ float gelu_tanh(float x) {
;     const float u = 0.7978845608028654f * (x + 0.044715f * x * x * x);
;     return x * sigmoidf_(2.0f * u);
; }
;     __device__ __forceinline__ void operator()(const AccT& acc, const Unit& u, int wr, int wc, int fr, int fq) const {
;     ...
;             for (int ai = 0; ai < 2; ++ai)
; #pragma unroll
;                 for (int m = 0; m < 4; ++m) {
;                     const int R = row0 + ai * HALF + m * 16;
;                     const u32x4 uu = uv[ai * 4 + m];
;                     f32x4 y0 = acc[ai][bj][m][0], y1 = acc[ai][bj][m][1];
;                     y0[0] += d0[0] * bflo(uu[0]); y0[1] += d0[1] * bfhi(uu[0]); y0[2] += d0[2] * bflo(uu[1]); y0[3] += d0[3] * bfhi(uu[1]);
;                     y1[0] += d1[0] * bflo(uu[2]); y1[1] += d1[1] * bfhi(uu[2]); y1[2] += d1[2] * bflo(uu[3]); y1[3] += d1[3] * bfhi(uu[3]);
; #pragma unroll
;                     for (int j = 0; j < 4; ++j) { y0[j] = gelu_tanh(y0[j]); y1[j] = gelu_tanh(y1[j]); }
;                     *(u32x4*)(Yact + (size_t)R * 256 + n) = pack8(y0, y1); __builtin_amdgcn_sched_barrier(0);
	v_mul_f32_e32 v46, v42, v46
	v_fma_f32 v45, v38, v45, v38
	v_fma_f32 v46, v42, v46, v42
	v_mul_f32_e32 v45, 0x3f4c422a, v45
	v_mul_f32_e32 v46, 0x3f4c422a, v46
	v_add_f32_e32 v45, v45, v45
	v_add_f32_e32 v46, v46, v46
	v_mul_f32_e32 v36, v36, v44
	v_add_f32_e32 v44, 1.0, v47
	v_mul_f32_e32 v45, 0xbfb8aa3b, v45
	v_mul_f32_e32 v46, 0xbfb8aa3b, v46
	v_rcp_f32_e32 v44, v44
	v_exp_f32_e32 v45, v45
	v_exp_f32_e32 v46, v46
	v_mul_f32_e32 v47, 0x3d372713, v43
	v_mul_f32_e32 v41, v41, v44
	v_add_f32_e32 v44, 1.0, v45
	v_add_f32_e32 v45, 1.0, v46
	v_mul_f32_e32 v46, 0x3d372713, v39
	v_mul_f32_e32 v46, v39, v46
	v_fma_f32 v46, v39, v46, v39
	v_mul_f32_e32 v47, v43, v47
	v_mul_f32_e32 v46, 0x3f4c422a, v46
	v_fma_f32 v47, v43, v47, v43
	v_add_f32_e32 v46, v46, v46
	v_mul_f32_e32 v47, 0x3f4c422a, v47
	v_mul_f32_e32 v46, 0xbfb8aa3b, v46
	v_add_f32_e32 v47, v47, v47
	v_exp_f32_e32 v46, v46
	v_mul_f32_e32 v47, 0xbfb8aa3b, v47
	v_exp_f32_e32 v47, v47
	v_rcp_f32_e32 v44, v44
	v_add_f32_e32 v46, 1.0, v46
	v_rcp_f32_e32 v46, v46
	v_add_f32_e32 v47, 1.0, v47
	v_rcp_f32_e32 v45, v45
	v_rcp_f32_e32 v47, v47
	v_mul_f32_e32 v38, v38, v44
	v_mul_f32_e32 v39, v39, v46
	v_mul_f32_e32 v42, v42, v45
	v_mul_f32_e32 v43, v43, v47
	v_cvt_pk_bf16_f32 v36, v36, v37
	v_cvt_pk_bf16_f32 v37, v38, v39
	v_cvt_pk_bf16_f32 v38, v40, v41
	v_cvt_pk_bf16_f32 v39, v42, v43
	global_store_dwordx4 v[116:117], v[36:39], off offset:256
	s_nop 1
	v_lshlrev_b32_e32 v36, 16, v88
	v_fma_f32 v28, v76, v36, v28
	v_mul_f32_e32 v37, 0x3d372713, v28
	v_mul_f32_e32 v37, v28, v37
	v_fma_f32 v37, v28, v37, v28
	v_and_b32_e32 v36, 0xffff0000, v88
	v_mul_f32_e32 v37, 0x3f4c422a, v37
	v_fma_f32 v29, v77, v36, v29
	v_lshlrev_b32_e32 v36, 16, v89
	v_add_f32_e32 v37, v37, v37
	v_fma_f32 v30, v78, v36, v30
	v_and_b32_e32 v36, 0xffff0000, v89
	v_mul_f32_e32 v37, 0xbfb8aa3b, v37
	v_fmac_f32_e32 v31, v79, v36
	v_lshlrev_b32_e32 v36, 16, v90
	v_exp_f32_e32 v37, v37
	v_fma_f32 v32, v68, v36, v32
	v_and_b32_e32 v36, 0xffff0000, v90
	v_fma_f32 v33, v69, v36, v33
	v_lshlrev_b32_e32 v36, 16, v91
	v_fma_f32 v34, v70, v36, v34
	v_and_b32_e32 v36, 0xffff0000, v91
	v_fmac_f32_e32 v35, v71, v36
	v_add_f32_e32 v36, 1.0, v37
	v_mul_f32_e32 v37, 0x3d372713, v32
	v_mul_f32_e32 v38, 0x3d372713, v29
	v_mul_f32_e32 v37, v32, v37
	v_mul_f32_e32 v38, v29, v38
	v_fma_f32 v37, v32, v37, v32
	v_fma_f32 v38, v29, v38, v29
	v_mul_f32_e32 v37, 0x3f4c422a, v37
	v_mul_f32_e32 v38, 0x3f4c422a, v38
	v_add_f32_e32 v37, v37, v37
	v_add_f32_e32 v38, v38, v38
	v_mul_f32_e32 v37, 0xbfb8aa3b, v37
	v_mul_f32_e32 v38, 0xbfb8aa3b, v38
	v_exp_f32_e32 v37, v37
	v_exp_f32_e32 v38, v38
	v_mul_f32_e32 v39, 0x3d372713, v33
	v_mul_f32_e32 v39, v33, v39
	v_add_f32_e32 v37, 1.0, v37
	v_add_f32_e32 v38, 1.0, v38
	v_rcp_f32_e32 v37, v37
	v_rcp_f32_e32 v38, v38
	v_fma_f32 v39, v33, v39, v33
	v_mul_f32_e32 v39, 0x3f4c422a, v39
	v_add_f32_e32 v39, v39, v39
	v_mul_f32_e32 v39, 0xbfb8aa3b, v39
	v_mul_f32_e32 v32, v32, v37
	v_mul_f32_e32 v29, v29, v38
	v_mul_f32_e32 v37, 0x3d372713, v30
	v_mul_f32_e32 v38, 0x3d372713, v34
	v_rcp_f32_e32 v36, v36
	v_exp_f32_e32 v39, v39
	v_mul_f32_e32 v37, v30, v37
	v_mul_f32_e32 v38, v34, v38
	v_fma_f32 v37, v30, v37, v30
	v_fma_f32 v38, v34, v38, v34
	v_mul_f32_e32 v37, 0x3f4c422a, v37
	v_mul_f32_e32 v38, 0x3f4c422a, v38
	v_add_f32_e32 v37, v37, v37
	v_add_f32_e32 v38, v38, v38
	v_mul_f32_e32 v28, v28, v36
	v_add_f32_e32 v36, 1.0, v39
	v_mul_f32_e32 v37, 0xbfb8aa3b, v37
	v_mul_f32_e32 v38, 0xbfb8aa3b, v38
	v_rcp_f32_e32 v36, v36
	v_exp_f32_e32 v37, v37
	v_exp_f32_e32 v38, v38
	v_mul_f32_e32 v39, 0x3d372713, v35
	v_mul_f32_e32 v33, v33, v36
	v_add_f32_e32 v36, 1.0, v37
	v_add_f32_e32 v37, 1.0, v38
	v_mul_f32_e32 v38, 0x3d372713, v31
	v_mul_f32_e32 v38, v31, v38
	v_fma_f32 v38, v31, v38, v31
	v_mul_f32_e32 v39, v35, v39
	v_mul_f32_e32 v38, 0x3f4c422a, v38
	v_fma_f32 v39, v35, v39, v35
	v_add_f32_e32 v38, v38, v38
	v_mul_f32_e32 v39, 0x3f4c422a, v39
	v_mul_f32_e32 v38, 0xbfb8aa3b, v38
	v_add_f32_e32 v39, v39, v39
	v_exp_f32_e32 v38, v38
	v_mul_f32_e32 v39, 0xbfb8aa3b, v39
	v_exp_f32_e32 v39, v39
	v_rcp_f32_e32 v36, v36
	v_add_f32_e32 v38, 1.0, v38
	v_rcp_f32_e32 v38, v38
	v_add_f32_e32 v39, 1.0, v39
	v_rcp_f32_e32 v37, v37
	v_rcp_f32_e32 v39, v39
	v_mul_f32_e32 v30, v30, v36
	v_mul_f32_e32 v31, v31, v38
	v_mul_f32_e32 v34, v34, v37
	v_mul_f32_e32 v35, v35, v39
	v_cvt_pk_bf16_f32 v28, v28, v29
	v_cvt_pk_bf16_f32 v29, v30, v31
	v_cvt_pk_bf16_f32 v30, v32, v33
	v_cvt_pk_bf16_f32 v31, v34, v35
	global_store_dwordx4 v[108:109], v[28:31], off offset:256
	s_nop 1
	v_lshlrev_b32_e32 v28, 16, v84
	v_fma_f32 v20, v76, v28, v20
	v_mul_f32_e32 v29, 0x3d372713, v20
	v_mul_f32_e32 v29, v20, v29
	v_fma_f32 v29, v20, v29, v20
	v_and_b32_e32 v28, 0xffff0000, v84
	v_mul_f32_e32 v29, 0x3f4c422a, v29
	v_fma_f32 v21, v77, v28, v21
	v_lshlrev_b32_e32 v28, 16, v85
	v_add_f32_e32 v29, v29, v29
	v_fma_f32 v22, v78, v28, v22
	v_and_b32_e32 v28, 0xffff0000, v85
	v_mul_f32_e32 v29, 0xbfb8aa3b, v29
	v_fmac_f32_e32 v23, v79, v28
	v_lshlrev_b32_e32 v28, 16, v86
	v_exp_f32_e32 v29, v29
	v_fma_f32 v24, v68, v28, v24
	v_and_b32_e32 v28, 0xffff0000, v86
	v_fma_f32 v25, v69, v28, v25
	v_lshlrev_b32_e32 v28, 16, v87
	v_fma_f32 v26, v70, v28, v26
	v_and_b32_e32 v28, 0xffff0000, v87
	v_fmac_f32_e32 v27, v71, v28
	v_add_f32_e32 v28, 1.0, v29
	v_mul_f32_e32 v29, 0x3d372713, v24
	v_mul_f32_e32 v30, 0x3d372713, v21
	v_mul_f32_e32 v29, v24, v29
	v_mul_f32_e32 v30, v21, v30
	v_fma_f32 v29, v24, v29, v24
	v_fma_f32 v30, v21, v30, v21
	v_mul_f32_e32 v29, 0x3f4c422a, v29
	v_mul_f32_e32 v30, 0x3f4c422a, v30
	v_add_f32_e32 v29, v29, v29
	v_add_f32_e32 v30, v30, v30
; __device__ __forceinline__ float bflo(unsigned w) { return __uint_as_float(w << 16); }
; __device__ __forceinline__ float bfhi(unsigned w) { return __uint_as_float(w & 0xffff0000u); }
; __device__ __forceinline__ u32x4 pack8(f32x4 a, f32x4 b) { u32x4 r; r[0] = cvt_pk_bf16(a[0], a[1]); r[1] = cvt_pk_bf16(a[2], a[3]); r[2] = cvt_pk_bf16(b[0], b[1]); r[3] = cvt_pk_bf16(b[2], b[3]); return r; }
; __device__ __forceinline__ float sigmoidf_(float x) { return fast_rcp(1.0f + fast_exp2(-1.4426950408889634f * x)); }
; __device__ __forceinline__ float gelu_tanh(float x) {
;     const float u = 0.7978845608028654f * (x + 0.044715f * x * x * x);
;     return x * sigmoidf_(2.0f * u);
; }
;     __device__ __forceinline__ void operator()(const AccT& acc, const Unit& u, int wr, int wc, int fr, int fq) const {
;     ...
;             for (int ai = 0; ai < 2; ++ai)
; #pragma unroll
;                 for (int m = 0; m < 4; ++m) {
;                     const int R = row0 + ai * HALF + m * 16;
;                     const u32x4 uu = uv[ai * 4 + m];
;                     f32x4 y0 = acc[ai][bj][m][0], y1 = acc[ai][bj][m][1];
;                     y0[0] += d0[0] * bflo(uu[0]); y0[1] += d0[1] * bfhi(uu[0]); y0[2] += d0[2] * bflo(uu[1]); y0[3] += d0[3] * bfhi(uu[1]);
;                     y1[0] += d1[0] * bflo(uu[2]); y1[1] += d1[1] * bfhi(uu[2]); y1[2] += d1[2] * bflo(uu[3]); y1[3] += d1[3] * bfhi(uu[3]);
; #pragma unroll
;                     for (int j = 0; j < 4; ++j) { y0[j] = gelu_tanh(y0[j]); y1[j] = gelu_tanh(y1[j]); }
;                     *(u32x4*)(Yact + (size_t)R * 256 + n) = pack8(y0, y1); __builtin_amdgcn_sched_barrier(0);
	v_mul_f32_e32 v29, 0xbfb8aa3b, v29
	v_mul_f32_e32 v30, 0xbfb8aa3b, v30
	v_exp_f32_e32 v29, v29
	v_exp_f32_e32 v30, v30
	v_mul_f32_e32 v31, 0x3d372713, v25
	v_mul_f32_e32 v31, v25, v31
	v_add_f32_e32 v29, 1.0, v29
	v_add_f32_e32 v30, 1.0, v30
	v_rcp_f32_e32 v29, v29
	v_rcp_f32_e32 v30, v30
	v_fma_f32 v31, v25, v31, v25
	v_mul_f32_e32 v31, 0x3f4c422a, v31
	v_add_f32_e32 v31, v31, v31
	v_mul_f32_e32 v31, 0xbfb8aa3b, v31
	v_mul_f32_e32 v24, v24, v29
	v_mul_f32_e32 v21, v21, v30
	v_mul_f32_e32 v29, 0x3d372713, v22
	v_mul_f32_e32 v30, 0x3d372713, v26
	v_rcp_f32_e32 v28, v28
	v_exp_f32_e32 v31, v31
	v_mul_f32_e32 v29, v22, v29
	v_mul_f32_e32 v30, v26, v30
	v_fma_f32 v29, v22, v29, v22
	v_fma_f32 v30, v26, v30, v26
	v_mul_f32_e32 v29, 0x3f4c422a, v29
	v_mul_f32_e32 v30, 0x3f4c422a, v30
	v_add_f32_e32 v29, v29, v29
	v_add_f32_e32 v30, v30, v30
	v_mul_f32_e32 v20, v20, v28
	v_add_f32_e32 v28, 1.0, v31
	v_mul_f32_e32 v29, 0xbfb8aa3b, v29
	v_mul_f32_e32 v30, 0xbfb8aa3b, v30
	v_rcp_f32_e32 v28, v28
	v_exp_f32_e32 v29, v29
	v_exp_f32_e32 v30, v30
	v_mul_f32_e32 v31, 0x3d372713, v27
	v_mul_f32_e32 v25, v25, v28
	v_add_f32_e32 v28, 1.0, v29
	v_add_f32_e32 v29, 1.0, v30
	v_mul_f32_e32 v30, 0x3d372713, v23
	v_mul_f32_e32 v30, v23, v30
	v_fma_f32 v30, v23, v30, v23
	v_mul_f32_e32 v31, v27, v31
	v_mul_f32_e32 v30, 0x3f4c422a, v30
	v_fma_f32 v31, v27, v31, v27
	v_add_f32_e32 v30, v30, v30
	v_mul_f32_e32 v31, 0x3f4c422a, v31
	v_mul_f32_e32 v30, 0xbfb8aa3b, v30
	v_add_f32_e32 v31, v31, v31
	v_exp_f32_e32 v30, v30
	v_mul_f32_e32 v31, 0xbfb8aa3b, v31
	v_exp_f32_e32 v31, v31
	v_rcp_f32_e32 v28, v28
	v_add_f32_e32 v30, 1.0, v30
	v_rcp_f32_e32 v30, v30
	v_add_f32_e32 v31, 1.0, v31
	v_rcp_f32_e32 v29, v29
	v_rcp_f32_e32 v31, v31
	v_mul_f32_e32 v22, v22, v28
	v_mul_f32_e32 v23, v23, v30
	v_mul_f32_e32 v26, v26, v29
	v_mul_f32_e32 v27, v27, v31
	v_cvt_pk_bf16_f32 v20, v20, v21
	v_cvt_pk_bf16_f32 v21, v22, v23
	v_cvt_pk_bf16_f32 v22, v24, v25
	v_cvt_pk_bf16_f32 v23, v26, v27
	global_store_dwordx4 v[100:101], v[20:23], off offset:256
	s_nop 1
	v_lshlrev_b32_e32 v20, 16, v80
	v_fma_f32 v12, v76, v20, v12
	v_mul_f32_e32 v21, 0x3d372713, v12
	v_mul_f32_e32 v21, v12, v21
	v_fma_f32 v21, v12, v21, v12
	v_and_b32_e32 v20, 0xffff0000, v80
	v_mul_f32_e32 v21, 0x3f4c422a, v21
	v_fma_f32 v13, v77, v20, v13
	v_lshlrev_b32_e32 v20, 16, v81
	v_add_f32_e32 v21, v21, v21
	v_fma_f32 v14, v78, v20, v14
	v_and_b32_e32 v20, 0xffff0000, v81
	v_mul_f32_e32 v21, 0xbfb8aa3b, v21
	v_fmac_f32_e32 v15, v79, v20
	v_lshlrev_b32_e32 v20, 16, v82
	v_exp_f32_e32 v21, v21
	v_fma_f32 v16, v68, v20, v16
	v_and_b32_e32 v20, 0xffff0000, v82
	v_fma_f32 v17, v69, v20, v17
	v_lshlrev_b32_e32 v20, 16, v83
	v_fma_f32 v18, v70, v20, v18
	v_and_b32_e32 v20, 0xffff0000, v83
	v_fmac_f32_e32 v19, v71, v20
	v_add_f32_e32 v20, 1.0, v21
	v_mul_f32_e32 v21, 0x3d372713, v16
	v_mul_f32_e32 v22, 0x3d372713, v13
	v_mul_f32_e32 v21, v16, v21
	v_mul_f32_e32 v22, v13, v22
	v_fma_f32 v21, v16, v21, v16
	v_fma_f32 v22, v13, v22, v13
	v_mul_f32_e32 v21, 0x3f4c422a, v21
	v_mul_f32_e32 v22, 0x3f4c422a, v22
	v_add_f32_e32 v21, v21, v21
	v_add_f32_e32 v22, v22, v22
	v_mul_f32_e32 v21, 0xbfb8aa3b, v21
	v_mul_f32_e32 v22, 0xbfb8aa3b, v22
	v_exp_f32_e32 v21, v21
	v_exp_f32_e32 v22, v22
	v_mul_f32_e32 v23, 0x3d372713, v17
	v_mul_f32_e32 v23, v17, v23
	v_add_f32_e32 v21, 1.0, v21
	v_add_f32_e32 v22, 1.0, v22
	v_rcp_f32_e32 v21, v21
	v_rcp_f32_e32 v22, v22
	v_fma_f32 v23, v17, v23, v17
	v_mul_f32_e32 v23, 0x3f4c422a, v23
	v_add_f32_e32 v23, v23, v23
	v_mul_f32_e32 v23, 0xbfb8aa3b, v23
	v_mul_f32_e32 v16, v16, v21
	v_mul_f32_e32 v13, v13, v22
	v_mul_f32_e32 v21, 0x3d372713, v14
	v_mul_f32_e32 v22, 0x3d372713, v18
	v_rcp_f32_e32 v20, v20
	v_exp_f32_e32 v23, v23
	v_mul_f32_e32 v21, v14, v21
	v_mul_f32_e32 v22, v18, v22
	v_fma_f32 v21, v14, v21, v14
	v_fma_f32 v22, v18, v22, v18
	v_mul_f32_e32 v21, 0x3f4c422a, v21
	v_mul_f32_e32 v22, 0x3f4c422a, v22
	v_add_f32_e32 v21, v21, v21
	v_add_f32_e32 v22, v22, v22
	v_mul_f32_e32 v12, v12, v20
	v_add_f32_e32 v20, 1.0, v23
	v_mul_f32_e32 v21, 0xbfb8aa3b, v21
	v_mul_f32_e32 v22, 0xbfb8aa3b, v22
	v_rcp_f32_e32 v20, v20
	v_exp_f32_e32 v21, v21
	v_exp_f32_e32 v22, v22
	v_mul_f32_e32 v23, 0x3d372713, v19
; __device__ __forceinline__ float bflo(unsigned w) { return __uint_as_float(w << 16); }
; __device__ __forceinline__ float bfhi(unsigned w) { return __uint_as_float(w & 0xffff0000u); }
; __device__ __forceinline__ u32x4 pack8(f32x4 a, f32x4 b) { u32x4 r; r[0] = cvt_pk_bf16(a[0], a[1]); r[1] = cvt_pk_bf16(a[2], a[3]); r[2] = cvt_pk_bf16(b[0], b[1]); r[3] = cvt_pk_bf16(b[2], b[3]); return r; }
; __device__ __forceinline__ int lane_id_asm() { int x; asm volatile("v_mbcnt_lo_u32_b32 %0, -1, 0\n\tv_mbcnt_hi_u32_b32 %0, -1, %0" : "=&v"(x)); return x; }
; template <class Epi, class Sched>
; __device__ __forceinline__ void gemm_phase(int wv, LAS unsigned char* lds, const Gemm g, const Sched& S, const Epi& E) { LIDS
;     ...
;         { const int l2 = lane_id_asm(); E(acc, cur, wr, wc, l2 & 15, l2 >> 4); }
;         if (!has_next) break;
;     __device__ __forceinline__ void operator()(const AccT& acc, const Unit& u, int wr, int wc, int fr, int fq) const {
;     ...
;             for (int ai = 0; ai < 2; ++ai)
; #pragma unroll
;                 for (int m = 0; m < 4; ++m) {
;                     const int R = row0 + ai * HALF + m * 16;
;                     const u32x4 uu = uv[ai * 4 + m];
;                     f32x4 y0 = acc[ai][bj][m][0], y1 = acc[ai][bj][m][1];
;                     y0[0] += d0[0] * bflo(uu[0]); y0[1] += d0[1] * bfhi(uu[0]); y0[2] += d0[2] * bflo(uu[1]); y0[3] += d0[3] * bfhi(uu[1]);
;                     y1[0] += d1[0] * bflo(uu[2]); y1[1] += d1[1] * bfhi(uu[2]); y1[2] += d1[2] * bflo(uu[3]); y1[3] += d1[3] * bfhi(uu[3]);
; #pragma unroll
;                     for (int j = 0; j < 4; ++j) { y0[j] = gelu_tanh(y0[j]); y1[j] = gelu_tanh(y1[j]); }
;                     *(u32x4*)(Yact + (size_t)R * 256 + n) = pack8(y0, y1); __builtin_amdgcn_sched_barrier(0);
	v_mul_f32_e32 v17, v17, v20
	v_add_f32_e32 v20, 1.0, v21
	v_add_f32_e32 v21, 1.0, v22
	v_mul_f32_e32 v22, 0x3d372713, v15
	v_mul_f32_e32 v22, v15, v22
	v_fma_f32 v22, v15, v22, v15
	v_mul_f32_e32 v23, v19, v23
	v_mul_f32_e32 v22, 0x3f4c422a, v22
	v_fma_f32 v23, v19, v23, v19
	v_add_f32_e32 v22, v22, v22
	v_mul_f32_e32 v23, 0x3f4c422a, v23
	v_mul_f32_e32 v22, 0xbfb8aa3b, v22
	v_add_f32_e32 v23, v23, v23
	v_exp_f32_e32 v22, v22
	v_mul_f32_e32 v23, 0xbfb8aa3b, v23
	v_exp_f32_e32 v23, v23
	v_rcp_f32_e32 v20, v20
	v_add_f32_e32 v22, 1.0, v22
	v_rcp_f32_e32 v22, v22
	v_add_f32_e32 v23, 1.0, v23
	v_rcp_f32_e32 v21, v21
	v_rcp_f32_e32 v23, v23
	v_mul_f32_e32 v14, v14, v20
	v_mul_f32_e32 v15, v15, v22
	v_mul_f32_e32 v18, v18, v21
	v_mul_f32_e32 v19, v19, v23
	v_cvt_pk_bf16_f32 v12, v12, v13
	v_cvt_pk_bf16_f32 v13, v14, v15
	v_cvt_pk_bf16_f32 v14, v16, v17
	v_cvt_pk_bf16_f32 v15, v18, v19
	global_store_dwordx4 v[102:103], v[12:15], off offset:256
	s_nop 1
	v_lshlrev_b32_e32 v12, 16, v72
	v_fma_f32 v4, v76, v12, v4
	v_mul_f32_e32 v13, 0x3d372713, v4
	v_mul_f32_e32 v13, v4, v13
	v_fma_f32 v13, v4, v13, v4
	v_and_b32_e32 v12, 0xffff0000, v72
	v_mul_f32_e32 v13, 0x3f4c422a, v13
	v_fma_f32 v5, v77, v12, v5
	v_lshlrev_b32_e32 v12, 16, v73
	v_add_f32_e32 v13, v13, v13
	v_fma_f32 v6, v78, v12, v6
	v_and_b32_e32 v12, 0xffff0000, v73
	v_mul_f32_e32 v13, 0xbfb8aa3b, v13
	v_fmac_f32_e32 v7, v79, v12
	v_lshlrev_b32_e32 v12, 16, v74
	v_exp_f32_e32 v13, v13
	v_fma_f32 v8, v68, v12, v8
	v_and_b32_e32 v12, 0xffff0000, v74
	v_fma_f32 v9, v69, v12, v9
	v_lshlrev_b32_e32 v12, 16, v75
	v_fma_f32 v10, v70, v12, v10
	v_and_b32_e32 v12, 0xffff0000, v75
	v_fmac_f32_e32 v11, v71, v12
	v_add_f32_e32 v12, 1.0, v13
	v_mul_f32_e32 v13, 0x3d372713, v8
	v_mul_f32_e32 v14, 0x3d372713, v5
	v_mul_f32_e32 v13, v8, v13
	v_mul_f32_e32 v14, v5, v14
	v_fma_f32 v13, v8, v13, v8
	v_fma_f32 v14, v5, v14, v5
	v_mul_f32_e32 v13, 0x3f4c422a, v13
	v_mul_f32_e32 v14, 0x3f4c422a, v14
	v_add_f32_e32 v13, v13, v13
	v_add_f32_e32 v14, v14, v14
	v_mul_f32_e32 v13, 0xbfb8aa3b, v13
	v_mul_f32_e32 v14, 0xbfb8aa3b, v14
	v_exp_f32_e32 v13, v13
	v_exp_f32_e32 v14, v14
	v_mul_f32_e32 v15, 0x3d372713, v9
	v_mul_f32_e32 v15, v9, v15
	v_add_f32_e32 v13, 1.0, v13
	v_add_f32_e32 v14, 1.0, v14
	v_rcp_f32_e32 v13, v13
	v_rcp_f32_e32 v14, v14
	v_fma_f32 v15, v9, v15, v9
	v_mul_f32_e32 v15, 0x3f4c422a, v15
	v_add_f32_e32 v15, v15, v15
	v_mul_f32_e32 v15, 0xbfb8aa3b, v15
	v_mul_f32_e32 v8, v8, v13
	v_mul_f32_e32 v5, v5, v14
	v_mul_f32_e32 v13, 0x3d372713, v6
	v_mul_f32_e32 v14, 0x3d372713, v10
	v_rcp_f32_e32 v12, v12
	v_exp_f32_e32 v15, v15
	v_mul_f32_e32 v13, v6, v13
	v_mul_f32_e32 v14, v10, v14
	v_fma_f32 v13, v6, v13, v6
	v_fma_f32 v14, v10, v14, v10
	v_mul_f32_e32 v13, 0x3f4c422a, v13
	v_mul_f32_e32 v14, 0x3f4c422a, v14
	v_add_f32_e32 v13, v13, v13
	v_add_f32_e32 v14, v14, v14
	v_mul_f32_e32 v4, v4, v12
	v_add_f32_e32 v12, 1.0, v15
	v_mul_f32_e32 v13, 0xbfb8aa3b, v13
	v_mul_f32_e32 v14, 0xbfb8aa3b, v14
	v_rcp_f32_e32 v12, v12
	v_exp_f32_e32 v13, v13
	v_exp_f32_e32 v14, v14
	v_mul_f32_e32 v15, 0x3d372713, v11
	v_mul_f32_e32 v9, v9, v12
	v_add_f32_e32 v12, 1.0, v13
	v_add_f32_e32 v13, 1.0, v14
	v_mul_f32_e32 v14, 0x3d372713, v7
	v_mul_f32_e32 v14, v7, v14
	v_fma_f32 v14, v7, v14, v7
	v_mul_f32_e32 v15, v11, v15
	v_mul_f32_e32 v14, 0x3f4c422a, v14
	v_fma_f32 v15, v11, v15, v11
	v_add_f32_e32 v14, v14, v14
	v_mul_f32_e32 v15, 0x3f4c422a, v15
	v_mul_f32_e32 v14, 0xbfb8aa3b, v14
	v_add_f32_e32 v15, v15, v15
	v_exp_f32_e32 v14, v14
	v_mul_f32_e32 v15, 0xbfb8aa3b, v15
	v_exp_f32_e32 v15, v15
	v_rcp_f32_e32 v12, v12
	v_add_f32_e32 v14, 1.0, v14
	v_rcp_f32_e32 v14, v14
	v_add_f32_e32 v15, 1.0, v15
	v_rcp_f32_e32 v13, v13
	v_rcp_f32_e32 v15, v15
	v_mul_f32_e32 v6, v6, v12
	v_mul_f32_e32 v7, v7, v14
	v_mul_f32_e32 v10, v10, v13
	v_mul_f32_e32 v11, v11, v15
	v_cvt_pk_bf16_f32 v4, v4, v5
	v_cvt_pk_bf16_f32 v5, v6, v7
	v_cvt_pk_bf16_f32 v6, v8, v9
	v_cvt_pk_bf16_f32 v7, v10, v11
	global_store_dwordx4 v[104:105], v[4:7], off offset:256
	s_andn2_b64 vcc, exec, s[10:11]
	s_mov_b32 s17, s55
	s_mov_b32 s16, s58
	s_mov_b64 s[72:73], s[12:13]
	s_mov_b64 s[78:79], s[8:9]
	v_readlane_b32 s6, v254, 46
	v_readlane_b32 s7, v254, 47
	s_cbranch_vccz .LBB0_72

; #define PG8_STAGE(bufoff, gbase, voff) do { _Pragma("unroll") for (int _i = 0; _i < 2; ++_i) { const char* _gb = (const char*)(gbase) + (size_t)_i * (voff##_q); asm volatile("" : "+s"(_gb)); \
;         __builtin_amdgcn_global_load_lds((const unsigned*)(_gb + (voff)), (LAS unsigned*)(lds + (bufoff) + ldsw + _i * 8192), 16, 0, 0); } } while (0)
; #define PG8_LDA(dst, b, h) do { _Pragma("unroll") for (int m = 0; m < 4; ++m) _Pragma("unroll") for (int k = 0; k < 2; ++k) dst[m][k] = *(const LAS bf16x8*)(lds + PG8_SA(b, h) + aoff + m * 2048 + k * 1024); } while (0)
; #define PG8_LDB(dst, b, h) do { _Pragma("unroll") for (int n = 0; n < 2; ++n) _Pragma("unroll") for (int k = 0; k < 2; ++k) dst[n][k] = *(const LAS bf16x8*)(lds + PG8_SB(b, h) + boff + n * 2048 + k * 1024); } while (0)
; #define PG8_MMA(ai, bj, At, Bt) do { __builtin_amdgcn_s_setprio(1); _Pragma("unroll") for (int m = 0; m < 4; ++m) _Pragma("unroll") for (int n = 0; n < 2; ++n) _Pragma("unroll") for (int k = 0; k < 2; ++k) \
;         acc[ai][bj][m][n] = __builtin_amdgcn_mfma_f32_16x16x32_bf16(Bt[n][k], At[m][k], acc[ai][bj][m][n], 0, 0, 0); __builtin_amdgcn_s_setprio(0); } while (0)
; #define PG8_WAIT_V(n) asm volatile("s_waitcnt vmcnt(" #n ")" ::: "memory")
; template <class Epi, class Sched>
; __device__ __forceinline__ void gemm_phase(int wv, LAS unsigned char* lds, const Gemm g, const Sched& S, const Epi& E) { LIDS
;     ...
;             const char* a1 = cA + (size_t)(t + 1) * kstepA;
;             const char* a2 = last ? nA : cA + (size_t)(t + 2) * kstepA; const char* b2 = last ? nB : cB + (size_t)(t + 2) * kstepB;
;             const char* a3 = a2 + kstepA; const char* b3 = b2 + kstepB;
;             asm volatile("" : "+s"(a1), "+s"(a2), "+s"(b2), "+s"(a3), "+s"(b3));
;             PG8_LDB(B0, 0, 0); PG8_SCHED; PG8_LDA(At, 0, 0); PG8_STAGE(PG8_SA(1, 1), a1 + hstepA, voffA);
;             PG8_WAIT_L(8); PG8_BAR; PG8_WAIT_L(0); PG8_MMA(0, 0, At, B0); PG8_BAR; PG8_SCHED;
;             PG8_LDB(B1, 0, 1); PG8_STAGE(PG8_SB(0, 0), b2, voffB);
;             PG8_BAR; PG8_WAIT_L(0); PG8_MMA(0, 1, At, B1); PG8_BAR;
;             PG8_LDA(At, 0, 1); PG8_STAGE(PG8_SA(0, 0), a2, voffA);
;             PG8_BAR; PG8_WAIT_L(0); PG8_MMA(1, 0, At, B0); PG8_BAR; PG8_SCHED;
;             PG8_STAGE(PG8_SB(0, 1), b2 + hstepB, voffB);
;             PG8_WAIT_V(6); PG8_BAR; PG8_MMA(1, 1, At, B1); PG8_BAR;
.LBB0_123:
	s_add_u32 s20, s68, 0x80
	s_addc_u32 s21, s69, 0
	s_add_u32 s68, s68, 0x100
	s_addc_u32 s69, s69, 0
	s_cmp_eq_u32 s18, 4
	s_cselect_b32 s84, s9, s68
	s_cselect_b32 s85, s7, s69
	s_cselect_b32 s89, s11, s17
	s_cselect_b32 s88, s13, s16
	s_add_u32 s86, s84, 0x80
	s_addc_u32 s87, s85, 0
	s_add_u32 s78, s88, 0x80
	s_addc_u32 s79, s89, 0
	s_add_i32 s19, 16, 0x10000
	v_add_u32_e32 v144, s19, v149
	ds_read_b128 v[128:131], v144
	ds_read_b128 v[132:135], v144 offset:1024
	ds_read_b128 v[140:143], v144 offset:2048
	ds_read_b128 v[144:147], v144 offset:3072
	s_add_u32 s22, s20, 0x100000
	s_addc_u32 s23, s21, 0
	s_add_i32 m0, s91, 0xc000
	s_add_u32 s20, s20, 0x180000
	ds_read_b128 v[152:155], v150
	ds_read_b128 v[156:159], v150 offset:1024
	ds_read_b128 v[160:163], v150 offset:2048
	ds_read_b128 v[164:167], v150 offset:3072
	ds_read_b128 v[168:171], v150 offset:4096
	ds_read_b128 v[172:175], v150 offset:5120
	ds_read_b128 v[194:197], v150 offset:6144
	ds_read_b128 v[198:201], v150 offset:7168
	s_addc_u32 s21, s21, 0
	v_lshl_add_u64 v[178:179], s[22:23], 0, v[136:137]
	global_load_lds_dwordx4 v[178:179], off
	s_add_i32 m0, s91, 0xe000
	v_lshl_add_u64 v[178:179], s[20:21], 0, v[136:137]
	global_load_lds_dwordx4 v[178:179], off
	s_waitcnt lgkmcnt(8)
	s_barrier
	s_waitcnt lgkmcnt(0)
	s_setprio 1
	v_mfma_f32_16x16x32_bf16 v[124:127], v[128:131], v[152:155], v[124:127]
	v_mfma_f32_16x16x32_bf16 v[120:123], v[140:143], v[152:155], v[120:123]
	v_mfma_f32_16x16x32_bf16 v[108:111], v[128:131], v[160:163], v[108:111]
	v_mfma_f32_16x16x32_bf16 v[104:107], v[140:143], v[160:163], v[104:107]
	v_mfma_f32_16x16x32_bf16 v[92:95], v[128:131], v[168:171], v[92:95]
	v_mfma_f32_16x16x32_bf16 v[88:91], v[140:143], v[168:171], v[88:91]
	v_mfma_f32_16x16x32_bf16 v[76:79], v[128:131], v[194:197], v[76:79]
	v_mfma_f32_16x16x32_bf16 v[72:75], v[140:143], v[194:197], v[72:75]
	v_mfma_f32_16x16x32_bf16 v[124:127], v[132:135], v[156:159], v[124:127]
	v_mfma_f32_16x16x32_bf16 v[120:123], v[144:147], v[156:159], v[120:123]
	v_mfma_f32_16x16x32_bf16 v[108:111], v[132:135], v[164:167], v[108:111]
	v_mfma_f32_16x16x32_bf16 v[104:107], v[144:147], v[164:167], v[104:107]
	v_mfma_f32_16x16x32_bf16 v[92:95], v[132:135], v[172:175], v[92:95]
	v_mfma_f32_16x16x32_bf16 v[88:91], v[144:147], v[172:175], v[88:91]
	v_mfma_f32_16x16x32_bf16 v[76:79], v[132:135], v[198:201], v[76:79]
	v_mfma_f32_16x16x32_bf16 v[72:75], v[144:147], v[198:201], v[72:75]
	s_setprio 0
	s_barrier
	s_add_i32 s22, 16, 0x14000
	v_add_u32_e32 v151, s22, v149
	s_mov_b64 s[20:21], s[88:89]
	ds_read_b128 v[202:205], v151
	ds_read_b128 v[206:209], v151 offset:1024
	ds_read_b128 v[218:221], v151 offset:2048
	ds_read_b128 v[222:225], v151 offset:3072
	s_add_i32 s19, s19, s90
	v_lshl_add_u64 v[178:179], s[20:21], 0, v[138:139]
	s_add_u32 s20, s88, 0x10000
	s_mov_b32 m0, s19
	s_addc_u32 s21, s89, 0
	global_load_lds_dwordx4 v[178:179], off
	s_add_i32 m0, s19, 0x2000
	v_lshl_add_u64 v[178:179], s[20:21], 0, v[138:139]
	global_load_lds_dwordx4 v[178:179], off
	s_barrier
	s_waitcnt lgkmcnt(0)
	s_setprio 1
	v_mfma_f32_16x16x32_bf16 v[116:119], v[202:205], v[152:155], v[116:119]
	v_mfma_f32_16x16x32_bf16 v[112:115], v[218:221], v[152:155], v[112:115]
	v_mfma_f32_16x16x32_bf16 v[100:103], v[202:205], v[160:163], v[100:103]
	v_mfma_f32_16x16x32_bf16 v[96:99], v[218:221], v[160:163], v[96:99]
	v_mfma_f32_16x16x32_bf16 v[84:87], v[202:205], v[168:171], v[84:87]
	v_mfma_f32_16x16x32_bf16 v[80:83], v[218:221], v[168:171], v[80:83]
	v_mfma_f32_16x16x32_bf16 v[68:71], v[202:205], v[194:197], v[68:71]
	v_mfma_f32_16x16x32_bf16 v[64:67], v[218:221], v[194:197], v[64:67]
	v_mfma_f32_16x16x32_bf16 v[116:119], v[206:209], v[156:159], v[116:119]
	v_mfma_f32_16x16x32_bf16 v[112:115], v[222:225], v[156:159], v[112:115]
	v_mfma_f32_16x16x32_bf16 v[100:103], v[206:209], v[164:167], v[100:103]
	v_mfma_f32_16x16x32_bf16 v[96:99], v[222:225], v[164:167], v[96:99]
	v_mfma_f32_16x16x32_bf16 v[84:87], v[206:209], v[172:175], v[84:87]
	v_mfma_f32_16x16x32_bf16 v[80:83], v[222:225], v[172:175], v[80:83]
	v_mfma_f32_16x16x32_bf16 v[68:71], v[206:209], v[198:201], v[68:71]
	v_mfma_f32_16x16x32_bf16 v[64:67], v[222:225], v[198:201], v[64:67]
	s_setprio 0
	s_mov_b64 s[20:21], s[84:85]
	s_barrier
	ds_read_b128 v[152:155], v150 offset:16384
	ds_read_b128 v[156:159], v150 offset:17408
	ds_read_b128 v[160:163], v150 offset:18432
	ds_read_b128 v[164:167], v150 offset:19456
	ds_read_b128 v[168:171], v150 offset:20480
	ds_read_b128 v[172:175], v150 offset:21504
	ds_read_b128 v[194:197], v150 offset:22528
	ds_read_b128 v[198:201], v150 offset:23552
	s_mov_b32 m0, s91
	v_lshl_add_u64 v[178:179], s[20:21], 0, v[136:137]
	s_add_u32 s20, s84, 0x80000
	s_addc_u32 s21, s85, 0
	global_load_lds_dwordx4 v[178:179], off
	s_mov_b32 m0, s94
	v_lshl_add_u64 v[178:179], s[20:21], 0, v[136:137]
	global_load_lds_dwordx4 v[178:179], off
	s_barrier
	s_waitcnt lgkmcnt(0)
	s_setprio 1
	v_mfma_f32_16x16x32_bf16 v[60:63], v[128:131], v[152:155], v[60:63]
	v_mfma_f32_16x16x32_bf16 v[56:59], v[140:143], v[152:155], v[56:59]
	v_mfma_f32_16x16x32_bf16 v[44:47], v[128:131], v[160:163], v[44:47]
	v_mfma_f32_16x16x32_bf16 v[40:43], v[140:143], v[160:163], v[40:43]
	v_mfma_f32_16x16x32_bf16 v[28:31], v[128:131], v[168:171], v[28:31]
	v_mfma_f32_16x16x32_bf16 v[24:27], v[140:143], v[168:171], v[24:27]
	v_mfma_f32_16x16x32_bf16 v[12:15], v[128:131], v[194:197], v[12:15]
	v_mfma_f32_16x16x32_bf16 v[8:11], v[140:143], v[194:197], v[8:11]
	v_mfma_f32_16x16x32_bf16 v[60:63], v[132:135], v[156:159], v[60:63]
	v_mfma_f32_16x16x32_bf16 v[56:59], v[144:147], v[156:159], v[56:59]
	v_mfma_f32_16x16x32_bf16 v[44:47], v[132:135], v[164:167], v[44:47]
	v_mfma_f32_16x16x32_bf16 v[40:43], v[144:147], v[164:167], v[40:43]
	v_mfma_f32_16x16x32_bf16 v[28:31], v[132:135], v[172:175], v[28:31]
	v_mfma_f32_16x16x32_bf16 v[24:27], v[144:147], v[172:175], v[24:27]
	v_mfma_f32_16x16x32_bf16 v[12:15], v[132:135], v[198:201], v[12:15]
	v_mfma_f32_16x16x32_bf16 v[8:11], v[144:147], v[198:201], v[8:11]
	s_setprio 0
	s_barrier
; #define PG8_STAGE(bufoff, gbase, voff) do { _Pragma("unroll") for (int _i = 0; _i < 2; ++_i) { const char* _gb = (const char*)(gbase) + (size_t)_i * (voff##_q); asm volatile("" : "+s"(_gb)); \
;         __builtin_amdgcn_global_load_lds((const unsigned*)(_gb + (voff)), (LAS unsigned*)(lds + (bufoff) + ldsw + _i * 8192), 16, 0, 0); } } while (0)
; #define PG8_LDA(dst, b, h) do { _Pragma("unroll") for (int m = 0; m < 4; ++m) _Pragma("unroll") for (int k = 0; k < 2; ++k) dst[m][k] = *(const LAS bf16x8*)(lds + PG8_SA(b, h) + aoff + m * 2048 + k * 1024); } while (0)
; #define PG8_LDB(dst, b, h) do { _Pragma("unroll") for (int n = 0; n < 2; ++n) _Pragma("unroll") for (int k = 0; k < 2; ++k) dst[n][k] = *(const LAS bf16x8*)(lds + PG8_SB(b, h) + boff + n * 2048 + k * 1024); } while (0)
; #define PG8_MMA(ai, bj, At, Bt) do { __builtin_amdgcn_s_setprio(1); _Pragma("unroll") for (int m = 0; m < 4; ++m) _Pragma("unroll") for (int n = 0; n < 2; ++n) _Pragma("unroll") for (int k = 0; k < 2; ++k) \
;         acc[ai][bj][m][n] = __builtin_amdgcn_mfma_f32_16x16x32_bf16(Bt[n][k], At[m][k], acc[ai][bj][m][n], 0, 0, 0); __builtin_amdgcn_s_setprio(0); } while (0)
; #define PG8_WAIT_V(n) asm volatile("s_waitcnt vmcnt(" #n ")" ::: "memory")
; #define PG8_WAIT_L(n) asm volatile("s_waitcnt lgkmcnt(" #n ")" ::: "memory")
; #define PG8_BAR __builtin_amdgcn_s_barrier()
; #define PG8_SCHED __builtin_amdgcn_sched_barrier(0)
; template <class Epi, class Sched>
; __device__ __forceinline__ void gemm_phase(int wv, LAS unsigned char* lds, const Gemm g, const Sched& S, const Epi& E) { LIDS
;     ...
;             PG8_STAGE(PG8_SB(0, 1), b2 + hstepB, voffB);
;             PG8_WAIT_V(6); PG8_BAR; PG8_MMA(1, 1, At, B1); PG8_BAR;
;             PG8_LDB(B0, 1, 0); PG8_SCHED; PG8_LDA(At, 1, 0); PG8_STAGE(PG8_SA(0, 1), a2 + hstepA, voffA);
;             PG8_WAIT_L(8); PG8_BAR; PG8_WAIT_L(0); PG8_MMA(0, 0, At, B0); PG8_BAR; PG8_SCHED;
;             PG8_LDB(B1, 1, 1); PG8_STAGE(PG8_SB(1, 0), b3, voffB);
;             PG8_BAR; PG8_WAIT_L(0); PG8_MMA(0, 1, At, B1); PG8_BAR;
;             PG8_LDA(At, 1, 1); PG8_STAGE(PG8_SA(1, 0), a3, voffA);
;             PG8_BAR; PG8_WAIT_L(0); PG8_MMA(1, 0, At, B0); PG8_BAR; PG8_SCHED;
;             PG8_STAGE(PG8_SB(1, 1), b3 + hstepB, voffB);
;             PG8_WAIT_V(6); PG8_BAR; PG8_MMA(1, 1, At, B1); PG8_BAR;
	s_add_u32 s20, s88, 0x20000
	s_addc_u32 s21, s89, 0
	s_add_i32 s19, s22, s90
	v_lshl_add_u64 v[128:129], s[20:21], 0, v[138:139]
	s_add_u32 s20, s88, 0x30000
	s_mov_b32 m0, s19
	s_addc_u32 s21, s89, 0
	global_load_lds_dwordx4 v[128:129], off
	s_add_i32 m0, s19, 0x2000
	v_lshl_add_u64 v[128:129], s[20:21], 0, v[138:139]
	global_load_lds_dwordx4 v[128:129], off
	s_waitcnt vmcnt(6)
	s_barrier
	s_setprio 1
	v_mfma_f32_16x16x32_bf16 v[52:55], v[202:205], v[152:155], v[52:55]
	v_mfma_f32_16x16x32_bf16 v[48:51], v[218:221], v[152:155], v[48:51]
	v_mfma_f32_16x16x32_bf16 v[36:39], v[202:205], v[160:163], v[36:39]
	v_mfma_f32_16x16x32_bf16 v[32:35], v[218:221], v[160:163], v[32:35]
	v_mfma_f32_16x16x32_bf16 v[20:23], v[202:205], v[168:171], v[20:23]
	v_mfma_f32_16x16x32_bf16 v[16:19], v[218:221], v[168:171], v[16:19]
	v_mfma_f32_16x16x32_bf16 v[4:7], v[202:205], v[194:197], v[4:7]
	v_mfma_f32_16x16x32_bf16 v[0:3], v[218:221], v[194:197], v[0:3]
	v_mfma_f32_16x16x32_bf16 v[52:55], v[206:209], v[156:159], v[52:55]
	v_mfma_f32_16x16x32_bf16 v[48:51], v[222:225], v[156:159], v[48:51]
	v_mfma_f32_16x16x32_bf16 v[36:39], v[206:209], v[164:167], v[36:39]
	v_mfma_f32_16x16x32_bf16 v[32:35], v[222:225], v[164:167], v[32:35]
	v_mfma_f32_16x16x32_bf16 v[20:23], v[206:209], v[172:175], v[20:23]
	v_mfma_f32_16x16x32_bf16 v[16:19], v[222:225], v[172:175], v[16:19]
	v_mfma_f32_16x16x32_bf16 v[4:7], v[206:209], v[198:201], v[4:7]
	v_mfma_f32_16x16x32_bf16 v[0:3], v[222:225], v[198:201], v[0:3]
	s_setprio 0
	s_add_i32 s19, 16, 0x18000
	v_add_u32_e32 v144, s19, v149
	s_barrier
	ds_read_b128 v[128:131], v144
	ds_read_b128 v[132:135], v144 offset:1024
	ds_read_b128 v[140:143], v144 offset:2048
	ds_read_b128 v[144:147], v144 offset:3072
	s_add_u32 s20, s84, 0x100000
	s_addc_u32 s21, s85, 0
	ds_read_b128 v[152:155], v150 offset:32768
	ds_read_b128 v[156:159], v150 offset:33792
	ds_read_b128 v[160:163], v150 offset:34816
	ds_read_b128 v[164:167], v150 offset:35840
	ds_read_b128 v[168:171], v150 offset:36864
	ds_read_b128 v[172:175], v150 offset:37888
	ds_read_b128 v[194:197], v150 offset:38912
	ds_read_b128 v[198:201], v150 offset:39936
	s_mov_b32 m0, s95
	v_lshl_add_u64 v[178:179], s[20:21], 0, v[136:137]
	s_add_u32 s20, s84, 0x180000
	s_addc_u32 s21, s85, 0
	global_load_lds_dwordx4 v[178:179], off
	s_mov_b32 m0, s59
	v_lshl_add_u64 v[178:179], s[20:21], 0, v[136:137]
	global_load_lds_dwordx4 v[178:179], off
	s_waitcnt lgkmcnt(8)
	s_barrier
	s_waitcnt lgkmcnt(0)
	s_setprio 1
	v_mfma_f32_16x16x32_bf16 v[124:127], v[128:131], v[152:155], v[124:127]
	v_mfma_f32_16x16x32_bf16 v[120:123], v[140:143], v[152:155], v[120:123]
	v_mfma_f32_16x16x32_bf16 v[108:111], v[128:131], v[160:163], v[108:111]
	v_mfma_f32_16x16x32_bf16 v[104:107], v[140:143], v[160:163], v[104:107]
	v_mfma_f32_16x16x32_bf16 v[92:95], v[128:131], v[168:171], v[92:95]
	v_mfma_f32_16x16x32_bf16 v[88:91], v[140:143], v[168:171], v[88:91]
	v_mfma_f32_16x16x32_bf16 v[76:79], v[128:131], v[194:197], v[76:79]
	v_mfma_f32_16x16x32_bf16 v[72:75], v[140:143], v[194:197], v[72:75]
	v_mfma_f32_16x16x32_bf16 v[124:127], v[132:135], v[156:159], v[124:127]
	v_mfma_f32_16x16x32_bf16 v[120:123], v[144:147], v[156:159], v[120:123]
	v_mfma_f32_16x16x32_bf16 v[108:111], v[132:135], v[164:167], v[108:111]
	v_mfma_f32_16x16x32_bf16 v[104:107], v[144:147], v[164:167], v[104:107]
	v_mfma_f32_16x16x32_bf16 v[92:95], v[132:135], v[172:175], v[92:95]
	v_mfma_f32_16x16x32_bf16 v[88:91], v[144:147], v[172:175], v[88:91]
	v_mfma_f32_16x16x32_bf16 v[76:79], v[132:135], v[198:201], v[76:79]
	v_mfma_f32_16x16x32_bf16 v[72:75], v[144:147], v[198:201], v[72:75]
	s_setprio 0
	s_barrier
	s_add_i32 s22, 16, 0x1c000
	v_add_u32_e32 v151, s22, v149
	s_mov_b64 s[20:21], s[78:79]
	ds_read_b128 v[202:205], v151
	ds_read_b128 v[206:209], v151 offset:1024
	ds_read_b128 v[218:221], v151 offset:2048
	ds_read_b128 v[222:225], v151 offset:3072
	s_add_i32 s19, s19, s90
	v_lshl_add_u64 v[178:179], s[20:21], 0, v[138:139]
	s_add_u32 s20, s78, 0x10000
	s_mov_b32 m0, s19
	s_addc_u32 s21, s79, 0
	global_load_lds_dwordx4 v[178:179], off
	s_add_i32 m0, s19, 0x2000
	v_lshl_add_u64 v[178:179], s[20:21], 0, v[138:139]
	global_load_lds_dwordx4 v[178:179], off
	s_barrier
	s_waitcnt lgkmcnt(0)
	s_setprio 1
	v_mfma_f32_16x16x32_bf16 v[116:119], v[202:205], v[152:155], v[116:119]
	v_mfma_f32_16x16x32_bf16 v[112:115], v[218:221], v[152:155], v[112:115]
	v_mfma_f32_16x16x32_bf16 v[100:103], v[202:205], v[160:163], v[100:103]
	v_mfma_f32_16x16x32_bf16 v[96:99], v[218:221], v[160:163], v[96:99]
	v_mfma_f32_16x16x32_bf16 v[84:87], v[202:205], v[168:171], v[84:87]
	v_mfma_f32_16x16x32_bf16 v[80:83], v[218:221], v[168:171], v[80:83]
	v_mfma_f32_16x16x32_bf16 v[68:71], v[202:205], v[194:197], v[68:71]
	v_mfma_f32_16x16x32_bf16 v[64:67], v[218:221], v[194:197], v[64:67]
	v_mfma_f32_16x16x32_bf16 v[116:119], v[206:209], v[156:159], v[116:119]
	v_mfma_f32_16x16x32_bf16 v[112:115], v[222:225], v[156:159], v[112:115]
	v_mfma_f32_16x16x32_bf16 v[100:103], v[206:209], v[164:167], v[100:103]
	v_mfma_f32_16x16x32_bf16 v[96:99], v[222:225], v[164:167], v[96:99]
	v_mfma_f32_16x16x32_bf16 v[84:87], v[206:209], v[172:175], v[84:87]
	v_mfma_f32_16x16x32_bf16 v[80:83], v[222:225], v[172:175], v[80:83]
	v_mfma_f32_16x16x32_bf16 v[68:71], v[206:209], v[198:201], v[68:71]
	v_mfma_f32_16x16x32_bf16 v[64:67], v[222:225], v[198:201], v[64:67]
	s_setprio 0
	s_mov_b64 s[20:21], s[86:87]
	s_barrier
; #define PG8_STAGE(bufoff, gbase, voff) do { _Pragma("unroll") for (int _i = 0; _i < 2; ++_i) { const char* _gb = (const char*)(gbase) + (size_t)_i * (voff##_q); asm volatile("" : "+s"(_gb)); \
;         __builtin_amdgcn_global_load_lds((const unsigned*)(_gb + (voff)), (LAS unsigned*)(lds + (bufoff) + ldsw + _i * 8192), 16, 0, 0); } } while (0)
; #define PG8_LDA(dst, b, h) do { _Pragma("unroll") for (int m = 0; m < 4; ++m) _Pragma("unroll") for (int k = 0; k < 2; ++k) dst[m][k] = *(const LAS bf16x8*)(lds + PG8_SA(b, h) + aoff + m * 2048 + k * 1024); } while (0)
; #define PG8_MMA(ai, bj, At, Bt) do { __builtin_amdgcn_s_setprio(1); _Pragma("unroll") for (int m = 0; m < 4; ++m) _Pragma("unroll") for (int n = 0; n < 2; ++n) _Pragma("unroll") for (int k = 0; k < 2; ++k) \
;         acc[ai][bj][m][n] = __builtin_amdgcn_mfma_f32_16x16x32_bf16(Bt[n][k], At[m][k], acc[ai][bj][m][n], 0, 0, 0); __builtin_amdgcn_s_setprio(0); } while (0)
; #define PG8_WAIT_V(n) asm volatile("s_waitcnt vmcnt(" #n ")" ::: "memory")
; #define PG8_WAIT_L(n) asm volatile("s_waitcnt lgkmcnt(" #n ")" ::: "memory")
; #define PG8_BAR __builtin_amdgcn_s_barrier()
; #define PG8_SCHED __builtin_amdgcn_sched_barrier(0)
; template <class Epi, class Sched>
; __device__ __forceinline__ void gemm_phase(int wv, LAS unsigned char* lds, const Gemm g, const Sched& S, const Epi& E) { LIDS
;     ...
;             PG8_LDA(At, 1, 1); PG8_STAGE(PG8_SA(1, 0), a3, voffA);
;             PG8_BAR; PG8_WAIT_L(0); PG8_MMA(1, 0, At, B0); PG8_BAR; PG8_SCHED;
;             PG8_STAGE(PG8_SB(1, 1), b3 + hstepB, voffB);
;             PG8_WAIT_V(6); PG8_BAR; PG8_MMA(1, 1, At, B1); PG8_BAR;
	ds_read_b128 v[152:155], v150 offset:49152
	ds_read_b128 v[156:159], v150 offset:50176
	ds_read_b128 v[160:163], v150 offset:51200
	ds_read_b128 v[164:167], v150 offset:52224
	ds_read_b128 v[168:171], v150 offset:53248
	ds_read_b128 v[172:175], v150 offset:54272
	ds_read_b128 v[194:197], v150 offset:55296
	ds_read_b128 v[198:201], v150 offset:56320
	s_mov_b32 m0, s55
	v_lshl_add_u64 v[178:179], s[20:21], 0, v[136:137]
	s_add_u32 s20, s86, 0x80000
	s_addc_u32 s21, s87, 0
	global_load_lds_dwordx4 v[178:179], off
	s_mov_b32 m0, s57
	v_lshl_add_u64 v[178:179], s[20:21], 0, v[136:137]
	global_load_lds_dwordx4 v[178:179], off
	s_barrier
	s_waitcnt lgkmcnt(0)
	s_setprio 1
	v_mfma_f32_16x16x32_bf16 v[60:63], v[128:131], v[152:155], v[60:63]
	v_mfma_f32_16x16x32_bf16 v[56:59], v[140:143], v[152:155], v[56:59]
	v_mfma_f32_16x16x32_bf16 v[44:47], v[128:131], v[160:163], v[44:47]
	v_mfma_f32_16x16x32_bf16 v[40:43], v[140:143], v[160:163], v[40:43]
	v_mfma_f32_16x16x32_bf16 v[28:31], v[128:131], v[168:171], v[28:31]
	v_mfma_f32_16x16x32_bf16 v[24:27], v[140:143], v[168:171], v[24:27]
	v_mfma_f32_16x16x32_bf16 v[12:15], v[128:131], v[194:197], v[12:15]
	v_mfma_f32_16x16x32_bf16 v[8:11], v[140:143], v[194:197], v[8:11]
	v_mfma_f32_16x16x32_bf16 v[60:63], v[132:135], v[156:159], v[60:63]
	v_mfma_f32_16x16x32_bf16 v[56:59], v[144:147], v[156:159], v[56:59]
	v_mfma_f32_16x16x32_bf16 v[44:47], v[132:135], v[164:167], v[44:47]
	v_mfma_f32_16x16x32_bf16 v[40:43], v[144:147], v[164:167], v[40:43]
	v_mfma_f32_16x16x32_bf16 v[28:31], v[132:135], v[172:175], v[28:31]
	v_mfma_f32_16x16x32_bf16 v[24:27], v[144:147], v[172:175], v[24:27]
	v_mfma_f32_16x16x32_bf16 v[12:15], v[132:135], v[198:201], v[12:15]
	v_mfma_f32_16x16x32_bf16 v[8:11], v[144:147], v[198:201], v[8:11]
	s_setprio 0
	s_barrier
	s_add_u32 s20, s78, 0x20000
	s_addc_u32 s21, s79, 0
	s_add_i32 s19, s22, s90
	v_lshl_add_u64 v[128:129], s[20:21], 0, v[138:139]
	s_add_u32 s20, s78, 0x30000
	s_mov_b32 m0, s19
	s_addc_u32 s21, s79, 0
	global_load_lds_dwordx4 v[128:129], off
	s_add_i32 m0, s19, 0x2000
	v_lshl_add_u64 v[128:129], s[20:21], 0, v[138:139]
	global_load_lds_dwordx4 v[128:129], off
	s_waitcnt vmcnt(6)
	s_barrier
	s_setprio 1
	v_mfma_f32_16x16x32_bf16 v[52:55], v[202:205], v[152:155], v[52:55]
	v_mfma_f32_16x16x32_bf16 v[48:51], v[218:221], v[152:155], v[48:51]
	v_mfma_f32_16x16x32_bf16 v[36:39], v[202:205], v[160:163], v[36:39]
	v_mfma_f32_16x16x32_bf16 v[32:35], v[218:221], v[160:163], v[32:35]
	v_mfma_f32_16x16x32_bf16 v[20:23], v[202:205], v[168:171], v[20:23]
	v_mfma_f32_16x16x32_bf16 v[16:19], v[218:221], v[168:171], v[16:19]
	v_mfma_f32_16x16x32_bf16 v[4:7], v[202:205], v[194:197], v[4:7]
	v_mfma_f32_16x16x32_bf16 v[0:3], v[218:221], v[194:197], v[0:3]
	v_mfma_f32_16x16x32_bf16 v[52:55], v[206:209], v[156:159], v[52:55]
	v_mfma_f32_16x16x32_bf16 v[48:51], v[222:225], v[156:159], v[48:51]
	v_mfma_f32_16x16x32_bf16 v[36:39], v[206:209], v[164:167], v[36:39]
	v_mfma_f32_16x16x32_bf16 v[32:35], v[222:225], v[164:167], v[32:35]
	v_mfma_f32_16x16x32_bf16 v[20:23], v[206:209], v[172:175], v[20:23]
	v_mfma_f32_16x16x32_bf16 v[16:19], v[222:225], v[172:175], v[16:19]
	v_mfma_f32_16x16x32_bf16 v[4:7], v[206:209], v[198:201], v[4:7]
	v_mfma_f32_16x16x32_bf16 v[0:3], v[222:225], v[198:201], v[0:3]
	s_setprio 0
	s_add_i32 s18, s18, 2
	s_add_u32 s16, s16, 0x100
	s_addc_u32 s17, s17, 0
	s_cmp_gt_u32 s18, 5
	s_barrier
	s_cbranch_scc0 .LBB0_123
;     __device__ __forceinline__ void operator()(const AccT& acc, const Unit& u, int wr, int wc, int fr, int fq) const {
;         EPI_ROWS(u)
; #pragma unroll
;         for (int ai = 0; ai < 2; ++ai)
; #pragma unroll
;             for (int m = 0; m < 4; ++m) {
;                 const int row = row0 + ai * HALF + m * 16;
;                 const f32x4 pa = *(const f32x4*)(ssp + (size_t)row * 16), pb = *(const f32x4*)(ssp + (size_t)row * 16 + 4);
;                 const float ssr = ((pa[0] + pa[1]) + (pa[2] + pa[3])) + ((pb[0] + pb[1]) + (pb[2] + pb[3]));
;                 const float sc = rsqrtf(ssr * (1.0f / 512.0f) + EPS) * (1.4426950408889634f * 0.07216878364870322f);
; #pragma unroll
;                 for (int bj = 0; bj < 2; ++bj) {
;                     const int col = colbase + bj * HALF; f32x4 v0 = acc[ai][bj][m][0], v1 = acc[ai][bj][m][1];
;                     const int d = col % 192;
;                     if (d >= 128) { const int i0 = (d - 128) >> 1;
;                         const f32x4 c4 = *(const f32x4*)(cosT + (size_t)row * 32 + i0), s4 = *(const f32x4*)(sinT + (size_t)row * 32 + i0);
	s_lshl_b32 s7, s8, 8
	s_add_i32 s7, s7, s52
	v_mbcnt_lo_u32_b32 v140, -1, 0
	v_mbcnt_hi_u32_b32 v140, -1, v140
	v_readlane_b32 s8, v253, 12
	v_and_or_b32 v142, v140, 15, s7
	v_ashrrev_i32_e32 v143, 31, v142
	v_lshlrev_b64 v[128:129], 6, v[142:143]
	v_readlane_b32 s9, v253, 13
	s_lshl_b32 s6, s6, 8
	v_ashrrev_i32_e32 v140, 1, v140
	v_lshl_add_u64 v[132:133], s[8:9], 0, v[128:129]
	global_load_dwordx4 v[128:131], v[132:133], off offset:16
	s_nop 0
	global_load_dwordx4 v[132:135], v[132:133], off
	s_or_b32 s6, s6, s53
	v_and_b32_e32 v140, -8, v140
	v_add_u32_e32 v140, s6, v140
	v_mul_hi_i32 v141, v140, s33
	v_lshlrev_b64 v[144:145], 5, v[142:143]
	v_lshrrev_b32_e32 v143, 31, v141
	v_lshrrev_b32_e32 v141, 5, v141
	v_add_u32_e32 v141, v141, v143
	s_movk_i32 s6, 0xc0
	v_mul_lo_u32 v141, v141, s6
	v_sub_u32_e32 v141, v140, v141
	s_movk_i32 s6, 0x7f
	v_cmp_lt_i32_e32 vcc, s6, v141
	v_readlane_b32 s6, v254, 48
	v_lshlrev_b64 v[144:145], 2, v[144:145]
	v_readlane_b32 s7, v254, 49
	v_add_u32_e32 v141, 0xffffff80, v141
	v_lshrrev_b32_e32 v176, 1, v141
	v_lshl_add_u64 v[146:147], s[6:7], 0, v[144:145]
	v_readlane_b32 s6, v253, 14
	v_readlane_b32 s7, v253, 15
	s_nop 1
	v_lshl_add_u64 v[144:145], s[6:7], 0, v[144:145]
	v_readlane_b32 s8, v253, 12
	v_readlane_b32 s9, v253, 13
	v_lshlrev_b64 v[188:189], 6, v[142:143]
	s_mov_b32 s6, 0x2000
	s_mov_b32 s7, 0
	v_lshl_add_u64 v[188:189], s[8:9], 0, v[188:189]
	v_lshl_add_u64 v[190:191], v[188:189], 0, s[6:7]
	global_load_dwordx4 v[194:197], v[188:189], off offset:1040
	global_load_dwordx4 v[198:201], v[188:189], off offset:1024
	global_load_dwordx4 v[202:205], v[188:189], off offset:2064
	global_load_dwordx4 v[206:209], v[188:189], off offset:2048
	global_load_dwordx4 v[218:221], v[188:189], off offset:3088
	global_load_dwordx4 v[222:225], v[188:189], off offset:3072
	global_load_dwordx4 v[226:229], v[190:191], off offset:16
	global_load_dwordx4 v[230:233], v[190:191], off
	global_load_dwordx4 v[234:237], v[190:191], off offset:1040
	global_load_dwordx4 v[238:241], v[190:191], off offset:1024
	global_load_dwordx4 v[242:245], v[190:191], off offset:2064
	global_load_dwordx4 v[246:249], v[190:191], off offset:2048
	global_load_dwordx4 v[168:171], v[190:191], off offset:3088
	global_load_dwordx4 v[172:175], v[190:191], off offset:3072
	s_waitcnt vmcnt(0)
	v_add_f32_e32 v198, v198, v199
	v_add_f32_e32 v200, v200, v201
	v_add_f32_e32 v194, v194, v195
	v_add_f32_e32 v196, v196, v197
	v_add_f32_e32 v206, v206, v207
	v_add_f32_e32 v208, v208, v209
	v_add_f32_e32 v202, v202, v203
	v_add_f32_e32 v204, v204, v205
	v_add_f32_e32 v222, v222, v223
	v_add_f32_e32 v224, v224, v225
	v_add_f32_e32 v218, v218, v219
	v_add_f32_e32 v220, v220, v221
	v_add_f32_e32 v230, v230, v231
	v_add_f32_e32 v232, v232, v233
	v_add_f32_e32 v226, v226, v227
	v_add_f32_e32 v228, v228, v229
	v_add_f32_e32 v238, v238, v239
	v_add_f32_e32 v240, v240, v241
	v_add_f32_e32 v234, v234, v235
	v_add_f32_e32 v236, v236, v237
	v_add_f32_e32 v246, v246, v247
	v_add_f32_e32 v248, v248, v249
	v_add_f32_e32 v242, v242, v243
	v_add_f32_e32 v244, v244, v245
	v_add_f32_e32 v172, v172, v173
	v_add_f32_e32 v174, v174, v175
	v_add_f32_e32 v168, v168, v169
	v_add_f32_e32 v170, v170, v171
	v_add_f32_e32 v198, v198, v200
	v_add_f32_e32 v194, v194, v196
	v_add_f32_e32 v206, v206, v208
	v_add_f32_e32 v202, v202, v204
	v_add_f32_e32 v222, v222, v224
	v_add_f32_e32 v218, v218, v220
	v_add_f32_e32 v230, v230, v232
	v_add_f32_e32 v226, v226, v228
	v_add_f32_e32 v238, v238, v240
	v_add_f32_e32 v234, v234, v236
	v_add_f32_e32 v246, v246, v248
	v_add_f32_e32 v242, v242, v244
	v_add_f32_e32 v172, v172, v174
	v_add_f32_e32 v168, v168, v170
	v_add_f32_e32 v180, v198, v194
	v_add_f32_e32 v181, v206, v202
	v_add_f32_e32 v182, v222, v218
	v_add_f32_e32 v183, v230, v226
	v_add_f32_e32 v184, v238, v234
	v_add_f32_e32 v185, v246, v242
	v_add_f32_e32 v186, v172, v168
	v_add_u32_e32 v187, 0x80, v140
	v_mul_hi_i32 v192, v187, s33
	v_lshrrev_b32_e32 v193, 31, v192
	v_lshrrev_b32_e32 v192, 5, v192
	v_add_u32_e32 v192, v192, v193
	s_movk_i32 s6, 0xc0
	v_mul_lo_u32 v192, v192, s6
	v_sub_u32_e32 v187, v187, v192
	s_movk_i32 s6, 0x7f
	v_cmp_lt_i32_e64 s[8:9], s6, v187
	v_add_u32_e32 v187, 0xffffff80, v187
	v_lshrrev_b32_e32 v187, 1, v187
	v_cndmask_b32_e32 v187, v187, v176, vcc
	s_nop 3
	s_or_b64 s[8:9], s[8:9], vcc
	s_and_saveexec_b64 s[6:7], s[8:9]
	s_cbranch_execz .Lq_norope
	v_lshlrev_b32_e32 v210, 2, v187
	v_mov_b32_e32 v211, 0
	s_mov_b32 s8, 0x1000
	s_mov_b32 s9, 0
	v_lshl_add_u64 v[190:191], v[146:147], 0, v[210:211]
	v_lshl_add_u64 v[192:193], v[144:145], 0, v[210:211]
	global_load_dwordx4 v[194:197], v[190:191], off offset:2048
	global_load_dwordx4 v[198:201], v[192:193], off offset:2048
	v_lshl_add_u64 v[190:191], v[190:191], 0, s[8:9]
	v_lshl_add_u64 v[192:193], v[192:193], 0, s[8:9]
	global_load_dwordx4 v[202:205], v[190:191], off
	global_load_dwordx4 v[206:209], v[192:193], off
	global_load_dwordx4 v[218:221], v[190:191], off offset:2048
	global_load_dwordx4 v[222:225], v[192:193], off offset:2048
	s_mov_b32 s8, 0x3000
	v_lshl_add_u64 v[190:191], v[190:191], 0, s[8:9]
	v_lshl_add_u64 v[192:193], v[192:193], 0, s[8:9]
	s_mov_b32 s8, 0x1000
	global_load_dwordx4 v[226:229], v[190:191], off
	global_load_dwordx4 v[230:233], v[192:193], off
	global_load_dwordx4 v[234:237], v[190:191], off offset:2048
	global_load_dwordx4 v[238:241], v[192:193], off offset:2048
	v_lshl_add_u64 v[190:191], v[190:191], 0, s[8:9]
	v_lshl_add_u64 v[192:193], v[192:193], 0, s[8:9]
	global_load_dwordx4 v[242:245], v[190:191], off
	global_load_dwordx4 v[246:249], v[192:193], off
	global_load_dwordx4 v[168:171], v[190:191], off offset:2048
	global_load_dwordx4 v[172:175], v[192:193], off offset:2048
	s_waitcnt vmcnt(0)

; #define PG8_STAGE(bufoff, gbase, voff) do { _Pragma("unroll") for (int _i = 0; _i < 2; ++_i) { const char* _gb = (const char*)(gbase) + (size_t)_i * (voff##_q); asm volatile("" : "+s"(_gb)); \
;         __builtin_amdgcn_global_load_lds((const unsigned*)(_gb + (voff)), (LAS unsigned*)(lds + (bufoff) + ldsw + _i * 8192), 16, 0, 0); } } while (0)
; #define PG8_LDA(dst, b, h) do { _Pragma("unroll") for (int m = 0; m < 4; ++m) _Pragma("unroll") for (int k = 0; k < 2; ++k) dst[m][k] = *(const LAS bf16x8*)(lds + PG8_SA(b, h) + aoff + m * 2048 + k * 1024); } while (0)
; #define PG8_LDB(dst, b, h) do { _Pragma("unroll") for (int n = 0; n < 2; ++n) _Pragma("unroll") for (int k = 0; k < 2; ++k) dst[n][k] = *(const LAS bf16x8*)(lds + PG8_SB(b, h) + boff + n * 2048 + k * 1024); } while (0)
; #define PG8_WAIT_V(n) asm volatile("s_waitcnt vmcnt(" #n ")" ::: "memory")
; #define PG8_WAIT_L(n) asm volatile("s_waitcnt lgkmcnt(" #n ")" ::: "memory")
; template <class Epi, class Sched>
; __device__ __forceinline__ void gemm_phase(int wv, LAS unsigned char* lds, const Gemm g, const Sched& S, const Epi& E) { LIDS
;     ...
;         const bool has_next = S.next(ui + 1, nxt);
;         const char* nA = has_next ? (const char*)g.A + (size_t)nxt.pm * g.tstepA : cA; const char* nB = has_next ? (const char*)g.Bt + (size_t)nxt.pn * g.tstepB : cB;
;         for (int t = 0; t < nt; t += 2) {
;             const bool last = (t == nt - 2);
;             const char* a1 = cA + (size_t)(t + 1) * kstepA;
;             const char* a2 = last ? nA : cA + (size_t)(t + 2) * kstepA; const char* b2 = last ? nB : cB + (size_t)(t + 2) * kstepB;
;             const char* a3 = a2 + kstepA; const char* b3 = b2 + kstepB;
;             asm volatile("" : "+s"(a1), "+s"(a2), "+s"(b2), "+s"(a3), "+s"(b3));
;             PG8_LDB(B0, 0, 0); PG8_SCHED; PG8_LDA(At, 0, 0); PG8_STAGE(PG8_SA(1, 1), a1 + hstepA, voffA);
;             PG8_WAIT_L(8); PG8_BAR; PG8_WAIT_L(0); PG8_MMA(0, 0, At, B0); PG8_BAR; PG8_SCHED;
;             PG8_LDB(B1, 0, 1); PG8_STAGE(PG8_SB(0, 0), b2, voffB);
;             PG8_BAR; PG8_WAIT_L(0); PG8_MMA(0, 1, At, B1); PG8_BAR;
;             PG8_LDA(At, 0, 1); PG8_STAGE(PG8_SA(0, 0), a2, voffA);
;             PG8_BAR; PG8_WAIT_L(0); PG8_MMA(1, 0, At, B0); PG8_BAR; PG8_SCHED;
;             PG8_STAGE(PG8_SB(0, 1), b2 + hstepB, voffB);
;             PG8_WAIT_V(6); PG8_BAR; PG8_MMA(1, 1, At, B1); PG8_BAR;
.LBB0_168:
	s_ashr_i32 s11, s10, 31
	s_lshl_b64 s[12:13], s[10:11], 21
	v_readlane_b32 s9, v253, 16
	v_mov_b64_e32 v[4:5], 0x100
	s_add_u32 s12, s9, s12
	v_readlane_b32 s9, v253, 17
	v_cmp_lt_i64_e32 vcc, s[6:7], v[4:5]
	s_addc_u32 s13, s9, s13
	s_and_b64 s[18:19], vcc, exec
	s_cselect_b32 s73, s13, s87
	s_cselect_b32 s72, s12, s86
	s_ashr_i32 s9, s8, 31
	s_lshl_b64 s[18:19], s[8:9], 17
	v_readlane_b32 s20, v253, 18
	v_readlane_b32 s21, v253, 19
	s_add_u32 s62, s20, s18
	s_addc_u32 s63, s21, s19
	s_and_b64 s[18:19], vcc, exec
	s_cselect_b32 s79, s63, s91
	s_cselect_b32 s78, s62, s90
	s_add_u32 s18, s86, 0x80
	s_addc_u32 s19, s87, 0
	s_add_u32 s88, s86, 0x100
	s_addc_u32 s89, s87, 0
	s_add_u32 s94, s90, 0x100
	s_addc_u32 s95, s91, 0
	s_add_u32 s86, s86, 0x180
	s_addc_u32 s87, s87, 0
	s_add_u32 s90, s90, 0x180
	s_addc_u32 s91, s91, 0
	s_add_i32 s11, 16, 0x10000
	s_mov_b64 s[84:85], s[86:87]
	v_add_u32_e32 v176, s11, v134
	ds_read_b128 v[4:7], v176
	ds_read_b128 v[8:11], v176 offset:1024
	ds_read_b128 v[12:15], v176 offset:2048
	ds_read_b128 v[16:19], v176 offset:3072
	s_add_u32 s20, s18, 0x100000
	s_addc_u32 s21, s19, 0
	s_add_i32 s22, s58, 0xc000
	s_add_u32 s18, s18, 0x180000
	ds_read_b128 v[20:23], v135
	ds_read_b128 v[24:27], v135 offset:1024
	ds_read_b128 v[28:31], v135 offset:2048
	ds_read_b128 v[32:35], v135 offset:3072
	ds_read_b128 v[36:39], v135 offset:4096
	ds_read_b128 v[40:43], v135 offset:5120
	ds_read_b128 v[44:47], v135 offset:6144
	ds_read_b128 v[48:51], v135 offset:7168
	s_mov_b32 m0, s22
	v_lshl_add_u64 v[52:53], s[20:21], 0, v[124:125]
	s_addc_u32 s19, s19, 0
	s_add_i32 s9, s58, 0xe000
	global_load_lds_dwordx4 v[52:53], off
	s_mov_b32 m0, s9
	v_lshl_add_u64 v[52:53], s[18:19], 0, v[124:125]
	global_load_lds_dwordx4 v[52:53], off
	s_waitcnt lgkmcnt(8)
	s_barrier
	s_waitcnt lgkmcnt(0)
	s_setprio 1
	v_mfma_f32_16x16x32_bf16 v[52:55], v[4:7], v[20:23], v[0:3]
	v_mfma_f32_16x16x32_bf16 v[56:59], v[12:15], v[20:23], v[0:3]
	v_mfma_f32_16x16x32_bf16 v[60:63], v[4:7], v[28:31], v[0:3]
	v_mfma_f32_16x16x32_bf16 v[64:67], v[12:15], v[28:31], v[0:3]
	v_mfma_f32_16x16x32_bf16 v[68:71], v[4:7], v[36:39], v[0:3]
	v_mfma_f32_16x16x32_bf16 v[72:75], v[12:15], v[36:39], v[0:3]
	v_mfma_f32_16x16x32_bf16 v[76:79], v[4:7], v[44:47], v[0:3]
	v_mfma_f32_16x16x32_bf16 v[80:83], v[12:15], v[44:47], v[0:3]
	v_mfma_f32_16x16x32_bf16 v[52:55], v[8:11], v[24:27], v[52:55]
	v_mfma_f32_16x16x32_bf16 v[56:59], v[16:19], v[24:27], v[56:59]
	v_mfma_f32_16x16x32_bf16 v[60:63], v[8:11], v[32:35], v[60:63]
	v_mfma_f32_16x16x32_bf16 v[64:67], v[16:19], v[32:35], v[64:67]
	v_mfma_f32_16x16x32_bf16 v[68:71], v[8:11], v[40:43], v[68:71]
	v_mfma_f32_16x16x32_bf16 v[72:75], v[16:19], v[40:43], v[72:75]
	v_mfma_f32_16x16x32_bf16 v[76:79], v[8:11], v[48:51], v[76:79]
	v_mfma_f32_16x16x32_bf16 v[80:83], v[16:19], v[48:51], v[80:83]
	s_setprio 0
	s_barrier
	s_add_i32 s21, 16, 0x14000
	v_add_u32_e32 v178, s21, v134
	s_mov_b64 s[18:19], s[94:95]
	ds_read_b128 v[84:87], v178
	ds_read_b128 v[88:91], v178 offset:1024
	ds_read_b128 v[92:95], v178 offset:2048
	ds_read_b128 v[96:99], v178 offset:3072
	s_add_i32 s20, s11, s57
	v_lshl_add_u64 v[100:101], s[18:19], 0, v[126:127]
	s_add_u32 s18, s94, 0x8000
	s_mov_b32 m0, s20
	s_addc_u32 s19, s95, 0
	s_add_i32 s11, s20, 0x2000
	global_load_lds_dwordx4 v[100:101], off
	s_mov_b32 m0, s11
	v_lshl_add_u64 v[100:101], s[18:19], 0, v[126:127]
	global_load_lds_dwordx4 v[100:101], off
	s_barrier
	s_waitcnt lgkmcnt(0)
	s_setprio 1
	v_mfma_f32_16x16x32_bf16 v[100:103], v[84:87], v[20:23], v[0:3]
	v_mfma_f32_16x16x32_bf16 v[20:23], v[92:95], v[20:23], v[0:3]
	v_mfma_f32_16x16x32_bf16 v[100:103], v[88:91], v[24:27], v[100:103]
	v_mfma_f32_16x16x32_bf16 v[20:23], v[96:99], v[24:27], v[20:23]
	v_mfma_f32_16x16x32_bf16 v[24:27], v[84:87], v[28:31], v[0:3]
	v_mfma_f32_16x16x32_bf16 v[28:31], v[92:95], v[28:31], v[0:3]
	v_mfma_f32_16x16x32_bf16 v[24:27], v[88:91], v[32:35], v[24:27]
	v_mfma_f32_16x16x32_bf16 v[28:31], v[96:99], v[32:35], v[28:31]
	v_mfma_f32_16x16x32_bf16 v[32:35], v[84:87], v[36:39], v[0:3]
	v_mfma_f32_16x16x32_bf16 v[36:39], v[92:95], v[36:39], v[0:3]
	v_mfma_f32_16x16x32_bf16 v[32:35], v[88:91], v[40:43], v[32:35]
	v_mfma_f32_16x16x32_bf16 v[36:39], v[96:99], v[40:43], v[36:39]
	v_mfma_f32_16x16x32_bf16 v[40:43], v[84:87], v[44:47], v[0:3]
	v_mfma_f32_16x16x32_bf16 v[44:47], v[92:95], v[44:47], v[0:3]
	v_mfma_f32_16x16x32_bf16 v[40:43], v[88:91], v[48:51], v[40:43]
	v_mfma_f32_16x16x32_bf16 v[44:47], v[96:99], v[48:51], v[44:47]
	s_setprio 0
	s_mov_b64 s[18:19], s[88:89]
	s_barrier
	ds_read_b128 v[48:51], v135 offset:16384
	ds_read_b128 v[104:107], v135 offset:17408
	ds_read_b128 v[108:111], v135 offset:18432
	ds_read_b128 v[112:115], v135 offset:19456
	ds_read_b128 v[116:119], v135 offset:20480
	ds_read_b128 v[120:123], v135 offset:21504
	ds_read_b128 v[128:131], v135 offset:22528
	ds_read_b128 v[136:139], v135 offset:23552
	s_mov_b32 m0, s58
	v_lshl_add_u64 v[132:133], s[18:19], 0, v[124:125]
	s_add_u32 s18, s88, 0x80000
	s_addc_u32 s19, s89, 0
	global_load_lds_dwordx4 v[132:133], off
	s_mov_b32 m0, s77
	v_lshl_add_u64 v[132:133], s[18:19], 0, v[124:125]
	global_load_lds_dwordx4 v[132:133], off
	s_barrier
; #define PG8_STAGE(bufoff, gbase, voff) do { _Pragma("unroll") for (int _i = 0; _i < 2; ++_i) { const char* _gb = (const char*)(gbase) + (size_t)_i * (voff##_q); asm volatile("" : "+s"(_gb)); \
;         __builtin_amdgcn_global_load_lds((const unsigned*)(_gb + (voff)), (LAS unsigned*)(lds + (bufoff) + ldsw + _i * 8192), 16, 0, 0); } } while (0)
; #define PG8_LDA(dst, b, h) do { _Pragma("unroll") for (int m = 0; m < 4; ++m) _Pragma("unroll") for (int k = 0; k < 2; ++k) dst[m][k] = *(const LAS bf16x8*)(lds + PG8_SA(b, h) + aoff + m * 2048 + k * 1024); } while (0)
; #define PG8_LDB(dst, b, h) do { _Pragma("unroll") for (int n = 0; n < 2; ++n) _Pragma("unroll") for (int k = 0; k < 2; ++k) dst[n][k] = *(const LAS bf16x8*)(lds + PG8_SB(b, h) + boff + n * 2048 + k * 1024); } while (0)
; #define PG8_MMA(ai, bj, At, Bt) do { __builtin_amdgcn_s_setprio(1); _Pragma("unroll") for (int m = 0; m < 4; ++m) _Pragma("unroll") for (int n = 0; n < 2; ++n) _Pragma("unroll") for (int k = 0; k < 2; ++k) \
;         acc[ai][bj][m][n] = __builtin_amdgcn_mfma_f32_16x16x32_bf16(Bt[n][k], At[m][k], acc[ai][bj][m][n], 0, 0, 0); __builtin_amdgcn_s_setprio(0); } while (0)
; #define PG8_WAIT_V(n) asm volatile("s_waitcnt vmcnt(" #n ")" ::: "memory")
; #define PG8_WAIT_L(n) asm volatile("s_waitcnt lgkmcnt(" #n ")" ::: "memory")
; template <class Epi, class Sched>
; __device__ __forceinline__ void gemm_phase(int wv, LAS unsigned char* lds, const Gemm g, const Sched& S, const Epi& E) { LIDS
;     ...
;             PG8_LDB(B1, 0, 1); PG8_STAGE(PG8_SB(0, 0), b2, voffB);
;             PG8_BAR; PG8_WAIT_L(0); PG8_MMA(0, 1, At, B1); PG8_BAR;
;             PG8_LDA(At, 0, 1); PG8_STAGE(PG8_SA(0, 0), a2, voffA);
;             PG8_BAR; PG8_WAIT_L(0); PG8_MMA(1, 0, At, B0); PG8_BAR; PG8_SCHED;
;             PG8_STAGE(PG8_SB(0, 1), b2 + hstepB, voffB);
;             PG8_WAIT_V(6); PG8_BAR; PG8_MMA(1, 1, At, B1); PG8_BAR;
;             PG8_LDB(B0, 1, 0); PG8_SCHED; PG8_LDA(At, 1, 0); PG8_STAGE(PG8_SA(0, 1), a2 + hstepA, voffA);
;             PG8_WAIT_L(8); PG8_BAR; PG8_WAIT_L(0); PG8_MMA(0, 0, At, B0); PG8_BAR; PG8_SCHED;
;             PG8_LDB(B1, 1, 1); PG8_STAGE(PG8_SB(1, 0), b3, voffB);
;             PG8_BAR; PG8_WAIT_L(0); PG8_MMA(0, 1, At, B1); PG8_BAR;
;             PG8_LDA(At, 1, 1); PG8_STAGE(PG8_SA(1, 0), a3, voffA);
;             PG8_BAR; PG8_WAIT_L(0); PG8_MMA(1, 0, At, B0); PG8_BAR; PG8_SCHED;
	s_waitcnt lgkmcnt(0)
	s_setprio 1
	v_mfma_f32_16x16x32_bf16 v[140:143], v[4:7], v[48:51], v[0:3]
	v_mfma_f32_16x16x32_bf16 v[148:151], v[4:7], v[108:111], v[0:3]
	v_mfma_f32_16x16x32_bf16 v[156:159], v[4:7], v[116:119], v[0:3]
	v_mfma_f32_16x16x32_bf16 v[4:7], v[4:7], v[128:131], v[0:3]
	v_mfma_f32_16x16x32_bf16 v[140:143], v[8:11], v[104:107], v[140:143]
	v_mfma_f32_16x16x32_bf16 v[144:147], v[12:15], v[48:51], v[0:3]
	v_mfma_f32_16x16x32_bf16 v[148:151], v[8:11], v[112:115], v[148:151]
	v_mfma_f32_16x16x32_bf16 v[152:155], v[12:15], v[108:111], v[0:3]
	v_mfma_f32_16x16x32_bf16 v[156:159], v[8:11], v[120:123], v[156:159]
	v_mfma_f32_16x16x32_bf16 v[160:163], v[12:15], v[116:119], v[0:3]
	v_mfma_f32_16x16x32_bf16 v[4:7], v[8:11], v[136:139], v[4:7]
	v_mfma_f32_16x16x32_bf16 v[8:11], v[12:15], v[128:131], v[0:3]
	v_mfma_f32_16x16x32_bf16 v[144:147], v[16:19], v[104:107], v[144:147]
	v_mfma_f32_16x16x32_bf16 v[152:155], v[16:19], v[112:115], v[152:155]
	v_mfma_f32_16x16x32_bf16 v[160:163], v[16:19], v[120:123], v[160:163]
	v_mfma_f32_16x16x32_bf16 v[8:11], v[16:19], v[136:139], v[8:11]
	s_setprio 0
	s_barrier
	s_add_u32 s18, s94, 0x10000
	s_addc_u32 s19, s95, 0
	s_add_i32 s21, s21, s57
	v_lshl_add_u64 v[12:13], s[18:19], 0, v[126:127]
	s_add_u32 s18, s94, 0x18000
	s_mov_b32 m0, s21
	s_addc_u32 s19, s95, 0
	s_add_i32 s17, s21, 0x2000
	global_load_lds_dwordx4 v[12:13], off
	s_mov_b32 m0, s17
	v_lshl_add_u64 v[12:13], s[18:19], 0, v[126:127]
	global_load_lds_dwordx4 v[12:13], off
	s_waitcnt vmcnt(6)
	s_barrier
	s_setprio 1
	v_mfma_f32_16x16x32_bf16 v[12:15], v[84:87], v[48:51], v[0:3]
	v_mfma_f32_16x16x32_bf16 v[16:19], v[92:95], v[48:51], v[0:3]
	v_mfma_f32_16x16x32_bf16 v[12:15], v[88:91], v[104:107], v[12:15]
	v_mfma_f32_16x16x32_bf16 v[16:19], v[96:99], v[104:107], v[16:19]
	v_mfma_f32_16x16x32_bf16 v[48:51], v[84:87], v[108:111], v[0:3]
	v_mfma_f32_16x16x32_bf16 v[104:107], v[92:95], v[108:111], v[0:3]
	v_mfma_f32_16x16x32_bf16 v[108:111], v[84:87], v[116:119], v[0:3]
	v_mfma_f32_16x16x32_bf16 v[84:87], v[84:87], v[128:131], v[0:3]
	v_mfma_f32_16x16x32_bf16 v[48:51], v[88:91], v[112:115], v[48:51]
	v_mfma_f32_16x16x32_bf16 v[104:107], v[96:99], v[112:115], v[104:107]
	v_mfma_f32_16x16x32_bf16 v[108:111], v[88:91], v[120:123], v[108:111]
	v_mfma_f32_16x16x32_bf16 v[112:115], v[92:95], v[116:119], v[0:3]
	v_mfma_f32_16x16x32_bf16 v[84:87], v[88:91], v[136:139], v[84:87]
	v_mfma_f32_16x16x32_bf16 v[88:91], v[92:95], v[128:131], v[0:3]
	v_mfma_f32_16x16x32_bf16 v[112:115], v[96:99], v[120:123], v[112:115]
	v_mfma_f32_16x16x32_bf16 v[88:91], v[96:99], v[136:139], v[88:91]
	s_setprio 0
	s_add_i32 s23, 16, 0x18000
	v_add_u32_e32 v179, s23, v134
	s_barrier
	ds_read_b128 v[92:95], v179
	ds_read_b128 v[96:99], v179 offset:1024
	ds_read_b128 v[116:119], v179 offset:2048
	ds_read_b128 v[120:123], v179 offset:3072
	s_add_u32 s18, s88, 0x100000
	s_addc_u32 s19, s89, 0
	ds_read_b128 v[128:131], v135 offset:32768
	ds_read_b128 v[136:139], v135 offset:33792
	ds_read_b128 v[164:167], v135 offset:34816
	ds_read_b128 v[168:171], v135 offset:35840
	ds_read_b128 v[172:175], v135 offset:36864
	ds_read_b128 v[194:197], v135 offset:37888
	ds_read_b128 v[198:201], v135 offset:38912
	ds_read_b128 v[202:205], v135 offset:39936
	s_mov_b32 m0, s82
	v_lshl_add_u64 v[132:133], s[18:19], 0, v[124:125]
	s_add_u32 s18, s88, 0x180000
	s_addc_u32 s19, s89, 0
	global_load_lds_dwordx4 v[132:133], off
	s_mov_b32 m0, s56
	v_lshl_add_u64 v[132:133], s[18:19], 0, v[124:125]
	global_load_lds_dwordx4 v[132:133], off
	s_waitcnt lgkmcnt(8)
	s_barrier
	s_waitcnt lgkmcnt(0)
	s_setprio 1
	v_mfma_f32_16x16x32_bf16 v[52:55], v[92:95], v[128:131], v[52:55]
	v_mfma_f32_16x16x32_bf16 v[56:59], v[116:119], v[128:131], v[56:59]
	v_mfma_f32_16x16x32_bf16 v[60:63], v[92:95], v[164:167], v[60:63]
	v_mfma_f32_16x16x32_bf16 v[64:67], v[116:119], v[164:167], v[64:67]
	v_mfma_f32_16x16x32_bf16 v[68:71], v[92:95], v[172:175], v[68:71]
	v_mfma_f32_16x16x32_bf16 v[72:75], v[116:119], v[172:175], v[72:75]
	v_mfma_f32_16x16x32_bf16 v[76:79], v[92:95], v[198:201], v[76:79]
	v_mfma_f32_16x16x32_bf16 v[80:83], v[116:119], v[198:201], v[80:83]
	v_mfma_f32_16x16x32_bf16 v[52:55], v[96:99], v[136:139], v[52:55]
	v_mfma_f32_16x16x32_bf16 v[56:59], v[120:123], v[136:139], v[56:59]
	v_mfma_f32_16x16x32_bf16 v[60:63], v[96:99], v[168:171], v[60:63]
	v_mfma_f32_16x16x32_bf16 v[64:67], v[120:123], v[168:171], v[64:67]
	v_mfma_f32_16x16x32_bf16 v[68:71], v[96:99], v[194:197], v[68:71]
	v_mfma_f32_16x16x32_bf16 v[72:75], v[120:123], v[194:197], v[72:75]
	v_mfma_f32_16x16x32_bf16 v[76:79], v[96:99], v[202:205], v[76:79]
	v_mfma_f32_16x16x32_bf16 v[80:83], v[120:123], v[202:205], v[80:83]
	s_setprio 0
	s_barrier
	s_add_i32 s26, 16, 0x1c000
	v_add_u32_e32 v190, s26, v134
	s_mov_b64 s[18:19], s[90:91]
	ds_read_b128 v[206:209], v190
	ds_read_b128 v[218:221], v190 offset:1024
	ds_read_b128 v[222:225], v190 offset:2048
	ds_read_b128 v[226:229], v190 offset:3072
	s_add_i32 s23, s23, s57
	v_lshl_add_u64 v[132:133], s[18:19], 0, v[126:127]
	s_add_u32 s18, s90, 0x8000
	s_mov_b32 m0, s23
	s_addc_u32 s19, s91, 0
	global_load_lds_dwordx4 v[132:133], off
	s_nop 0
	v_lshl_add_u64 v[132:133], s[18:19], 0, v[126:127]
	s_add_i32 s18, s23, 0x2000
	s_mov_b32 m0, s18
	s_nop 0
	global_load_lds_dwordx4 v[132:133], off
	s_barrier
; #define PG8_STAGE(bufoff, gbase, voff) do { _Pragma("unroll") for (int _i = 0; _i < 2; ++_i) { const char* _gb = (const char*)(gbase) + (size_t)_i * (voff##_q); asm volatile("" : "+s"(_gb)); \
;         __builtin_amdgcn_global_load_lds((const unsigned*)(_gb + (voff)), (LAS unsigned*)(lds + (bufoff) + ldsw + _i * 8192), 16, 0, 0); } } while (0)
; #define PG8_LDA(dst, b, h) do { _Pragma("unroll") for (int m = 0; m < 4; ++m) _Pragma("unroll") for (int k = 0; k < 2; ++k) dst[m][k] = *(const LAS bf16x8*)(lds + PG8_SA(b, h) + aoff + m * 2048 + k * 1024); } while (0)
; #define PG8_LDB(dst, b, h) do { _Pragma("unroll") for (int n = 0; n < 2; ++n) _Pragma("unroll") for (int k = 0; k < 2; ++k) dst[n][k] = *(const LAS bf16x8*)(lds + PG8_SB(b, h) + boff + n * 2048 + k * 1024); } while (0)
; #define PG8_MMA(ai, bj, At, Bt) do { __builtin_amdgcn_s_setprio(1); _Pragma("unroll") for (int m = 0; m < 4; ++m) _Pragma("unroll") for (int n = 0; n < 2; ++n) _Pragma("unroll") for (int k = 0; k < 2; ++k) \
;         acc[ai][bj][m][n] = __builtin_amdgcn_mfma_f32_16x16x32_bf16(Bt[n][k], At[m][k], acc[ai][bj][m][n], 0, 0, 0); __builtin_amdgcn_s_setprio(0); } while (0)
; #define PG8_WAIT_V(n) asm volatile("s_waitcnt vmcnt(" #n ")" ::: "memory")
; #define PG8_WAIT_L(n) asm volatile("s_waitcnt lgkmcnt(" #n ")" ::: "memory")
; #define PG8_BAR __builtin_amdgcn_s_barrier()
; #define PG8_SCHED __builtin_amdgcn_sched_barrier(0)
; template <class Epi, class Sched>
; __device__ __forceinline__ void gemm_phase(int wv, LAS unsigned char* lds, const Gemm g, const Sched& S, const Epi& E) { LIDS
;     ...
;             PG8_BAR; PG8_WAIT_L(0); PG8_MMA(0, 1, At, B1); PG8_BAR;
;             PG8_LDA(At, 0, 1); PG8_STAGE(PG8_SA(0, 0), a2, voffA);
;             PG8_BAR; PG8_WAIT_L(0); PG8_MMA(1, 0, At, B0); PG8_BAR; PG8_SCHED;
;             PG8_STAGE(PG8_SB(0, 1), b2 + hstepB, voffB);
;             PG8_WAIT_V(6); PG8_BAR; PG8_MMA(1, 1, At, B1); PG8_BAR;
;             PG8_LDB(B0, 1, 0); PG8_SCHED; PG8_LDA(At, 1, 0); PG8_STAGE(PG8_SA(0, 1), a2 + hstepA, voffA);
;             PG8_WAIT_L(8); PG8_BAR; PG8_WAIT_L(0); PG8_MMA(0, 0, At, B0); PG8_BAR; PG8_SCHED;
	s_waitcnt lgkmcnt(0)
	s_setprio 1
	v_mfma_f32_16x16x32_bf16 v[100:103], v[206:209], v[128:131], v[100:103]
	v_mfma_f32_16x16x32_bf16 v[20:23], v[222:225], v[128:131], v[20:23]
	v_mfma_f32_16x16x32_bf16 v[24:27], v[206:209], v[164:167], v[24:27]
	v_mfma_f32_16x16x32_bf16 v[28:31], v[222:225], v[164:167], v[28:31]
	v_mfma_f32_16x16x32_bf16 v[32:35], v[206:209], v[172:175], v[32:35]
	v_mfma_f32_16x16x32_bf16 v[36:39], v[222:225], v[172:175], v[36:39]
	v_mfma_f32_16x16x32_bf16 v[40:43], v[206:209], v[198:201], v[40:43]
	v_mfma_f32_16x16x32_bf16 v[44:47], v[222:225], v[198:201], v[44:47]
	v_mfma_f32_16x16x32_bf16 v[100:103], v[218:221], v[136:139], v[100:103]
	v_mfma_f32_16x16x32_bf16 v[20:23], v[226:229], v[136:139], v[20:23]
	v_mfma_f32_16x16x32_bf16 v[24:27], v[218:221], v[168:171], v[24:27]
	v_mfma_f32_16x16x32_bf16 v[28:31], v[226:229], v[168:171], v[28:31]
	v_mfma_f32_16x16x32_bf16 v[32:35], v[218:221], v[194:197], v[32:35]
	v_mfma_f32_16x16x32_bf16 v[36:39], v[226:229], v[194:197], v[36:39]
	v_mfma_f32_16x16x32_bf16 v[40:43], v[218:221], v[202:205], v[40:43]
	v_mfma_f32_16x16x32_bf16 v[44:47], v[226:229], v[202:205], v[44:47]
	s_setprio 0
	s_mov_b64 s[24:25], s[84:85]
	s_barrier
	ds_read_b128 v[128:131], v135 offset:49152
	ds_read_b128 v[136:139], v135 offset:50176
	ds_read_b128 v[164:167], v135 offset:51200
	ds_read_b128 v[168:171], v135 offset:52224
	ds_read_b128 v[172:175], v135 offset:53248
	ds_read_b128 v[194:197], v135 offset:54272
	ds_read_b128 v[198:201], v135 offset:55296
	ds_read_b128 v[202:205], v135 offset:56320
	s_mov_b32 m0, s0
	v_lshl_add_u64 v[132:133], s[24:25], 0, v[124:125]
	s_add_u32 s24, s84, 0x80000
	s_addc_u32 s25, s85, 0
	global_load_lds_dwordx4 v[132:133], off
	s_mov_b32 m0, s59
	v_lshl_add_u64 v[132:133], s[24:25], 0, v[124:125]
	global_load_lds_dwordx4 v[132:133], off
	s_barrier
	s_waitcnt lgkmcnt(0)
	s_setprio 1
	v_mfma_f32_16x16x32_bf16 v[140:143], v[92:95], v[128:131], v[140:143]
	v_mfma_f32_16x16x32_bf16 v[144:147], v[116:119], v[128:131], v[144:147]
	v_mfma_f32_16x16x32_bf16 v[148:151], v[92:95], v[164:167], v[148:151]
	v_mfma_f32_16x16x32_bf16 v[152:155], v[116:119], v[164:167], v[152:155]
	v_mfma_f32_16x16x32_bf16 v[156:159], v[92:95], v[172:175], v[156:159]
	v_mfma_f32_16x16x32_bf16 v[160:163], v[116:119], v[172:175], v[160:163]
	v_mfma_f32_16x16x32_bf16 v[4:7], v[92:95], v[198:201], v[4:7]
	v_mfma_f32_16x16x32_bf16 v[8:11], v[116:119], v[198:201], v[8:11]
	v_mfma_f32_16x16x32_bf16 v[140:143], v[96:99], v[136:139], v[140:143]
	v_mfma_f32_16x16x32_bf16 v[144:147], v[120:123], v[136:139], v[144:147]
	v_mfma_f32_16x16x32_bf16 v[148:151], v[96:99], v[168:171], v[148:151]
	v_mfma_f32_16x16x32_bf16 v[152:155], v[120:123], v[168:171], v[152:155]
	v_mfma_f32_16x16x32_bf16 v[156:159], v[96:99], v[194:197], v[156:159]
	v_mfma_f32_16x16x32_bf16 v[160:163], v[120:123], v[194:197], v[160:163]
	v_mfma_f32_16x16x32_bf16 v[4:7], v[96:99], v[202:205], v[4:7]
	v_mfma_f32_16x16x32_bf16 v[8:11], v[120:123], v[202:205], v[8:11]
	s_setprio 0
	s_barrier
	s_add_u32 s24, s90, 0x10000
	s_addc_u32 s25, s91, 0
	s_nop 0
	v_lshl_add_u64 v[92:93], s[24:25], 0, v[126:127]
	s_add_i32 s24, s26, s57
	s_add_u32 s26, s90, 0x18000
	s_mov_b32 m0, s24
	s_addc_u32 s27, s91, 0
	s_add_i32 s19, s24, 0x2000
	global_load_lds_dwordx4 v[92:93], off
	s_mov_b32 m0, s19
	v_lshl_add_u64 v[92:93], s[26:27], 0, v[126:127]
	global_load_lds_dwordx4 v[92:93], off
	s_waitcnt vmcnt(6)
	s_barrier
	s_setprio 1
	v_mfma_f32_16x16x32_bf16 v[12:15], v[206:209], v[128:131], v[12:15]
	v_mfma_f32_16x16x32_bf16 v[16:19], v[222:225], v[128:131], v[16:19]
	v_mfma_f32_16x16x32_bf16 v[48:51], v[206:209], v[164:167], v[48:51]
	v_mfma_f32_16x16x32_bf16 v[92:95], v[222:225], v[164:167], v[104:107]
	v_mfma_f32_16x16x32_bf16 v[96:99], v[206:209], v[172:175], v[108:111]
	v_mfma_f32_16x16x32_bf16 v[104:107], v[222:225], v[172:175], v[112:115]
	v_mfma_f32_16x16x32_bf16 v[84:87], v[206:209], v[198:201], v[84:87]
	v_mfma_f32_16x16x32_bf16 v[88:91], v[222:225], v[198:201], v[88:91]
	v_mfma_f32_16x16x32_bf16 v[12:15], v[218:221], v[136:139], v[12:15]
	v_mfma_f32_16x16x32_bf16 v[16:19], v[226:229], v[136:139], v[16:19]
	v_mfma_f32_16x16x32_bf16 v[48:51], v[218:221], v[168:171], v[48:51]
	v_mfma_f32_16x16x32_bf16 v[92:95], v[226:229], v[168:171], v[92:95]
	v_mfma_f32_16x16x32_bf16 v[96:99], v[218:221], v[194:197], v[96:99]
	v_mfma_f32_16x16x32_bf16 v[104:107], v[226:229], v[194:197], v[104:107]
	v_mfma_f32_16x16x32_bf16 v[84:87], v[218:221], v[202:205], v[84:87]
	v_mfma_f32_16x16x32_bf16 v[88:91], v[226:229], v[202:205], v[88:91]
	s_setprio 0
	s_add_u32 s84, s72, 0x80
	s_addc_u32 s85, s73, 0
	s_add_u32 s90, s78, 0x80
	s_addc_u32 s91, s79, 0
	s_barrier
	ds_read_b128 v[108:111], v176
	ds_read_b128 v[112:115], v176 offset:1024
	ds_read_b128 v[116:119], v176 offset:2048
	ds_read_b128 v[120:123], v176 offset:3072
	s_add_u32 s26, s86, 0x100000
	s_addc_u32 s27, s87, 0
	ds_read_b128 v[128:131], v135
	ds_read_b128 v[136:139], v135 offset:1024
	ds_read_b128 v[164:167], v135 offset:2048
	ds_read_b128 v[168:171], v135 offset:3072
	ds_read_b128 v[172:175], v135 offset:4096
	ds_read_b128 v[194:197], v135 offset:5120
	ds_read_b128 v[198:201], v135 offset:6144
	ds_read_b128 v[202:205], v135 offset:7168
	s_mov_b32 m0, s22
	v_lshl_add_u64 v[132:133], s[26:27], 0, v[124:125]
	s_add_u32 s26, s86, 0x180000
	s_addc_u32 s27, s87, 0
	global_load_lds_dwordx4 v[132:133], off
	s_mov_b32 m0, s9
	v_lshl_add_u64 v[132:133], s[26:27], 0, v[124:125]
	global_load_lds_dwordx4 v[132:133], off
	s_waitcnt lgkmcnt(8)
	s_barrier
; #define PG8_STAGE(bufoff, gbase, voff) do { _Pragma("unroll") for (int _i = 0; _i < 2; ++_i) { const char* _gb = (const char*)(gbase) + (size_t)_i * (voff##_q); asm volatile("" : "+s"(_gb)); \
;         __builtin_amdgcn_global_load_lds((const unsigned*)(_gb + (voff)), (LAS unsigned*)(lds + (bufoff) + ldsw + _i * 8192), 16, 0, 0); } } while (0)
; #define PG8_LDA(dst, b, h) do { _Pragma("unroll") for (int m = 0; m < 4; ++m) _Pragma("unroll") for (int k = 0; k < 2; ++k) dst[m][k] = *(const LAS bf16x8*)(lds + PG8_SA(b, h) + aoff + m * 2048 + k * 1024); } while (0)
; #define PG8_LDB(dst, b, h) do { _Pragma("unroll") for (int n = 0; n < 2; ++n) _Pragma("unroll") for (int k = 0; k < 2; ++k) dst[n][k] = *(const LAS bf16x8*)(lds + PG8_SB(b, h) + boff + n * 2048 + k * 1024); } while (0)
; #define PG8_WAIT_V(n) asm volatile("s_waitcnt vmcnt(" #n ")" ::: "memory")
; #define PG8_WAIT_L(n) asm volatile("s_waitcnt lgkmcnt(" #n ")" ::: "memory")
; template <class Epi, class Sched>
; __device__ __forceinline__ void gemm_phase(int wv, LAS unsigned char* lds, const Gemm g, const Sched& S, const Epi& E) { LIDS
;     ...
;             PG8_LDB(B0, 0, 0); PG8_SCHED; PG8_LDA(At, 0, 0); PG8_STAGE(PG8_SA(1, 1), a1 + hstepA, voffA);
;             PG8_WAIT_L(8); PG8_BAR; PG8_WAIT_L(0); PG8_MMA(0, 0, At, B0); PG8_BAR; PG8_SCHED;
;             PG8_LDB(B1, 0, 1); PG8_STAGE(PG8_SB(0, 0), b2, voffB);
;             PG8_BAR; PG8_WAIT_L(0); PG8_MMA(0, 1, At, B1); PG8_BAR;
;             PG8_LDA(At, 0, 1); PG8_STAGE(PG8_SA(0, 0), a2, voffA);
;             PG8_BAR; PG8_WAIT_L(0); PG8_MMA(1, 0, At, B0); PG8_BAR; PG8_SCHED;
;             PG8_STAGE(PG8_SB(0, 1), b2 + hstepB, voffB);
;             PG8_WAIT_V(6); PG8_BAR; PG8_MMA(1, 1, At, B1); PG8_BAR;
;             PG8_LDB(B0, 1, 0); PG8_SCHED; PG8_LDA(At, 1, 0); PG8_STAGE(PG8_SA(0, 1), a2 + hstepA, voffA);
;             PG8_WAIT_L(8); PG8_BAR; PG8_WAIT_L(0); PG8_MMA(0, 0, At, B0); PG8_BAR; PG8_SCHED;
;             PG8_LDB(B1, 1, 1); PG8_STAGE(PG8_SB(1, 0), b3, voffB);
;             PG8_BAR; PG8_WAIT_L(0); PG8_MMA(0, 1, At, B1); PG8_BAR;
;             PG8_LDA(At, 1, 1); PG8_STAGE(PG8_SA(1, 0), a3, voffA);
;             PG8_BAR; PG8_WAIT_L(0); PG8_MMA(1, 0, At, B0); PG8_BAR; PG8_SCHED;
;             PG8_STAGE(PG8_SB(1, 1), b3 + hstepB, voffB);
;             PG8_WAIT_V(6); PG8_BAR; PG8_MMA(1, 1, At, B1); PG8_BAR;
	s_waitcnt lgkmcnt(0)
	s_setprio 1
	v_mfma_f32_16x16x32_bf16 v[52:55], v[108:111], v[128:131], v[52:55]
	v_mfma_f32_16x16x32_bf16 v[56:59], v[116:119], v[128:131], v[56:59]
	v_mfma_f32_16x16x32_bf16 v[60:63], v[108:111], v[164:167], v[60:63]
	v_mfma_f32_16x16x32_bf16 v[64:67], v[116:119], v[164:167], v[64:67]
	v_mfma_f32_16x16x32_bf16 v[68:71], v[108:111], v[172:175], v[68:71]
	v_mfma_f32_16x16x32_bf16 v[72:75], v[116:119], v[172:175], v[72:75]
	v_mfma_f32_16x16x32_bf16 v[76:79], v[108:111], v[198:201], v[76:79]
	v_mfma_f32_16x16x32_bf16 v[80:83], v[116:119], v[198:201], v[80:83]
	v_mfma_f32_16x16x32_bf16 v[52:55], v[112:115], v[136:139], v[52:55]
	v_mfma_f32_16x16x32_bf16 v[56:59], v[120:123], v[136:139], v[56:59]
	v_mfma_f32_16x16x32_bf16 v[60:63], v[112:115], v[168:171], v[60:63]
	v_mfma_f32_16x16x32_bf16 v[64:67], v[120:123], v[168:171], v[64:67]
	v_mfma_f32_16x16x32_bf16 v[68:71], v[112:115], v[194:197], v[68:71]
	v_mfma_f32_16x16x32_bf16 v[72:75], v[120:123], v[194:197], v[72:75]
	v_mfma_f32_16x16x32_bf16 v[76:79], v[112:115], v[202:205], v[76:79]
	v_mfma_f32_16x16x32_bf16 v[80:83], v[120:123], v[202:205], v[80:83]
	s_setprio 0
	s_barrier
	s_mov_b64 s[26:27], s[78:79]
	ds_read_b128 v[206:209], v178
	ds_read_b128 v[218:221], v178 offset:1024
	ds_read_b128 v[222:225], v178 offset:2048
	ds_read_b128 v[226:229], v178 offset:3072
	s_mov_b32 m0, s20
	v_lshl_add_u64 v[132:133], s[26:27], 0, v[126:127]
	s_add_u32 s26, s78, 0x8000
	s_addc_u32 s27, s79, 0
	global_load_lds_dwordx4 v[132:133], off
	s_mov_b32 m0, s11
	v_lshl_add_u64 v[132:133], s[26:27], 0, v[126:127]
	global_load_lds_dwordx4 v[132:133], off
	s_barrier
	s_waitcnt lgkmcnt(0)
	s_setprio 1
	v_mfma_f32_16x16x32_bf16 v[100:103], v[206:209], v[128:131], v[100:103]
	v_mfma_f32_16x16x32_bf16 v[20:23], v[222:225], v[128:131], v[20:23]
	v_mfma_f32_16x16x32_bf16 v[24:27], v[206:209], v[164:167], v[24:27]
	v_mfma_f32_16x16x32_bf16 v[28:31], v[222:225], v[164:167], v[28:31]
	v_mfma_f32_16x16x32_bf16 v[32:35], v[206:209], v[172:175], v[32:35]
	v_mfma_f32_16x16x32_bf16 v[36:39], v[222:225], v[172:175], v[36:39]
	v_mfma_f32_16x16x32_bf16 v[40:43], v[206:209], v[198:201], v[40:43]
	v_mfma_f32_16x16x32_bf16 v[44:47], v[222:225], v[198:201], v[44:47]
	v_mfma_f32_16x16x32_bf16 v[230:233], v[218:221], v[136:139], v[100:103]
	v_mfma_f32_16x16x32_bf16 v[20:23], v[226:229], v[136:139], v[20:23]
	v_mfma_f32_16x16x32_bf16 v[24:27], v[218:221], v[168:171], v[24:27]
	v_mfma_f32_16x16x32_bf16 v[28:31], v[226:229], v[168:171], v[28:31]
	v_mfma_f32_16x16x32_bf16 v[32:35], v[218:221], v[194:197], v[32:35]
	v_mfma_f32_16x16x32_bf16 v[36:39], v[226:229], v[194:197], v[36:39]
	v_mfma_f32_16x16x32_bf16 v[40:43], v[218:221], v[202:205], v[40:43]
	v_mfma_f32_16x16x32_bf16 v[44:47], v[226:229], v[202:205], v[44:47]
	s_setprio 0
	s_mov_b64 s[26:27], s[72:73]
	s_barrier
	ds_read_b128 v[100:103], v135 offset:16384
	ds_read_b128 v[128:131], v135 offset:17408
	ds_read_b128 v[136:139], v135 offset:18432
	ds_read_b128 v[164:167], v135 offset:19456
	ds_read_b128 v[168:171], v135 offset:20480
	ds_read_b128 v[172:175], v135 offset:21504
	ds_read_b128 v[194:197], v135 offset:22528
	ds_read_b128 v[198:201], v135 offset:23552
	s_mov_b32 m0, s58
	v_lshl_add_u64 v[132:133], s[26:27], 0, v[124:125]
	s_add_u32 s26, s72, 0x80000
	s_addc_u32 s27, s73, 0
	global_load_lds_dwordx4 v[132:133], off
	s_mov_b32 m0, s77
	v_lshl_add_u64 v[132:133], s[26:27], 0, v[124:125]
	global_load_lds_dwordx4 v[132:133], off
	s_barrier
	s_waitcnt lgkmcnt(0)
	s_setprio 1
	v_mfma_f32_16x16x32_bf16 v[140:143], v[108:111], v[100:103], v[140:143]
	v_mfma_f32_16x16x32_bf16 v[144:147], v[116:119], v[100:103], v[144:147]
	v_mfma_f32_16x16x32_bf16 v[148:151], v[108:111], v[136:139], v[148:151]
	v_mfma_f32_16x16x32_bf16 v[152:155], v[116:119], v[136:139], v[152:155]
	v_mfma_f32_16x16x32_bf16 v[156:159], v[108:111], v[168:171], v[156:159]
	v_mfma_f32_16x16x32_bf16 v[160:163], v[116:119], v[168:171], v[160:163]
	v_mfma_f32_16x16x32_bf16 v[4:7], v[108:111], v[194:197], v[4:7]
	v_mfma_f32_16x16x32_bf16 v[8:11], v[116:119], v[194:197], v[8:11]
	v_mfma_f32_16x16x32_bf16 v[140:143], v[112:115], v[128:131], v[140:143]
	v_mfma_f32_16x16x32_bf16 v[144:147], v[120:123], v[128:131], v[144:147]
	v_mfma_f32_16x16x32_bf16 v[148:151], v[112:115], v[164:167], v[148:151]
	v_mfma_f32_16x16x32_bf16 v[152:155], v[120:123], v[164:167], v[152:155]
	v_mfma_f32_16x16x32_bf16 v[156:159], v[112:115], v[172:175], v[156:159]
	v_mfma_f32_16x16x32_bf16 v[160:163], v[120:123], v[172:175], v[160:163]
	v_mfma_f32_16x16x32_bf16 v[4:7], v[112:115], v[198:201], v[4:7]
	v_mfma_f32_16x16x32_bf16 v[8:11], v[120:123], v[198:201], v[8:11]
	s_setprio 0
	s_barrier
	s_add_u32 s20, s78, 0x10000
	s_mov_b32 m0, s21
	s_addc_u32 s21, s79, 0
	s_nop 0
	v_lshl_add_u64 v[108:109], s[20:21], 0, v[126:127]
	s_add_u32 s20, s78, 0x18000
	s_addc_u32 s21, s79, 0
	global_load_lds_dwordx4 v[108:109], off
	s_mov_b32 m0, s17
	v_lshl_add_u64 v[108:109], s[20:21], 0, v[126:127]
	global_load_lds_dwordx4 v[108:109], off
	s_waitcnt vmcnt(6)
	s_barrier
	s_setprio 1
	v_mfma_f32_16x16x32_bf16 v[12:15], v[206:209], v[100:103], v[12:15]
	v_mfma_f32_16x16x32_bf16 v[16:19], v[222:225], v[100:103], v[16:19]
	v_mfma_f32_16x16x32_bf16 v[92:95], v[222:225], v[136:139], v[92:95]
	v_mfma_f32_16x16x32_bf16 v[12:15], v[218:221], v[128:131], v[12:15]
	v_mfma_f32_16x16x32_bf16 v[16:19], v[226:229], v[128:131], v[16:19]
	v_mfma_f32_16x16x32_bf16 v[128:131], v[226:229], v[164:167], v[92:95]
	v_mfma_f32_16x16x32_bf16 v[92:95], v[206:209], v[168:171], v[96:99]
	v_mfma_f32_16x16x32_bf16 v[84:87], v[206:209], v[194:197], v[84:87]
	v_mfma_f32_16x16x32_bf16 v[48:51], v[206:209], v[136:139], v[48:51]
	v_mfma_f32_16x16x32_bf16 v[136:139], v[218:221], v[172:175], v[92:95]
	v_mfma_f32_16x16x32_bf16 v[92:95], v[222:225], v[168:171], v[104:107]
	v_mfma_f32_16x16x32_bf16 v[168:171], v[218:221], v[198:201], v[84:87]
	v_mfma_f32_16x16x32_bf16 v[84:87], v[222:225], v[194:197], v[88:91]
	v_mfma_f32_16x16x32_bf16 v[48:51], v[218:221], v[164:167], v[48:51]
	v_mfma_f32_16x16x32_bf16 v[164:167], v[226:229], v[172:175], v[92:95]
	v_mfma_f32_16x16x32_bf16 v[172:175], v[226:229], v[198:201], v[84:87]
	s_setprio 0
	s_barrier
; #define PG8_STAGE(bufoff, gbase, voff) do { _Pragma("unroll") for (int _i = 0; _i < 2; ++_i) { const char* _gb = (const char*)(gbase) + (size_t)_i * (voff##_q); asm volatile("" : "+s"(_gb)); \
;         __builtin_amdgcn_global_load_lds((const unsigned*)(_gb + (voff)), (LAS unsigned*)(lds + (bufoff) + ldsw + _i * 8192), 16, 0, 0); } } while (0)
; #define PG8_LDA(dst, b, h) do { _Pragma("unroll") for (int m = 0; m < 4; ++m) _Pragma("unroll") for (int k = 0; k < 2; ++k) dst[m][k] = *(const LAS bf16x8*)(lds + PG8_SA(b, h) + aoff + m * 2048 + k * 1024); } while (0)
; #define PG8_LDB(dst, b, h) do { _Pragma("unroll") for (int n = 0; n < 2; ++n) _Pragma("unroll") for (int k = 0; k < 2; ++k) dst[n][k] = *(const LAS bf16x8*)(lds + PG8_SB(b, h) + boff + n * 2048 + k * 1024); } while (0)
; #define PG8_MMA(ai, bj, At, Bt) do { __builtin_amdgcn_s_setprio(1); _Pragma("unroll") for (int m = 0; m < 4; ++m) _Pragma("unroll") for (int n = 0; n < 2; ++n) _Pragma("unroll") for (int k = 0; k < 2; ++k) \
;         acc[ai][bj][m][n] = __builtin_amdgcn_mfma_f32_16x16x32_bf16(Bt[n][k], At[m][k], acc[ai][bj][m][n], 0, 0, 0); __builtin_amdgcn_s_setprio(0); } while (0)
; #define PG8_WAIT_L(n) asm volatile("s_waitcnt lgkmcnt(" #n ")" ::: "memory")
; #define PG8_BAR __builtin_amdgcn_s_barrier()
; #define PG8_SCHED __builtin_amdgcn_sched_barrier(0)
; template <class Epi, class Sched>
; __device__ __forceinline__ void gemm_phase(int wv, LAS unsigned char* lds, const Gemm g, const Sched& S, const Epi& E) { LIDS
;     ...
;             PG8_LDB(B0, 1, 0); PG8_SCHED; PG8_LDA(At, 1, 0); PG8_STAGE(PG8_SA(0, 1), a2 + hstepA, voffA);
;             PG8_WAIT_L(8); PG8_BAR; PG8_WAIT_L(0); PG8_MMA(0, 0, At, B0); PG8_BAR; PG8_SCHED;
;             PG8_LDB(B1, 1, 1); PG8_STAGE(PG8_SB(1, 0), b3, voffB);
;             PG8_BAR; PG8_WAIT_L(0); PG8_MMA(0, 1, At, B1); PG8_BAR;
;             PG8_LDA(At, 1, 1); PG8_STAGE(PG8_SA(1, 0), a3, voffA);
;             PG8_BAR; PG8_WAIT_L(0); PG8_MMA(1, 0, At, B0); PG8_BAR; PG8_SCHED;
	ds_read_b128 v[194:197], v179
	ds_read_b128 v[198:201], v179 offset:1024
	ds_read_b128 v[202:205], v179 offset:2048
	ds_read_b128 v[206:209], v179 offset:3072
	s_add_u32 s20, s72, 0x100000
	s_addc_u32 s21, s73, 0
	ds_read_b128 v[92:95], v135 offset:32768
	ds_read_b128 v[96:99], v135 offset:33792
	ds_read_b128 v[112:115], v135 offset:34816
	ds_read_b128 v[218:221], v135 offset:35840
	ds_read_b128 v[222:225], v135 offset:36864
	ds_read_b128 v[226:229], v135 offset:37888
	ds_read_b128 v[234:237], v135 offset:38912
	ds_read_b128 v[238:241], v135 offset:39936
	s_mov_b32 m0, s82
	v_lshl_add_u64 v[84:85], s[20:21], 0, v[124:125]
	s_add_u32 s20, s72, 0x180000
	s_addc_u32 s21, s73, 0
	global_load_lds_dwordx4 v[84:85], off
	s_mov_b32 m0, s56
	v_lshl_add_u64 v[84:85], s[20:21], 0, v[124:125]
	global_load_lds_dwordx4 v[84:85], off
	s_waitcnt lgkmcnt(8)
	s_barrier
	s_waitcnt lgkmcnt(0)
	s_setprio 1
	v_mfma_f32_16x16x32_bf16 v[52:55], v[194:197], v[92:95], v[52:55]
	v_mfma_f32_16x16x32_bf16 v[242:245], v[198:201], v[96:99], v[52:55]
	v_mfma_f32_16x16x32_bf16 v[52:55], v[202:205], v[92:95], v[56:59]
	v_mfma_f32_16x16x32_bf16 v[246:249], v[206:209], v[96:99], v[52:55]
	v_mfma_f32_16x16x32_bf16 v[52:55], v[194:197], v[112:115], v[60:63]
	v_mfma_f32_16x16x32_bf16 v[100:103], v[198:201], v[218:221], v[52:55]
	v_mfma_f32_16x16x32_bf16 v[52:55], v[202:205], v[112:115], v[64:67]
	v_mfma_f32_16x16x32_bf16 v[104:107], v[206:209], v[218:221], v[52:55]
	v_mfma_f32_16x16x32_bf16 v[52:55], v[194:197], v[222:225], v[68:71]
	v_mfma_f32_16x16x32_bf16 v[84:87], v[198:201], v[226:229], v[52:55]
	v_mfma_f32_16x16x32_bf16 v[52:55], v[202:205], v[222:225], v[72:75]
	v_mfma_f32_16x16x32_bf16 v[88:91], v[206:209], v[226:229], v[52:55]
	v_mfma_f32_16x16x32_bf16 v[52:55], v[194:197], v[234:237], v[76:79]
	v_mfma_f32_16x16x32_bf16 v[68:71], v[198:201], v[238:241], v[52:55]
	v_mfma_f32_16x16x32_bf16 v[52:55], v[202:205], v[234:237], v[80:83]
	v_mfma_f32_16x16x32_bf16 v[72:75], v[206:209], v[238:241], v[52:55]
	s_setprio 0
	s_barrier
	s_mov_b64 s[20:21], s[90:91]
	ds_read_b128 v[182:185], v190
	ds_read_b128 v[178:181], v190 offset:1024
	ds_read_b128 v[186:189], v190 offset:2048
	ds_read_b128 v[190:193], v190 offset:3072
	s_mov_b32 m0, s23
	v_lshl_add_u64 v[52:53], s[20:21], 0, v[126:127]
	s_add_u32 s20, s90, 0x8000
	s_addc_u32 s21, s91, 0
	global_load_lds_dwordx4 v[52:53], off
	s_mov_b32 m0, s18
	v_lshl_add_u64 v[52:53], s[20:21], 0, v[126:127]
	global_load_lds_dwordx4 v[52:53], off
	s_barrier
	s_waitcnt lgkmcnt(0)
	s_setprio 1
	v_mfma_f32_16x16x32_bf16 v[20:23], v[186:189], v[92:95], v[20:23]
	v_mfma_f32_16x16x32_bf16 v[120:123], v[190:193], v[96:99], v[20:23]
	v_mfma_f32_16x16x32_bf16 v[20:23], v[182:185], v[112:115], v[24:27]
	v_mfma_f32_16x16x32_bf16 v[108:111], v[178:181], v[218:221], v[20:23]
	v_mfma_f32_16x16x32_bf16 v[20:23], v[186:189], v[112:115], v[28:31]
	v_mfma_f32_16x16x32_bf16 v[112:115], v[190:193], v[218:221], v[20:23]
	v_mfma_f32_16x16x32_bf16 v[20:23], v[182:185], v[222:225], v[32:35]
	v_mfma_f32_16x16x32_bf16 v[52:55], v[182:185], v[92:95], v[230:233]
	v_mfma_f32_16x16x32_bf16 v[92:95], v[178:181], v[226:229], v[20:23]
	v_mfma_f32_16x16x32_bf16 v[20:23], v[186:189], v[222:225], v[36:39]
	v_mfma_f32_16x16x32_bf16 v[116:119], v[178:181], v[96:99], v[52:55]
	v_mfma_f32_16x16x32_bf16 v[96:99], v[190:193], v[226:229], v[20:23]
	v_mfma_f32_16x16x32_bf16 v[20:23], v[182:185], v[234:237], v[40:43]
	v_mfma_f32_16x16x32_bf16 v[76:79], v[178:181], v[238:241], v[20:23]
	v_mfma_f32_16x16x32_bf16 v[20:23], v[186:189], v[234:237], v[44:47]
	v_mfma_f32_16x16x32_bf16 v[80:83], v[190:193], v[238:241], v[20:23]
	s_setprio 0
	s_mov_b64 s[20:21], s[84:85]
	s_barrier
	ds_read_b128 v[28:31], v135 offset:49152
	ds_read_b128 v[32:35], v135 offset:50176
	ds_read_b128 v[218:221], v135 offset:51200
	ds_read_b128 v[222:225], v135 offset:52224
	ds_read_b128 v[226:229], v135 offset:53248
	ds_read_b128 v[230:233], v135 offset:54272
	ds_read_b128 v[234:237], v135 offset:55296
	ds_read_b128 v[238:241], v135 offset:56320
	s_mov_b32 m0, s0
	v_lshl_add_u64 v[20:21], s[20:21], 0, v[124:125]
	s_add_u32 s20, s84, 0x80000
	s_addc_u32 s21, s85, 0
	global_load_lds_dwordx4 v[20:21], off
	s_mov_b32 m0, s59
	v_lshl_add_u64 v[20:21], s[20:21], 0, v[124:125]
	global_load_lds_dwordx4 v[20:21], off
	s_barrier
	s_waitcnt lgkmcnt(0)
	s_setprio 1
	v_mfma_f32_16x16x32_bf16 v[20:23], v[194:197], v[28:31], v[140:143]
	v_mfma_f32_16x16x32_bf16 v[52:55], v[198:201], v[32:35], v[20:23]
	v_mfma_f32_16x16x32_bf16 v[20:23], v[202:205], v[28:31], v[144:147]
	v_mfma_f32_16x16x32_bf16 v[56:59], v[206:209], v[32:35], v[20:23]
	v_mfma_f32_16x16x32_bf16 v[20:23], v[194:197], v[218:221], v[148:151]
	v_mfma_f32_16x16x32_bf16 v[36:39], v[198:201], v[222:225], v[20:23]
	v_mfma_f32_16x16x32_bf16 v[20:23], v[202:205], v[218:221], v[152:155]
	v_mfma_f32_16x16x32_bf16 v[40:43], v[206:209], v[222:225], v[20:23]
	v_mfma_f32_16x16x32_bf16 v[20:23], v[194:197], v[226:229], v[156:159]
	v_mfma_f32_16x16x32_bf16 v[24:27], v[202:205], v[226:229], v[160:163]
	v_mfma_f32_16x16x32_bf16 v[4:7], v[194:197], v[234:237], v[4:7]
	v_mfma_f32_16x16x32_bf16 v[8:11], v[202:205], v[234:237], v[8:11]
	v_mfma_f32_16x16x32_bf16 v[20:23], v[198:201], v[230:233], v[20:23]
	v_mfma_f32_16x16x32_bf16 v[24:27], v[206:209], v[230:233], v[24:27]
	v_mfma_f32_16x16x32_bf16 v[4:7], v[198:201], v[238:241], v[4:7]
	v_mfma_f32_16x16x32_bf16 v[8:11], v[206:209], v[238:241], v[8:11]
	s_setprio 0
	s_barrier
; __device__ __forceinline__ u32x4 pack8(f32x4 a, f32x4 b) { u32x4 r; r[0] = cvt_pk_bf16(a[0], a[1]); r[1] = cvt_pk_bf16(a[2], a[3]); r[2] = cvt_pk_bf16(b[0], b[1]); r[3] = cvt_pk_bf16(b[2], b[3]); return r; }
; #define PG8_STAGE(bufoff, gbase, voff) do { _Pragma("unroll") for (int _i = 0; _i < 2; ++_i) { const char* _gb = (const char*)(gbase) + (size_t)_i * (voff##_q); asm volatile("" : "+s"(_gb)); \
;         __builtin_amdgcn_global_load_lds((const unsigned*)(_gb + (voff)), (LAS unsigned*)(lds + (bufoff) + ldsw + _i * 8192), 16, 0, 0); } } while (0)
; #define PG8_MMA(ai, bj, At, Bt) do { __builtin_amdgcn_s_setprio(1); _Pragma("unroll") for (int m = 0; m < 4; ++m) _Pragma("unroll") for (int n = 0; n < 2; ++n) _Pragma("unroll") for (int k = 0; k < 2; ++k) \
;         acc[ai][bj][m][n] = __builtin_amdgcn_mfma_f32_16x16x32_bf16(Bt[n][k], At[m][k], acc[ai][bj][m][n], 0, 0, 0); __builtin_amdgcn_s_setprio(0); } while (0)
; #define PG8_WAIT_V(n) asm volatile("s_waitcnt vmcnt(" #n ")" ::: "memory")
; #define PG8_BAR __builtin_amdgcn_s_barrier()
; template <class Epi, class Sched>
; __device__ __forceinline__ void gemm_phase(int wv, LAS unsigned char* lds, const Gemm g, const Sched& S, const Epi& E) { LIDS
;     ...
;             PG8_STAGE(PG8_SB(1, 1), b3 + hstepB, voffB);
;             PG8_WAIT_V(6); PG8_BAR; PG8_MMA(1, 1, At, B1); PG8_BAR;
;     __device__ __forceinline__ void operator()(const AccT& acc, const Unit& u, int wr, int wc, int fr, int fq) const {
;         EPI_ROWS(u)
; #pragma unroll
;         for (int ai = 0; ai < 2; ++ai)
; #pragma unroll
;             for (int m = 0; m < 4; ++m) {
;                 const int row = row0 + ai * HALF + m * 16;
;                 const f32x4 pc = *(const f32x4*)(ssp + (size_t)row * 16 + 8);
;                 const float sc = rsqrtf(((pc[0] + pc[1]) + (pc[2] + pc[3])) * (1.0f / 256.0f) + EPS);
; #pragma unroll
;                 for (int bj = 0; bj < 2; ++bj) {
;                     const int col = colbase + bj * HALF, head = col >> 7, d = col & 127;
;                     *(u32x4*)(Kf + (size_t)row * NKF + head * 192 + d) = pack8(acc[ai][bj][m][0] * sc, acc[ai][bj][m][1] * sc);
	s_add_u32 s20, s90, 0x10000
	s_addc_u32 s21, s91, 0
	s_mov_b32 m0, s24
	v_lshl_add_u64 v[44:45], s[20:21], 0, v[126:127]
	s_add_u32 s20, s90, 0x18000
	s_addc_u32 s21, s91, 0
	global_load_lds_dwordx4 v[44:45], off
	s_mov_b32 m0, s19
	v_lshl_add_u64 v[44:45], s[20:21], 0, v[126:127]
	global_load_lds_dwordx4 v[44:45], off
	s_waitcnt vmcnt(6)
	s_barrier
	s_setprio 1
	v_mfma_f32_16x16x32_bf16 v[12:15], v[182:185], v[28:31], v[12:15]
	v_mfma_f32_16x16x32_bf16 v[60:63], v[178:181], v[32:35], v[12:15]
	v_mfma_f32_16x16x32_bf16 v[12:15], v[186:189], v[28:31], v[16:19]
	v_mfma_f32_16x16x32_bf16 v[64:67], v[190:193], v[32:35], v[12:15]
	v_mfma_f32_16x16x32_bf16 v[12:15], v[182:185], v[218:221], v[48:51]
	v_mfma_f32_16x16x32_bf16 v[44:47], v[178:181], v[222:225], v[12:15]
	v_mfma_f32_16x16x32_bf16 v[12:15], v[186:189], v[218:221], v[128:131]
	v_mfma_f32_16x16x32_bf16 v[48:51], v[190:193], v[222:225], v[12:15]
	v_mfma_f32_16x16x32_bf16 v[12:15], v[182:185], v[226:229], v[136:139]
	v_mfma_f32_16x16x32_bf16 v[28:31], v[178:181], v[230:233], v[12:15]
	v_mfma_f32_16x16x32_bf16 v[12:15], v[186:189], v[226:229], v[164:167]
	v_mfma_f32_16x16x32_bf16 v[32:35], v[190:193], v[230:233], v[12:15]
	v_mfma_f32_16x16x32_bf16 v[12:15], v[182:185], v[234:237], v[168:171]
	v_mfma_f32_16x16x32_bf16 v[16:19], v[186:189], v[234:237], v[172:175]
	v_mfma_f32_16x16x32_bf16 v[12:15], v[178:181], v[238:241], v[12:15]
	v_mfma_f32_16x16x32_bf16 v[16:19], v[190:193], v[238:241], v[16:19]
	s_setprio 0
	s_lshl_b32 s9, s68, 8
	s_barrier
	v_mbcnt_lo_u32_b32 v129, -1, 0
	v_mbcnt_hi_u32_b32 v129, -1, v129
	s_add_i32 s9, s9, s83
	v_and_or_b32 v128, v129, 15, s9
	s_lshl_b32 s9, s16, 8
	v_ashrrev_i32_e32 v129, 1, v129
	s_or_b32 s9, s9, s92
	v_and_b32_e32 v129, -8, v129
	v_add_u32_e32 v141, s9, v129
	v_ashrrev_i32_e32 v129, 31, v128
	v_readlane_b32 s18, v253, 12
	v_lshlrev_b64 v[130:131], 6, v[128:129]
	v_readlane_b32 s19, v253, 13
	v_ashrrev_i32_e32 v144, 7, v141
	s_movk_i32 s9, 0xc0
	v_lshl_add_u64 v[130:131], s[18:19], 0, v[130:131]
	global_load_dwordx4 v[194:197], v[130:131], off offset:32
	global_load_dwordx4 v[198:201], v[130:131], off offset:1056
	global_load_dwordx4 v[202:205], v[130:131], off offset:2080
	global_load_dwordx4 v[206:209], v[130:131], off offset:3104
	v_add_co_u32_e32 v234, vcc, 0x2000, v130
	v_addc_co_u32_e32 v235, vcc, 0, v131, vcc
	global_load_dwordx4 v[218:221], v[234:235], off offset:32
	global_load_dwordx4 v[222:225], v[234:235], off offset:1056
	global_load_dwordx4 v[226:229], v[234:235], off offset:2080
	global_load_dwordx4 v[230:233], v[234:235], off offset:3104
	v_and_b32_e32 v146, 0x78, v141
	v_lshlrev_b32_e32 v176, 1, v146
	s_add_i32 s69, s69, s55
	s_mov_b32 s68, s10
	s_mov_b64 s[90:91], s[62:63]
	s_mov_b64 s[86:87], s[12:13]
	s_waitcnt vmcnt(0)
	v_mov_b32_e32 v130, v194
	v_mov_b32_e32 v131, v195
	v_mov_b32_e32 v132, v196
	v_mov_b32_e32 v133, v197
	v_mov_b32_e32 v136, v131
	v_mov_b32_e32 v137, v132
	v_mov_b32_e32 v131, v133
	v_pk_add_f32 v[130:131], v[136:137], v[130:131]
	s_nop 0
	v_add_f32_e32 v129, v130, v131
	v_fmamk_f32 v129, v129, 0x3b800000, v252
	v_cmp_gt_f32_e32 vcc, s53, v129
	v_mul_f32_e32 v130, 0x4b800000, v129
	s_nop 0
	v_cndmask_b32_e32 v129, v129, v130, vcc
	v_rsq_f32_e32 v129, v129
	s_nop 0
	v_mul_f32_e32 v130, 0x45800000, v129
	v_cndmask_b32_e32 v140, v129, v130, vcc
	v_pk_mul_f32 v[132:133], v[242:243], v[140:141] op_sel_hi:[1,0]
	v_pk_mul_f32 v[130:131], v[244:245], v[140:141] op_sel_hi:[1,0]
	v_cvt_pk_bf16_f32 v136, v132, v133
	v_mul_lo_u32 v132, v144, s9
	v_pk_mul_f32 v[142:143], v[248:249], v[140:141] op_sel_hi:[1,0]
	v_pk_mul_f32 v[138:139], v[246:247], v[140:141] op_sel_hi:[1,0]
	v_cvt_pk_bf16_f32 v137, v130, v131
	v_mov_b64_e32 v[130:131], s[30:31]
	v_ashrrev_i32_e32 v133, 31, v132
	v_cvt_pk_bf16_f32 v138, v138, v139
	v_cvt_pk_bf16_f32 v139, v142, v143
	v_mad_i64_i32 v[142:143], s[16:17], v128, s52, v[130:131]
	v_lshlrev_b64 v[132:133], 1, v[132:133]
	v_lshl_add_u64 v[144:145], v[142:143], 0, v[132:133]
	v_add_u32_e32 v129, 0x80, v141
	v_lshl_add_u64 v[144:145], v[144:145], 0, v[176:177]
	v_ashrrev_i32_e32 v129, 7, v129
	v_pk_mul_f32 v[116:117], v[116:117], v[140:141] op_sel_hi:[1,0]
	global_store_dwordx4 v[144:145], v[136:139], off
	v_pk_mul_f32 v[122:123], v[122:123], v[140:141] op_sel_hi:[1,0]
	v_pk_mul_f32 v[120:121], v[120:121], v[140:141] op_sel_hi:[1,0]
	v_pk_mul_f32 v[136:137], v[118:119], v[140:141] op_sel_hi:[1,0]
	v_cvt_pk_bf16_f32 v118, v116, v117
	v_mul_lo_u32 v116, v129, s9
	v_ashrrev_i32_e32 v117, 31, v116
	v_lshlrev_b64 v[116:117], 1, v[116:117]
	v_cvt_pk_bf16_f32 v119, v136, v137
	v_cvt_pk_bf16_f32 v120, v120, v121
	v_cvt_pk_bf16_f32 v121, v122, v123
	v_lshl_add_u64 v[122:123], v[142:143], 0, v[116:117]
	v_lshl_add_u64 v[122:123], v[122:123], 0, v[176:177]
	global_store_dwordx4 v[122:123], v[118:121], off
	v_or_b32_e32 v122, 16, v128
	v_ashrrev_i32_e32 v123, 31, v122
	v_lshlrev_b64 v[118:119], 6, v[122:123]
	v_lshl_add_u64 v[118:119], s[18:19], 0, v[118:119]
	v_mov_b32_e32 v118, v198
	v_mov_b32_e32 v119, v199
	v_mov_b32_e32 v120, v200
	v_mov_b32_e32 v121, v201
	v_mov_b32_e32 v136, v119
	v_mov_b32_e32 v137, v120
	v_mov_b32_e32 v119, v121
	v_pk_add_f32 v[118:119], v[136:137], v[118:119]
	s_nop 0
	v_add_f32_e32 v118, v118, v119
	v_fmamk_f32 v118, v118, 0x3b800000, v252
	v_cmp_gt_f32_e32 vcc, s53, v118
	v_mul_f32_e32 v119, 0x4b800000, v118
	s_nop 0
	v_cndmask_b32_e32 v118, v118, v119, vcc
	v_rsq_f32_e32 v118, v118
	s_nop 0
	v_mul_f32_e32 v119, 0x45800000, v118
	v_cndmask_b32_e32 v118, v118, v119, vcc
	v_pk_mul_f32 v[102:103], v[102:103], v[118:119] op_sel_hi:[1,0]
	v_pk_mul_f32 v[100:101], v[100:101], v[118:119] op_sel_hi:[1,0]
; __device__ __forceinline__ u32x4 pack8(f32x4 a, f32x4 b) { u32x4 r; r[0] = cvt_pk_bf16(a[0], a[1]); r[1] = cvt_pk_bf16(a[2], a[3]); r[2] = cvt_pk_bf16(b[0], b[1]); r[3] = cvt_pk_bf16(b[2], b[3]); return r; }
;     __device__ __forceinline__ void operator()(const AccT& acc, const Unit& u, int wr, int wc, int fr, int fq) const {
;     ...
;         for (int ai = 0; ai < 2; ++ai)
; #pragma unroll
;             for (int m = 0; m < 4; ++m) {
;                 const int row = row0 + ai * HALF + m * 16;
;                 const f32x4 pc = *(const f32x4*)(ssp + (size_t)row * 16 + 8);
;                 const float sc = rsqrtf(((pc[0] + pc[1]) + (pc[2] + pc[3])) * (1.0f / 256.0f) + EPS);
; #pragma unroll
;                 for (int bj = 0; bj < 2; ++bj) {
;                     const int col = colbase + bj * HALF, head = col >> 7, d = col & 127;
;                     *(u32x4*)(Kf + (size_t)row * NKF + head * 192 + d) = pack8(acc[ai][bj][m][0] * sc, acc[ai][bj][m][1] * sc);
;                 }
	v_pk_mul_f32 v[104:105], v[104:105], v[118:119] op_sel_hi:[1,0]
	v_pk_mul_f32 v[106:107], v[106:107], v[118:119] op_sel_hi:[1,0]
	v_cvt_pk_bf16_f32 v100, v100, v101
	v_cvt_pk_bf16_f32 v101, v102, v103
	v_cvt_pk_bf16_f32 v102, v104, v105
	v_mad_i64_i32 v[104:105], s[16:17], v122, s52, v[130:131]
	v_cvt_pk_bf16_f32 v103, v106, v107
	v_lshl_add_u64 v[106:107], v[104:105], 0, v[132:133]
	v_lshl_add_u64 v[106:107], v[106:107], 0, v[176:177]
	v_lshl_add_u64 v[104:105], v[104:105], 0, v[116:117]
	global_store_dwordx4 v[106:107], v[100:103], off
	v_lshl_add_u64 v[104:105], v[104:105], 0, v[176:177]
	v_pk_mul_f32 v[106:107], v[114:115], v[118:119] op_sel_hi:[1,0]
	v_pk_mul_f32 v[102:103], v[110:111], v[118:119] op_sel_hi:[1,0]
	v_pk_mul_f32 v[100:101], v[108:109], v[118:119] op_sel_hi:[1,0]
	v_pk_mul_f32 v[108:109], v[112:113], v[118:119] op_sel_hi:[1,0]
	v_cvt_pk_bf16_f32 v100, v100, v101
	v_cvt_pk_bf16_f32 v101, v102, v103
	s_nop 0
	v_cvt_pk_bf16_f32 v102, v108, v109
	v_cvt_pk_bf16_f32 v103, v106, v107
	global_store_dwordx4 v[104:105], v[100:103], off
	v_or_b32_e32 v104, 32, v128
	v_ashrrev_i32_e32 v105, 31, v104
	v_lshlrev_b64 v[100:101], 6, v[104:105]
	v_lshl_add_u64 v[100:101], s[18:19], 0, v[100:101]
	v_mov_b32_e32 v100, v202
	v_mov_b32_e32 v101, v203
	v_mov_b32_e32 v102, v204
	v_mov_b32_e32 v103, v205
	v_mov_b32_e32 v106, v101
	v_mov_b32_e32 v107, v102
	v_mov_b32_e32 v101, v103
	v_pk_add_f32 v[100:101], v[106:107], v[100:101]
	s_nop 0
	v_add_f32_e32 v100, v100, v101
	v_fmamk_f32 v100, v100, 0x3b800000, v252
	v_cmp_gt_f32_e32 vcc, s53, v100
	v_mul_f32_e32 v101, 0x4b800000, v100
	s_nop 0
	v_cndmask_b32_e32 v100, v100, v101, vcc
	v_rsq_f32_e32 v100, v100
	s_nop 0
	v_mul_f32_e32 v101, 0x45800000, v100
	v_cndmask_b32_e32 v100, v100, v101, vcc
	v_pk_mul_f32 v[86:87], v[86:87], v[100:101] op_sel_hi:[1,0]
	v_pk_mul_f32 v[84:85], v[84:85], v[100:101] op_sel_hi:[1,0]
	v_pk_mul_f32 v[88:89], v[88:89], v[100:101] op_sel_hi:[1,0]
	v_pk_mul_f32 v[90:91], v[90:91], v[100:101] op_sel_hi:[1,0]
	v_cvt_pk_bf16_f32 v84, v84, v85
	v_cvt_pk_bf16_f32 v85, v86, v87
	v_cvt_pk_bf16_f32 v86, v88, v89
	v_mad_i64_i32 v[88:89], s[16:17], v104, s52, v[130:131]
	v_cvt_pk_bf16_f32 v87, v90, v91
	v_lshl_add_u64 v[90:91], v[88:89], 0, v[132:133]
	v_lshl_add_u64 v[90:91], v[90:91], 0, v[176:177]
	v_lshl_add_u64 v[88:89], v[88:89], 0, v[116:117]
	global_store_dwordx4 v[90:91], v[84:87], off
	v_lshl_add_u64 v[88:89], v[88:89], 0, v[176:177]
	v_pk_mul_f32 v[90:91], v[98:99], v[100:101] op_sel_hi:[1,0]
	v_pk_mul_f32 v[86:87], v[94:95], v[100:101] op_sel_hi:[1,0]
	v_pk_mul_f32 v[84:85], v[92:93], v[100:101] op_sel_hi:[1,0]
	v_pk_mul_f32 v[92:93], v[96:97], v[100:101] op_sel_hi:[1,0]
	v_cvt_pk_bf16_f32 v84, v84, v85
	v_cvt_pk_bf16_f32 v85, v86, v87
	s_nop 0
	v_cvt_pk_bf16_f32 v86, v92, v93
	v_cvt_pk_bf16_f32 v87, v90, v91
	global_store_dwordx4 v[88:89], v[84:87], off
	v_or_b32_e32 v88, 48, v128
	v_ashrrev_i32_e32 v89, 31, v88
	v_lshlrev_b64 v[84:85], 6, v[88:89]
	v_lshl_add_u64 v[84:85], s[18:19], 0, v[84:85]
	v_mov_b32_e32 v84, v206
	v_mov_b32_e32 v85, v207
	v_mov_b32_e32 v86, v208
	v_mov_b32_e32 v87, v209
	v_mov_b32_e32 v90, v85
	v_mov_b32_e32 v91, v86
	v_mov_b32_e32 v85, v87
	v_pk_add_f32 v[84:85], v[90:91], v[84:85]
	s_nop 0
	v_add_f32_e32 v84, v84, v85
	v_fmamk_f32 v84, v84, 0x3b800000, v252
	v_cmp_gt_f32_e32 vcc, s53, v84
	v_mul_f32_e32 v85, 0x4b800000, v84
	s_nop 0
	v_cndmask_b32_e32 v84, v84, v85, vcc
	v_rsq_f32_e32 v84, v84
	s_nop 0
	v_mul_f32_e32 v85, 0x45800000, v84
	v_cndmask_b32_e32 v84, v84, v85, vcc
	v_pk_mul_f32 v[70:71], v[70:71], v[84:85] op_sel_hi:[1,0]
	v_pk_mul_f32 v[68:69], v[68:69], v[84:85] op_sel_hi:[1,0]
	v_pk_mul_f32 v[72:73], v[72:73], v[84:85] op_sel_hi:[1,0]
	v_pk_mul_f32 v[74:75], v[74:75], v[84:85] op_sel_hi:[1,0]
	v_cvt_pk_bf16_f32 v68, v68, v69
	v_cvt_pk_bf16_f32 v69, v70, v71
	v_cvt_pk_bf16_f32 v70, v72, v73
	v_mad_i64_i32 v[72:73], s[16:17], v88, s52, v[130:131]
	v_cvt_pk_bf16_f32 v71, v74, v75
	v_lshl_add_u64 v[74:75], v[72:73], 0, v[132:133]
	v_lshl_add_u64 v[74:75], v[74:75], 0, v[176:177]
	v_lshl_add_u64 v[72:73], v[72:73], 0, v[116:117]
	global_store_dwordx4 v[74:75], v[68:71], off
	v_lshl_add_u64 v[72:73], v[72:73], 0, v[176:177]
	v_pk_mul_f32 v[74:75], v[82:83], v[84:85] op_sel_hi:[1,0]
	v_pk_mul_f32 v[70:71], v[78:79], v[84:85] op_sel_hi:[1,0]
	v_pk_mul_f32 v[68:69], v[76:77], v[84:85] op_sel_hi:[1,0]
	v_pk_mul_f32 v[76:77], v[80:81], v[84:85] op_sel_hi:[1,0]
	v_cvt_pk_bf16_f32 v68, v68, v69
	v_cvt_pk_bf16_f32 v69, v70, v71
	s_nop 0
	v_cvt_pk_bf16_f32 v70, v76, v77
	v_cvt_pk_bf16_f32 v71, v74, v75
	global_store_dwordx4 v[72:73], v[68:71], off
	v_add_u32_e32 v72, 0x80, v128
	v_ashrrev_i32_e32 v73, 31, v72
	v_lshlrev_b64 v[68:69], 6, v[72:73]
	v_lshl_add_u64 v[68:69], s[18:19], 0, v[68:69]
	v_mov_b32_e32 v68, v218
	v_mov_b32_e32 v69, v219
	v_mov_b32_e32 v70, v220
	v_mov_b32_e32 v71, v221
	v_mov_b32_e32 v74, v69
	v_mov_b32_e32 v75, v70
	v_mov_b32_e32 v69, v71
	v_pk_add_f32 v[68:69], v[74:75], v[68:69]
	s_nop 0
	v_add_f32_e32 v68, v68, v69
	v_fmamk_f32 v68, v68, 0x3b800000, v252
	v_cmp_gt_f32_e32 vcc, s53, v68
	v_mul_f32_e32 v69, 0x4b800000, v68
	s_nop 0
	v_cndmask_b32_e32 v68, v68, v69, vcc
	v_rsq_f32_e32 v68, v68
	s_nop 0
	v_mul_f32_e32 v69, 0x45800000, v68
	v_cndmask_b32_e32 v68, v68, v69, vcc
	v_pk_mul_f32 v[54:55], v[54:55], v[68:69] op_sel_hi:[1,0]
	v_pk_mul_f32 v[52:53], v[52:53], v[68:69] op_sel_hi:[1,0]
	v_pk_mul_f32 v[56:57], v[56:57], v[68:69] op_sel_hi:[1,0]
	v_pk_mul_f32 v[58:59], v[58:59], v[68:69] op_sel_hi:[1,0]
	v_cvt_pk_bf16_f32 v52, v52, v53
	v_cvt_pk_bf16_f32 v53, v54, v55
	v_cvt_pk_bf16_f32 v54, v56, v57
; __device__ __forceinline__ u32x4 pack8(f32x4 a, f32x4 b) { u32x4 r; r[0] = cvt_pk_bf16(a[0], a[1]); r[1] = cvt_pk_bf16(a[2], a[3]); r[2] = cvt_pk_bf16(b[0], b[1]); r[3] = cvt_pk_bf16(b[2], b[3]); return r; }
; __device__ __forceinline__ int lane_id_asm() { int x; asm volatile("v_mbcnt_lo_u32_b32 %0, -1, 0\n\tv_mbcnt_hi_u32_b32 %0, -1, %0" : "=&v"(x)); return x; }
; template <class Epi, class Sched>
; __device__ __forceinline__ void gemm_phase(int wv, LAS unsigned char* lds, const Gemm g, const Sched& S, const Epi& E) { LIDS
;     ...
;         { const int l2 = lane_id_asm(); E(acc, cur, wr, wc, l2 & 15, l2 >> 4); }
;         if (!has_next) break;
;     __device__ __forceinline__ void operator()(const AccT& acc, const Unit& u, int wr, int wc, int fr, int fq) const {
;     ...
;         for (int ai = 0; ai < 2; ++ai)
; #pragma unroll
;             for (int m = 0; m < 4; ++m) {
;                 const int row = row0 + ai * HALF + m * 16;
;                 const f32x4 pc = *(const f32x4*)(ssp + (size_t)row * 16 + 8);
;                 const float sc = rsqrtf(((pc[0] + pc[1]) + (pc[2] + pc[3])) * (1.0f / 256.0f) + EPS);
; #pragma unroll
;                 for (int bj = 0; bj < 2; ++bj) {
;                     const int col = colbase + bj * HALF, head = col >> 7, d = col & 127;
;                     *(u32x4*)(Kf + (size_t)row * NKF + head * 192 + d) = pack8(acc[ai][bj][m][0] * sc, acc[ai][bj][m][1] * sc);
;                 }
	v_mad_i64_i32 v[56:57], s[16:17], v72, s52, v[130:131]
	v_cvt_pk_bf16_f32 v55, v58, v59
	v_lshl_add_u64 v[58:59], v[56:57], 0, v[132:133]
	v_lshl_add_u64 v[58:59], v[58:59], 0, v[176:177]
	v_lshl_add_u64 v[56:57], v[56:57], 0, v[116:117]
	global_store_dwordx4 v[58:59], v[52:55], off
	v_lshl_add_u64 v[56:57], v[56:57], 0, v[176:177]
	v_pk_mul_f32 v[58:59], v[66:67], v[68:69] op_sel_hi:[1,0]
	v_pk_mul_f32 v[54:55], v[62:63], v[68:69] op_sel_hi:[1,0]
	v_pk_mul_f32 v[52:53], v[60:61], v[68:69] op_sel_hi:[1,0]
	v_pk_mul_f32 v[60:61], v[64:65], v[68:69] op_sel_hi:[1,0]
	v_cvt_pk_bf16_f32 v52, v52, v53
	v_cvt_pk_bf16_f32 v53, v54, v55
	s_nop 0
	v_cvt_pk_bf16_f32 v54, v60, v61
	v_cvt_pk_bf16_f32 v55, v58, v59
	global_store_dwordx4 v[56:57], v[52:55], off
	v_add_u32_e32 v56, 0x90, v128
	v_ashrrev_i32_e32 v57, 31, v56
	v_lshlrev_b64 v[52:53], 6, v[56:57]
	v_lshl_add_u64 v[52:53], s[18:19], 0, v[52:53]
	v_mov_b32_e32 v52, v222
	v_mov_b32_e32 v53, v223
	v_mov_b32_e32 v54, v224
	v_mov_b32_e32 v55, v225
	v_mov_b32_e32 v58, v53
	v_mov_b32_e32 v59, v54
	v_mov_b32_e32 v53, v55
	v_pk_add_f32 v[52:53], v[58:59], v[52:53]
	s_nop 0
	v_add_f32_e32 v52, v52, v53
	v_fmamk_f32 v52, v52, 0x3b800000, v252
	v_cmp_gt_f32_e32 vcc, s53, v52
	v_mul_f32_e32 v53, 0x4b800000, v52
	s_nop 0
	v_cndmask_b32_e32 v52, v52, v53, vcc
	v_rsq_f32_e32 v52, v52
	s_nop 0
	v_mul_f32_e32 v53, 0x45800000, v52
	v_cndmask_b32_e32 v52, v52, v53, vcc
	v_pk_mul_f32 v[38:39], v[38:39], v[52:53] op_sel_hi:[1,0]
	v_pk_mul_f32 v[36:37], v[36:37], v[52:53] op_sel_hi:[1,0]
	v_pk_mul_f32 v[40:41], v[40:41], v[52:53] op_sel_hi:[1,0]
	v_pk_mul_f32 v[42:43], v[42:43], v[52:53] op_sel_hi:[1,0]
	v_cvt_pk_bf16_f32 v36, v36, v37
	v_cvt_pk_bf16_f32 v37, v38, v39
	v_cvt_pk_bf16_f32 v38, v40, v41
	v_mad_i64_i32 v[40:41], s[16:17], v56, s52, v[130:131]
	v_cvt_pk_bf16_f32 v39, v42, v43
	v_lshl_add_u64 v[42:43], v[40:41], 0, v[132:133]
	v_lshl_add_u64 v[42:43], v[42:43], 0, v[176:177]
	v_lshl_add_u64 v[40:41], v[40:41], 0, v[116:117]
	global_store_dwordx4 v[42:43], v[36:39], off
	v_lshl_add_u64 v[40:41], v[40:41], 0, v[176:177]
	v_pk_mul_f32 v[42:43], v[50:51], v[52:53] op_sel_hi:[1,0]
	v_pk_mul_f32 v[38:39], v[46:47], v[52:53] op_sel_hi:[1,0]
	v_pk_mul_f32 v[36:37], v[44:45], v[52:53] op_sel_hi:[1,0]
	v_pk_mul_f32 v[44:45], v[48:49], v[52:53] op_sel_hi:[1,0]
	v_cvt_pk_bf16_f32 v36, v36, v37
	v_cvt_pk_bf16_f32 v37, v38, v39
	s_nop 0
	v_cvt_pk_bf16_f32 v38, v44, v45
	v_cvt_pk_bf16_f32 v39, v42, v43
	global_store_dwordx4 v[40:41], v[36:39], off
	v_add_u32_e32 v40, 0xa0, v128
	v_ashrrev_i32_e32 v41, 31, v40
	v_lshlrev_b64 v[36:37], 6, v[40:41]
	v_lshl_add_u64 v[36:37], s[18:19], 0, v[36:37]
	v_mov_b32_e32 v36, v226
	v_mov_b32_e32 v37, v227
	v_mov_b32_e32 v38, v228
	v_mov_b32_e32 v39, v229
	v_mov_b32_e32 v42, v37
	v_mov_b32_e32 v43, v38
	v_mov_b32_e32 v37, v39
	v_pk_add_f32 v[36:37], v[42:43], v[36:37]
	s_nop 0
	v_add_f32_e32 v36, v36, v37
	v_fmamk_f32 v36, v36, 0x3b800000, v252
	v_cmp_gt_f32_e32 vcc, s53, v36
	v_mul_f32_e32 v37, 0x4b800000, v36
	s_nop 0
	v_cndmask_b32_e32 v36, v36, v37, vcc
	v_rsq_f32_e32 v36, v36
	s_nop 0
	v_mul_f32_e32 v37, 0x45800000, v36
	v_cndmask_b32_e32 v36, v36, v37, vcc
	v_pk_mul_f32 v[22:23], v[22:23], v[36:37] op_sel_hi:[1,0]
	v_pk_mul_f32 v[20:21], v[20:21], v[36:37] op_sel_hi:[1,0]
	v_pk_mul_f32 v[24:25], v[24:25], v[36:37] op_sel_hi:[1,0]
	v_pk_mul_f32 v[26:27], v[26:27], v[36:37] op_sel_hi:[1,0]
	v_cvt_pk_bf16_f32 v20, v20, v21
	v_cvt_pk_bf16_f32 v21, v22, v23
	v_cvt_pk_bf16_f32 v22, v24, v25
	v_mad_i64_i32 v[24:25], s[16:17], v40, s52, v[130:131]
	v_cvt_pk_bf16_f32 v23, v26, v27
	v_lshl_add_u64 v[26:27], v[24:25], 0, v[132:133]
	v_lshl_add_u64 v[26:27], v[26:27], 0, v[176:177]
	v_lshl_add_u64 v[24:25], v[24:25], 0, v[116:117]
	global_store_dwordx4 v[26:27], v[20:23], off
	v_lshl_add_u64 v[24:25], v[24:25], 0, v[176:177]
	v_pk_mul_f32 v[26:27], v[34:35], v[36:37] op_sel_hi:[1,0]
	v_pk_mul_f32 v[22:23], v[30:31], v[36:37] op_sel_hi:[1,0]
	v_pk_mul_f32 v[20:21], v[28:29], v[36:37] op_sel_hi:[1,0]
	v_pk_mul_f32 v[28:29], v[32:33], v[36:37] op_sel_hi:[1,0]
	v_cvt_pk_bf16_f32 v20, v20, v21
	v_cvt_pk_bf16_f32 v21, v22, v23
	s_nop 0
	v_cvt_pk_bf16_f32 v22, v28, v29
	v_cvt_pk_bf16_f32 v23, v26, v27
	global_store_dwordx4 v[24:25], v[20:23], off
	v_add_u32_e32 v24, 0xb0, v128
	v_ashrrev_i32_e32 v25, 31, v24
	v_lshlrev_b64 v[20:21], 6, v[24:25]
	v_lshl_add_u64 v[20:21], s[18:19], 0, v[20:21]
	v_mov_b32_e32 v20, v230
	v_mov_b32_e32 v21, v231
	v_mov_b32_e32 v22, v232
	v_mov_b32_e32 v23, v233
	v_mov_b32_e32 v26, v21
	v_mov_b32_e32 v27, v22
	v_mov_b32_e32 v21, v23
	v_pk_add_f32 v[20:21], v[26:27], v[20:21]
	s_nop 0
	v_add_f32_e32 v20, v20, v21
	v_fmamk_f32 v20, v20, 0x3b800000, v252
	v_cmp_gt_f32_e32 vcc, s53, v20
	v_mul_f32_e32 v21, 0x4b800000, v20
	s_nop 0
	v_cndmask_b32_e32 v20, v20, v21, vcc
	v_rsq_f32_e32 v20, v20
	s_nop 0
	v_mul_f32_e32 v21, 0x45800000, v20
	v_cndmask_b32_e32 v20, v20, v21, vcc
	v_pk_mul_f32 v[6:7], v[6:7], v[20:21] op_sel_hi:[1,0]
	v_pk_mul_f32 v[4:5], v[4:5], v[20:21] op_sel_hi:[1,0]
	v_pk_mul_f32 v[8:9], v[8:9], v[20:21] op_sel_hi:[1,0]
	v_pk_mul_f32 v[10:11], v[10:11], v[20:21] op_sel_hi:[1,0]
	v_cvt_pk_bf16_f32 v4, v4, v5
	v_cvt_pk_bf16_f32 v5, v6, v7
	v_cvt_pk_bf16_f32 v6, v8, v9
	v_mad_i64_i32 v[8:9], s[16:17], v24, s52, v[130:131]
	v_cvt_pk_bf16_f32 v7, v10, v11
	v_lshl_add_u64 v[10:11], v[8:9], 0, v[132:133]
	v_lshl_add_u64 v[10:11], v[10:11], 0, v[176:177]
	v_lshl_add_u64 v[8:9], v[8:9], 0, v[116:117]
	global_store_dwordx4 v[10:11], v[4:7], off
	v_lshl_add_u64 v[8:9], v[8:9], 0, v[176:177]
	s_andn2_b64 vcc, exec, s[4:5]
	v_pk_mul_f32 v[6:7], v[14:15], v[20:21] op_sel_hi:[1,0]
	v_pk_mul_f32 v[4:5], v[12:13], v[20:21] op_sel_hi:[1,0]
	s_mov_b32 s16, s8
	v_readlane_b32 s4, v254, 46
	v_pk_mul_f32 v[10:11], v[18:19], v[20:21] op_sel_hi:[1,0]
	v_pk_mul_f32 v[12:13], v[16:17], v[20:21] op_sel_hi:[1,0]
	v_cvt_pk_bf16_f32 v4, v4, v5
	v_cvt_pk_bf16_f32 v5, v6, v7
	v_readlane_b32 s5, v254, 47
	v_cvt_pk_bf16_f32 v6, v12, v13
	v_cvt_pk_bf16_f32 v7, v10, v11
	global_store_dwordx4 v[8:9], v[4:7], off
	s_cbranch_vccz .LBB0_174

; #define PG8_STAGE(bufoff, gbase, voff) do { _Pragma("unroll") for (int _i = 0; _i < 2; ++_i) { const char* _gb = (const char*)(gbase) + (size_t)_i * (voff##_q); asm volatile("" : "+s"(_gb)); \
;         __builtin_amdgcn_global_load_lds((const unsigned*)(_gb + (voff)), (LAS unsigned*)(lds + (bufoff) + ldsw + _i * 8192), 16, 0, 0); } } while (0)
; #define PG8_LDA(dst, b, h) do { _Pragma("unroll") for (int m = 0; m < 4; ++m) _Pragma("unroll") for (int k = 0; k < 2; ++k) dst[m][k] = *(const LAS bf16x8*)(lds + PG8_SA(b, h) + aoff + m * 2048 + k * 1024); } while (0)
; #define PG8_LDB(dst, b, h) do { _Pragma("unroll") for (int n = 0; n < 2; ++n) _Pragma("unroll") for (int k = 0; k < 2; ++k) dst[n][k] = *(const LAS bf16x8*)(lds + PG8_SB(b, h) + boff + n * 2048 + k * 1024); } while (0)
; #define PG8_WAIT_V(n) asm volatile("s_waitcnt vmcnt(" #n ")" ::: "memory")
; #define PG8_WAIT_L(n) asm volatile("s_waitcnt lgkmcnt(" #n ")" ::: "memory")
; template <class Epi, class Sched>
; __device__ __forceinline__ void gemm_phase(int wv, LAS unsigned char* lds, const Gemm g, const Sched& S, const Epi& E) { LIDS
;     ...
;         const bool has_next = S.next(ui + 1, nxt);
;         const char* nA = has_next ? (const char*)g.A + (size_t)nxt.pm * g.tstepA : cA; const char* nB = has_next ? (const char*)g.Bt + (size_t)nxt.pn * g.tstepB : cB;
;         for (int t = 0; t < nt; t += 2) {
;             const bool last = (t == nt - 2);
;             const char* a1 = cA + (size_t)(t + 1) * kstepA;
;             const char* a2 = last ? nA : cA + (size_t)(t + 2) * kstepA; const char* b2 = last ? nB : cB + (size_t)(t + 2) * kstepB;
;             const char* a3 = a2 + kstepA; const char* b3 = b2 + kstepB;
;             asm volatile("" : "+s"(a1), "+s"(a2), "+s"(b2), "+s"(a3), "+s"(b3));
;             PG8_LDB(B0, 0, 0); PG8_SCHED; PG8_LDA(At, 0, 0); PG8_STAGE(PG8_SA(1, 1), a1 + hstepA, voffA);
;             PG8_WAIT_L(8); PG8_BAR; PG8_WAIT_L(0); PG8_MMA(0, 0, At, B0); PG8_BAR; PG8_SCHED;
;             PG8_LDB(B1, 0, 1); PG8_STAGE(PG8_SB(0, 0), b2, voffB);
;             PG8_BAR; PG8_WAIT_L(0); PG8_MMA(0, 1, At, B1); PG8_BAR;
;             PG8_LDA(At, 0, 1); PG8_STAGE(PG8_SA(0, 0), a2, voffA);
;             PG8_BAR; PG8_WAIT_L(0); PG8_MMA(1, 0, At, B0); PG8_BAR; PG8_SCHED;
;             PG8_STAGE(PG8_SB(0, 1), b2 + hstepB, voffB);
;             PG8_WAIT_V(6); PG8_BAR; PG8_MMA(1, 1, At, B1); PG8_BAR;
.LBB0_186:
	s_ashr_i32 s13, s12, 31
	s_lshl_b64 s[28:29], s[12:13], 17
	v_readlane_b32 s30, v253, 20
	v_mov_b64_e32 v[4:5], 0x100
	v_readlane_b32 s31, v253, 21
	s_add_u32 s62, s30, s28
	v_cmp_lt_i64_e32 vcc, s[8:9], v[4:5]
	s_addc_u32 s63, s31, s29
	s_and_b64 s[28:29], vcc, exec
	s_cselect_b32 s73, s63, s87
	s_cselect_b32 s72, s62, s86
	s_ashr_i32 s11, s10, 31
	s_lshl_b64 s[28:29], s[10:11], 21
	v_readlane_b32 s11, v253, 16
	s_add_u32 s68, s11, s28
	v_readlane_b32 s11, v253, 17
	s_addc_u32 s69, s11, s29
	s_and_b64 s[28:29], vcc, exec
	s_cselect_b32 s79, s69, s91
	s_cselect_b32 s78, s68, s90
	s_add_u32 s28, s86, 0x80
	s_addc_u32 s29, s87, 0
	s_add_u32 s88, s86, 0x100
	s_addc_u32 s89, s87, 0
	s_add_u32 s94, s90, 0x100
	s_addc_u32 s95, s91, 0
	s_add_u32 s86, s86, 0x180
	s_addc_u32 s87, s87, 0
	s_add_u32 s90, s90, 0x180
	s_addc_u32 s91, s91, 0
	s_add_i32 s13, 16, 0x10000
	s_mov_b64 s[84:85], s[86:87]
	v_add_u32_e32 v174, s13, v156
	ds_read_b128 v[4:7], v174
	ds_read_b128 v[8:11], v174 offset:1024
	ds_read_b128 v[12:15], v174 offset:2048
	ds_read_b128 v[16:19], v174 offset:3072
	s_add_u32 s30, s28, 0x10000
	s_addc_u32 s31, s29, 0
	s_add_i32 s52, s18, 0xc000
	s_add_u32 s28, s28, 0x18000
	ds_read_b128 v[20:23], v157
	ds_read_b128 v[24:27], v157 offset:1024
	ds_read_b128 v[28:31], v157 offset:2048
	ds_read_b128 v[32:35], v157 offset:3072
	ds_read_b128 v[36:39], v157 offset:4096
	ds_read_b128 v[40:43], v157 offset:5120
	ds_read_b128 v[44:47], v157 offset:6144
	ds_read_b128 v[48:51], v157 offset:7168
	s_mov_b32 m0, s52
	v_lshl_add_u64 v[52:53], s[30:31], 0, v[140:141]
	s_addc_u32 s29, s29, 0
	s_add_i32 s11, s18, 0xe000
	global_load_lds_dwordx4 v[52:53], off
	s_mov_b32 m0, s11
	v_lshl_add_u64 v[52:53], s[28:29], 0, v[140:141]
	global_load_lds_dwordx4 v[52:53], off
	s_waitcnt lgkmcnt(8)
	s_barrier
	s_waitcnt lgkmcnt(0)
	s_setprio 1
	v_mfma_f32_16x16x32_bf16 v[52:55], v[4:7], v[20:23], v[0:3]
	v_mfma_f32_16x16x32_bf16 v[56:59], v[12:15], v[20:23], v[0:3]
	v_mfma_f32_16x16x32_bf16 v[60:63], v[4:7], v[28:31], v[0:3]
	v_mfma_f32_16x16x32_bf16 v[64:67], v[12:15], v[28:31], v[0:3]
	v_mfma_f32_16x16x32_bf16 v[68:71], v[4:7], v[36:39], v[0:3]
	v_mfma_f32_16x16x32_bf16 v[72:75], v[12:15], v[36:39], v[0:3]
	v_mfma_f32_16x16x32_bf16 v[76:79], v[4:7], v[44:47], v[0:3]
	v_mfma_f32_16x16x32_bf16 v[80:83], v[12:15], v[44:47], v[0:3]
	v_mfma_f32_16x16x32_bf16 v[52:55], v[8:11], v[24:27], v[52:55]
	v_mfma_f32_16x16x32_bf16 v[56:59], v[16:19], v[24:27], v[56:59]
	v_mfma_f32_16x16x32_bf16 v[60:63], v[8:11], v[32:35], v[60:63]
	v_mfma_f32_16x16x32_bf16 v[64:67], v[16:19], v[32:35], v[64:67]
	v_mfma_f32_16x16x32_bf16 v[68:71], v[8:11], v[40:43], v[68:71]
	v_mfma_f32_16x16x32_bf16 v[72:75], v[16:19], v[40:43], v[72:75]
	v_mfma_f32_16x16x32_bf16 v[76:79], v[8:11], v[48:51], v[76:79]
	v_mfma_f32_16x16x32_bf16 v[80:83], v[16:19], v[48:51], v[80:83]
	s_setprio 0
	s_barrier
	s_add_i32 s31, 16, 0x14000
	v_add_u32_e32 v175, s31, v156
	s_mov_b64 s[28:29], s[94:95]
	ds_read_b128 v[84:87], v175
	ds_read_b128 v[88:91], v175 offset:1024
	ds_read_b128 v[92:95], v175 offset:2048
	ds_read_b128 v[96:99], v175 offset:3072
	s_add_i32 s30, s13, s17
	v_lshl_add_u64 v[100:101], s[28:29], 0, v[176:177]
	s_add_u32 s28, s94, 0x80000
	s_mov_b32 m0, s30
	s_addc_u32 s29, s95, 0
	s_add_i32 s13, s30, 0x2000
	global_load_lds_dwordx4 v[100:101], off
	s_mov_b32 m0, s13
	v_lshl_add_u64 v[100:101], s[28:29], 0, v[176:177]
	global_load_lds_dwordx4 v[100:101], off
	s_barrier
	s_waitcnt lgkmcnt(0)
	s_setprio 1
	v_mfma_f32_16x16x32_bf16 v[100:103], v[84:87], v[20:23], v[0:3]
	v_mfma_f32_16x16x32_bf16 v[20:23], v[92:95], v[20:23], v[0:3]
	v_mfma_f32_16x16x32_bf16 v[100:103], v[88:91], v[24:27], v[100:103]
	v_mfma_f32_16x16x32_bf16 v[20:23], v[96:99], v[24:27], v[20:23]
	v_mfma_f32_16x16x32_bf16 v[24:27], v[84:87], v[28:31], v[0:3]
	v_mfma_f32_16x16x32_bf16 v[28:31], v[92:95], v[28:31], v[0:3]
	v_mfma_f32_16x16x32_bf16 v[24:27], v[88:91], v[32:35], v[24:27]
	v_mfma_f32_16x16x32_bf16 v[28:31], v[96:99], v[32:35], v[28:31]
	v_mfma_f32_16x16x32_bf16 v[32:35], v[84:87], v[36:39], v[0:3]
	v_mfma_f32_16x16x32_bf16 v[36:39], v[92:95], v[36:39], v[0:3]
	v_mfma_f32_16x16x32_bf16 v[32:35], v[88:91], v[40:43], v[32:35]
	v_mfma_f32_16x16x32_bf16 v[36:39], v[96:99], v[40:43], v[36:39]
	v_mfma_f32_16x16x32_bf16 v[40:43], v[84:87], v[44:47], v[0:3]
	v_mfma_f32_16x16x32_bf16 v[44:47], v[92:95], v[44:47], v[0:3]
	v_mfma_f32_16x16x32_bf16 v[40:43], v[88:91], v[48:51], v[40:43]
	v_mfma_f32_16x16x32_bf16 v[44:47], v[96:99], v[48:51], v[44:47]
	s_setprio 0
	s_mov_b64 s[28:29], s[88:89]
	s_barrier
	ds_read_b128 v[48:51], v157 offset:16384
	ds_read_b128 v[104:107], v157 offset:17408
	ds_read_b128 v[108:111], v157 offset:18432
	ds_read_b128 v[112:115], v157 offset:19456
	ds_read_b128 v[116:119], v157 offset:20480
	ds_read_b128 v[120:123], v157 offset:21504
	ds_read_b128 v[124:127], v157 offset:22528
	ds_read_b128 v[128:131], v157 offset:23552
	s_mov_b32 m0, s18
	v_lshl_add_u64 v[132:133], s[28:29], 0, v[140:141]
	s_add_u32 s28, s88, 0x8000
	s_addc_u32 s29, s89, 0
	global_load_lds_dwordx4 v[132:133], off
	s_mov_b32 m0, s19
	v_lshl_add_u64 v[132:133], s[28:29], 0, v[140:141]
	global_load_lds_dwordx4 v[132:133], off
	s_barrier
; #define PG8_STAGE(bufoff, gbase, voff) do { _Pragma("unroll") for (int _i = 0; _i < 2; ++_i) { const char* _gb = (const char*)(gbase) + (size_t)_i * (voff##_q); asm volatile("" : "+s"(_gb)); \
;         __builtin_amdgcn_global_load_lds((const unsigned*)(_gb + (voff)), (LAS unsigned*)(lds + (bufoff) + ldsw + _i * 8192), 16, 0, 0); } } while (0)
; #define PG8_LDA(dst, b, h) do { _Pragma("unroll") for (int m = 0; m < 4; ++m) _Pragma("unroll") for (int k = 0; k < 2; ++k) dst[m][k] = *(const LAS bf16x8*)(lds + PG8_SA(b, h) + aoff + m * 2048 + k * 1024); } while (0)
; #define PG8_LDB(dst, b, h) do { _Pragma("unroll") for (int n = 0; n < 2; ++n) _Pragma("unroll") for (int k = 0; k < 2; ++k) dst[n][k] = *(const LAS bf16x8*)(lds + PG8_SB(b, h) + boff + n * 2048 + k * 1024); } while (0)
; #define PG8_MMA(ai, bj, At, Bt) do { __builtin_amdgcn_s_setprio(1); _Pragma("unroll") for (int m = 0; m < 4; ++m) _Pragma("unroll") for (int n = 0; n < 2; ++n) _Pragma("unroll") for (int k = 0; k < 2; ++k) \
;         acc[ai][bj][m][n] = __builtin_amdgcn_mfma_f32_16x16x32_bf16(Bt[n][k], At[m][k], acc[ai][bj][m][n], 0, 0, 0); __builtin_amdgcn_s_setprio(0); } while (0)
; #define PG8_WAIT_V(n) asm volatile("s_waitcnt vmcnt(" #n ")" ::: "memory")
; #define PG8_WAIT_L(n) asm volatile("s_waitcnt lgkmcnt(" #n ")" ::: "memory")
; template <class Epi, class Sched>
; __device__ __forceinline__ void gemm_phase(int wv, LAS unsigned char* lds, const Gemm g, const Sched& S, const Epi& E) { LIDS
;     ...
;             PG8_LDB(B1, 0, 1); PG8_STAGE(PG8_SB(0, 0), b2, voffB);
;             PG8_BAR; PG8_WAIT_L(0); PG8_MMA(0, 1, At, B1); PG8_BAR;
;             PG8_LDA(At, 0, 1); PG8_STAGE(PG8_SA(0, 0), a2, voffA);
;             PG8_BAR; PG8_WAIT_L(0); PG8_MMA(1, 0, At, B0); PG8_BAR; PG8_SCHED;
;             PG8_STAGE(PG8_SB(0, 1), b2 + hstepB, voffB);
;             PG8_WAIT_V(6); PG8_BAR; PG8_MMA(1, 1, At, B1); PG8_BAR;
;             PG8_LDB(B0, 1, 0); PG8_SCHED; PG8_LDA(At, 1, 0); PG8_STAGE(PG8_SA(0, 1), a2 + hstepA, voffA);
;             PG8_WAIT_L(8); PG8_BAR; PG8_WAIT_L(0); PG8_MMA(0, 0, At, B0); PG8_BAR; PG8_SCHED;
;             PG8_LDB(B1, 1, 1); PG8_STAGE(PG8_SB(1, 0), b3, voffB);
;             PG8_BAR; PG8_WAIT_L(0); PG8_MMA(0, 1, At, B1); PG8_BAR;
;             PG8_LDA(At, 1, 1); PG8_STAGE(PG8_SA(1, 0), a3, voffA);
;             PG8_BAR; PG8_WAIT_L(0); PG8_MMA(1, 0, At, B0); PG8_BAR; PG8_SCHED;
	s_waitcnt lgkmcnt(0)
	s_setprio 1
	v_mfma_f32_16x16x32_bf16 v[132:135], v[4:7], v[48:51], v[0:3]
	v_mfma_f32_16x16x32_bf16 v[142:145], v[4:7], v[108:111], v[0:3]
	v_mfma_f32_16x16x32_bf16 v[150:153], v[4:7], v[116:119], v[0:3]
	v_mfma_f32_16x16x32_bf16 v[4:7], v[4:7], v[124:127], v[0:3]
	v_mfma_f32_16x16x32_bf16 v[132:135], v[8:11], v[104:107], v[132:135]
	v_mfma_f32_16x16x32_bf16 v[136:139], v[12:15], v[48:51], v[0:3]
	v_mfma_f32_16x16x32_bf16 v[142:145], v[8:11], v[112:115], v[142:145]
	v_mfma_f32_16x16x32_bf16 v[146:149], v[12:15], v[108:111], v[0:3]
	v_mfma_f32_16x16x32_bf16 v[150:153], v[8:11], v[120:123], v[150:153]
	v_mfma_f32_16x16x32_bf16 v[158:161], v[12:15], v[116:119], v[0:3]
	v_mfma_f32_16x16x32_bf16 v[4:7], v[8:11], v[128:131], v[4:7]
	v_mfma_f32_16x16x32_bf16 v[8:11], v[12:15], v[124:127], v[0:3]
	v_mfma_f32_16x16x32_bf16 v[136:139], v[16:19], v[104:107], v[136:139]
	v_mfma_f32_16x16x32_bf16 v[146:149], v[16:19], v[112:115], v[146:149]
	v_mfma_f32_16x16x32_bf16 v[158:161], v[16:19], v[120:123], v[158:161]
	v_mfma_f32_16x16x32_bf16 v[8:11], v[16:19], v[128:131], v[8:11]
	s_setprio 0
	s_barrier
	s_add_u32 s28, s94, 0x100000
	s_addc_u32 s29, s95, 0
	s_add_i32 s31, s31, s17
	v_lshl_add_u64 v[12:13], s[28:29], 0, v[176:177]
	s_add_u32 s28, s94, 0x180000
	s_mov_b32 m0, s31
	s_addc_u32 s29, s95, 0
	s_add_i32 s27, s31, 0x2000
	global_load_lds_dwordx4 v[12:13], off
	s_mov_b32 m0, s27
	v_lshl_add_u64 v[12:13], s[28:29], 0, v[176:177]
	global_load_lds_dwordx4 v[12:13], off
	s_waitcnt vmcnt(6)
	s_barrier
	s_setprio 1
	v_mfma_f32_16x16x32_bf16 v[12:15], v[84:87], v[48:51], v[0:3]
	v_mfma_f32_16x16x32_bf16 v[16:19], v[92:95], v[48:51], v[0:3]
	v_mfma_f32_16x16x32_bf16 v[12:15], v[88:91], v[104:107], v[12:15]
	v_mfma_f32_16x16x32_bf16 v[16:19], v[96:99], v[104:107], v[16:19]
	v_mfma_f32_16x16x32_bf16 v[48:51], v[84:87], v[108:111], v[0:3]
	v_mfma_f32_16x16x32_bf16 v[104:107], v[92:95], v[108:111], v[0:3]
	v_mfma_f32_16x16x32_bf16 v[108:111], v[84:87], v[116:119], v[0:3]
	v_mfma_f32_16x16x32_bf16 v[84:87], v[84:87], v[124:127], v[0:3]
	v_mfma_f32_16x16x32_bf16 v[48:51], v[88:91], v[112:115], v[48:51]
	v_mfma_f32_16x16x32_bf16 v[104:107], v[96:99], v[112:115], v[104:107]
	v_mfma_f32_16x16x32_bf16 v[108:111], v[88:91], v[120:123], v[108:111]
	v_mfma_f32_16x16x32_bf16 v[112:115], v[92:95], v[116:119], v[0:3]
	v_mfma_f32_16x16x32_bf16 v[84:87], v[88:91], v[128:131], v[84:87]
	v_mfma_f32_16x16x32_bf16 v[88:91], v[92:95], v[124:127], v[0:3]
	v_mfma_f32_16x16x32_bf16 v[112:115], v[96:99], v[120:123], v[112:115]
	v_mfma_f32_16x16x32_bf16 v[88:91], v[96:99], v[128:131], v[88:91]
	s_setprio 0
	s_add_i32 s55, 16, 0x18000
	v_add_u32_e32 v210, s55, v156
	s_barrier
	ds_read_b128 v[92:95], v210
	ds_read_b128 v[96:99], v210 offset:1024
	ds_read_b128 v[116:119], v210 offset:2048
	ds_read_b128 v[120:123], v210 offset:3072
	s_add_u32 s28, s88, 0x10000
	s_addc_u32 s29, s89, 0
	ds_read_b128 v[124:127], v157 offset:32768
	ds_read_b128 v[128:131], v157 offset:33792
	ds_read_b128 v[162:165], v157 offset:34816
	ds_read_b128 v[166:169], v157 offset:35840
	ds_read_b128 v[170:173], v157 offset:36864
	ds_read_b128 v[178:181], v157 offset:37888
	ds_read_b128 v[182:185], v157 offset:38912
	ds_read_b128 v[186:189], v157 offset:39936
	s_mov_b32 m0, s20
	v_lshl_add_u64 v[154:155], s[28:29], 0, v[140:141]
	s_add_u32 s28, s88, 0x18000
	s_addc_u32 s29, s89, 0
	global_load_lds_dwordx4 v[154:155], off
	s_mov_b32 m0, s21
	v_lshl_add_u64 v[154:155], s[28:29], 0, v[140:141]
	global_load_lds_dwordx4 v[154:155], off
	s_waitcnt lgkmcnt(8)
	s_barrier
	s_waitcnt lgkmcnt(0)
	s_setprio 1
	v_mfma_f32_16x16x32_bf16 v[52:55], v[92:95], v[124:127], v[52:55]
	v_mfma_f32_16x16x32_bf16 v[56:59], v[116:119], v[124:127], v[56:59]
	v_mfma_f32_16x16x32_bf16 v[60:63], v[92:95], v[162:165], v[60:63]
	v_mfma_f32_16x16x32_bf16 v[64:67], v[116:119], v[162:165], v[64:67]
	v_mfma_f32_16x16x32_bf16 v[68:71], v[92:95], v[170:173], v[68:71]
	v_mfma_f32_16x16x32_bf16 v[72:75], v[116:119], v[170:173], v[72:75]
	v_mfma_f32_16x16x32_bf16 v[76:79], v[92:95], v[182:185], v[76:79]
	v_mfma_f32_16x16x32_bf16 v[80:83], v[116:119], v[182:185], v[80:83]
	v_mfma_f32_16x16x32_bf16 v[52:55], v[96:99], v[128:131], v[52:55]
	v_mfma_f32_16x16x32_bf16 v[56:59], v[120:123], v[128:131], v[56:59]
	v_mfma_f32_16x16x32_bf16 v[60:63], v[96:99], v[166:169], v[60:63]
	v_mfma_f32_16x16x32_bf16 v[64:67], v[120:123], v[166:169], v[64:67]
	v_mfma_f32_16x16x32_bf16 v[68:71], v[96:99], v[178:181], v[68:71]
	v_mfma_f32_16x16x32_bf16 v[72:75], v[120:123], v[178:181], v[72:75]
	v_mfma_f32_16x16x32_bf16 v[76:79], v[96:99], v[186:189], v[76:79]
	v_mfma_f32_16x16x32_bf16 v[80:83], v[120:123], v[186:189], v[80:83]
	s_setprio 0
	s_barrier
	s_add_i32 s58, 16, 0x1c000
	v_add_u32_e32 v211, s58, v156
	s_mov_b64 s[28:29], s[90:91]
	ds_read_b128 v[190:193], v211
	ds_read_b128 v[194:197], v211 offset:1024
	ds_read_b128 v[198:201], v211 offset:2048
	ds_read_b128 v[202:205], v211 offset:3072
	s_add_i32 s55, s55, s17
	v_lshl_add_u64 v[154:155], s[28:29], 0, v[176:177]
	s_add_u32 s28, s90, 0x80000
	s_mov_b32 m0, s55
	s_addc_u32 s29, s91, 0
	global_load_lds_dwordx4 v[154:155], off
	s_nop 0
	v_lshl_add_u64 v[154:155], s[28:29], 0, v[176:177]
	s_add_i32 s28, s55, 0x2000
	s_mov_b32 m0, s28
	s_nop 0
	global_load_lds_dwordx4 v[154:155], off
	s_barrier
; #define PG8_STAGE(bufoff, gbase, voff) do { _Pragma("unroll") for (int _i = 0; _i < 2; ++_i) { const char* _gb = (const char*)(gbase) + (size_t)_i * (voff##_q); asm volatile("" : "+s"(_gb)); \
;         __builtin_amdgcn_global_load_lds((const unsigned*)(_gb + (voff)), (LAS unsigned*)(lds + (bufoff) + ldsw + _i * 8192), 16, 0, 0); } } while (0)
; #define PG8_LDA(dst, b, h) do { _Pragma("unroll") for (int m = 0; m < 4; ++m) _Pragma("unroll") for (int k = 0; k < 2; ++k) dst[m][k] = *(const LAS bf16x8*)(lds + PG8_SA(b, h) + aoff + m * 2048 + k * 1024); } while (0)
; #define PG8_LDB(dst, b, h) do { _Pragma("unroll") for (int n = 0; n < 2; ++n) _Pragma("unroll") for (int k = 0; k < 2; ++k) dst[n][k] = *(const LAS bf16x8*)(lds + PG8_SB(b, h) + boff + n * 2048 + k * 1024); } while (0)
; #define PG8_WAIT_V(n) asm volatile("s_waitcnt vmcnt(" #n ")" ::: "memory")
; #define PG8_WAIT_L(n) asm volatile("s_waitcnt lgkmcnt(" #n ")" ::: "memory")
; template <class Epi, class Sched>
; __device__ __forceinline__ void gemm_phase(int wv, LAS unsigned char* lds, const Gemm g, const Sched& S, const Epi& E) { LIDS
;     ...
;             PG8_LDB(B0, 0, 0); PG8_SCHED; PG8_LDA(At, 0, 0); PG8_STAGE(PG8_SA(1, 1), a1 + hstepA, voffA);
;             PG8_WAIT_L(8); PG8_BAR; PG8_WAIT_L(0); PG8_MMA(0, 0, At, B0); PG8_BAR; PG8_SCHED;
;             PG8_LDB(B1, 0, 1); PG8_STAGE(PG8_SB(0, 0), b2, voffB);
;             PG8_BAR; PG8_WAIT_L(0); PG8_MMA(0, 1, At, B1); PG8_BAR;
;             PG8_LDA(At, 0, 1); PG8_STAGE(PG8_SA(0, 0), a2, voffA);
;             PG8_BAR; PG8_WAIT_L(0); PG8_MMA(1, 0, At, B0); PG8_BAR; PG8_SCHED;
;             PG8_STAGE(PG8_SB(0, 1), b2 + hstepB, voffB);
;             PG8_WAIT_V(6); PG8_BAR; PG8_MMA(1, 1, At, B1); PG8_BAR;
;             PG8_LDB(B0, 1, 0); PG8_SCHED; PG8_LDA(At, 1, 0); PG8_STAGE(PG8_SA(0, 1), a2 + hstepA, voffA);
;             PG8_WAIT_L(8); PG8_BAR; PG8_WAIT_L(0); PG8_MMA(0, 0, At, B0); PG8_BAR; PG8_SCHED;
;             PG8_LDB(B1, 1, 1); PG8_STAGE(PG8_SB(1, 0), b3, voffB);
;             PG8_BAR; PG8_WAIT_L(0); PG8_MMA(0, 1, At, B1); PG8_BAR;
;             PG8_LDA(At, 1, 1); PG8_STAGE(PG8_SA(1, 0), a3, voffA);
;             PG8_BAR; PG8_WAIT_L(0); PG8_MMA(1, 0, At, B0); PG8_BAR; PG8_SCHED;
;             PG8_STAGE(PG8_SB(1, 1), b3 + hstepB, voffB);
;             PG8_WAIT_V(6); PG8_BAR; PG8_MMA(1, 1, At, B1); PG8_BAR;
	s_waitcnt lgkmcnt(0)
	s_setprio 1
	v_mfma_f32_16x16x32_bf16 v[100:103], v[190:193], v[124:127], v[100:103]
	v_mfma_f32_16x16x32_bf16 v[20:23], v[198:201], v[124:127], v[20:23]
	v_mfma_f32_16x16x32_bf16 v[24:27], v[190:193], v[162:165], v[24:27]
	v_mfma_f32_16x16x32_bf16 v[28:31], v[198:201], v[162:165], v[28:31]
	v_mfma_f32_16x16x32_bf16 v[32:35], v[190:193], v[170:173], v[32:35]
	v_mfma_f32_16x16x32_bf16 v[36:39], v[198:201], v[170:173], v[36:39]
	v_mfma_f32_16x16x32_bf16 v[40:43], v[190:193], v[182:185], v[40:43]
	v_mfma_f32_16x16x32_bf16 v[44:47], v[198:201], v[182:185], v[44:47]
	v_mfma_f32_16x16x32_bf16 v[100:103], v[194:197], v[128:131], v[100:103]
	v_mfma_f32_16x16x32_bf16 v[20:23], v[202:205], v[128:131], v[20:23]
	v_mfma_f32_16x16x32_bf16 v[24:27], v[194:197], v[166:169], v[24:27]
	v_mfma_f32_16x16x32_bf16 v[28:31], v[202:205], v[166:169], v[28:31]
	v_mfma_f32_16x16x32_bf16 v[32:35], v[194:197], v[178:181], v[32:35]
	v_mfma_f32_16x16x32_bf16 v[36:39], v[202:205], v[178:181], v[36:39]
	v_mfma_f32_16x16x32_bf16 v[40:43], v[194:197], v[186:189], v[40:43]
	v_mfma_f32_16x16x32_bf16 v[44:47], v[202:205], v[186:189], v[44:47]
	s_setprio 0
	s_mov_b64 s[56:57], s[84:85]
	s_barrier
	ds_read_b128 v[124:127], v157 offset:49152
	ds_read_b128 v[128:131], v157 offset:50176
	ds_read_b128 v[162:165], v157 offset:51200
	ds_read_b128 v[166:169], v157 offset:52224
	ds_read_b128 v[170:173], v157 offset:53248
	ds_read_b128 v[178:181], v157 offset:54272
	ds_read_b128 v[182:185], v157 offset:55296
	ds_read_b128 v[186:189], v157 offset:56320
	s_mov_b32 m0, s24
	v_lshl_add_u64 v[154:155], s[56:57], 0, v[140:141]
	s_add_u32 s56, s84, 0x8000
	s_addc_u32 s57, s85, 0
	global_load_lds_dwordx4 v[154:155], off
	s_mov_b32 m0, s25
	v_lshl_add_u64 v[154:155], s[56:57], 0, v[140:141]
	global_load_lds_dwordx4 v[154:155], off
	s_barrier
	s_waitcnt lgkmcnt(0)
	s_setprio 1
	v_mfma_f32_16x16x32_bf16 v[132:135], v[92:95], v[124:127], v[132:135]
	v_mfma_f32_16x16x32_bf16 v[136:139], v[116:119], v[124:127], v[136:139]
	v_mfma_f32_16x16x32_bf16 v[142:145], v[92:95], v[162:165], v[142:145]
	v_mfma_f32_16x16x32_bf16 v[146:149], v[116:119], v[162:165], v[146:149]
	v_mfma_f32_16x16x32_bf16 v[150:153], v[92:95], v[170:173], v[150:153]
	v_mfma_f32_16x16x32_bf16 v[158:161], v[116:119], v[170:173], v[158:161]
	v_mfma_f32_16x16x32_bf16 v[4:7], v[92:95], v[182:185], v[4:7]
	v_mfma_f32_16x16x32_bf16 v[8:11], v[116:119], v[182:185], v[8:11]
	v_mfma_f32_16x16x32_bf16 v[132:135], v[96:99], v[128:131], v[132:135]
	v_mfma_f32_16x16x32_bf16 v[136:139], v[120:123], v[128:131], v[136:139]
	v_mfma_f32_16x16x32_bf16 v[142:145], v[96:99], v[166:169], v[142:145]
	v_mfma_f32_16x16x32_bf16 v[146:149], v[120:123], v[166:169], v[146:149]
	v_mfma_f32_16x16x32_bf16 v[150:153], v[96:99], v[178:181], v[150:153]
	v_mfma_f32_16x16x32_bf16 v[158:161], v[120:123], v[178:181], v[158:161]
	v_mfma_f32_16x16x32_bf16 v[4:7], v[96:99], v[186:189], v[4:7]
	v_mfma_f32_16x16x32_bf16 v[8:11], v[120:123], v[186:189], v[8:11]
	s_setprio 0
	s_barrier
	s_add_u32 s56, s90, 0x100000
	s_addc_u32 s57, s91, 0
	s_nop 0
	v_lshl_add_u64 v[92:93], s[56:57], 0, v[176:177]
	s_add_i32 s56, s58, s17
	s_add_u32 s58, s90, 0x180000
	s_mov_b32 m0, s56
	s_addc_u32 s59, s91, 0
	s_add_i32 s29, s56, 0x2000
	global_load_lds_dwordx4 v[92:93], off
	s_mov_b32 m0, s29
	v_lshl_add_u64 v[92:93], s[58:59], 0, v[176:177]
	global_load_lds_dwordx4 v[92:93], off
	s_waitcnt vmcnt(6)
	s_barrier
	s_setprio 1
	v_mfma_f32_16x16x32_bf16 v[12:15], v[190:193], v[124:127], v[12:15]
	v_mfma_f32_16x16x32_bf16 v[16:19], v[198:201], v[124:127], v[16:19]
	v_mfma_f32_16x16x32_bf16 v[48:51], v[190:193], v[162:165], v[48:51]
	v_mfma_f32_16x16x32_bf16 v[92:95], v[198:201], v[162:165], v[104:107]
	v_mfma_f32_16x16x32_bf16 v[96:99], v[190:193], v[170:173], v[108:111]
	v_mfma_f32_16x16x32_bf16 v[104:107], v[198:201], v[170:173], v[112:115]
	v_mfma_f32_16x16x32_bf16 v[84:87], v[190:193], v[182:185], v[84:87]
	v_mfma_f32_16x16x32_bf16 v[88:91], v[198:201], v[182:185], v[88:91]
	v_mfma_f32_16x16x32_bf16 v[12:15], v[194:197], v[128:131], v[12:15]
	v_mfma_f32_16x16x32_bf16 v[16:19], v[202:205], v[128:131], v[16:19]
	v_mfma_f32_16x16x32_bf16 v[48:51], v[194:197], v[166:169], v[48:51]
	v_mfma_f32_16x16x32_bf16 v[92:95], v[202:205], v[166:169], v[92:95]
	v_mfma_f32_16x16x32_bf16 v[96:99], v[194:197], v[178:181], v[96:99]
	v_mfma_f32_16x16x32_bf16 v[104:107], v[202:205], v[178:181], v[104:107]
	v_mfma_f32_16x16x32_bf16 v[84:87], v[194:197], v[186:189], v[84:87]
	v_mfma_f32_16x16x32_bf16 v[88:91], v[202:205], v[186:189], v[88:91]
	s_setprio 0
	s_add_u32 s84, s72, 0x80
	s_addc_u32 s85, s73, 0
	s_add_u32 s90, s78, 0x80
	s_addc_u32 s91, s79, 0
	s_barrier
	ds_read_b128 v[108:111], v174
	ds_read_b128 v[112:115], v174 offset:1024
	ds_read_b128 v[116:119], v174 offset:2048
	ds_read_b128 v[120:123], v174 offset:3072
	s_add_u32 s58, s86, 0x10000
	s_addc_u32 s59, s87, 0
	ds_read_b128 v[124:127], v157
	ds_read_b128 v[128:131], v157 offset:1024
	ds_read_b128 v[162:165], v157 offset:2048
	ds_read_b128 v[166:169], v157 offset:3072
	ds_read_b128 v[170:173], v157 offset:4096
	ds_read_b128 v[178:181], v157 offset:5120
	ds_read_b128 v[182:185], v157 offset:6144
	ds_read_b128 v[186:189], v157 offset:7168
	s_mov_b32 m0, s52
	v_lshl_add_u64 v[154:155], s[58:59], 0, v[140:141]
	s_add_u32 s58, s86, 0x18000
	s_addc_u32 s59, s87, 0
	global_load_lds_dwordx4 v[154:155], off
	s_mov_b32 m0, s11
	v_lshl_add_u64 v[154:155], s[58:59], 0, v[140:141]
	global_load_lds_dwordx4 v[154:155], off
	s_waitcnt lgkmcnt(8)
	s_barrier
; #define PG8_STAGE(bufoff, gbase, voff) do { _Pragma("unroll") for (int _i = 0; _i < 2; ++_i) { const char* _gb = (const char*)(gbase) + (size_t)_i * (voff##_q); asm volatile("" : "+s"(_gb)); \
;         __builtin_amdgcn_global_load_lds((const unsigned*)(_gb + (voff)), (LAS unsigned*)(lds + (bufoff) + ldsw + _i * 8192), 16, 0, 0); } } while (0)
; #define PG8_LDA(dst, b, h) do { _Pragma("unroll") for (int m = 0; m < 4; ++m) _Pragma("unroll") for (int k = 0; k < 2; ++k) dst[m][k] = *(const LAS bf16x8*)(lds + PG8_SA(b, h) + aoff + m * 2048 + k * 1024); } while (0)
; #define PG8_LDB(dst, b, h) do { _Pragma("unroll") for (int n = 0; n < 2; ++n) _Pragma("unroll") for (int k = 0; k < 2; ++k) dst[n][k] = *(const LAS bf16x8*)(lds + PG8_SB(b, h) + boff + n * 2048 + k * 1024); } while (0)
; #define PG8_WAIT_V(n) asm volatile("s_waitcnt vmcnt(" #n ")" ::: "memory")
; #define PG8_WAIT_L(n) asm volatile("s_waitcnt lgkmcnt(" #n ")" ::: "memory")
; template <class Epi, class Sched>
; __device__ __forceinline__ void gemm_phase(int wv, LAS unsigned char* lds, const Gemm g, const Sched& S, const Epi& E) { LIDS
;     ...
;             PG8_LDB(B0, 0, 0); PG8_SCHED; PG8_LDA(At, 0, 0); PG8_STAGE(PG8_SA(1, 1), a1 + hstepA, voffA);
;             PG8_WAIT_L(8); PG8_BAR; PG8_WAIT_L(0); PG8_MMA(0, 0, At, B0); PG8_BAR; PG8_SCHED;
;             PG8_LDB(B1, 0, 1); PG8_STAGE(PG8_SB(0, 0), b2, voffB);
;             PG8_BAR; PG8_WAIT_L(0); PG8_MMA(0, 1, At, B1); PG8_BAR;
;             PG8_LDA(At, 0, 1); PG8_STAGE(PG8_SA(0, 0), a2, voffA);
;             PG8_BAR; PG8_WAIT_L(0); PG8_MMA(1, 0, At, B0); PG8_BAR; PG8_SCHED;
;             PG8_STAGE(PG8_SB(0, 1), b2 + hstepB, voffB);
;             PG8_WAIT_V(6); PG8_BAR; PG8_MMA(1, 1, At, B1); PG8_BAR;
;             PG8_LDB(B0, 1, 0); PG8_SCHED; PG8_LDA(At, 1, 0); PG8_STAGE(PG8_SA(0, 1), a2 + hstepA, voffA);
;             PG8_WAIT_L(8); PG8_BAR; PG8_WAIT_L(0); PG8_MMA(0, 0, At, B0); PG8_BAR; PG8_SCHED;
;             PG8_LDB(B1, 1, 1); PG8_STAGE(PG8_SB(1, 0), b3, voffB);
;             PG8_BAR; PG8_WAIT_L(0); PG8_MMA(0, 1, At, B1); PG8_BAR;
;             PG8_LDA(At, 1, 1); PG8_STAGE(PG8_SA(1, 0), a3, voffA);
;             PG8_BAR; PG8_WAIT_L(0); PG8_MMA(1, 0, At, B0); PG8_BAR; PG8_SCHED;
;             PG8_STAGE(PG8_SB(1, 1), b3 + hstepB, voffB);
;             PG8_WAIT_V(6); PG8_BAR; PG8_MMA(1, 1, At, B1); PG8_BAR;
	s_waitcnt lgkmcnt(0)
	s_setprio 1
	v_mfma_f32_16x16x32_bf16 v[52:55], v[108:111], v[124:127], v[52:55]
	v_mfma_f32_16x16x32_bf16 v[56:59], v[116:119], v[124:127], v[56:59]
	v_mfma_f32_16x16x32_bf16 v[60:63], v[108:111], v[162:165], v[60:63]
	v_mfma_f32_16x16x32_bf16 v[64:67], v[116:119], v[162:165], v[64:67]
	v_mfma_f32_16x16x32_bf16 v[68:71], v[108:111], v[170:173], v[68:71]
	v_mfma_f32_16x16x32_bf16 v[72:75], v[116:119], v[170:173], v[72:75]
	v_mfma_f32_16x16x32_bf16 v[76:79], v[108:111], v[182:185], v[76:79]
	v_mfma_f32_16x16x32_bf16 v[80:83], v[116:119], v[182:185], v[80:83]
	v_mfma_f32_16x16x32_bf16 v[52:55], v[112:115], v[128:131], v[52:55]
	v_mfma_f32_16x16x32_bf16 v[56:59], v[120:123], v[128:131], v[56:59]
	v_mfma_f32_16x16x32_bf16 v[60:63], v[112:115], v[166:169], v[60:63]
	v_mfma_f32_16x16x32_bf16 v[64:67], v[120:123], v[166:169], v[64:67]
	v_mfma_f32_16x16x32_bf16 v[68:71], v[112:115], v[178:181], v[68:71]
	v_mfma_f32_16x16x32_bf16 v[72:75], v[120:123], v[178:181], v[72:75]
	v_mfma_f32_16x16x32_bf16 v[76:79], v[112:115], v[186:189], v[76:79]
	v_mfma_f32_16x16x32_bf16 v[80:83], v[120:123], v[186:189], v[80:83]
	s_setprio 0
	s_barrier
	s_mov_b64 s[58:59], s[78:79]
	ds_read_b128 v[190:193], v175
	ds_read_b128 v[194:197], v175 offset:1024
	ds_read_b128 v[198:201], v175 offset:2048
	ds_read_b128 v[202:205], v175 offset:3072
	s_mov_b32 m0, s30
	v_lshl_add_u64 v[154:155], s[58:59], 0, v[176:177]
	s_add_u32 s58, s78, 0x80000
	s_addc_u32 s59, s79, 0
	global_load_lds_dwordx4 v[154:155], off
	s_mov_b32 m0, s13
	v_lshl_add_u64 v[154:155], s[58:59], 0, v[176:177]
	global_load_lds_dwordx4 v[154:155], off
	s_barrier
	s_waitcnt lgkmcnt(0)
	s_setprio 1
	v_mfma_f32_16x16x32_bf16 v[100:103], v[190:193], v[124:127], v[100:103]
	v_mfma_f32_16x16x32_bf16 v[20:23], v[198:201], v[124:127], v[20:23]
	v_mfma_f32_16x16x32_bf16 v[24:27], v[190:193], v[162:165], v[24:27]
	v_mfma_f32_16x16x32_bf16 v[28:31], v[198:201], v[162:165], v[28:31]
	v_mfma_f32_16x16x32_bf16 v[32:35], v[190:193], v[170:173], v[32:35]
	v_mfma_f32_16x16x32_bf16 v[36:39], v[198:201], v[170:173], v[36:39]
	v_mfma_f32_16x16x32_bf16 v[40:43], v[190:193], v[182:185], v[40:43]
	v_mfma_f32_16x16x32_bf16 v[44:47], v[198:201], v[182:185], v[44:47]
	v_mfma_f32_16x16x32_bf16 v[206:209], v[194:197], v[128:131], v[100:103]
	v_mfma_f32_16x16x32_bf16 v[20:23], v[202:205], v[128:131], v[20:23]
	v_mfma_f32_16x16x32_bf16 v[24:27], v[194:197], v[166:169], v[24:27]
	v_mfma_f32_16x16x32_bf16 v[28:31], v[202:205], v[166:169], v[28:31]
	v_mfma_f32_16x16x32_bf16 v[32:35], v[194:197], v[178:181], v[32:35]
	v_mfma_f32_16x16x32_bf16 v[36:39], v[202:205], v[178:181], v[36:39]
	v_mfma_f32_16x16x32_bf16 v[40:43], v[194:197], v[186:189], v[40:43]
	v_mfma_f32_16x16x32_bf16 v[162:165], v[202:205], v[186:189], v[44:47]
	s_setprio 0
	s_mov_b64 s[58:59], s[72:73]
	s_barrier
	ds_read_b128 v[44:47], v157 offset:16384
	ds_read_b128 v[100:103], v157 offset:17408
	ds_read_b128 v[124:127], v157 offset:18432
	ds_read_b128 v[128:131], v157 offset:19456
	ds_read_b128 v[166:169], v157 offset:20480
	ds_read_b128 v[170:173], v157 offset:21504
	ds_read_b128 v[178:181], v157 offset:22528
	ds_read_b128 v[182:185], v157 offset:23552
	s_mov_b32 m0, s18
	v_lshl_add_u64 v[154:155], s[58:59], 0, v[140:141]
	s_add_u32 s58, s72, 0x8000
	s_addc_u32 s59, s73, 0
	global_load_lds_dwordx4 v[154:155], off
	s_mov_b32 m0, s19
	v_lshl_add_u64 v[154:155], s[58:59], 0, v[140:141]
	global_load_lds_dwordx4 v[154:155], off
	s_barrier
	s_waitcnt lgkmcnt(0)
	s_setprio 1
	v_mfma_f32_16x16x32_bf16 v[132:135], v[108:111], v[44:47], v[132:135]
	v_mfma_f32_16x16x32_bf16 v[136:139], v[116:119], v[44:47], v[136:139]
	v_mfma_f32_16x16x32_bf16 v[142:145], v[108:111], v[124:127], v[142:145]
	v_mfma_f32_16x16x32_bf16 v[146:149], v[116:119], v[124:127], v[146:149]
	v_mfma_f32_16x16x32_bf16 v[150:153], v[108:111], v[166:169], v[150:153]
	v_mfma_f32_16x16x32_bf16 v[158:161], v[116:119], v[166:169], v[158:161]
	v_mfma_f32_16x16x32_bf16 v[4:7], v[108:111], v[178:181], v[4:7]
	v_mfma_f32_16x16x32_bf16 v[8:11], v[116:119], v[178:181], v[8:11]
	v_mfma_f32_16x16x32_bf16 v[132:135], v[112:115], v[100:103], v[132:135]
	v_mfma_f32_16x16x32_bf16 v[136:139], v[120:123], v[100:103], v[136:139]
	v_mfma_f32_16x16x32_bf16 v[142:145], v[112:115], v[128:131], v[142:145]
	v_mfma_f32_16x16x32_bf16 v[146:149], v[120:123], v[128:131], v[146:149]
	v_mfma_f32_16x16x32_bf16 v[150:153], v[112:115], v[170:173], v[150:153]
	v_mfma_f32_16x16x32_bf16 v[158:161], v[120:123], v[170:173], v[158:161]
	v_mfma_f32_16x16x32_bf16 v[4:7], v[112:115], v[182:185], v[4:7]
	v_mfma_f32_16x16x32_bf16 v[8:11], v[120:123], v[182:185], v[8:11]
	s_setprio 0
	s_barrier
	s_add_u32 s30, s78, 0x100000
	s_mov_b32 m0, s31
	s_addc_u32 s31, s79, 0
	s_nop 0
	v_lshl_add_u64 v[108:109], s[30:31], 0, v[176:177]
	s_add_u32 s30, s78, 0x180000
	s_addc_u32 s31, s79, 0
	global_load_lds_dwordx4 v[108:109], off
	s_mov_b32 m0, s27
	v_lshl_add_u64 v[108:109], s[30:31], 0, v[176:177]
	global_load_lds_dwordx4 v[108:109], off
	s_waitcnt vmcnt(6)
	s_barrier
	s_setprio 1
	v_mfma_f32_16x16x32_bf16 v[12:15], v[190:193], v[44:47], v[12:15]
	v_mfma_f32_16x16x32_bf16 v[186:189], v[194:197], v[100:103], v[12:15]
	v_mfma_f32_16x16x32_bf16 v[12:15], v[198:201], v[44:47], v[16:19]
	v_mfma_f32_16x16x32_bf16 v[218:221], v[202:205], v[100:103], v[12:15]
	v_mfma_f32_16x16x32_bf16 v[12:15], v[190:193], v[124:127], v[48:51]
	v_mfma_f32_16x16x32_bf16 v[222:225], v[194:197], v[128:131], v[12:15]
	v_mfma_f32_16x16x32_bf16 v[12:15], v[198:201], v[124:127], v[92:95]
	v_mfma_f32_16x16x32_bf16 v[226:229], v[202:205], v[128:131], v[12:15]
	v_mfma_f32_16x16x32_bf16 v[12:15], v[190:193], v[166:169], v[96:99]
	v_mfma_f32_16x16x32_bf16 v[230:233], v[194:197], v[170:173], v[12:15]
	v_mfma_f32_16x16x32_bf16 v[12:15], v[198:201], v[166:169], v[104:107]
	v_mfma_f32_16x16x32_bf16 v[166:169], v[202:205], v[170:173], v[12:15]
	v_mfma_f32_16x16x32_bf16 v[12:15], v[190:193], v[178:181], v[84:87]
	v_mfma_f32_16x16x32_bf16 v[170:173], v[194:197], v[182:185], v[12:15]
	v_mfma_f32_16x16x32_bf16 v[12:15], v[198:201], v[178:181], v[88:91]
	v_mfma_f32_16x16x32_bf16 v[178:181], v[202:205], v[182:185], v[12:15]
	s_setprio 0
	s_barrier
; #define PG8_STAGE(bufoff, gbase, voff) do { _Pragma("unroll") for (int _i = 0; _i < 2; ++_i) { const char* _gb = (const char*)(gbase) + (size_t)_i * (voff##_q); asm volatile("" : "+s"(_gb)); \
;         __builtin_amdgcn_global_load_lds((const unsigned*)(_gb + (voff)), (LAS unsigned*)(lds + (bufoff) + ldsw + _i * 8192), 16, 0, 0); } } while (0)
; #define PG8_LDA(dst, b, h) do { _Pragma("unroll") for (int m = 0; m < 4; ++m) _Pragma("unroll") for (int k = 0; k < 2; ++k) dst[m][k] = *(const LAS bf16x8*)(lds + PG8_SA(b, h) + aoff + m * 2048 + k * 1024); } while (0)
; #define PG8_LDB(dst, b, h) do { _Pragma("unroll") for (int n = 0; n < 2; ++n) _Pragma("unroll") for (int k = 0; k < 2; ++k) dst[n][k] = *(const LAS bf16x8*)(lds + PG8_SB(b, h) + boff + n * 2048 + k * 1024); } while (0)
; #define PG8_WAIT_V(n) asm volatile("s_waitcnt vmcnt(" #n ")" ::: "memory")
; #define PG8_WAIT_L(n) asm volatile("s_waitcnt lgkmcnt(" #n ")" ::: "memory")
; template <class Epi, class Sched>
; __device__ __forceinline__ void gemm_phase(int wv, LAS unsigned char* lds, const Gemm g, const Sched& S, const Epi& E) { LIDS
;     ...
;             PG8_LDB(B0, 0, 0); PG8_SCHED; PG8_LDA(At, 0, 0); PG8_STAGE(PG8_SA(1, 1), a1 + hstepA, voffA);
;             PG8_WAIT_L(8); PG8_BAR; PG8_WAIT_L(0); PG8_MMA(0, 0, At, B0); PG8_BAR; PG8_SCHED;
;             PG8_LDB(B1, 0, 1); PG8_STAGE(PG8_SB(0, 0), b2, voffB);
;             PG8_BAR; PG8_WAIT_L(0); PG8_MMA(0, 1, At, B1); PG8_BAR;
;             PG8_LDA(At, 0, 1); PG8_STAGE(PG8_SA(0, 0), a2, voffA);
;             PG8_BAR; PG8_WAIT_L(0); PG8_MMA(1, 0, At, B0); PG8_BAR; PG8_SCHED;
;             PG8_STAGE(PG8_SB(0, 1), b2 + hstepB, voffB);
;             PG8_WAIT_V(6); PG8_BAR; PG8_MMA(1, 1, At, B1); PG8_BAR;
;             PG8_LDB(B0, 1, 0); PG8_SCHED; PG8_LDA(At, 1, 0); PG8_STAGE(PG8_SA(0, 1), a2 + hstepA, voffA);
;             PG8_WAIT_L(8); PG8_BAR; PG8_WAIT_L(0); PG8_MMA(0, 0, At, B0); PG8_BAR; PG8_SCHED;
;             PG8_LDB(B1, 1, 1); PG8_STAGE(PG8_SB(1, 0), b3, voffB);
;             PG8_BAR; PG8_WAIT_L(0); PG8_MMA(0, 1, At, B1); PG8_BAR;
;             PG8_LDA(At, 1, 1); PG8_STAGE(PG8_SA(1, 0), a3, voffA);
;             PG8_BAR; PG8_WAIT_L(0); PG8_MMA(1, 0, At, B0); PG8_BAR; PG8_SCHED;
;             PG8_STAGE(PG8_SB(1, 1), b3 + hstepB, voffB);
;             PG8_WAIT_V(6); PG8_BAR; PG8_MMA(1, 1, At, B1); PG8_BAR;
	ds_read_b128 v[182:185], v210
	ds_read_b128 v[190:193], v210 offset:1024
	ds_read_b128 v[194:197], v210 offset:2048
	ds_read_b128 v[198:201], v210 offset:3072
	s_add_u32 s30, s72, 0x10000
	s_addc_u32 s31, s73, 0
	ds_read_b128 v[12:15], v157 offset:32768
	ds_read_b128 v[16:19], v157 offset:33792
	ds_read_b128 v[44:47], v157 offset:34816
	ds_read_b128 v[92:95], v157 offset:35840
	ds_read_b128 v[96:99], v157 offset:36864
	ds_read_b128 v[108:111], v157 offset:37888
	ds_read_b128 v[112:115], v157 offset:38912
	ds_read_b128 v[202:205], v157 offset:39936
	s_mov_b32 m0, s20
	v_lshl_add_u64 v[48:49], s[30:31], 0, v[140:141]
	s_add_u32 s30, s72, 0x18000
	s_addc_u32 s31, s73, 0
	global_load_lds_dwordx4 v[48:49], off
	s_mov_b32 m0, s21
	v_lshl_add_u64 v[48:49], s[30:31], 0, v[140:141]
	global_load_lds_dwordx4 v[48:49], off
	s_waitcnt lgkmcnt(8)
	s_barrier
	s_waitcnt lgkmcnt(0)
	s_setprio 1
	v_mfma_f32_16x16x32_bf16 v[48:51], v[182:185], v[12:15], v[52:55]
	v_mfma_f32_16x16x32_bf16 v[128:131], v[190:193], v[16:19], v[48:51]
	v_mfma_f32_16x16x32_bf16 v[48:51], v[194:197], v[12:15], v[56:59]
	v_mfma_f32_16x16x32_bf16 v[124:127], v[198:201], v[16:19], v[48:51]
	v_mfma_f32_16x16x32_bf16 v[48:51], v[182:185], v[44:47], v[60:63]
	v_mfma_f32_16x16x32_bf16 v[120:123], v[190:193], v[92:95], v[48:51]
	v_mfma_f32_16x16x32_bf16 v[48:51], v[194:197], v[44:47], v[64:67]
	v_mfma_f32_16x16x32_bf16 v[116:119], v[198:201], v[92:95], v[48:51]
	v_mfma_f32_16x16x32_bf16 v[48:51], v[182:185], v[96:99], v[68:71]
	v_mfma_f32_16x16x32_bf16 v[104:107], v[190:193], v[108:111], v[48:51]
	v_mfma_f32_16x16x32_bf16 v[48:51], v[194:197], v[96:99], v[72:75]
	v_mfma_f32_16x16x32_bf16 v[100:103], v[198:201], v[108:111], v[48:51]
	v_mfma_f32_16x16x32_bf16 v[48:51], v[182:185], v[112:115], v[76:79]
	v_mfma_f32_16x16x32_bf16 v[88:91], v[190:193], v[202:205], v[48:51]
	v_mfma_f32_16x16x32_bf16 v[48:51], v[194:197], v[112:115], v[80:83]
	v_mfma_f32_16x16x32_bf16 v[84:87], v[198:201], v[202:205], v[48:51]
	s_setprio 0
	s_barrier
	s_mov_b64 s[30:31], s[90:91]
	ds_read_b128 v[234:237], v211
	ds_read_b128 v[238:241], v211 offset:1024
	ds_read_b128 v[242:245], v211 offset:2048
	ds_read_b128 v[246:249], v211 offset:3072
	s_mov_b32 m0, s55
	v_lshl_add_u64 v[48:49], s[30:31], 0, v[176:177]
	s_add_u32 s30, s90, 0x80000
	s_addc_u32 s31, s91, 0
	global_load_lds_dwordx4 v[48:49], off
	s_mov_b32 m0, s28
	v_lshl_add_u64 v[48:49], s[30:31], 0, v[176:177]
	global_load_lds_dwordx4 v[48:49], off
	s_barrier
	s_waitcnt lgkmcnt(0)
	s_setprio 1
	v_mfma_f32_16x16x32_bf16 v[48:51], v[234:237], v[12:15], v[206:209]
	v_mfma_f32_16x16x32_bf16 v[12:15], v[242:245], v[12:15], v[20:23]
	v_mfma_f32_16x16x32_bf16 v[60:63], v[246:249], v[16:19], v[12:15]
	v_mfma_f32_16x16x32_bf16 v[12:15], v[234:237], v[44:47], v[24:27]
	v_mfma_f32_16x16x32_bf16 v[64:67], v[238:241], v[16:19], v[48:51]
	v_mfma_f32_16x16x32_bf16 v[48:51], v[238:241], v[92:95], v[12:15]
	v_mfma_f32_16x16x32_bf16 v[12:15], v[242:245], v[44:47], v[28:31]
	v_mfma_f32_16x16x32_bf16 v[44:47], v[246:249], v[92:95], v[12:15]
	v_mfma_f32_16x16x32_bf16 v[12:15], v[234:237], v[96:99], v[32:35]
	v_mfma_f32_16x16x32_bf16 v[32:35], v[238:241], v[108:111], v[12:15]
	v_mfma_f32_16x16x32_bf16 v[12:15], v[242:245], v[96:99], v[36:39]
	v_mfma_f32_16x16x32_bf16 v[28:31], v[246:249], v[108:111], v[12:15]
	v_mfma_f32_16x16x32_bf16 v[12:15], v[234:237], v[112:115], v[40:43]
	v_mfma_f32_16x16x32_bf16 v[16:19], v[238:241], v[202:205], v[12:15]
	v_mfma_f32_16x16x32_bf16 v[12:15], v[242:245], v[112:115], v[162:165]
	v_mfma_f32_16x16x32_bf16 v[12:15], v[246:249], v[202:205], v[12:15]
	s_setprio 0
	s_mov_b64 s[30:31], s[84:85]
	s_barrier
	ds_read_b128 v[20:23], v157 offset:49152
	ds_read_b128 v[24:27], v157 offset:50176
	ds_read_b128 v[36:39], v157 offset:51200
	ds_read_b128 v[162:165], v157 offset:52224
	ds_read_b128 v[202:205], v157 offset:53248
	ds_read_b128 v[206:209], v157 offset:54272
	ds_read_b128 v[210:213], v157 offset:55296
	ds_read_b128 v[40:43], v157 offset:56320
	s_mov_b32 m0, s24
	v_lshl_add_u64 v[52:53], s[30:31], 0, v[140:141]
	s_add_u32 s30, s84, 0x8000
	s_addc_u32 s31, s85, 0
	global_load_lds_dwordx4 v[52:53], off
	s_mov_b32 m0, s25
	v_lshl_add_u64 v[52:53], s[30:31], 0, v[140:141]
	global_load_lds_dwordx4 v[52:53], off
	s_barrier
	s_waitcnt lgkmcnt(0)
	s_setprio 1
	v_mfma_f32_16x16x32_bf16 v[52:55], v[182:185], v[20:23], v[132:135]
	v_mfma_f32_16x16x32_bf16 v[112:115], v[190:193], v[24:27], v[52:55]
	v_mfma_f32_16x16x32_bf16 v[52:55], v[194:197], v[20:23], v[136:139]
	v_mfma_f32_16x16x32_bf16 v[108:111], v[198:201], v[24:27], v[52:55]
	v_mfma_f32_16x16x32_bf16 v[52:55], v[182:185], v[36:39], v[142:145]
	v_mfma_f32_16x16x32_bf16 v[96:99], v[190:193], v[162:165], v[52:55]
	v_mfma_f32_16x16x32_bf16 v[52:55], v[194:197], v[36:39], v[146:149]
	v_mfma_f32_16x16x32_bf16 v[92:95], v[198:201], v[162:165], v[52:55]
	v_mfma_f32_16x16x32_bf16 v[52:55], v[182:185], v[202:205], v[150:153]
	v_mfma_f32_16x16x32_bf16 v[4:7], v[182:185], v[210:213], v[4:7]
	v_mfma_f32_16x16x32_bf16 v[80:83], v[190:193], v[206:209], v[52:55]
	v_mfma_f32_16x16x32_bf16 v[52:55], v[194:197], v[202:205], v[158:161]
	v_mfma_f32_16x16x32_bf16 v[72:75], v[190:193], v[40:43], v[4:7]
	v_mfma_f32_16x16x32_bf16 v[4:7], v[194:197], v[210:213], v[8:11]
	v_mfma_f32_16x16x32_bf16 v[76:79], v[198:201], v[206:209], v[52:55]
	v_mfma_f32_16x16x32_bf16 v[68:71], v[198:201], v[40:43], v[4:7]
	s_setprio 0
	s_barrier
	s_add_u32 s30, s90, 0x100000
	s_addc_u32 s31, s91, 0
	s_mov_b32 m0, s56
	s_nop 0
	v_lshl_add_u64 v[4:5], s[30:31], 0, v[176:177]
	s_add_u32 s30, s90, 0x180000
	s_addc_u32 s31, s91, 0
	global_load_lds_dwordx4 v[4:5], off
	s_mov_b32 m0, s29
	v_lshl_add_u64 v[4:5], s[30:31], 0, v[176:177]
	global_load_lds_dwordx4 v[4:5], off
	s_waitcnt vmcnt(6)
	s_barrier
; __device__ __forceinline__ u32x4 pack8(f32x4 a, f32x4 b) { u32x4 r; r[0] = cvt_pk_bf16(a[0], a[1]); r[1] = cvt_pk_bf16(a[2], a[3]); r[2] = cvt_pk_bf16(b[0], b[1]); r[3] = cvt_pk_bf16(b[2], b[3]); return r; }
; __device__ __forceinline__ int lane_id_asm() { int x; asm volatile("v_mbcnt_lo_u32_b32 %0, -1, 0\n\tv_mbcnt_hi_u32_b32 %0, -1, %0" : "=&v"(x)); return x; }
; #define PG8_STAGE(bufoff, gbase, voff) do { _Pragma("unroll") for (int _i = 0; _i < 2; ++_i) { const char* _gb = (const char*)(gbase) + (size_t)_i * (voff##_q); asm volatile("" : "+s"(_gb)); \
;         __builtin_amdgcn_global_load_lds((const unsigned*)(_gb + (voff)), (LAS unsigned*)(lds + (bufoff) + ldsw + _i * 8192), 16, 0, 0); } } while (0)
; #define PG8_WAIT_V(n) asm volatile("s_waitcnt vmcnt(" #n ")" ::: "memory")
; #define PG8_WAIT_L(n) asm volatile("s_waitcnt lgkmcnt(" #n ")" ::: "memory")
; #define PG8_BAR __builtin_amdgcn_s_barrier()
; #define PG8_SCHED __builtin_amdgcn_sched_barrier(0)
; template <class Epi, class Sched>
; __device__ __forceinline__ void gemm_phase(int wv, LAS unsigned char* lds, const Gemm g, const Sched& S, const Epi& E) { LIDS
;     ...
;             PG8_BAR; PG8_WAIT_L(0); PG8_MMA(1, 0, At, B0); PG8_BAR; PG8_SCHED;
;             PG8_STAGE(PG8_SB(1, 1), b3 + hstepB, voffB);
;             PG8_WAIT_V(6); PG8_BAR; PG8_MMA(1, 1, At, B1); PG8_BAR;
;         }
;         { const int l2 = lane_id_asm(); E(acc, cur, wr, wc, l2 & 15, l2 >> 4); }
;     __device__ __forceinline__ void operator()(const AccT& acc, const Unit& u, int wr, int wc, int fr, int fq) const {
;     ...
;         for (int bj = 0; bj < 2; ++bj) {
;             const int col = colbase + bj * HALF;
;             f32x4 s0, s1;
; #pragma unroll
;             for (int j = 0; j < 4; ++j) { const f32x4 pc = *(const f32x4*)(ssp + (size_t)(col + j) * 16 + 8), pd = *(const f32x4*)(ssp + (size_t)(col + 4 + j) * 16 + 8);
;                 s0[j] = rsqrtf(((pc[0] + pc[1]) + (pc[2] + pc[3])) * (1.0f / 256.0f) + EPS); s1[j] = rsqrtf(((pd[0] + pd[1]) + (pd[2] + pd[3])) * (1.0f / 256.0f) + EPS); }
; #pragma unroll
;             for (int ai = 0; ai < 2; ++ai)
; #pragma unroll
;                 for (int m = 0; m < 4; ++m) {
;                     const int row = row0 + ai * HALF + m * 16;
;                     *(u32x4*)(Vt + (size_t)row * SEQ + col) = pack8(acc[ai][bj][m][0] * s0, acc[ai][bj][m][1] * s1);
	s_setprio 1
	v_mfma_f32_16x16x32_bf16 v[4:7], v[234:237], v[20:23], v[186:189]
	v_mfma_f32_16x16x32_bf16 v[56:59], v[238:241], v[24:27], v[4:7]
	v_mfma_f32_16x16x32_bf16 v[4:7], v[242:245], v[20:23], v[218:221]
	v_mfma_f32_16x16x32_bf16 v[52:55], v[246:249], v[24:27], v[4:7]
	v_mfma_f32_16x16x32_bf16 v[4:7], v[234:237], v[36:39], v[222:225]
	v_mfma_f32_16x16x32_bf16 v[158:161], v[238:241], v[162:165], v[4:7]
	v_mfma_f32_16x16x32_bf16 v[4:7], v[242:245], v[36:39], v[226:229]
	v_mfma_f32_16x16x32_bf16 v[36:39], v[246:249], v[162:165], v[4:7]
	v_mfma_f32_16x16x32_bf16 v[4:7], v[234:237], v[202:205], v[230:233]
	v_mfma_f32_16x16x32_bf16 v[24:27], v[238:241], v[206:209], v[4:7]
	v_mfma_f32_16x16x32_bf16 v[4:7], v[242:245], v[202:205], v[166:169]
	v_mfma_f32_16x16x32_bf16 v[20:23], v[246:249], v[206:209], v[4:7]
	v_mfma_f32_16x16x32_bf16 v[4:7], v[234:237], v[210:213], v[170:173]
	v_mfma_f32_16x16x32_bf16 v[8:11], v[238:241], v[40:43], v[4:7]
	v_mfma_f32_16x16x32_bf16 v[4:7], v[242:245], v[210:213], v[178:181]
	v_mfma_f32_16x16x32_bf16 v[4:7], v[246:249], v[40:43], v[4:7]
	s_setprio 0
	s_lshl_b32 s6, s6, 8
	s_barrier
	v_mbcnt_lo_u32_b32 v40, -1, 0
	v_mbcnt_hi_u32_b32 v40, -1, v40
	s_add_i32 s6, s6, s22
	v_and_or_b32 v152, v40, 15, s6
	s_lshl_b32 s6, s7, 8
	v_ashrrev_i32_e32 v40, 1, v40
	s_or_b32 s6, s6, s23
	v_and_b32_e32 v40, -8, v40
	v_add_u32_e32 v144, s6, v40
	v_or_b32_e32 v132, 4, v144
	v_or_b32_e32 v136, 1, v144
	v_ashrrev_i32_e32 v145, 31, v144
	v_readlane_b32 s28, v253, 12
	v_ashrrev_i32_e32 v133, 31, v132
	v_ashrrev_i32_e32 v137, 31, v136
	v_lshlrev_b64 v[40:41], 6, v[144:145]
	v_readlane_b32 s29, v253, 13
	v_lshlrev_b64 v[132:133], 6, v[132:133]
	v_lshlrev_b64 v[136:137], 6, v[136:137]
	v_lshl_add_u64 v[146:147], s[28:29], 0, v[40:41]
	v_lshl_add_u64 v[132:133], s[28:29], 0, v[132:133]
	v_lshl_add_u64 v[136:137], s[28:29], 0, v[136:137]
	global_load_dwordx4 v[178:181], v[146:147], off offset:32
	global_load_dwordx4 v[182:185], v[146:147], off offset:96
	global_load_dwordx4 v[186:189], v[146:147], off offset:160
	global_load_dwordx4 v[190:193], v[146:147], off offset:224
	global_load_dwordx4 v[194:197], v[146:147], off offset:288
	global_load_dwordx4 v[198:201], v[146:147], off offset:352
	global_load_dwordx4 v[202:205], v[146:147], off offset:416
	global_load_dwordx4 v[206:209], v[146:147], off offset:480
	v_add_co_u32_e32 v212, vcc, 0x2000, v146
	v_addc_co_u32_e32 v213, vcc, 0, v147, vcc
	global_load_dwordx4 v[218:221], v[212:213], off offset:32
	global_load_dwordx4 v[222:225], v[212:213], off offset:96
	global_load_dwordx4 v[226:229], v[212:213], off offset:160
	global_load_dwordx4 v[230:233], v[212:213], off offset:224
	global_load_dwordx4 v[234:237], v[212:213], off offset:288
	global_load_dwordx4 v[238:241], v[212:213], off offset:352
	global_load_dwordx4 v[242:245], v[212:213], off offset:416
	global_load_dwordx4 v[246:249], v[212:213], off offset:480
	s_waitcnt vmcnt(0)
	v_mov_b32_e32 v40, v178
	v_mov_b32_e32 v41, v179
	v_mov_b32_e32 v42, v180
	v_mov_b32_e32 v43, v181
	v_or_b32_e32 v142, 5, v144
	v_mov_b32_e32 v132, v194
	v_mov_b32_e32 v133, v195
	v_mov_b32_e32 v134, v196
	v_mov_b32_e32 v135, v197
	v_ashrrev_i32_e32 v143, 31, v142
	v_mov_b32_e32 v136, v182
	v_mov_b32_e32 v137, v183
	v_mov_b32_e32 v138, v184
	v_mov_b32_e32 v139, v185
	v_lshlrev_b64 v[142:143], 6, v[142:143]
	v_lshl_add_u64 v[142:143], s[28:29], 0, v[142:143]
	v_mov_b32_e32 v162, v198
	v_mov_b32_e32 v163, v199
	v_mov_b32_e32 v164, v200
	v_mov_b32_e32 v165, v201
	s_mov_b32 s6, 0x358637bd
	s_mov_b32 s52, 0x3b800000
	s_mov_b32 s11, 0x800000
	s_mov_b32 s30, 0x45800000
	v_ashrrev_i32_e32 v153, 31, v152
	v_readlane_b32 s56, v254, 48
	v_readlane_b32 s58, v253, 14
	s_mov_b32 s92, 0x800000
	s_add_i32 s26, s26, s53
	s_mov_b64 s[90:91], s[68:69]
	s_mov_b64 s[86:87], s[62:63]
	v_readlane_b32 s57, v254, 49
	v_readlane_b32 s59, v253, 15
	v_mov_b32_e32 v142, v40
	v_mov_b32_e32 v143, v136
	v_mov_b32_e32 v136, v41
	v_pk_add_f32 v[40:41], v[142:143], v[136:137]
	v_mov_b32_e32 v136, v42
	v_mov_b32_e32 v137, v138
	v_mov_b32_e32 v138, v43
	v_pk_add_f32 v[42:43], v[136:137], v[138:139]
	v_mov_b64_e32 v[142:143], s[6:7]
	v_pk_add_f32 v[40:41], v[40:41], v[42:43]
	v_or_b32_e32 v136, 3, v144
	v_pk_fma_f32 v[40:41], v[40:41], s[52:53], v[142:143] op_sel_hi:[1,0,0]
	v_ashrrev_i32_e32 v137, 31, v136
	v_mul_f32_e32 v42, 0x4b800000, v40
	v_cmp_gt_f32_e64 s[6:7], s11, v40
	v_cmp_gt_f32_e32 vcc, s11, v41
	v_lshlrev_b64 v[136:137], 6, v[136:137]
	v_cndmask_b32_e64 v40, v40, v42, s[6:7]
	v_mul_f32_e32 v42, 0x4b800000, v41
	v_cndmask_b32_e32 v41, v41, v42, vcc
	v_rsq_f32_e32 v40, v40
	v_rsq_f32_e32 v41, v41
	v_lshl_add_u64 v[136:137], s[28:29], 0, v[136:137]
	v_pk_mul_f32 v[42:43], v[40:41], s[30:31] op_sel_hi:[1,0]
	s_nop 0
	v_cndmask_b32_e32 v149, v41, v43, vcc
	v_cndmask_b32_e64 v148, v40, v42, s[6:7]
	v_mov_b32_e32 v40, v132
	v_mov_b32_e32 v41, v162
	v_mov_b32_e32 v162, v133
	v_mov_b32_e32 v42, v134
	v_mov_b32_e32 v43, v164
	v_mov_b32_e32 v164, v135
	v_pk_add_f32 v[40:41], v[40:41], v[162:163]
	v_pk_add_f32 v[42:43], v[42:43], v[164:165]
	v_mov_b32_e32 v162, v190
	v_mov_b32_e32 v163, v191
	v_mov_b32_e32 v164, v192
	v_mov_b32_e32 v165, v193
	v_pk_add_f32 v[40:41], v[40:41], v[42:43]
	v_or_b32_e32 v132, 6, v144
	v_pk_fma_f32 v[40:41], v[40:41], s[52:53], v[142:143] op_sel_hi:[1,0,0]
	v_or_b32_e32 v136, 7, v144
	v_mul_f32_e32 v42, 0x4b800000, v40
	v_cmp_gt_f32_e64 s[6:7], s11, v40
	v_cmp_gt_f32_e32 vcc, s11, v41
	v_ashrrev_i32_e32 v133, 31, v132
	v_cndmask_b32_e64 v40, v40, v42, s[6:7]
	v_mul_f32_e32 v42, 0x4b800000, v41
	v_cndmask_b32_e32 v41, v41, v42, vcc
	v_rsq_f32_e32 v40, v40
; __device__ __forceinline__ u32x4 pack8(f32x4 a, f32x4 b) { u32x4 r; r[0] = cvt_pk_bf16(a[0], a[1]); r[1] = cvt_pk_bf16(a[2], a[3]); r[2] = cvt_pk_bf16(b[0], b[1]); r[3] = cvt_pk_bf16(b[2], b[3]); return r; }
;     __device__ __forceinline__ void operator()(const AccT& acc, const Unit& u, int wr, int wc, int fr, int fq) const {
;     ...
;         for (int bj = 0; bj < 2; ++bj) {
;             const int col = colbase + bj * HALF;
;             f32x4 s0, s1;
; #pragma unroll
;             for (int j = 0; j < 4; ++j) { const f32x4 pc = *(const f32x4*)(ssp + (size_t)(col + j) * 16 + 8), pd = *(const f32x4*)(ssp + (size_t)(col + 4 + j) * 16 + 8);
;                 s0[j] = rsqrtf(((pc[0] + pc[1]) + (pc[2] + pc[3])) * (1.0f / 256.0f) + EPS); s1[j] = rsqrtf(((pd[0] + pd[1]) + (pd[2] + pd[3])) * (1.0f / 256.0f) + EPS); }
; #pragma unroll
;             for (int ai = 0; ai < 2; ++ai)
; #pragma unroll
;                 for (int m = 0; m < 4; ++m) {
;                     const int row = row0 + ai * HALF + m * 16;
;                     *(u32x4*)(Vt + (size_t)row * SEQ + col) = pack8(acc[ai][bj][m][0] * s0, acc[ai][bj][m][1] * s1);
	v_rsq_f32_e32 v41, v41
	v_ashrrev_i32_e32 v137, 31, v136
	v_lshlrev_b64 v[132:133], 6, v[132:133]
	v_lshlrev_b64 v[136:137], 6, v[136:137]
	v_pk_mul_f32 v[42:43], v[40:41], s[30:31] op_sel_hi:[1,0]
	v_lshl_add_u64 v[132:133], s[28:29], 0, v[132:133]
	v_cndmask_b32_e64 v150, v40, v42, s[6:7]
	v_or_b32_e32 v40, 2, v144
	v_cndmask_b32_e32 v151, v41, v43, vcc
	v_ashrrev_i32_e32 v41, 31, v40
	v_lshlrev_b64 v[40:41], 6, v[40:41]
	v_lshl_add_u64 v[40:41], s[28:29], 0, v[40:41]
	v_mov_b32_e32 v40, v186
	v_mov_b32_e32 v41, v187
	v_mov_b32_e32 v42, v188
	v_mov_b32_e32 v43, v189
	v_lshl_add_u64 v[136:137], s[28:29], 0, v[136:137]
	v_mov_b32_e32 v132, v202
	v_mov_b32_e32 v133, v203
	v_mov_b32_e32 v134, v204
	v_mov_b32_e32 v135, v205
	v_pk_mul_f32 v[124:125], v[124:125], v[150:151]
	v_mov_b32_e32 v136, v206
	v_mov_b32_e32 v137, v207
	v_mov_b32_e32 v138, v208
	v_mov_b32_e32 v139, v209
	v_pk_mul_f32 v[116:117], v[116:117], v[150:151]
	v_pk_mul_f32 v[100:101], v[100:101], v[150:151]
	v_pk_mul_f32 v[84:85], v[84:85], v[150:151]
	v_pk_mul_f32 v[76:77], v[76:77], v[150:151]
	v_pk_mul_f32 v[68:69], v[68:69], v[150:151]
	v_mov_b32_e32 v155, v162
	v_mov_b32_e32 v154, v40
	v_mov_b32_e32 v162, v41
	v_pk_add_f32 v[40:41], v[154:155], v[162:163]
	v_mov_b32_e32 v154, v42
	v_mov_b32_e32 v155, v164
	v_mov_b32_e32 v164, v43
	v_pk_add_f32 v[42:43], v[154:155], v[164:165]
	s_nop 0
	v_pk_add_f32 v[40:41], v[40:41], v[42:43]
	s_nop 0
	v_pk_fma_f32 v[40:41], v[40:41], s[52:53], v[142:143] op_sel_hi:[1,0,0]
	s_nop 0
	v_mul_f32_e32 v42, 0x4b800000, v40
	v_cmp_gt_f32_e64 s[6:7], s11, v40
	v_cmp_gt_f32_e32 vcc, s11, v41
	s_nop 0
	v_cndmask_b32_e64 v40, v40, v42, s[6:7]
	v_mul_f32_e32 v42, 0x4b800000, v41
	v_cndmask_b32_e32 v41, v41, v42, vcc
	v_rsq_f32_e32 v40, v40
	v_rsq_f32_e32 v41, v41
	s_nop 0
	v_pk_mul_f32 v[42:43], v[40:41], s[30:31] op_sel_hi:[1,0]
	s_nop 0
	v_cndmask_b32_e32 v155, v41, v43, vcc
	v_cndmask_b32_e64 v154, v40, v42, s[6:7]
	v_mov_b32_e32 v40, v132
	v_mov_b32_e32 v41, v136
	v_mov_b32_e32 v136, v133
	v_mov_b32_e32 v42, v134
	v_mov_b32_e32 v43, v138
	v_mov_b32_e32 v138, v135
	v_pk_add_f32 v[40:41], v[40:41], v[136:137]
	v_pk_add_f32 v[42:43], v[42:43], v[138:139]
	s_nop 0
	v_pk_add_f32 v[40:41], v[40:41], v[42:43]
	s_nop 0
	v_pk_fma_f32 v[40:41], v[40:41], s[52:53], v[142:143] op_sel_hi:[1,0,0]
	s_nop 0
	v_mul_f32_e32 v42, 0x4b800000, v40
	v_cmp_gt_f32_e64 s[6:7], s11, v40
	v_cmp_gt_f32_e32 vcc, s11, v41
	s_nop 0
	v_cndmask_b32_e64 v40, v40, v42, s[6:7]
	v_mul_f32_e32 v42, 0x4b800000, v41
	v_cndmask_b32_e32 v41, v41, v42, vcc
	v_rsq_f32_e32 v40, v40
	v_rsq_f32_e32 v41, v41
	s_nop 0
	v_pk_mul_f32 v[42:43], v[40:41], s[30:31] op_sel_hi:[1,0]
	s_nop 0
	v_cndmask_b32_e32 v133, v41, v43, vcc
	v_cndmask_b32_e64 v132, v40, v42, s[6:7]
	v_pk_mul_f32 v[42:43], v[130:131], v[154:155]
	v_pk_mul_f32 v[40:41], v[128:129], v[148:149]
	v_readlane_b32 s6, v253, 8
	v_pk_mul_f32 v[126:127], v[126:127], v[132:133]
	v_cvt_pk_bf16_f32 v40, v40, v41
	v_cvt_pk_bf16_f32 v41, v42, v43
	v_cvt_pk_bf16_f32 v42, v124, v125
	v_lshlrev_b64 v[124:125], 15, v[152:153]
	v_readlane_b32 s7, v253, 9
	v_cvt_pk_bf16_f32 v43, v126, v127
	v_lshlrev_b64 v[126:127], 1, v[144:145]
	v_or_b32_e32 v128, 16, v152
	v_lshl_add_u64 v[124:125], s[6:7], 0, v[124:125]
	v_lshl_add_u64 v[124:125], v[124:125], 0, v[126:127]
	global_store_dwordx4 v[124:125], v[40:43], off
	v_ashrrev_i32_e32 v129, 31, v128
	v_pk_mul_f32 v[118:119], v[118:119], v[132:133]
	v_pk_mul_f32 v[42:43], v[122:123], v[154:155]
	v_pk_mul_f32 v[40:41], v[120:121], v[148:149]
	v_pk_mul_f32 v[102:103], v[102:103], v[132:133]
	v_cvt_pk_bf16_f32 v40, v40, v41
	v_cvt_pk_bf16_f32 v41, v42, v43
	v_cvt_pk_bf16_f32 v42, v116, v117
	v_lshlrev_b64 v[116:117], 15, v[128:129]
	v_lshl_add_u64 v[116:117], s[6:7], 0, v[116:117]
	v_cvt_pk_bf16_f32 v43, v118, v119
	v_lshl_add_u64 v[116:117], v[116:117], 0, v[126:127]
	v_or_b32_e32 v118, 32, v152
	global_store_dwordx4 v[116:117], v[40:43], off
	v_ashrrev_i32_e32 v119, 31, v118
	v_pk_mul_f32 v[86:87], v[86:87], v[132:133]
	v_pk_mul_f32 v[42:43], v[106:107], v[154:155]
	v_pk_mul_f32 v[40:41], v[104:105], v[148:149]
	v_pk_mul_f32 v[78:79], v[78:79], v[132:133]
	v_cvt_pk_bf16_f32 v40, v40, v41
	v_cvt_pk_bf16_f32 v41, v42, v43
	v_cvt_pk_bf16_f32 v42, v100, v101
	v_lshlrev_b64 v[100:101], 15, v[118:119]
	v_lshl_add_u64 v[100:101], s[6:7], 0, v[100:101]
	v_cvt_pk_bf16_f32 v43, v102, v103
	v_lshl_add_u64 v[100:101], v[100:101], 0, v[126:127]
	v_or_b32_e32 v102, 48, v152
	global_store_dwordx4 v[100:101], v[40:43], off
	v_ashrrev_i32_e32 v103, 31, v102
	v_pk_mul_f32 v[70:71], v[70:71], v[132:133]
	v_pk_mul_f32 v[42:43], v[90:91], v[154:155]
	v_pk_mul_f32 v[40:41], v[88:89], v[148:149]
	v_pk_mul_f32 v[88:89], v[108:109], v[150:151]
	v_cvt_pk_bf16_f32 v40, v40, v41
	v_cvt_pk_bf16_f32 v41, v42, v43
	v_cvt_pk_bf16_f32 v42, v84, v85
	v_lshlrev_b64 v[84:85], 15, v[102:103]
	v_lshl_add_u64 v[84:85], s[6:7], 0, v[84:85]
	v_cvt_pk_bf16_f32 v43, v86, v87
	v_lshl_add_u64 v[86:87], v[84:85], 0, v[126:127]
	global_store_dwordx4 v[86:87], v[40:43], off
	v_pk_mul_f32 v[84:85], v[110:111], v[132:133]
	s_mov_b64 s[6:7], 0x400000
	v_pk_mul_f32 v[42:43], v[114:115], v[154:155]
	v_pk_mul_f32 v[40:41], v[112:113], v[148:149]
	v_pk_mul_f32 v[90:91], v[92:93], v[150:151]
	v_cvt_pk_bf16_f32 v40, v40, v41
	v_cvt_pk_bf16_f32 v41, v42, v43
	v_cvt_pk_bf16_f32 v42, v88, v89
	v_cvt_pk_bf16_f32 v43, v84, v85
	v_lshl_add_u64 v[84:85], v[124:125], 0, s[6:7]
	s_mov_b32 s6, 0x400000
	v_add_co_u32_e32 v88, vcc, s6, v124
	s_mov_b64 s[6:7], 0x480000
	s_nop 0
	v_addc_co_u32_e32 v89, vcc, 0, v125, vcc
	global_store_dwordx4 v[88:89], v[40:43], off
; __device__ __forceinline__ u32x4 pack8(f32x4 a, f32x4 b) { u32x4 r; r[0] = cvt_pk_bf16(a[0], a[1]); r[1] = cvt_pk_bf16(a[2], a[3]); r[2] = cvt_pk_bf16(b[0], b[1]); r[3] = cvt_pk_bf16(b[2], b[3]); return r; }
;     __device__ __forceinline__ void operator()(const AccT& acc, const Unit& u, int wr, int wc, int fr, int fq) const {
;     ...
;         for (int bj = 0; bj < 2; ++bj) {
;             const int col = colbase + bj * HALF;
;             f32x4 s0, s1;
; #pragma unroll
;             for (int j = 0; j < 4; ++j) { const f32x4 pc = *(const f32x4*)(ssp + (size_t)(col + j) * 16 + 8), pd = *(const f32x4*)(ssp + (size_t)(col + 4 + j) * 16 + 8);
;                 s0[j] = rsqrtf(((pc[0] + pc[1]) + (pc[2] + pc[3])) * (1.0f / 256.0f) + EPS); s1[j] = rsqrtf(((pd[0] + pd[1]) + (pd[2] + pd[3])) * (1.0f / 256.0f) + EPS); }
; #pragma unroll
;             for (int ai = 0; ai < 2; ++ai)
; #pragma unroll
;                 for (int m = 0; m < 4; ++m) {
;                     const int row = row0 + ai * HALF + m * 16;
;                     *(u32x4*)(Vt + (size_t)row * SEQ + col) = pack8(acc[ai][bj][m][0] * s0, acc[ai][bj][m][1] * s1);
	v_pk_mul_f32 v[88:89], v[94:95], v[132:133]
	s_nop 0
	v_pk_mul_f32 v[42:43], v[98:99], v[154:155]
	v_pk_mul_f32 v[40:41], v[96:97], v[148:149]
	s_nop 0
	v_cvt_pk_bf16_f32 v40, v40, v41
	v_cvt_pk_bf16_f32 v41, v42, v43
	v_cvt_pk_bf16_f32 v42, v90, v91
	v_cvt_pk_bf16_f32 v43, v88, v89
	v_lshl_add_u64 v[88:89], v[124:125], 0, s[6:7]
	s_mov_b32 s6, 0x480000
	v_add_co_u32_e32 v90, vcc, s6, v124
	s_mov_b64 s[6:7], 0x500000
	s_nop 0
	v_addc_co_u32_e32 v91, vcc, 0, v125, vcc
	global_store_dwordx4 v[90:91], v[40:43], off
	s_nop 1
	v_pk_mul_f32 v[42:43], v[82:83], v[154:155]
	v_pk_mul_f32 v[40:41], v[80:81], v[148:149]
	v_add_u32_e32 v80, 0x85, v144
	v_cvt_pk_bf16_f32 v40, v40, v41
	v_cvt_pk_bf16_f32 v41, v42, v43
	v_cvt_pk_bf16_f32 v42, v76, v77
	v_lshl_add_u64 v[76:77], v[124:125], 0, s[6:7]
	s_mov_b32 s6, 0x500000
	v_cvt_pk_bf16_f32 v43, v78, v79
	v_add_co_u32_e32 v78, vcc, s6, v124
	s_mov_b64 s[6:7], 0x580000
	s_nop 0
	v_addc_co_u32_e32 v79, vcc, 0, v125, vcc
	global_store_dwordx4 v[78:79], v[40:43], off
	v_lshl_add_u64 v[78:79], v[124:125], 0, s[6:7]
	s_mov_b32 s6, 0x580000
	v_pk_mul_f32 v[42:43], v[74:75], v[154:155]
	v_pk_mul_f32 v[40:41], v[72:73], v[148:149]
	v_add_u32_e32 v72, 0x81, v144
	v_cvt_pk_bf16_f32 v40, v40, v41
	v_cvt_pk_bf16_f32 v41, v42, v43
	v_cvt_pk_bf16_f32 v42, v68, v69
	v_add_co_u32_e32 v68, vcc, s6, v124
	s_movk_i32 s6, 0x2000
	s_nop 0
	v_addc_co_u32_e32 v69, vcc, 0, v125, vcc
	v_ashrrev_i32_e32 v73, 31, v72
	v_cvt_pk_bf16_f32 v43, v70, v71
	global_store_dwordx4 v[68:69], v[40:43], off
	v_lshlrev_b64 v[72:73], 6, v[72:73]
	v_lshl_add_u64 v[72:73], s[28:29], 0, v[72:73]
	v_add_co_u32_e32 v40, vcc, s6, v146
	v_mov_b32_e32 v72, v222
	v_mov_b32_e32 v73, v223
	v_mov_b32_e32 v74, v224
	v_mov_b32_e32 v75, v225
	s_nop 0
	v_addc_co_u32_e32 v41, vcc, 0, v147, vcc
	v_mov_b32_e32 v40, v218
	v_mov_b32_e32 v41, v219
	v_mov_b32_e32 v42, v220
	v_mov_b32_e32 v43, v221
	v_add_u32_e32 v68, 0x84, v144
	v_ashrrev_i32_e32 v69, 31, v68
	v_ashrrev_i32_e32 v81, 31, v80
	v_lshlrev_b64 v[68:69], 6, v[68:69]
	v_lshlrev_b64 v[80:81], 6, v[80:81]
	v_lshl_add_u64 v[68:69], s[28:29], 0, v[68:69]
	v_lshl_add_u64 v[80:81], s[28:29], 0, v[80:81]
	v_mov_b32_e32 v68, v234
	v_mov_b32_e32 v69, v235
	v_mov_b32_e32 v70, v236
	v_mov_b32_e32 v71, v237
	s_nop 0
	v_mov_b32_e32 v90, v238
	v_mov_b32_e32 v91, v239
	v_mov_b32_e32 v92, v240
	v_mov_b32_e32 v93, v241
	v_mov_b32_e32 v81, v72
	v_mov_b32_e32 v80, v40
	v_mov_b32_e32 v72, v41
	v_pk_add_f32 v[40:41], v[80:81], v[72:73]
	v_mov_b32_e32 v72, v42
	v_mov_b32_e32 v73, v74
	v_mov_b32_e32 v74, v43
	v_pk_add_f32 v[42:43], v[72:73], v[74:75]
	s_nop 0
	v_pk_add_f32 v[40:41], v[40:41], v[42:43]
	s_nop 0
	v_pk_fma_f32 v[40:41], v[40:41], s[52:53], v[142:143] op_sel_hi:[1,0,0]
	s_nop 0
	v_mul_f32_e32 v42, 0x4b800000, v40
	v_cmp_gt_f32_e64 s[6:7], s11, v40
	v_cmp_gt_f32_e32 vcc, s11, v41
	s_nop 0
	v_cndmask_b32_e64 v40, v40, v42, s[6:7]
	v_mul_f32_e32 v42, 0x4b800000, v41
	v_cndmask_b32_e32 v41, v41, v42, vcc
	v_rsq_f32_e32 v40, v40
	v_rsq_f32_e32 v41, v41
	s_nop 0
	v_pk_mul_f32 v[42:43], v[40:41], s[30:31] op_sel_hi:[1,0]
	s_nop 0
	v_cndmask_b32_e32 v81, v41, v43, vcc
	v_cndmask_b32_e64 v80, v40, v42, s[6:7]
	v_mov_b32_e32 v40, v68
	v_mov_b32_e32 v41, v90
	v_mov_b32_e32 v90, v69
	v_mov_b32_e32 v42, v70
	v_mov_b32_e32 v43, v92
	v_mov_b32_e32 v92, v71
	v_pk_add_f32 v[40:41], v[40:41], v[90:91]
	v_pk_add_f32 v[42:43], v[42:43], v[92:93]
	v_add_u32_e32 v90, 0x87, v144
	v_pk_add_f32 v[40:41], v[40:41], v[42:43]
	v_ashrrev_i32_e32 v91, 31, v90
	v_pk_fma_f32 v[40:41], v[40:41], s[52:53], v[142:143] op_sel_hi:[1,0,0]
	v_lshlrev_b64 v[90:91], 6, v[90:91]
	v_mul_f32_e32 v42, 0x4b800000, v40
	v_cmp_gt_f32_e64 s[6:7], s11, v40
	v_cmp_gt_f32_e32 vcc, s11, v41
	v_lshl_add_u64 v[90:91], s[28:29], 0, v[90:91]
	v_cndmask_b32_e64 v40, v40, v42, s[6:7]
	v_mul_f32_e32 v42, 0x4b800000, v41
	v_cndmask_b32_e32 v41, v41, v42, vcc
	v_rsq_f32_e32 v40, v40
	v_rsq_f32_e32 v41, v41
	v_mov_b32_e32 v90, v246
	v_mov_b32_e32 v91, v247
	v_mov_b32_e32 v92, v248
	v_mov_b32_e32 v93, v249
	v_pk_mul_f32 v[32:33], v[32:33], v[80:81]
	v_pk_mul_f32 v[16:17], v[16:17], v[80:81]
	v_pk_mul_f32 v[42:43], v[40:41], s[30:31] op_sel_hi:[1,0]
	v_pk_mul_f32 v[8:9], v[8:9], v[80:81]
	v_cndmask_b32_e64 v82, v40, v42, s[6:7]
	v_add_u32_e32 v40, 0x82, v144
	v_cndmask_b32_e32 v83, v41, v43, vcc
	v_ashrrev_i32_e32 v41, 31, v40
	v_lshlrev_b64 v[40:41], 6, v[40:41]
	v_lshl_add_u64 v[40:41], s[28:29], 0, v[40:41]
	v_mov_b32_e32 v72, v226
	v_mov_b32_e32 v73, v227
	v_mov_b32_e32 v74, v228
	v_mov_b32_e32 v75, v229
	v_add_u32_e32 v40, 0x86, v144
	v_ashrrev_i32_e32 v41, 31, v40
	v_lshlrev_b64 v[40:41], 6, v[40:41]
	v_lshl_add_u64 v[40:41], s[28:29], 0, v[40:41]
	v_mov_b32_e32 v68, v242
	v_mov_b32_e32 v69, v243
	v_mov_b32_e32 v70, v244
	v_mov_b32_e32 v71, v245
	v_add_u32_e32 v40, 0x83, v144
	v_ashrrev_i32_e32 v41, 31, v40
; __device__ __forceinline__ u32x4 pack8(f32x4 a, f32x4 b) { u32x4 r; r[0] = cvt_pk_bf16(a[0], a[1]); r[1] = cvt_pk_bf16(a[2], a[3]); r[2] = cvt_pk_bf16(b[0], b[1]); r[3] = cvt_pk_bf16(b[2], b[3]); return r; }
;     __device__ __forceinline__ void operator()(const AccT& acc, const Unit& u, int wr, int wc, int fr, int fq) const {
;     ...
;         for (int bj = 0; bj < 2; ++bj) {
;             const int col = colbase + bj * HALF;
;             f32x4 s0, s1;
; #pragma unroll
;             for (int j = 0; j < 4; ++j) { const f32x4 pc = *(const f32x4*)(ssp + (size_t)(col + j) * 16 + 8), pd = *(const f32x4*)(ssp + (size_t)(col + 4 + j) * 16 + 8);
;                 s0[j] = rsqrtf(((pc[0] + pc[1]) + (pc[2] + pc[3])) * (1.0f / 256.0f) + EPS); s1[j] = rsqrtf(((pd[0] + pd[1]) + (pd[2] + pd[3])) * (1.0f / 256.0f) + EPS); }
; #pragma unroll
;             for (int ai = 0; ai < 2; ++ai)
; #pragma unroll
;                 for (int m = 0; m < 4; ++m) {
;                     const int row = row0 + ai * HALF + m * 16;
;                     *(u32x4*)(Vt + (size_t)row * SEQ + col) = pack8(acc[ai][bj][m][0] * s0, acc[ai][bj][m][1] * s1);
	v_lshlrev_b64 v[40:41], 6, v[40:41]
	v_lshl_add_u64 v[40:41], s[28:29], 0, v[40:41]
	v_mov_b32_e32 v40, v230
	v_mov_b32_e32 v41, v231
	v_mov_b32_e32 v42, v232
	v_mov_b32_e32 v43, v233
	v_pk_mul_f32 v[60:61], v[60:61], v[82:83]
	v_pk_mul_f32 v[44:45], v[44:45], v[82:83]
	v_readlane_b32 s28, v254, 44
	v_readlane_b32 s29, v254, 45
	v_mov_b32_e32 v94, v72
	v_mov_b32_e32 v72, v74
	v_mov_b32_e32 v95, v40
	v_mov_b32_e32 v40, v73
	v_mov_b32_e32 v73, v42
	v_mov_b32_e32 v42, v75
	v_pk_add_f32 v[40:41], v[94:95], v[40:41]
	v_pk_add_f32 v[42:43], v[72:73], v[42:43]
	s_nop 0
	v_pk_add_f32 v[40:41], v[40:41], v[42:43]
	s_nop 0
	v_pk_fma_f32 v[40:41], v[40:41], s[52:53], v[142:143] op_sel_hi:[1,0,0]
	s_nop 0
	v_mul_f32_e32 v42, 0x4b800000, v40
	v_cmp_gt_f32_e64 s[6:7], s11, v40
	v_cmp_gt_f32_e32 vcc, s11, v41
	s_nop 0
	v_cndmask_b32_e64 v40, v40, v42, s[6:7]
	v_mul_f32_e32 v42, 0x4b800000, v41
	v_cndmask_b32_e32 v41, v41, v42, vcc
	v_rsq_f32_e32 v40, v40
	v_rsq_f32_e32 v41, v41
	s_nop 0
	v_pk_mul_f32 v[42:43], v[40:41], s[30:31] op_sel_hi:[1,0]
	s_nop 0
	v_cndmask_b32_e32 v73, v41, v43, vcc
	v_cndmask_b32_e64 v72, v40, v42, s[6:7]
	v_mov_b32_e32 v40, v68
	v_mov_b32_e32 v41, v90
	v_mov_b32_e32 v90, v69
	v_mov_b32_e32 v42, v70
	v_mov_b32_e32 v43, v92
	v_mov_b32_e32 v92, v71
	v_pk_add_f32 v[40:41], v[40:41], v[90:91]
	v_pk_add_f32 v[42:43], v[42:43], v[92:93]
	v_pk_mul_f32 v[34:35], v[34:35], v[72:73]
	v_pk_add_f32 v[40:41], v[40:41], v[42:43]
	v_pk_mul_f32 v[18:19], v[18:19], v[72:73]
	v_pk_fma_f32 v[40:41], v[40:41], s[52:53], v[142:143] op_sel_hi:[1,0,0]
	v_pk_mul_f32 v[10:11], v[10:11], v[72:73]
	v_mul_f32_e32 v42, 0x4b800000, v40
	v_cmp_gt_f32_e64 s[6:7], s11, v40
	v_cmp_gt_f32_e32 vcc, s11, v41
	s_nop 0
	v_cndmask_b32_e64 v40, v40, v42, s[6:7]
	v_mul_f32_e32 v42, 0x4b800000, v41
	v_cndmask_b32_e32 v41, v41, v42, vcc
	v_rsq_f32_e32 v40, v40
	v_rsq_f32_e32 v41, v41
	s_nop 0
	v_pk_mul_f32 v[42:43], v[40:41], s[30:31] op_sel_hi:[1,0]
	s_nop 0
	v_cndmask_b32_e32 v69, v41, v43, vcc
	v_cndmask_b32_e64 v68, v40, v42, s[6:7]
	v_pk_mul_f32 v[40:41], v[64:65], v[80:81]
	v_pk_mul_f32 v[42:43], v[66:67], v[72:73]
	v_cvt_pk_bf16_f32 v40, v40, v41
	v_pk_mul_f32 v[62:63], v[62:63], v[68:69]
	v_cvt_pk_bf16_f32 v41, v42, v43
	v_cvt_pk_bf16_f32 v42, v60, v61
	v_pk_mul_f32 v[46:47], v[46:47], v[68:69]
	v_cvt_pk_bf16_f32 v43, v62, v63
	global_store_dwordx4 v[124:125], v[40:43], off offset:256
	v_readlane_b32 s30, v254, 42
	s_andn2_b64 vcc, exec, s[4:5]
	v_pk_mul_f32 v[40:41], v[48:49], v[80:81]
	v_pk_mul_f32 v[42:43], v[50:51], v[72:73]
	v_cvt_pk_bf16_f32 v40, v40, v41
	s_mov_b32 s7, s10
	v_cvt_pk_bf16_f32 v41, v42, v43
	v_cvt_pk_bf16_f32 v42, v44, v45
	v_cvt_pk_bf16_f32 v43, v46, v47
	global_store_dwordx4 v[116:117], v[40:43], off offset:256
	s_mov_b32 s6, s12
	v_readlane_b32 s31, v254, 43
	v_pk_mul_f32 v[40:41], v[30:31], v[68:69]
	v_pk_mul_f32 v[30:31], v[28:29], v[82:83]
	v_cvt_pk_bf16_f32 v28, v32, v33
	v_cvt_pk_bf16_f32 v29, v34, v35
	v_readlane_b32 s4, v254, 46
	v_cvt_pk_bf16_f32 v30, v30, v31
	v_cvt_pk_bf16_f32 v31, v40, v41
	global_store_dwordx4 v[100:101], v[28:31], off offset:256
	v_readlane_b32 s5, v254, 47
	s_nop 0
	v_pk_mul_f32 v[28:29], v[14:15], v[68:69]
	v_pk_mul_f32 v[14:15], v[12:13], v[82:83]
	v_cvt_pk_bf16_f32 v12, v16, v17
	v_cvt_pk_bf16_f32 v13, v18, v19
	v_pk_mul_f32 v[16:17], v[54:55], v[68:69]
	v_cvt_pk_bf16_f32 v14, v14, v15
	v_cvt_pk_bf16_f32 v15, v28, v29
	global_store_dwordx4 v[86:87], v[12:15], off offset:256
	v_pk_mul_f32 v[18:19], v[52:53], v[82:83]
	s_nop 0
	v_pk_mul_f32 v[12:13], v[56:57], v[80:81]
	v_pk_mul_f32 v[14:15], v[58:59], v[72:73]
	v_cvt_pk_bf16_f32 v12, v12, v13
	s_nop 0
	v_cvt_pk_bf16_f32 v13, v14, v15
	v_cvt_pk_bf16_f32 v14, v18, v19
	v_cvt_pk_bf16_f32 v15, v16, v17
	global_store_dwordx4 v[84:85], v[12:15], off offset:256
	v_pk_mul_f32 v[16:17], v[38:39], v[68:69]
	v_pk_mul_f32 v[18:19], v[36:37], v[82:83]
	v_pk_mul_f32 v[12:13], v[158:159], v[80:81]
	v_pk_mul_f32 v[14:15], v[160:161], v[72:73]
	v_cvt_pk_bf16_f32 v12, v12, v13
	s_nop 0
	v_cvt_pk_bf16_f32 v13, v14, v15
	v_cvt_pk_bf16_f32 v14, v18, v19
	v_cvt_pk_bf16_f32 v15, v16, v17
	global_store_dwordx4 v[88:89], v[12:15], off offset:256
	v_pk_mul_f32 v[16:17], v[22:23], v[68:69]
	v_pk_mul_f32 v[18:19], v[20:21], v[82:83]
	v_pk_mul_f32 v[12:13], v[24:25], v[80:81]
	v_pk_mul_f32 v[14:15], v[26:27], v[72:73]
	v_cvt_pk_bf16_f32 v12, v12, v13
	s_nop 0
	v_cvt_pk_bf16_f32 v13, v14, v15
	v_cvt_pk_bf16_f32 v14, v18, v19
	v_cvt_pk_bf16_f32 v15, v16, v17
	global_store_dwordx4 v[76:77], v[12:15], off offset:256
	s_nop 1
	v_pk_mul_f32 v[12:13], v[6:7], v[68:69]
	v_pk_mul_f32 v[6:7], v[4:5], v[82:83]
	v_cvt_pk_bf16_f32 v4, v8, v9
	v_cvt_pk_bf16_f32 v5, v10, v11
	s_nop 0
	v_cvt_pk_bf16_f32 v6, v6, v7
	v_cvt_pk_bf16_f32 v7, v12, v13
	global_store_dwordx4 v[78:79], v[4:7], off offset:256
	s_cbranch_vccz .LBB0_192

; #define PG8_LDA(dst, b, h) do { _Pragma("unroll") for (int m = 0; m < 4; ++m) _Pragma("unroll") for (int k = 0; k < 2; ++k) dst[m][k] = *(const LAS bf16x8*)(lds + PG8_SA(b, h) + aoff + m * 2048 + k * 1024); } while (0)
; #define PG8_WAIT_V(n) asm volatile("s_waitcnt vmcnt(" #n ")" ::: "memory")
; template <class Epi, class Sched>
; __device__ __forceinline__ void gemm_phase(int wv, LAS unsigned char* lds, const Gemm g, const Sched& S, const Epi& E) { LIDS
;     ...
;         const bool has_next = S.next(ui + 1, nxt);
;         const char* nA = has_next ? (const char*)g.A + (size_t)nxt.pm * g.tstepA : cA; const char* nB = has_next ? (const char*)g.Bt + (size_t)nxt.pn * g.tstepB : cB;
;         for (int t = 0; t < nt; t += 2) {
;             const bool last = (t == nt - 2);
;             const char* a1 = cA + (size_t)(t + 1) * kstepA;
;             const char* a2 = last ? nA : cA + (size_t)(t + 2) * kstepA; const char* b2 = last ? nB : cB + (size_t)(t + 2) * kstepB;
;             const char* a3 = a2 + kstepA; const char* b3 = b2 + kstepB;
;             asm volatile("" : "+s"(a1), "+s"(a2), "+s"(b2), "+s"(a3), "+s"(b3));
;             PG8_LDB(B0, 0, 0); PG8_SCHED; PG8_LDA(At, 0, 0); PG8_STAGE(PG8_SA(1, 1), a1 + hstepA, voffA);
;             PG8_WAIT_L(8); PG8_BAR; PG8_WAIT_L(0); PG8_MMA(0, 0, At, B0); PG8_BAR; PG8_SCHED;
;             PG8_LDB(B1, 0, 1); PG8_STAGE(PG8_SB(0, 0), b2, voffB);
;             PG8_BAR; PG8_WAIT_L(0); PG8_MMA(0, 1, At, B1); PG8_BAR;
;             PG8_LDA(At, 0, 1); PG8_STAGE(PG8_SA(0, 0), a2, voffA);
;             PG8_BAR; PG8_WAIT_L(0); PG8_MMA(1, 0, At, B0); PG8_BAR; PG8_SCHED;
;             PG8_STAGE(PG8_SB(0, 1), b2 + hstepB, voffB);
;             PG8_WAIT_V(6); PG8_BAR; PG8_MMA(1, 1, At, B1); PG8_BAR;
;             PG8_LDB(B0, 1, 0); PG8_SCHED; PG8_LDA(At, 1, 0); PG8_STAGE(PG8_SA(0, 1), a2 + hstepA, voffA);
;             PG8_WAIT_L(8); PG8_BAR; PG8_WAIT_L(0); PG8_MMA(0, 0, At, B0); PG8_BAR; PG8_SCHED;
;             PG8_LDB(B1, 1, 1); PG8_STAGE(PG8_SB(1, 0), b3, voffB);
;             PG8_BAR; PG8_WAIT_L(0); PG8_MMA(0, 1, At, B1); PG8_BAR;
;             PG8_LDA(At, 1, 1); PG8_STAGE(PG8_SA(1, 0), a3, voffA);
;             PG8_BAR; PG8_WAIT_L(0); PG8_MMA(1, 0, At, B0); PG8_BAR; PG8_SCHED;
;             PG8_STAGE(PG8_SB(1, 1), b3 + hstepB, voffB);
;             PG8_WAIT_V(6); PG8_BAR; PG8_MMA(1, 1, At, B1); PG8_BAR;
.LBB0_205:
	s_ashr_i32 s9, s8, 31
	s_lshl_b64 s[58:59], s[8:9], 16
	s_add_u32 s62, s17, s58
	s_addc_u32 s63, s18, s59
	s_and_b64 s[58:59], s[72:73], exec
	s_cselect_b32 s73, s63, s87
	s_cselect_b32 s72, s62, s86
	s_add_u32 s58, s78, 0x80
	s_addc_u32 s59, s79, 0
	s_add_u32 s88, s78, 0x100
	s_addc_u32 s89, s79, 0
	s_add_u32 s90, s86, 0x100
	s_addc_u32 s91, s87, 0
	s_add_u32 s78, s78, 0x180
	s_addc_u32 s79, s79, 0
	s_add_u32 s84, s86, 0x180
	s_addc_u32 s85, s87, 0
	s_add_i32 s70, 16, 0x10000
	s_mov_b64 s[86:87], s[78:79]
	v_add_u32_e32 v124, s70, v8
	ds_read_b128 v[10:13], v124
	ds_read_b128 v[14:17], v124 offset:1024
	ds_read_b128 v[18:21], v124 offset:2048
	ds_read_b128 v[22:25], v124 offset:3072
	s_add_u32 s76, s58, 0x18000
	s_addc_u32 s77, s59, 0
	ds_read_b128 v[26:29], v9
	ds_read_b128 v[30:33], v9 offset:1024
	ds_read_b128 v[34:37], v9 offset:2048
	ds_read_b128 v[38:41], v9 offset:3072
	ds_read_b128 v[42:45], v9 offset:4096
	ds_read_b128 v[46:49], v9 offset:5120
	ds_read_b128 v[50:53], v9 offset:6144
	ds_read_b128 v[54:57], v9 offset:7168
	s_nop 0
	v_lshl_add_u64 v[58:59], s[76:77], 0, v[4:5]
	s_add_i32 s77, s20, 0xc000
	s_add_u32 s58, s58, 0x24000
	s_mov_b32 m0, s77
	s_addc_u32 s59, s59, 0
	s_add_i32 s9, s20, 0xe000
	global_load_lds_dwordx4 v[58:59], off
	s_mov_b32 m0, s9
	v_lshl_add_u64 v[58:59], s[58:59], 0, v[4:5]
	global_load_lds_dwordx4 v[58:59], off
	s_waitcnt lgkmcnt(8)
	s_barrier
	s_waitcnt lgkmcnt(0)
	s_setprio 1
	v_mfma_f32_16x16x32_bf16 v[58:61], v[10:13], v[26:29], v[0:3]
	v_mfma_f32_16x16x32_bf16 v[26:29], v[18:21], v[26:29], v[0:3]
	v_mfma_f32_16x16x32_bf16 v[58:61], v[14:17], v[30:33], v[58:61]
	v_mfma_f32_16x16x32_bf16 v[26:29], v[22:25], v[30:33], v[26:29]
	v_mfma_f32_16x16x32_bf16 v[30:33], v[10:13], v[34:37], v[0:3]
	v_mfma_f32_16x16x32_bf16 v[34:37], v[18:21], v[34:37], v[0:3]
	v_mfma_f32_16x16x32_bf16 v[30:33], v[14:17], v[38:41], v[30:33]
	v_mfma_f32_16x16x32_bf16 v[34:37], v[22:25], v[38:41], v[34:37]
	v_mfma_f32_16x16x32_bf16 v[38:41], v[10:13], v[42:45], v[0:3]
	v_mfma_f32_16x16x32_bf16 v[42:45], v[18:21], v[42:45], v[0:3]
	v_mfma_f32_16x16x32_bf16 v[38:41], v[14:17], v[46:49], v[38:41]
	v_mfma_f32_16x16x32_bf16 v[42:45], v[22:25], v[46:49], v[42:45]
	v_mfma_f32_16x16x32_bf16 v[46:49], v[10:13], v[50:53], v[0:3]
	v_mfma_f32_16x16x32_bf16 v[50:53], v[18:21], v[50:53], v[0:3]
	v_mfma_f32_16x16x32_bf16 v[46:49], v[14:17], v[54:57], v[46:49]
	v_mfma_f32_16x16x32_bf16 v[50:53], v[22:25], v[54:57], v[50:53]
	s_setprio 0
	s_barrier
	s_mov_b64 s[58:59], s[90:91]
	s_add_i32 s70, s70, s19
	v_lshl_add_u64 v[54:55], s[58:59], 0, v[6:7]
	s_add_u32 s58, s90, 0x8000
	s_mov_b32 m0, s70
	s_addc_u32 s59, s91, 0
	global_load_lds_dwordx4 v[54:55], off
	s_nop 0
	v_lshl_add_u64 v[54:55], s[58:59], 0, v[6:7]
	s_add_i32 s58, s70, 0x2000
	s_mov_b32 m0, s58
	s_nop 0
	global_load_lds_dwordx4 v[54:55], off
	s_barrier
	s_waitcnt lgkmcnt(0)
	s_setprio 1
	s_setprio 0
	s_mov_b64 s[82:83], s[88:89]
	s_barrier
	ds_read_b128 v[54:57], v9 offset:16384
	ds_read_b128 v[62:65], v9 offset:17408
	ds_read_b128 v[66:69], v9 offset:18432
	ds_read_b128 v[70:73], v9 offset:19456
	ds_read_b128 v[74:77], v9 offset:20480
	ds_read_b128 v[78:81], v9 offset:21504
	ds_read_b128 v[82:85], v9 offset:22528
	ds_read_b128 v[86:89], v9 offset:23552
	s_mov_b32 m0, s20
	v_lshl_add_u64 v[90:91], s[82:83], 0, v[4:5]
	s_add_u32 s82, s88, 0xc000
	s_addc_u32 s83, s89, 0
	global_load_lds_dwordx4 v[90:91], off
	s_mov_b32 m0, s22
	v_lshl_add_u64 v[90:91], s[82:83], 0, v[4:5]
	global_load_lds_dwordx4 v[90:91], off
	s_barrier
	s_waitcnt lgkmcnt(0)
	s_setprio 1
	v_mfma_f32_16x16x32_bf16 v[90:93], v[10:13], v[54:57], v[0:3]
	v_mfma_f32_16x16x32_bf16 v[54:57], v[18:21], v[54:57], v[0:3]
	v_mfma_f32_16x16x32_bf16 v[90:93], v[14:17], v[62:65], v[90:93]
	v_mfma_f32_16x16x32_bf16 v[54:57], v[22:25], v[62:65], v[54:57]
	v_mfma_f32_16x16x32_bf16 v[62:65], v[10:13], v[66:69], v[0:3]
	v_mfma_f32_16x16x32_bf16 v[66:69], v[18:21], v[66:69], v[0:3]
	v_mfma_f32_16x16x32_bf16 v[62:65], v[14:17], v[70:73], v[62:65]
	v_mfma_f32_16x16x32_bf16 v[66:69], v[22:25], v[70:73], v[66:69]
	v_mfma_f32_16x16x32_bf16 v[70:73], v[10:13], v[74:77], v[0:3]
	v_mfma_f32_16x16x32_bf16 v[10:13], v[10:13], v[82:85], v[0:3]
	v_mfma_f32_16x16x32_bf16 v[70:73], v[14:17], v[78:81], v[70:73]
	v_mfma_f32_16x16x32_bf16 v[74:77], v[18:21], v[74:77], v[0:3]
	v_mfma_f32_16x16x32_bf16 v[10:13], v[14:17], v[86:89], v[10:13]
	v_mfma_f32_16x16x32_bf16 v[14:17], v[18:21], v[82:85], v[0:3]
	v_mfma_f32_16x16x32_bf16 v[74:77], v[22:25], v[78:81], v[74:77]
	v_mfma_f32_16x16x32_bf16 v[14:17], v[22:25], v[86:89], v[14:17]
	s_setprio 0
	s_barrier
	s_add_u32 s82, s90, 0x10000
	s_addc_u32 s83, s91, 0
	s_mov_b32 m0, s23
	v_lshl_add_u64 v[18:19], s[82:83], 0, v[6:7]
	s_add_u32 s82, s90, 0x18000
	s_addc_u32 s83, s91, 0
	global_load_lds_dwordx4 v[18:19], off
	s_mov_b32 m0, s24
	v_lshl_add_u64 v[18:19], s[82:83], 0, v[6:7]
	global_load_lds_dwordx4 v[18:19], off
	s_waitcnt vmcnt(6)
	s_barrier
	s_setprio 1
	s_setprio 0
	s_add_i32 s76, 16, 0x18000
	v_add_u32_e32 v125, s76, v8
	s_barrier
	ds_read_b128 v[18:21], v125
	ds_read_b128 v[22:25], v125 offset:1024
	ds_read_b128 v[78:81], v125 offset:2048
	ds_read_b128 v[82:85], v125 offset:3072
	s_add_u32 s82, s88, 0x18000
	s_addc_u32 s83, s89, 0
	ds_read_b128 v[86:89], v9 offset:32768
	ds_read_b128 v[94:97], v9 offset:33792
	ds_read_b128 v[98:101], v9 offset:34816
	ds_read_b128 v[102:105], v9 offset:35840
	ds_read_b128 v[106:109], v9 offset:36864
	ds_read_b128 v[110:113], v9 offset:37888
	ds_read_b128 v[114:117], v9 offset:38912
	ds_read_b128 v[118:121], v9 offset:39936
	s_mov_b32 m0, s25
	v_lshl_add_u64 v[122:123], s[82:83], 0, v[4:5]
	s_add_u32 s82, s88, 0x24000
	s_addc_u32 s83, s89, 0
	global_load_lds_dwordx4 v[122:123], off
	s_mov_b32 m0, s26
	v_lshl_add_u64 v[122:123], s[82:83], 0, v[4:5]
	global_load_lds_dwordx4 v[122:123], off
	s_waitcnt lgkmcnt(8)
	s_barrier
; #define PG8_STAGE(bufoff, gbase, voff) do { _Pragma("unroll") for (int _i = 0; _i < 2; ++_i) { const char* _gb = (const char*)(gbase) + (size_t)_i * (voff##_q); asm volatile("" : "+s"(_gb)); \
;         __builtin_amdgcn_global_load_lds((const unsigned*)(_gb + (voff)), (LAS unsigned*)(lds + (bufoff) + ldsw + _i * 8192), 16, 0, 0); } } while (0)
; #define PG8_LDA(dst, b, h) do { _Pragma("unroll") for (int m = 0; m < 4; ++m) _Pragma("unroll") for (int k = 0; k < 2; ++k) dst[m][k] = *(const LAS bf16x8*)(lds + PG8_SA(b, h) + aoff + m * 2048 + k * 1024); } while (0)
; #define PG8_LDB(dst, b, h) do { _Pragma("unroll") for (int n = 0; n < 2; ++n) _Pragma("unroll") for (int k = 0; k < 2; ++k) dst[n][k] = *(const LAS bf16x8*)(lds + PG8_SB(b, h) + boff + n * 2048 + k * 1024); } while (0)
; #define PG8_WAIT_V(n) asm volatile("s_waitcnt vmcnt(" #n ")" ::: "memory")
; #define PG8_WAIT_L(n) asm volatile("s_waitcnt lgkmcnt(" #n ")" ::: "memory")
; template <class Epi, class Sched>
; __device__ __forceinline__ void gemm_phase(int wv, LAS unsigned char* lds, const Gemm g, const Sched& S, const Epi& E) { LIDS
;     ...
;             PG8_LDB(B0, 0, 0); PG8_SCHED; PG8_LDA(At, 0, 0); PG8_STAGE(PG8_SA(1, 1), a1 + hstepA, voffA);
;             PG8_WAIT_L(8); PG8_BAR; PG8_WAIT_L(0); PG8_MMA(0, 0, At, B0); PG8_BAR; PG8_SCHED;
;             PG8_LDB(B1, 0, 1); PG8_STAGE(PG8_SB(0, 0), b2, voffB);
;             PG8_BAR; PG8_WAIT_L(0); PG8_MMA(0, 1, At, B1); PG8_BAR;
;             PG8_LDA(At, 0, 1); PG8_STAGE(PG8_SA(0, 0), a2, voffA);
;             PG8_BAR; PG8_WAIT_L(0); PG8_MMA(1, 0, At, B0); PG8_BAR; PG8_SCHED;
;             PG8_STAGE(PG8_SB(0, 1), b2 + hstepB, voffB);
;             PG8_WAIT_V(6); PG8_BAR; PG8_MMA(1, 1, At, B1); PG8_BAR;
;             PG8_LDB(B0, 1, 0); PG8_SCHED; PG8_LDA(At, 1, 0); PG8_STAGE(PG8_SA(0, 1), a2 + hstepA, voffA);
;             PG8_WAIT_L(8); PG8_BAR; PG8_WAIT_L(0); PG8_MMA(0, 0, At, B0); PG8_BAR; PG8_SCHED;
;             PG8_LDB(B1, 1, 1); PG8_STAGE(PG8_SB(1, 0), b3, voffB);
;             PG8_BAR; PG8_WAIT_L(0); PG8_MMA(0, 1, At, B1); PG8_BAR;
;             PG8_LDA(At, 1, 1); PG8_STAGE(PG8_SA(1, 0), a3, voffA);
;             PG8_BAR; PG8_WAIT_L(0); PG8_MMA(1, 0, At, B0); PG8_BAR; PG8_SCHED;
;             PG8_STAGE(PG8_SB(1, 1), b3 + hstepB, voffB);
;             PG8_WAIT_V(6); PG8_BAR; PG8_MMA(1, 1, At, B1); PG8_BAR;
	s_waitcnt lgkmcnt(0)
	s_setprio 1
	v_mfma_f32_16x16x32_bf16 v[58:61], v[18:21], v[86:89], v[58:61]
	v_mfma_f32_16x16x32_bf16 v[26:29], v[78:81], v[86:89], v[26:29]
	v_mfma_f32_16x16x32_bf16 v[30:33], v[18:21], v[98:101], v[30:33]
	v_mfma_f32_16x16x32_bf16 v[34:37], v[78:81], v[98:101], v[34:37]
	v_mfma_f32_16x16x32_bf16 v[38:41], v[18:21], v[106:109], v[38:41]
	v_mfma_f32_16x16x32_bf16 v[42:45], v[78:81], v[106:109], v[42:45]
	v_mfma_f32_16x16x32_bf16 v[46:49], v[18:21], v[114:117], v[46:49]
	v_mfma_f32_16x16x32_bf16 v[50:53], v[78:81], v[114:117], v[50:53]
	v_mfma_f32_16x16x32_bf16 v[58:61], v[22:25], v[94:97], v[58:61]
	v_mfma_f32_16x16x32_bf16 v[26:29], v[82:85], v[94:97], v[26:29]
	v_mfma_f32_16x16x32_bf16 v[30:33], v[22:25], v[102:105], v[30:33]
	v_mfma_f32_16x16x32_bf16 v[34:37], v[82:85], v[102:105], v[34:37]
	v_mfma_f32_16x16x32_bf16 v[38:41], v[22:25], v[110:113], v[38:41]
	v_mfma_f32_16x16x32_bf16 v[42:45], v[82:85], v[110:113], v[42:45]
	v_mfma_f32_16x16x32_bf16 v[46:49], v[22:25], v[118:121], v[46:49]
	v_mfma_f32_16x16x32_bf16 v[50:53], v[82:85], v[118:121], v[50:53]
	s_setprio 0
	s_barrier
	s_mov_b64 s[82:83], s[84:85]
	s_add_i32 s76, s76, s19
	v_lshl_add_u64 v[86:87], s[82:83], 0, v[6:7]
	s_add_u32 s82, s84, 0x8000
	s_mov_b32 m0, s76
	s_addc_u32 s83, s85, 0
	s_add_i32 s59, s76, 0x2000
	global_load_lds_dwordx4 v[86:87], off
	s_mov_b32 m0, s59
	v_lshl_add_u64 v[86:87], s[82:83], 0, v[6:7]
	global_load_lds_dwordx4 v[86:87], off
	s_barrier
	s_waitcnt lgkmcnt(0)
	s_setprio 1
	s_setprio 0
	s_mov_b64 s[82:83], s[86:87]
	s_barrier
	ds_read_b128 v[86:89], v9 offset:49152
	ds_read_b128 v[94:97], v9 offset:50176
	ds_read_b128 v[98:101], v9 offset:51200
	ds_read_b128 v[102:105], v9 offset:52224
	ds_read_b128 v[106:109], v9 offset:53248
	ds_read_b128 v[110:113], v9 offset:54272
	ds_read_b128 v[114:117], v9 offset:55296
	ds_read_b128 v[118:121], v9 offset:56320
	s_mov_b32 m0, s29
	v_lshl_add_u64 v[122:123], s[82:83], 0, v[4:5]
	s_add_u32 s82, s86, 0xc000
	s_addc_u32 s83, s87, 0
	global_load_lds_dwordx4 v[122:123], off
	s_mov_b32 m0, s30
	v_lshl_add_u64 v[122:123], s[82:83], 0, v[4:5]
	global_load_lds_dwordx4 v[122:123], off
	s_barrier
	s_waitcnt lgkmcnt(0)
	s_setprio 1
	v_mfma_f32_16x16x32_bf16 v[90:93], v[18:21], v[86:89], v[90:93]
	v_mfma_f32_16x16x32_bf16 v[54:57], v[78:81], v[86:89], v[54:57]
	v_mfma_f32_16x16x32_bf16 v[62:65], v[18:21], v[98:101], v[62:65]
	v_mfma_f32_16x16x32_bf16 v[66:69], v[78:81], v[98:101], v[66:69]
	v_mfma_f32_16x16x32_bf16 v[70:73], v[18:21], v[106:109], v[70:73]
	v_mfma_f32_16x16x32_bf16 v[74:77], v[78:81], v[106:109], v[74:77]
	v_mfma_f32_16x16x32_bf16 v[10:13], v[18:21], v[114:117], v[10:13]
	v_mfma_f32_16x16x32_bf16 v[14:17], v[78:81], v[114:117], v[14:17]
	v_mfma_f32_16x16x32_bf16 v[90:93], v[22:25], v[94:97], v[90:93]
	v_mfma_f32_16x16x32_bf16 v[54:57], v[82:85], v[94:97], v[54:57]
	v_mfma_f32_16x16x32_bf16 v[62:65], v[22:25], v[102:105], v[62:65]
	v_mfma_f32_16x16x32_bf16 v[66:69], v[82:85], v[102:105], v[66:69]
	v_mfma_f32_16x16x32_bf16 v[70:73], v[22:25], v[110:113], v[70:73]
	v_mfma_f32_16x16x32_bf16 v[74:77], v[82:85], v[110:113], v[74:77]
	v_mfma_f32_16x16x32_bf16 v[10:13], v[22:25], v[118:121], v[10:13]
	v_mfma_f32_16x16x32_bf16 v[14:17], v[82:85], v[118:121], v[14:17]
	s_setprio 0
	s_barrier
	s_add_u32 s82, s84, 0x10000
	s_addc_u32 s83, s85, 0
	s_mov_b32 m0, s31
	v_lshl_add_u64 v[18:19], s[82:83], 0, v[6:7]
	s_add_u32 s82, s84, 0x18000
	s_addc_u32 s83, s85, 0
	global_load_lds_dwordx4 v[18:19], off
	s_mov_b32 m0, s52
	v_lshl_add_u64 v[18:19], s[82:83], 0, v[6:7]
	global_load_lds_dwordx4 v[18:19], off
	s_waitcnt vmcnt(6)
	s_barrier
	s_setprio 1
	s_setprio 0
	s_add_u32 s86, s68, 0x80
	s_addc_u32 s87, s69, 0
	s_add_u32 s84, s72, 0x80
	s_addc_u32 s85, s73, 0
	s_barrier
	ds_read_b128 v[18:21], v124
	ds_read_b128 v[22:25], v124 offset:1024
	ds_read_b128 v[78:81], v124 offset:2048
	ds_read_b128 v[82:85], v124 offset:3072
	s_add_u32 s82, s78, 0x18000
	s_addc_u32 s83, s79, 0
	s_add_u32 s78, s78, 0x24000
	s_mov_b32 m0, s77
	ds_read_b128 v[86:89], v9
	ds_read_b128 v[94:97], v9 offset:1024
	ds_read_b128 v[98:101], v9 offset:2048
	ds_read_b128 v[102:105], v9 offset:3072
	ds_read_b128 v[106:109], v9 offset:4096
	ds_read_b128 v[110:113], v9 offset:5120
	ds_read_b128 v[114:117], v9 offset:6144
	ds_read_b128 v[118:121], v9 offset:7168
	s_addc_u32 s79, s79, 0
	v_lshl_add_u64 v[122:123], s[82:83], 0, v[4:5]
	global_load_lds_dwordx4 v[122:123], off
	s_mov_b32 m0, s9
	v_lshl_add_u64 v[122:123], s[78:79], 0, v[4:5]
	global_load_lds_dwordx4 v[122:123], off
	s_waitcnt lgkmcnt(8)
	s_barrier
	s_waitcnt lgkmcnt(0)
	s_setprio 1
	v_mfma_f32_16x16x32_bf16 v[58:61], v[18:21], v[86:89], v[58:61]
	v_mfma_f32_16x16x32_bf16 v[26:29], v[78:81], v[86:89], v[26:29]
	v_mfma_f32_16x16x32_bf16 v[30:33], v[18:21], v[98:101], v[30:33]
	v_mfma_f32_16x16x32_bf16 v[34:37], v[78:81], v[98:101], v[34:37]
	v_mfma_f32_16x16x32_bf16 v[38:41], v[18:21], v[106:109], v[38:41]
	v_mfma_f32_16x16x32_bf16 v[42:45], v[78:81], v[106:109], v[42:45]
	v_mfma_f32_16x16x32_bf16 v[46:49], v[18:21], v[114:117], v[46:49]
	v_mfma_f32_16x16x32_bf16 v[50:53], v[78:81], v[114:117], v[50:53]
	v_mfma_f32_16x16x32_bf16 v[58:61], v[22:25], v[94:97], v[58:61]
	v_mfma_f32_16x16x32_bf16 v[26:29], v[82:85], v[94:97], v[26:29]
	v_mfma_f32_16x16x32_bf16 v[30:33], v[22:25], v[102:105], v[30:33]
	v_mfma_f32_16x16x32_bf16 v[34:37], v[82:85], v[102:105], v[34:37]
	v_mfma_f32_16x16x32_bf16 v[38:41], v[22:25], v[110:113], v[38:41]
	v_mfma_f32_16x16x32_bf16 v[42:45], v[82:85], v[110:113], v[42:45]
	v_mfma_f32_16x16x32_bf16 v[46:49], v[22:25], v[118:121], v[46:49]
	v_mfma_f32_16x16x32_bf16 v[50:53], v[82:85], v[118:121], v[50:53]
	s_setprio 0
	s_barrier
; #define PG8_STAGE(bufoff, gbase, voff) do { _Pragma("unroll") for (int _i = 0; _i < 2; ++_i) { const char* _gb = (const char*)(gbase) + (size_t)_i * (voff##_q); asm volatile("" : "+s"(_gb)); \
;         __builtin_amdgcn_global_load_lds((const unsigned*)(_gb + (voff)), (LAS unsigned*)(lds + (bufoff) + ldsw + _i * 8192), 16, 0, 0); } } while (0)
; #define PG8_LDA(dst, b, h) do { _Pragma("unroll") for (int m = 0; m < 4; ++m) _Pragma("unroll") for (int k = 0; k < 2; ++k) dst[m][k] = *(const LAS bf16x8*)(lds + PG8_SA(b, h) + aoff + m * 2048 + k * 1024); } while (0)
; #define PG8_LDB(dst, b, h) do { _Pragma("unroll") for (int n = 0; n < 2; ++n) _Pragma("unroll") for (int k = 0; k < 2; ++k) dst[n][k] = *(const LAS bf16x8*)(lds + PG8_SB(b, h) + boff + n * 2048 + k * 1024); } while (0)
; #define PG8_WAIT_V(n) asm volatile("s_waitcnt vmcnt(" #n ")" ::: "memory")
; #define PG8_WAIT_L(n) asm volatile("s_waitcnt lgkmcnt(" #n ")" ::: "memory")
; template <class Epi, class Sched>
; __device__ __forceinline__ void gemm_phase(int wv, LAS unsigned char* lds, const Gemm g, const Sched& S, const Epi& E) { LIDS
;     ...
;             PG8_LDB(B0, 0, 0); PG8_SCHED; PG8_LDA(At, 0, 0); PG8_STAGE(PG8_SA(1, 1), a1 + hstepA, voffA);
;             PG8_WAIT_L(8); PG8_BAR; PG8_WAIT_L(0); PG8_MMA(0, 0, At, B0); PG8_BAR; PG8_SCHED;
;             PG8_LDB(B1, 0, 1); PG8_STAGE(PG8_SB(0, 0), b2, voffB);
;             PG8_BAR; PG8_WAIT_L(0); PG8_MMA(0, 1, At, B1); PG8_BAR;
;             PG8_LDA(At, 0, 1); PG8_STAGE(PG8_SA(0, 0), a2, voffA);
;             PG8_BAR; PG8_WAIT_L(0); PG8_MMA(1, 0, At, B0); PG8_BAR; PG8_SCHED;
;             PG8_STAGE(PG8_SB(0, 1), b2 + hstepB, voffB);
;             PG8_WAIT_V(6); PG8_BAR; PG8_MMA(1, 1, At, B1); PG8_BAR;
;             PG8_LDB(B0, 1, 0); PG8_SCHED; PG8_LDA(At, 1, 0); PG8_STAGE(PG8_SA(0, 1), a2 + hstepA, voffA);
;             PG8_WAIT_L(8); PG8_BAR; PG8_WAIT_L(0); PG8_MMA(0, 0, At, B0); PG8_BAR; PG8_SCHED;
;             PG8_LDB(B1, 1, 1); PG8_STAGE(PG8_SB(1, 0), b3, voffB);
;             PG8_BAR; PG8_WAIT_L(0); PG8_MMA(0, 1, At, B1); PG8_BAR;
;             PG8_LDA(At, 1, 1); PG8_STAGE(PG8_SA(1, 0), a3, voffA);
;             PG8_BAR; PG8_WAIT_L(0); PG8_MMA(1, 0, At, B0); PG8_BAR; PG8_SCHED;
;             PG8_STAGE(PG8_SB(1, 1), b3 + hstepB, voffB);
;             PG8_WAIT_V(6); PG8_BAR; PG8_MMA(1, 1, At, B1); PG8_BAR;
	s_mov_b64 s[78:79], s[72:73]
	s_mov_b32 m0, s70
	v_lshl_add_u64 v[86:87], s[78:79], 0, v[6:7]
	s_add_u32 s78, s72, 0x8000
	s_addc_u32 s79, s73, 0
	global_load_lds_dwordx4 v[86:87], off
	s_mov_b32 m0, s58
	v_lshl_add_u64 v[86:87], s[78:79], 0, v[6:7]
	global_load_lds_dwordx4 v[86:87], off
	s_barrier
	s_waitcnt lgkmcnt(0)
	s_setprio 1
	s_setprio 0
	s_mov_b64 s[78:79], s[68:69]
	s_barrier
	ds_read_b128 v[86:89], v9 offset:16384
	ds_read_b128 v[94:97], v9 offset:17408
	ds_read_b128 v[98:101], v9 offset:18432
	ds_read_b128 v[102:105], v9 offset:19456
	ds_read_b128 v[106:109], v9 offset:20480
	ds_read_b128 v[110:113], v9 offset:21504
	ds_read_b128 v[114:117], v9 offset:22528
	ds_read_b128 v[118:121], v9 offset:23552
	s_mov_b32 m0, s20
	v_lshl_add_u64 v[122:123], s[78:79], 0, v[4:5]
	s_add_u32 s78, s68, 0xc000
	s_addc_u32 s79, s69, 0
	global_load_lds_dwordx4 v[122:123], off
	s_mov_b32 m0, s22
	v_lshl_add_u64 v[122:123], s[78:79], 0, v[4:5]
	global_load_lds_dwordx4 v[122:123], off
	s_barrier
	s_waitcnt lgkmcnt(0)
	s_setprio 1
	v_mfma_f32_16x16x32_bf16 v[90:93], v[18:21], v[86:89], v[90:93]
	v_mfma_f32_16x16x32_bf16 v[54:57], v[78:81], v[86:89], v[54:57]
	v_mfma_f32_16x16x32_bf16 v[62:65], v[18:21], v[98:101], v[62:65]
	v_mfma_f32_16x16x32_bf16 v[66:69], v[78:81], v[98:101], v[66:69]
	v_mfma_f32_16x16x32_bf16 v[70:73], v[18:21], v[106:109], v[70:73]
	v_mfma_f32_16x16x32_bf16 v[74:77], v[78:81], v[106:109], v[74:77]
	v_mfma_f32_16x16x32_bf16 v[10:13], v[18:21], v[114:117], v[10:13]
	v_mfma_f32_16x16x32_bf16 v[14:17], v[78:81], v[114:117], v[14:17]
	v_mfma_f32_16x16x32_bf16 v[90:93], v[22:25], v[94:97], v[90:93]
	v_mfma_f32_16x16x32_bf16 v[54:57], v[82:85], v[94:97], v[54:57]
	v_mfma_f32_16x16x32_bf16 v[62:65], v[22:25], v[102:105], v[62:65]
	v_mfma_f32_16x16x32_bf16 v[66:69], v[82:85], v[102:105], v[66:69]
	v_mfma_f32_16x16x32_bf16 v[70:73], v[22:25], v[110:113], v[70:73]
	v_mfma_f32_16x16x32_bf16 v[74:77], v[82:85], v[110:113], v[74:77]
	v_mfma_f32_16x16x32_bf16 v[10:13], v[22:25], v[118:121], v[10:13]
	v_mfma_f32_16x16x32_bf16 v[14:17], v[82:85], v[118:121], v[14:17]
	s_setprio 0
	s_barrier
	s_add_u32 s78, s72, 0x10000
	s_addc_u32 s79, s73, 0
	s_add_u32 s72, s72, 0x18000
	s_mov_b32 m0, s23
	s_addc_u32 s73, s73, 0
	v_lshl_add_u64 v[18:19], s[78:79], 0, v[6:7]
	global_load_lds_dwordx4 v[18:19], off
	s_mov_b32 m0, s24
	v_lshl_add_u64 v[18:19], s[72:73], 0, v[6:7]
	global_load_lds_dwordx4 v[18:19], off
	s_waitcnt vmcnt(6)
	s_barrier
	s_setprio 1
	s_setprio 0
	s_barrier
	ds_read_b128 v[18:21], v125
	ds_read_b128 v[22:25], v125 offset:1024
	ds_read_b128 v[78:81], v125 offset:2048
	ds_read_b128 v[82:85], v125 offset:3072
	s_add_u32 s72, s68, 0x18000
	s_addc_u32 s73, s69, 0
	s_add_u32 s68, s68, 0x24000
	s_mov_b32 m0, s25
	ds_read_b128 v[86:89], v9 offset:32768
	ds_read_b128 v[94:97], v9 offset:33792
	ds_read_b128 v[98:101], v9 offset:34816
	ds_read_b128 v[102:105], v9 offset:35840
	ds_read_b128 v[106:109], v9 offset:36864
	ds_read_b128 v[110:113], v9 offset:37888
	ds_read_b128 v[114:117], v9 offset:38912
	ds_read_b128 v[118:121], v9 offset:39936
	s_addc_u32 s69, s69, 0
	v_lshl_add_u64 v[122:123], s[72:73], 0, v[4:5]
	global_load_lds_dwordx4 v[122:123], off
	s_mov_b32 m0, s26
	v_lshl_add_u64 v[122:123], s[68:69], 0, v[4:5]
	global_load_lds_dwordx4 v[122:123], off
	s_waitcnt lgkmcnt(8)
	s_barrier
	s_waitcnt lgkmcnt(0)
	s_setprio 1
	v_mfma_f32_16x16x32_bf16 v[58:61], v[18:21], v[86:89], v[58:61]
	v_mfma_f32_16x16x32_bf16 v[26:29], v[78:81], v[86:89], v[26:29]
	v_mfma_f32_16x16x32_bf16 v[30:33], v[18:21], v[98:101], v[30:33]
	v_mfma_f32_16x16x32_bf16 v[34:37], v[78:81], v[98:101], v[34:37]
	v_mfma_f32_16x16x32_bf16 v[38:41], v[18:21], v[106:109], v[38:41]
	v_mfma_f32_16x16x32_bf16 v[42:45], v[78:81], v[106:109], v[42:45]
	v_mfma_f32_16x16x32_bf16 v[46:49], v[18:21], v[114:117], v[46:49]
	v_mfma_f32_16x16x32_bf16 v[50:53], v[78:81], v[114:117], v[50:53]
	v_mfma_f32_16x16x32_bf16 v[58:61], v[22:25], v[94:97], v[58:61]
	v_mfma_f32_16x16x32_bf16 v[26:29], v[82:85], v[94:97], v[26:29]
	v_mfma_f32_16x16x32_bf16 v[30:33], v[22:25], v[102:105], v[30:33]
	v_mfma_f32_16x16x32_bf16 v[34:37], v[82:85], v[102:105], v[34:37]
	v_mfma_f32_16x16x32_bf16 v[38:41], v[22:25], v[110:113], v[38:41]
	v_mfma_f32_16x16x32_bf16 v[42:45], v[82:85], v[110:113], v[42:45]
	v_mfma_f32_16x16x32_bf16 v[46:49], v[22:25], v[118:121], v[46:49]
	v_mfma_f32_16x16x32_bf16 v[50:53], v[82:85], v[118:121], v[50:53]
	s_setprio 0
	s_barrier
	s_mov_b64 s[68:69], s[84:85]
	s_mov_b32 m0, s76
	v_lshl_add_u64 v[86:87], s[68:69], 0, v[6:7]
	s_add_u32 s68, s84, 0x8000
	s_addc_u32 s69, s85, 0
	global_load_lds_dwordx4 v[86:87], off
	s_mov_b32 m0, s59
	v_lshl_add_u64 v[86:87], s[68:69], 0, v[6:7]
	global_load_lds_dwordx4 v[86:87], off
	s_barrier
	s_waitcnt lgkmcnt(0)
	s_setprio 1
	s_setprio 0
	s_mov_b64 s[58:59], s[86:87]
	s_barrier
	ds_read_b128 v[86:89], v9 offset:49152
	ds_read_b128 v[94:97], v9 offset:50176
	ds_read_b128 v[98:101], v9 offset:51200
	ds_read_b128 v[102:105], v9 offset:52224
	ds_read_b128 v[106:109], v9 offset:53248
	ds_read_b128 v[110:113], v9 offset:54272
	ds_read_b128 v[114:117], v9 offset:55296
	ds_read_b128 v[118:121], v9 offset:56320
	s_mov_b32 m0, s29
	v_lshl_add_u64 v[122:123], s[58:59], 0, v[4:5]
	s_add_u32 s58, s86, 0xc000
	s_addc_u32 s59, s87, 0
	global_load_lds_dwordx4 v[122:123], off
	s_mov_b32 m0, s30
	v_lshl_add_u64 v[122:123], s[58:59], 0, v[4:5]
	global_load_lds_dwordx4 v[122:123], off
	s_barrier
; __device__ __forceinline__ size_t erow_off(int R) { return (size_t)(R >> 2) * 1024 + 512 + (size_t)(R & 3) * 128; }
; __device__ __forceinline__ int lane_id_asm() { int x; asm volatile("v_mbcnt_lo_u32_b32 %0, -1, 0\n\tv_mbcnt_hi_u32_b32 %0, -1, %0" : "=&v"(x)); return x; }
; #define PG8_MMA(ai, bj, At, Bt) do { __builtin_amdgcn_s_setprio(1); _Pragma("unroll") for (int m = 0; m < 4; ++m) _Pragma("unroll") for (int n = 0; n < 2; ++n) _Pragma("unroll") for (int k = 0; k < 2; ++k) \
;         acc[ai][bj][m][n] = __builtin_amdgcn_mfma_f32_16x16x32_bf16(Bt[n][k], At[m][k], acc[ai][bj][m][n], 0, 0, 0); __builtin_amdgcn_s_setprio(0); } while (0)
; #define PG8_WAIT_V(n) asm volatile("s_waitcnt vmcnt(" #n ")" ::: "memory")
; #define PG8_BAR __builtin_amdgcn_s_barrier()
; template <class Epi, class Sched>
; __device__ __forceinline__ void gemm_phase(int wv, LAS unsigned char* lds, const Gemm g, const Sched& S, const Epi& E) { LIDS
;     ...
;             PG8_WAIT_V(6); PG8_BAR; PG8_MMA(1, 1, At, B1); PG8_BAR;
;         }
;         { const int l2 = lane_id_asm(); E(acc, cur, wr, wc, l2 & 15, l2 >> 4); }
;         if (!has_next) break;
;     __device__ __forceinline__ void operator()(const AccT& acc, const Unit& u, int wr, int wc, int fr, int fq) const {
;         const int row0 = u.pm * BM + wr * 64 + fr, cc = wc * 32 + 8 * fq;
; #pragma unroll
;         for (int ai = 0; ai < 2; ++ai)
; #pragma unroll
;             for (int m = 0; m < 4; ++m) {
;                 const int row = row0 + ai * HALF + m * 16;
;                 *(f32x4*)(Ebuf + erow_off(row) + cc) = acc[ai][0][m][0]; *(f32x4*)(Ebuf + erow_off(row) + cc + 4) = acc[ai][0][m][1];
;             }
	s_waitcnt lgkmcnt(0)
	s_setprio 1
	v_mfma_f32_16x16x32_bf16 v[90:93], v[18:21], v[86:89], v[90:93]
	v_mfma_f32_16x16x32_bf16 v[54:57], v[78:81], v[86:89], v[54:57]
	v_mfma_f32_16x16x32_bf16 v[62:65], v[18:21], v[98:101], v[62:65]
	v_mfma_f32_16x16x32_bf16 v[66:69], v[78:81], v[98:101], v[66:69]
	v_mfma_f32_16x16x32_bf16 v[70:73], v[18:21], v[106:109], v[70:73]
	v_mfma_f32_16x16x32_bf16 v[74:77], v[78:81], v[106:109], v[74:77]
	v_mfma_f32_16x16x32_bf16 v[10:13], v[18:21], v[114:117], v[10:13]
	v_mfma_f32_16x16x32_bf16 v[14:17], v[78:81], v[114:117], v[14:17]
	v_mfma_f32_16x16x32_bf16 v[90:93], v[22:25], v[94:97], v[90:93]
	v_mfma_f32_16x16x32_bf16 v[54:57], v[82:85], v[94:97], v[54:57]
	v_mfma_f32_16x16x32_bf16 v[62:65], v[22:25], v[102:105], v[62:65]
	v_mfma_f32_16x16x32_bf16 v[66:69], v[82:85], v[102:105], v[66:69]
	v_mfma_f32_16x16x32_bf16 v[70:73], v[22:25], v[110:113], v[70:73]
	v_mfma_f32_16x16x32_bf16 v[74:77], v[82:85], v[110:113], v[74:77]
	v_mfma_f32_16x16x32_bf16 v[10:13], v[22:25], v[118:121], v[10:13]
	v_mfma_f32_16x16x32_bf16 v[14:17], v[82:85], v[118:121], v[14:17]
	s_setprio 0
	s_barrier
	s_add_u32 s58, s84, 0x10000
	s_addc_u32 s59, s85, 0
	s_mov_b32 m0, s31
	v_lshl_add_u64 v[18:19], s[58:59], 0, v[6:7]
	s_add_u32 s58, s84, 0x18000
	s_addc_u32 s59, s85, 0
	global_load_lds_dwordx4 v[18:19], off
	s_mov_b32 m0, s52
	v_lshl_add_u64 v[18:19], s[58:59], 0, v[6:7]
	global_load_lds_dwordx4 v[18:19], off
	s_waitcnt vmcnt(6)
	s_barrier
	s_setprio 1
	s_setprio 0
	s_lshl_b32 s9, s21, 8
	s_add_i32 s9, s9, s27
	s_barrier
	v_mbcnt_lo_u32_b32 v24, -1, 0
	v_mbcnt_hi_u32_b32 v24, -1, v24
	v_readlane_b32 s58, v254, 50
	v_and_or_b32 v25, v24, 15, s9
	v_ashrrev_i32_e32 v18, 1, v24
	v_ashrrev_i32_e32 v20, 2, v25
	v_and_b32_e32 v18, -8, v18
	v_ashrrev_i32_e32 v21, 31, v20
	v_add_u32_e32 v18, s28, v18
	v_lshlrev_b64 v[22:23], 12, v[20:21]
	v_readlane_b32 s59, v254, 51
	v_lshlrev_b32_e32 v21, 9, v24
	v_ashrrev_i32_e32 v19, 31, v18
	v_lshl_add_u64 v[22:23], s[58:59], 0, v[22:23]
	v_and_b32_e32 v176, 0x600, v21
	v_lshl_add_u64 v[22:23], v[22:23], 0, v[176:177]
	v_lshlrev_b64 v[18:19], 2, v[18:19]
	v_lshl_add_u64 v[22:23], v[22:23], 0, v[18:19]
	global_store_dwordx4 v[22:23], v[58:61], off offset:2048
	global_store_dwordx4 v[22:23], v[26:29], off offset:2064
	v_or_b32_e32 v22, 4, v20
	v_ashrrev_i32_e32 v23, 31, v22
	v_lshlrev_b64 v[22:23], 12, v[22:23]
	v_lshl_add_u64 v[22:23], s[58:59], 0, v[22:23]
	v_lshl_add_u64 v[22:23], v[22:23], 0, v[176:177]
	v_lshl_add_u64 v[22:23], v[22:23], 0, v[18:19]
	global_store_dwordx4 v[22:23], v[30:33], off offset:2048
	global_store_dwordx4 v[22:23], v[34:37], off offset:2064
	v_or_b32_e32 v22, 8, v20
	v_or_b32_e32 v20, 12, v20
	v_ashrrev_i32_e32 v23, 31, v22
	v_ashrrev_i32_e32 v21, 31, v20
	v_lshlrev_b64 v[22:23], 12, v[22:23]
	v_lshlrev_b64 v[20:21], 12, v[20:21]
	v_lshl_add_u64 v[22:23], s[58:59], 0, v[22:23]
	v_lshl_add_u64 v[20:21], s[58:59], 0, v[20:21]
	v_lshl_add_u64 v[22:23], v[22:23], 0, v[176:177]
	v_lshl_add_u64 v[20:21], v[20:21], 0, v[176:177]
	v_lshl_add_u64 v[22:23], v[22:23], 0, v[18:19]
	v_lshl_add_u64 v[20:21], v[20:21], 0, v[18:19]
	global_store_dwordx4 v[22:23], v[38:41], off offset:2048
	global_store_dwordx4 v[22:23], v[42:45], off offset:2064
	global_store_dwordx4 v[20:21], v[46:49], off offset:2048
	global_store_dwordx4 v[20:21], v[50:53], off offset:2064
	v_add_u32_e32 v20, 0x80, v25
	v_ashrrev_i32_e32 v20, 2, v20
	v_ashrrev_i32_e32 v21, 31, v20
	v_lshlrev_b64 v[20:21], 12, v[20:21]
	v_lshl_add_u64 v[20:21], s[58:59], 0, v[20:21]
	v_lshl_add_u64 v[20:21], v[20:21], 0, v[176:177]
	v_lshl_add_u64 v[20:21], v[20:21], 0, v[18:19]
	global_store_dwordx4 v[20:21], v[90:93], off offset:2048
	global_store_dwordx4 v[20:21], v[54:57], off offset:2064
	v_add_u32_e32 v20, 0x90, v25
	v_ashrrev_i32_e32 v20, 2, v20
	v_ashrrev_i32_e32 v21, 31, v20
	v_lshlrev_b64 v[20:21], 12, v[20:21]
	v_lshl_add_u64 v[20:21], s[58:59], 0, v[20:21]
	v_lshl_add_u64 v[20:21], v[20:21], 0, v[176:177]
	v_lshl_add_u64 v[20:21], v[20:21], 0, v[18:19]
	global_store_dwordx4 v[20:21], v[62:65], off offset:2048
	global_store_dwordx4 v[20:21], v[66:69], off offset:2064
	v_add_u32_e32 v20, 0xa0, v25
	v_ashrrev_i32_e32 v20, 2, v20
	v_ashrrev_i32_e32 v21, 31, v20
	v_lshlrev_b64 v[20:21], 12, v[20:21]
	v_lshl_add_u64 v[20:21], s[58:59], 0, v[20:21]
	v_lshl_add_u64 v[20:21], v[20:21], 0, v[176:177]
	v_lshl_add_u64 v[20:21], v[20:21], 0, v[18:19]
	global_store_dwordx4 v[20:21], v[70:73], off offset:2048
	global_store_dwordx4 v[20:21], v[74:77], off offset:2064
	v_add_u32_e32 v20, 0xb0, v25
	v_ashrrev_i32_e32 v20, 2, v20
	v_ashrrev_i32_e32 v21, 31, v20
	v_lshlrev_b64 v[20:21], 12, v[20:21]
	v_lshl_add_u64 v[20:21], s[58:59], 0, v[20:21]
	v_lshl_add_u64 v[20:21], v[20:21], 0, v[176:177]
	v_readlane_b32 s58, v253, 14
	v_lshl_add_u64 v[18:19], v[20:21], 0, v[18:19]
	s_add_i32 s55, s55, -1
	s_add_i32 s56, s56, s0
	s_andn2_b64 vcc, exec, s[10:11]
	s_mov_b32 s21, s57
	s_mov_b64 s[86:87], s[62:63]
	s_mov_b64 s[78:79], s[12:13]
	v_readlane_b32 s10, v254, 38
	v_readlane_b32 s12, v254, 40
	v_readlane_b32 s62, v254, 46
	v_readlane_b32 s59, v253, 15
	v_readlane_b32 s70, v254, 52
	global_store_dwordx4 v[18:19], v[10:13], off offset:2048
	global_store_dwordx4 v[18:19], v[14:17], off offset:2064
	v_readlane_b32 s11, v254, 39
	v_readlane_b32 s13, v254, 41
	v_readlane_b32 s63, v254, 47
	s_cbranch_vccz .LBB0_214

; #define PG8_STAGE(bufoff, gbase, voff) do { _Pragma("unroll") for (int _i = 0; _i < 2; ++_i) { const char* _gb = (const char*)(gbase) + (size_t)_i * (voff##_q); asm volatile("" : "+s"(_gb)); \
;         __builtin_amdgcn_global_load_lds((const unsigned*)(_gb + (voff)), (LAS unsigned*)(lds + (bufoff) + ldsw + _i * 8192), 16, 0, 0); } } while (0)
; #define PG8_LDA(dst, b, h) do { _Pragma("unroll") for (int m = 0; m < 4; ++m) _Pragma("unroll") for (int k = 0; k < 2; ++k) dst[m][k] = *(const LAS bf16x8*)(lds + PG8_SA(b, h) + aoff + m * 2048 + k * 1024); } while (0)
; #define PG8_LDB(dst, b, h) do { _Pragma("unroll") for (int n = 0; n < 2; ++n) _Pragma("unroll") for (int k = 0; k < 2; ++k) dst[n][k] = *(const LAS bf16x8*)(lds + PG8_SB(b, h) + boff + n * 2048 + k * 1024); } while (0)
; #define PG8_WAIT_V(n) asm volatile("s_waitcnt vmcnt(" #n ")" ::: "memory")
; #define PG8_WAIT_L(n) asm volatile("s_waitcnt lgkmcnt(" #n ")" ::: "memory")
; template <class Epi, class Sched>
; __device__ __forceinline__ void gemm_phase(int wv, LAS unsigned char* lds, const Gemm g, const Sched& S, const Epi& E) { LIDS
;     ...
;             PG8_LDB(B0, 0, 0); PG8_SCHED; PG8_LDA(At, 0, 0); PG8_STAGE(PG8_SA(1, 1), a1 + hstepA, voffA);
;             PG8_WAIT_L(8); PG8_BAR; PG8_WAIT_L(0); PG8_MMA(0, 0, At, B0); PG8_BAR; PG8_SCHED;
;             PG8_LDB(B1, 0, 1); PG8_STAGE(PG8_SB(0, 0), b2, voffB);
;             PG8_BAR; PG8_WAIT_L(0); PG8_MMA(0, 1, At, B1); PG8_BAR;
;             PG8_LDA(At, 0, 1); PG8_STAGE(PG8_SA(0, 0), a2, voffA);
;             PG8_BAR; PG8_WAIT_L(0); PG8_MMA(1, 0, At, B0); PG8_BAR; PG8_SCHED;
;             PG8_STAGE(PG8_SB(0, 1), b2 + hstepB, voffB);
;             PG8_WAIT_V(6); PG8_BAR; PG8_MMA(1, 1, At, B1); PG8_BAR;
;             PG8_LDB(B0, 1, 0); PG8_SCHED; PG8_LDA(At, 1, 0); PG8_STAGE(PG8_SA(0, 1), a2 + hstepA, voffA);
;             PG8_WAIT_L(8); PG8_BAR; PG8_WAIT_L(0); PG8_MMA(0, 0, At, B0); PG8_BAR; PG8_SCHED;
;             PG8_LDB(B1, 1, 1); PG8_STAGE(PG8_SB(1, 0), b3, voffB);
;             PG8_BAR; PG8_WAIT_L(0); PG8_MMA(0, 1, At, B1); PG8_BAR;
;             PG8_LDA(At, 1, 1); PG8_STAGE(PG8_SA(1, 0), a3, voffA);
;             PG8_BAR; PG8_WAIT_L(0); PG8_MMA(1, 0, At, B0); PG8_BAR; PG8_SCHED;
;             PG8_STAGE(PG8_SB(1, 1), b3 + hstepB, voffB);
;             PG8_WAIT_V(6); PG8_BAR; PG8_MMA(1, 1, At, B1); PG8_BAR;
.LBB0_345:
	s_add_u32 s22, s8, 0x80
	s_addc_u32 s23, s9, 0
	s_add_u32 s8, s8, 0x100
	s_addc_u32 s9, s9, 0
	s_cmp_eq_u32 s20, 28
	s_cselect_b32 s84, s7, s8
	s_cselect_b32 s85, s0, s9
	s_cselect_b32 s89, s13, s19
	s_cselect_b32 s88, s17, s18
	s_add_u32 s86, s84, 0x80
	s_addc_u32 s87, s85, 0
	s_add_u32 s10, s88, 0x80
	s_addc_u32 s11, s89, 0
	s_add_i32 s21, 16, 0x10000
	v_add_u32_e32 v147, s21, v145
	ds_read_b128 v[128:131], v147
	ds_read_b128 v[136:139], v147 offset:1024
	ds_read_b128 v[140:143], v147 offset:2048
	ds_read_b128 v[148:151], v147 offset:3072
	s_add_u32 s24, s22, 0x80000
	s_addc_u32 s25, s23, 0
	s_add_i32 m0, s59, 0xc000
	s_add_u32 s22, s22, 0xc0000
	ds_read_b128 v[152:155], v146
	ds_read_b128 v[156:159], v146 offset:1024
	ds_read_b128 v[160:163], v146 offset:2048
	ds_read_b128 v[164:167], v146 offset:3072
	ds_read_b128 v[168:171], v146 offset:4096
	ds_read_b128 v[172:175], v146 offset:5120
	ds_read_b128 v[194:197], v146 offset:6144
	ds_read_b128 v[198:201], v146 offset:7168
	s_addc_u32 s23, s23, 0
	v_lshl_add_u64 v[178:179], s[24:25], 0, v[132:133]
	global_load_lds_dwordx4 v[178:179], off
	s_add_i32 m0, s59, 0xe000
	v_lshl_add_u64 v[178:179], s[22:23], 0, v[132:133]
	global_load_lds_dwordx4 v[178:179], off
	s_waitcnt lgkmcnt(8)
	s_barrier
	s_waitcnt lgkmcnt(0)
	s_setprio 1
	v_mfma_f32_16x16x32_bf16 v[124:127], v[128:131], v[152:155], v[124:127]
	v_mfma_f32_16x16x32_bf16 v[120:123], v[140:143], v[152:155], v[120:123]
	v_mfma_f32_16x16x32_bf16 v[108:111], v[128:131], v[160:163], v[108:111]
	v_mfma_f32_16x16x32_bf16 v[104:107], v[140:143], v[160:163], v[104:107]
	v_mfma_f32_16x16x32_bf16 v[92:95], v[128:131], v[168:171], v[92:95]
	v_mfma_f32_16x16x32_bf16 v[88:91], v[140:143], v[168:171], v[88:91]
	v_mfma_f32_16x16x32_bf16 v[76:79], v[128:131], v[194:197], v[76:79]
	v_mfma_f32_16x16x32_bf16 v[72:75], v[140:143], v[194:197], v[72:75]
	v_mfma_f32_16x16x32_bf16 v[124:127], v[136:139], v[156:159], v[124:127]
	v_mfma_f32_16x16x32_bf16 v[120:123], v[148:151], v[156:159], v[120:123]
	v_mfma_f32_16x16x32_bf16 v[108:111], v[136:139], v[164:167], v[108:111]
	v_mfma_f32_16x16x32_bf16 v[104:107], v[148:151], v[164:167], v[104:107]
	v_mfma_f32_16x16x32_bf16 v[92:95], v[136:139], v[172:175], v[92:95]
	v_mfma_f32_16x16x32_bf16 v[88:91], v[148:151], v[172:175], v[88:91]
	v_mfma_f32_16x16x32_bf16 v[76:79], v[136:139], v[198:201], v[76:79]
	v_mfma_f32_16x16x32_bf16 v[72:75], v[148:151], v[198:201], v[72:75]
	s_setprio 0
	s_barrier
	s_add_i32 s24, 16, 0x14000
	v_add_u32_e32 v147, s24, v145
	s_mov_b64 s[22:23], s[88:89]
	ds_read_b128 v[202:205], v147
	ds_read_b128 v[206:209], v147 offset:1024
	ds_read_b128 v[218:221], v147 offset:2048
	ds_read_b128 v[222:225], v147 offset:3072
	s_add_i32 s21, s21, s58
	v_lshl_add_u64 v[178:179], s[22:23], 0, v[134:135]
	s_add_u32 s22, s88, 0x40000
	s_mov_b32 m0, s21
	s_addc_u32 s23, s89, 0
	global_load_lds_dwordx4 v[178:179], off
	s_add_i32 m0, s21, 0x2000
	v_lshl_add_u64 v[178:179], s[22:23], 0, v[134:135]
	global_load_lds_dwordx4 v[178:179], off
	s_barrier
	s_waitcnt lgkmcnt(0)
	s_setprio 1
	v_mfma_f32_16x16x32_bf16 v[116:119], v[202:205], v[152:155], v[116:119]
	v_mfma_f32_16x16x32_bf16 v[112:115], v[218:221], v[152:155], v[112:115]
	v_mfma_f32_16x16x32_bf16 v[100:103], v[202:205], v[160:163], v[100:103]
	v_mfma_f32_16x16x32_bf16 v[96:99], v[218:221], v[160:163], v[96:99]
	v_mfma_f32_16x16x32_bf16 v[84:87], v[202:205], v[168:171], v[84:87]
	v_mfma_f32_16x16x32_bf16 v[80:83], v[218:221], v[168:171], v[80:83]
	v_mfma_f32_16x16x32_bf16 v[68:71], v[202:205], v[194:197], v[68:71]
	v_mfma_f32_16x16x32_bf16 v[64:67], v[218:221], v[194:197], v[64:67]
	v_mfma_f32_16x16x32_bf16 v[116:119], v[206:209], v[156:159], v[116:119]
	v_mfma_f32_16x16x32_bf16 v[112:115], v[222:225], v[156:159], v[112:115]
	v_mfma_f32_16x16x32_bf16 v[100:103], v[206:209], v[164:167], v[100:103]
	v_mfma_f32_16x16x32_bf16 v[96:99], v[222:225], v[164:167], v[96:99]
	v_mfma_f32_16x16x32_bf16 v[84:87], v[206:209], v[172:175], v[84:87]
	v_mfma_f32_16x16x32_bf16 v[80:83], v[222:225], v[172:175], v[80:83]
	v_mfma_f32_16x16x32_bf16 v[68:71], v[206:209], v[198:201], v[68:71]
	v_mfma_f32_16x16x32_bf16 v[64:67], v[222:225], v[198:201], v[64:67]
	s_setprio 0
	s_mov_b64 s[22:23], s[84:85]
	s_barrier
	ds_read_b128 v[152:155], v146 offset:16384
	ds_read_b128 v[156:159], v146 offset:17408
	ds_read_b128 v[160:163], v146 offset:18432
	ds_read_b128 v[164:167], v146 offset:19456
	ds_read_b128 v[168:171], v146 offset:20480
	ds_read_b128 v[172:175], v146 offset:21504
	ds_read_b128 v[194:197], v146 offset:22528
	ds_read_b128 v[198:201], v146 offset:23552
	s_mov_b32 m0, s59
	v_lshl_add_u64 v[178:179], s[22:23], 0, v[132:133]
	s_add_u32 s22, s84, 0x40000
	s_addc_u32 s23, s85, 0
	global_load_lds_dwordx4 v[178:179], off
	s_mov_b32 m0, s94
	v_lshl_add_u64 v[178:179], s[22:23], 0, v[132:133]
	global_load_lds_dwordx4 v[178:179], off
	s_barrier
	s_waitcnt lgkmcnt(0)
	s_setprio 1
	v_mfma_f32_16x16x32_bf16 v[60:63], v[128:131], v[152:155], v[60:63]
	v_mfma_f32_16x16x32_bf16 v[56:59], v[140:143], v[152:155], v[56:59]
	v_mfma_f32_16x16x32_bf16 v[44:47], v[128:131], v[160:163], v[44:47]
	v_mfma_f32_16x16x32_bf16 v[40:43], v[140:143], v[160:163], v[40:43]
	v_mfma_f32_16x16x32_bf16 v[28:31], v[128:131], v[168:171], v[28:31]
	v_mfma_f32_16x16x32_bf16 v[24:27], v[140:143], v[168:171], v[24:27]
	v_mfma_f32_16x16x32_bf16 v[12:15], v[128:131], v[194:197], v[12:15]
	v_mfma_f32_16x16x32_bf16 v[8:11], v[140:143], v[194:197], v[8:11]
	v_mfma_f32_16x16x32_bf16 v[60:63], v[136:139], v[156:159], v[60:63]
	v_mfma_f32_16x16x32_bf16 v[56:59], v[148:151], v[156:159], v[56:59]
	v_mfma_f32_16x16x32_bf16 v[44:47], v[136:139], v[164:167], v[44:47]
	v_mfma_f32_16x16x32_bf16 v[40:43], v[148:151], v[164:167], v[40:43]
	v_mfma_f32_16x16x32_bf16 v[28:31], v[136:139], v[172:175], v[28:31]
	v_mfma_f32_16x16x32_bf16 v[24:27], v[148:151], v[172:175], v[24:27]
	v_mfma_f32_16x16x32_bf16 v[12:15], v[136:139], v[198:201], v[12:15]
	v_mfma_f32_16x16x32_bf16 v[8:11], v[148:151], v[198:201], v[8:11]
	s_setprio 0
	s_barrier
; #define PG8_STAGE(bufoff, gbase, voff) do { _Pragma("unroll") for (int _i = 0; _i < 2; ++_i) { const char* _gb = (const char*)(gbase) + (size_t)_i * (voff##_q); asm volatile("" : "+s"(_gb)); \
;         __builtin_amdgcn_global_load_lds((const unsigned*)(_gb + (voff)), (LAS unsigned*)(lds + (bufoff) + ldsw + _i * 8192), 16, 0, 0); } } while (0)
; #define PG8_LDA(dst, b, h) do { _Pragma("unroll") for (int m = 0; m < 4; ++m) _Pragma("unroll") for (int k = 0; k < 2; ++k) dst[m][k] = *(const LAS bf16x8*)(lds + PG8_SA(b, h) + aoff + m * 2048 + k * 1024); } while (0)
; #define PG8_LDB(dst, b, h) do { _Pragma("unroll") for (int n = 0; n < 2; ++n) _Pragma("unroll") for (int k = 0; k < 2; ++k) dst[n][k] = *(const LAS bf16x8*)(lds + PG8_SB(b, h) + boff + n * 2048 + k * 1024); } while (0)
; #define PG8_WAIT_V(n) asm volatile("s_waitcnt vmcnt(" #n ")" ::: "memory")
; #define PG8_WAIT_L(n) asm volatile("s_waitcnt lgkmcnt(" #n ")" ::: "memory")
; template <class Epi, class Sched>
; __device__ __forceinline__ void gemm_phase(int wv, LAS unsigned char* lds, const Gemm g, const Sched& S, const Epi& E) { LIDS
;     ...
;             PG8_LDB(B0, 0, 0); PG8_SCHED; PG8_LDA(At, 0, 0); PG8_STAGE(PG8_SA(1, 1), a1 + hstepA, voffA);
;             PG8_WAIT_L(8); PG8_BAR; PG8_WAIT_L(0); PG8_MMA(0, 0, At, B0); PG8_BAR; PG8_SCHED;
;             PG8_LDB(B1, 0, 1); PG8_STAGE(PG8_SB(0, 0), b2, voffB);
;             PG8_BAR; PG8_WAIT_L(0); PG8_MMA(0, 1, At, B1); PG8_BAR;
;             PG8_LDA(At, 0, 1); PG8_STAGE(PG8_SA(0, 0), a2, voffA);
;             PG8_BAR; PG8_WAIT_L(0); PG8_MMA(1, 0, At, B0); PG8_BAR; PG8_SCHED;
;             PG8_STAGE(PG8_SB(0, 1), b2 + hstepB, voffB);
;             PG8_WAIT_V(6); PG8_BAR; PG8_MMA(1, 1, At, B1); PG8_BAR;
;             PG8_LDB(B0, 1, 0); PG8_SCHED; PG8_LDA(At, 1, 0); PG8_STAGE(PG8_SA(0, 1), a2 + hstepA, voffA);
;             PG8_WAIT_L(8); PG8_BAR; PG8_WAIT_L(0); PG8_MMA(0, 0, At, B0); PG8_BAR; PG8_SCHED;
;             PG8_LDB(B1, 1, 1); PG8_STAGE(PG8_SB(1, 0), b3, voffB);
;             PG8_BAR; PG8_WAIT_L(0); PG8_MMA(0, 1, At, B1); PG8_BAR;
;             PG8_LDA(At, 1, 1); PG8_STAGE(PG8_SA(1, 0), a3, voffA);
;             PG8_BAR; PG8_WAIT_L(0); PG8_MMA(1, 0, At, B0); PG8_BAR; PG8_SCHED;
;             PG8_STAGE(PG8_SB(1, 1), b3 + hstepB, voffB);
;             PG8_WAIT_V(6); PG8_BAR; PG8_MMA(1, 1, At, B1); PG8_BAR;
	s_add_u32 s22, s88, 0x80000
	s_addc_u32 s23, s89, 0
	s_add_i32 s21, s24, s58
	v_lshl_add_u64 v[128:129], s[22:23], 0, v[134:135]
	s_add_u32 s22, s88, 0xc0000
	s_mov_b32 m0, s21
	s_addc_u32 s23, s89, 0
	global_load_lds_dwordx4 v[128:129], off
	s_add_i32 m0, s21, 0x2000
	v_lshl_add_u64 v[128:129], s[22:23], 0, v[134:135]
	global_load_lds_dwordx4 v[128:129], off
	s_waitcnt vmcnt(6)
	s_barrier
	s_setprio 1
	v_mfma_f32_16x16x32_bf16 v[52:55], v[202:205], v[152:155], v[52:55]
	v_mfma_f32_16x16x32_bf16 v[48:51], v[218:221], v[152:155], v[48:51]
	v_mfma_f32_16x16x32_bf16 v[36:39], v[202:205], v[160:163], v[36:39]
	v_mfma_f32_16x16x32_bf16 v[32:35], v[218:221], v[160:163], v[32:35]
	v_mfma_f32_16x16x32_bf16 v[20:23], v[202:205], v[168:171], v[20:23]
	v_mfma_f32_16x16x32_bf16 v[16:19], v[218:221], v[168:171], v[16:19]
	v_mfma_f32_16x16x32_bf16 v[4:7], v[202:205], v[194:197], v[4:7]
	v_mfma_f32_16x16x32_bf16 v[0:3], v[218:221], v[194:197], v[0:3]
	v_mfma_f32_16x16x32_bf16 v[52:55], v[206:209], v[156:159], v[52:55]
	v_mfma_f32_16x16x32_bf16 v[48:51], v[222:225], v[156:159], v[48:51]
	v_mfma_f32_16x16x32_bf16 v[36:39], v[206:209], v[164:167], v[36:39]
	v_mfma_f32_16x16x32_bf16 v[32:35], v[222:225], v[164:167], v[32:35]
	v_mfma_f32_16x16x32_bf16 v[20:23], v[206:209], v[172:175], v[20:23]
	v_mfma_f32_16x16x32_bf16 v[16:19], v[222:225], v[172:175], v[16:19]
	v_mfma_f32_16x16x32_bf16 v[4:7], v[206:209], v[198:201], v[4:7]
	v_mfma_f32_16x16x32_bf16 v[0:3], v[222:225], v[198:201], v[0:3]
	s_setprio 0
	s_add_i32 s21, 16, 0x18000
	v_add_u32_e32 v147, s21, v145
	s_barrier
	ds_read_b128 v[128:131], v147
	ds_read_b128 v[136:139], v147 offset:1024
	ds_read_b128 v[140:143], v147 offset:2048
	ds_read_b128 v[148:151], v147 offset:3072
	s_add_u32 s22, s84, 0x80000
	s_addc_u32 s23, s85, 0
	ds_read_b128 v[152:155], v146 offset:32768
	ds_read_b128 v[156:159], v146 offset:33792
	ds_read_b128 v[160:163], v146 offset:34816
	ds_read_b128 v[164:167], v146 offset:35840
	ds_read_b128 v[168:171], v146 offset:36864
	ds_read_b128 v[172:175], v146 offset:37888
	ds_read_b128 v[194:197], v146 offset:38912
	ds_read_b128 v[198:201], v146 offset:39936
	s_mov_b32 m0, s95
	v_lshl_add_u64 v[178:179], s[22:23], 0, v[132:133]
	s_add_u32 s22, s84, 0xc0000
	s_addc_u32 s23, s85, 0
	global_load_lds_dwordx4 v[178:179], off
	s_mov_b32 m0, s57
	v_lshl_add_u64 v[178:179], s[22:23], 0, v[132:133]
	global_load_lds_dwordx4 v[178:179], off
	s_waitcnt lgkmcnt(8)
	s_barrier
	s_waitcnt lgkmcnt(0)
	s_setprio 1
	v_mfma_f32_16x16x32_bf16 v[124:127], v[128:131], v[152:155], v[124:127]
	v_mfma_f32_16x16x32_bf16 v[120:123], v[140:143], v[152:155], v[120:123]
	v_mfma_f32_16x16x32_bf16 v[108:111], v[128:131], v[160:163], v[108:111]
	v_mfma_f32_16x16x32_bf16 v[104:107], v[140:143], v[160:163], v[104:107]
	v_mfma_f32_16x16x32_bf16 v[92:95], v[128:131], v[168:171], v[92:95]
	v_mfma_f32_16x16x32_bf16 v[88:91], v[140:143], v[168:171], v[88:91]
	v_mfma_f32_16x16x32_bf16 v[76:79], v[128:131], v[194:197], v[76:79]
	v_mfma_f32_16x16x32_bf16 v[72:75], v[140:143], v[194:197], v[72:75]
	v_mfma_f32_16x16x32_bf16 v[124:127], v[136:139], v[156:159], v[124:127]
	v_mfma_f32_16x16x32_bf16 v[120:123], v[148:151], v[156:159], v[120:123]
	v_mfma_f32_16x16x32_bf16 v[108:111], v[136:139], v[164:167], v[108:111]
	v_mfma_f32_16x16x32_bf16 v[104:107], v[148:151], v[164:167], v[104:107]
	v_mfma_f32_16x16x32_bf16 v[92:95], v[136:139], v[172:175], v[92:95]
	v_mfma_f32_16x16x32_bf16 v[88:91], v[148:151], v[172:175], v[88:91]
	v_mfma_f32_16x16x32_bf16 v[76:79], v[136:139], v[198:201], v[76:79]
	v_mfma_f32_16x16x32_bf16 v[72:75], v[148:151], v[198:201], v[72:75]
	s_setprio 0
	s_barrier
	s_add_i32 s24, 16, 0x1c000
	v_add_u32_e32 v147, s24, v145
	s_mov_b64 s[22:23], s[10:11]
	ds_read_b128 v[202:205], v147
	ds_read_b128 v[206:209], v147 offset:1024
	ds_read_b128 v[218:221], v147 offset:2048
	ds_read_b128 v[222:225], v147 offset:3072
	s_add_i32 s21, s21, s58
	v_lshl_add_u64 v[178:179], s[22:23], 0, v[134:135]
	s_add_u32 s22, s10, 0x40000
	s_mov_b32 m0, s21
	s_addc_u32 s23, s11, 0
	global_load_lds_dwordx4 v[178:179], off
	s_add_i32 m0, s21, 0x2000
	v_lshl_add_u64 v[178:179], s[22:23], 0, v[134:135]
	global_load_lds_dwordx4 v[178:179], off
	s_barrier
	s_waitcnt lgkmcnt(0)
	s_setprio 1
	v_mfma_f32_16x16x32_bf16 v[116:119], v[202:205], v[152:155], v[116:119]
	v_mfma_f32_16x16x32_bf16 v[112:115], v[218:221], v[152:155], v[112:115]
	v_mfma_f32_16x16x32_bf16 v[100:103], v[202:205], v[160:163], v[100:103]
	v_mfma_f32_16x16x32_bf16 v[96:99], v[218:221], v[160:163], v[96:99]
	v_mfma_f32_16x16x32_bf16 v[84:87], v[202:205], v[168:171], v[84:87]
	v_mfma_f32_16x16x32_bf16 v[80:83], v[218:221], v[168:171], v[80:83]
	v_mfma_f32_16x16x32_bf16 v[68:71], v[202:205], v[194:197], v[68:71]
	v_mfma_f32_16x16x32_bf16 v[64:67], v[218:221], v[194:197], v[64:67]
	v_mfma_f32_16x16x32_bf16 v[116:119], v[206:209], v[156:159], v[116:119]
	v_mfma_f32_16x16x32_bf16 v[112:115], v[222:225], v[156:159], v[112:115]
	v_mfma_f32_16x16x32_bf16 v[100:103], v[206:209], v[164:167], v[100:103]
	v_mfma_f32_16x16x32_bf16 v[96:99], v[222:225], v[164:167], v[96:99]
	v_mfma_f32_16x16x32_bf16 v[84:87], v[206:209], v[172:175], v[84:87]
	v_mfma_f32_16x16x32_bf16 v[80:83], v[222:225], v[172:175], v[80:83]
	v_mfma_f32_16x16x32_bf16 v[68:71], v[206:209], v[198:201], v[68:71]
	v_mfma_f32_16x16x32_bf16 v[64:67], v[222:225], v[198:201], v[64:67]
	s_setprio 0
	s_mov_b64 s[22:23], s[86:87]
	s_barrier
; __device__ __forceinline__ u32x4 pack8(f32x4 a, f32x4 b) { u32x4 r; r[0] = cvt_pk_bf16(a[0], a[1]); r[1] = cvt_pk_bf16(a[2], a[3]); r[2] = cvt_pk_bf16(b[0], b[1]); r[3] = cvt_pk_bf16(b[2], b[3]); return r; }
; #define PG8_STAGE(bufoff, gbase, voff) do { _Pragma("unroll") for (int _i = 0; _i < 2; ++_i) { const char* _gb = (const char*)(gbase) + (size_t)_i * (voff##_q); asm volatile("" : "+s"(_gb)); \
;         __builtin_amdgcn_global_load_lds((const unsigned*)(_gb + (voff)), (LAS unsigned*)(lds + (bufoff) + ldsw + _i * 8192), 16, 0, 0); } } while (0)
; #define PG8_MMA(ai, bj, At, Bt) do { __builtin_amdgcn_s_setprio(1); _Pragma("unroll") for (int m = 0; m < 4; ++m) _Pragma("unroll") for (int n = 0; n < 2; ++n) _Pragma("unroll") for (int k = 0; k < 2; ++k) \
;         acc[ai][bj][m][n] = __builtin_amdgcn_mfma_f32_16x16x32_bf16(Bt[n][k], At[m][k], acc[ai][bj][m][n], 0, 0, 0); __builtin_amdgcn_s_setprio(0); } while (0)
; #define PG8_WAIT_V(n) asm volatile("s_waitcnt vmcnt(" #n ")" ::: "memory")
; #define PG8_BAR __builtin_amdgcn_s_barrier()
; template <class Epi, class Sched>
; __device__ __forceinline__ void gemm_phase(int wv, LAS unsigned char* lds, const Gemm g, const Sched& S, const Epi& E) { LIDS
;     ...
;             PG8_BAR; PG8_WAIT_L(0); PG8_MMA(1, 0, At, B0); PG8_BAR; PG8_SCHED;
;             PG8_STAGE(PG8_SB(1, 1), b3 + hstepB, voffB);
;             PG8_WAIT_V(6); PG8_BAR; PG8_MMA(1, 1, At, B1); PG8_BAR;
;         }
;     __device__ __forceinline__ void operator()(const AccT& acc, const Unit& u, int wr, int wc, int fr, int fq) const {
;         EPI_ROWS(u)
;         const bool do_ss = (u.pn <= 2);
; #pragma unroll
;         for (int ai = 0; ai < 2; ++ai)
; #pragma unroll
;             for (int m = 0; m < 4; ++m) {
;                 const int row = row0 + ai * HALF + m * 16; float ss = 0.f;
; #pragma unroll
;                 for (int bj = 0; bj < 2; ++bj) {
;                     const int col = colbase + bj * HALF; const f32x4 v0 = acc[ai][bj][m][0], v1 = acc[ai][bj][m][1];
;                     const u32x4 pk = pack8(v0, v1);
;                     if (col >= C_U && col < C_GS) { const int ch = col - C_U, gg = ch >> 4, hh = ch & 15;
;                         *(u32x4*)(ucat + ((size_t)(gg * NCH + (row >> 4)) * KCAT + (row & 15) * 16 + hh)) = pk; }
;                     else if (col < NIN_REAL) *(u32x4*)(proj + (size_t)row * NIN + col) = pk;
	ds_read_b128 v[152:155], v146 offset:49152
	ds_read_b128 v[156:159], v146 offset:50176
	ds_read_b128 v[160:163], v146 offset:51200
	ds_read_b128 v[164:167], v146 offset:52224
	ds_read_b128 v[168:171], v146 offset:53248
	ds_read_b128 v[172:175], v146 offset:54272
	ds_read_b128 v[194:197], v146 offset:55296
	ds_read_b128 v[198:201], v146 offset:56320
	s_mov_b32 m0, s82
	v_lshl_add_u64 v[178:179], s[22:23], 0, v[132:133]
	s_add_u32 s22, s86, 0x40000
	s_addc_u32 s23, s87, 0
	global_load_lds_dwordx4 v[178:179], off
	s_mov_b32 m0, s83
	v_lshl_add_u64 v[178:179], s[22:23], 0, v[132:133]
	global_load_lds_dwordx4 v[178:179], off
	s_barrier
	s_waitcnt lgkmcnt(0)
	s_setprio 1
	v_mfma_f32_16x16x32_bf16 v[60:63], v[128:131], v[152:155], v[60:63]
	v_mfma_f32_16x16x32_bf16 v[56:59], v[140:143], v[152:155], v[56:59]
	v_mfma_f32_16x16x32_bf16 v[44:47], v[128:131], v[160:163], v[44:47]
	v_mfma_f32_16x16x32_bf16 v[40:43], v[140:143], v[160:163], v[40:43]
	v_mfma_f32_16x16x32_bf16 v[28:31], v[128:131], v[168:171], v[28:31]
	v_mfma_f32_16x16x32_bf16 v[24:27], v[140:143], v[168:171], v[24:27]
	v_mfma_f32_16x16x32_bf16 v[12:15], v[128:131], v[194:197], v[12:15]
	v_mfma_f32_16x16x32_bf16 v[8:11], v[140:143], v[194:197], v[8:11]
	v_mfma_f32_16x16x32_bf16 v[60:63], v[136:139], v[156:159], v[60:63]
	v_mfma_f32_16x16x32_bf16 v[56:59], v[148:151], v[156:159], v[56:59]
	v_mfma_f32_16x16x32_bf16 v[44:47], v[136:139], v[164:167], v[44:47]
	v_mfma_f32_16x16x32_bf16 v[40:43], v[148:151], v[164:167], v[40:43]
	v_mfma_f32_16x16x32_bf16 v[28:31], v[136:139], v[172:175], v[28:31]
	v_mfma_f32_16x16x32_bf16 v[24:27], v[148:151], v[172:175], v[24:27]
	v_mfma_f32_16x16x32_bf16 v[12:15], v[136:139], v[198:201], v[12:15]
	v_mfma_f32_16x16x32_bf16 v[8:11], v[148:151], v[198:201], v[8:11]
	s_setprio 0
	s_barrier
	s_add_u32 s22, s10, 0x80000
	s_addc_u32 s23, s11, 0
	s_add_i32 s21, s24, s58
	s_add_u32 s10, s10, 0xc0000
	s_mov_b32 m0, s21
	v_lshl_add_u64 v[128:129], s[22:23], 0, v[134:135]
	s_addc_u32 s11, s11, 0
	global_load_lds_dwordx4 v[128:129], off
	s_add_i32 m0, s21, 0x2000
	v_lshl_add_u64 v[128:129], s[10:11], 0, v[134:135]
	global_load_lds_dwordx4 v[128:129], off
	s_waitcnt vmcnt(6)
	s_barrier
	s_setprio 1
	v_mfma_f32_16x16x32_bf16 v[52:55], v[202:205], v[152:155], v[52:55]
	v_mfma_f32_16x16x32_bf16 v[48:51], v[218:221], v[152:155], v[48:51]
	v_mfma_f32_16x16x32_bf16 v[36:39], v[202:205], v[160:163], v[36:39]
	v_mfma_f32_16x16x32_bf16 v[32:35], v[218:221], v[160:163], v[32:35]
	v_mfma_f32_16x16x32_bf16 v[20:23], v[202:205], v[168:171], v[20:23]
	v_mfma_f32_16x16x32_bf16 v[16:19], v[218:221], v[168:171], v[16:19]
	v_mfma_f32_16x16x32_bf16 v[4:7], v[202:205], v[194:197], v[4:7]
	v_mfma_f32_16x16x32_bf16 v[0:3], v[218:221], v[194:197], v[0:3]
	v_mfma_f32_16x16x32_bf16 v[52:55], v[206:209], v[156:159], v[52:55]
	v_mfma_f32_16x16x32_bf16 v[48:51], v[222:225], v[156:159], v[48:51]
	v_mfma_f32_16x16x32_bf16 v[36:39], v[206:209], v[164:167], v[36:39]
	v_mfma_f32_16x16x32_bf16 v[32:35], v[222:225], v[164:167], v[32:35]
	v_mfma_f32_16x16x32_bf16 v[20:23], v[206:209], v[172:175], v[20:23]
	v_mfma_f32_16x16x32_bf16 v[16:19], v[222:225], v[172:175], v[16:19]
	v_mfma_f32_16x16x32_bf16 v[4:7], v[206:209], v[198:201], v[4:7]
	v_mfma_f32_16x16x32_bf16 v[0:3], v[222:225], v[198:201], v[0:3]
	s_setprio 0
	s_add_i32 s20, s20, 2
	s_add_u32 s18, s18, 0x100
	s_addc_u32 s19, s19, 0
	s_cmp_gt_u32 s20, 29
	s_barrier
	s_cbranch_scc0 .LBB0_345
	v_mbcnt_lo_u32_b32 v148, -1, 0
	v_mbcnt_hi_u32_b32 v148, -1, v148
	s_lshl_b32 s0, s6, 8
	s_lshl_b32 s6, s12, 8
	v_ashrrev_i32_e32 v139, 1, v148
	v_and_b32_e32 v138, 15, v148
	s_add_i32 s0, s0, s76
	s_or_b32 s6, s6, s77
	v_and_b32_e32 v128, -8, v139
	v_or_b32_e32 v140, s0, v138
	v_add_u32_e32 v136, s6, v128
	v_ashrrev_i32_e32 v141, 31, v140
	v_add_u32_e32 v137, 0xfffff8c0, v136
	s_movk_i32 s6, 0x3ff
	v_lshlrev_b64 v[142:143], 13, v[140:141]
	v_cmp_lt_u32_e64 s[8:9], s6, v137
	v_cvt_pk_bf16_f32 v128, v124, v125
	v_cvt_pk_bf16_f32 v129, v126, v127
	v_cvt_pk_bf16_f32 v130, v120, v121
	v_cvt_pk_bf16_f32 v131, v122, v123
	s_and_saveexec_b64 s[6:7], s[8:9]
	s_xor_b64 s[6:7], exec, s[6:7]
	s_movk_i32 s17, 0x300
	s_movk_i32 s22, 0xec0
	s_cbranch_execz .LBB0_350
	s_movk_i32 s10, 0xf40
	v_cmp_gt_i32_e32 vcc, s10, v136
	s_and_saveexec_b64 s[10:11], vcc
	s_cbranch_execz .LBB0_349
	v_readlane_b32 s18, v254, 46
	v_readlane_b32 s19, v254, 47
	v_ashrrev_i32_e32 v137, 31, v136
	s_nop 0
	v_lshl_add_u64 v[150:151], s[18:19], 0, v[142:143]
	v_lshl_add_u64 v[150:151], v[136:137], 1, v[150:151]
	global_store_dwordx4 v[150:151], v[128:131], off
